# all GEMM-phase epilogue x2/x4 output stores (in-proj, up, w_out, ff1, ff2, ple) marked nt
# baseline (speedup 1.0000x reference)
; template <class F>
; DI void gemm8_epi_staged(f32x4 (&acc)[8][4], int m0, int n0, bf16_t* L0, F f, bf16_t* dst, size_t ld, int nmax) {
;     ...
; #pragma unroll
;     for (int it = 0; it < 8; ++it) {
;       const int idx = tid + 512 * it;
;       const int row = idx >> 5, ch = idx & 31;
;       const u32x4 v = *(const u32x4*)(L + row * 264 + ch * 8);
;       const int n = n0 + ch * 8;
;       if (n < nmax) *(u32x4*)(dst + (size_t)(m0 + half * 128 + row) * ld + n) = v;
;     }
;     __syncthreads();
.LBB0_772:
	s_or_b64 exec, exec, s[0:1]
	s_waitcnt lgkmcnt(0)
	s_barrier
	ds_read_b128 v[2:5], v141
	v_add_u32_e32 v0, s13, v136
	v_mad_i64_i32 v[6:7], s[0:1], v0, s35, v[132:133]
	v_add_u32_e32 v0, s13, v137
	s_waitcnt lgkmcnt(0)
	global_store_dwordx4 v[6:7], v[2:5], off nt
	ds_read_b128 v[2:5], v142
	v_mad_i64_i32 v[6:7], s[0:1], v0, s35, v[132:133]
	v_add_u32_e32 v0, s13, v143
	s_mov_b64 s[6:7], -1
	s_waitcnt lgkmcnt(0)
	global_store_dwordx4 v[6:7], v[2:5], off nt
	ds_read_b128 v[2:5], v145
	v_mad_i64_i32 v[6:7], s[0:1], v0, s35, v[132:133]
	v_add_u32_e32 v0, s13, v144
	s_andn2_b64 vcc, exec, s[2:3]
	s_waitcnt lgkmcnt(0)
	global_store_dwordx4 v[6:7], v[2:5], off nt
	ds_read_b128 v[2:5], v146
	v_mad_i64_i32 v[6:7], s[0:1], v0, s35, v[132:133]
	v_add_u32_e32 v0, s13, v147
	s_mov_b32 s24, s21
	s_waitcnt lgkmcnt(0)
	global_store_dwordx4 v[6:7], v[2:5], off nt
	ds_read_b128 v[2:5], v149
	v_mad_i64_i32 v[6:7], s[0:1], v0, s35, v[132:133]
	v_add_u32_e32 v0, s13, v148
	s_waitcnt lgkmcnt(0)
	global_store_dwordx4 v[6:7], v[2:5], off nt
	ds_read_b128 v[2:5], v150
	v_mad_i64_i32 v[6:7], s[0:1], v0, s35, v[132:133]
	v_add_u32_e32 v0, s13, v151
	s_waitcnt lgkmcnt(0)
	global_store_dwordx4 v[6:7], v[2:5], off nt
	ds_read_b128 v[2:5], v153
	v_mad_i64_i32 v[6:7], s[0:1], v0, s35, v[132:133]
	v_add_u32_e32 v0, s13, v152
	s_waitcnt lgkmcnt(0)
	global_store_dwordx4 v[6:7], v[2:5], off nt
	ds_read_b128 v[2:5], v154
	v_mad_i64_i32 v[6:7], s[0:1], v0, s35, v[132:133]
	v_readlane_b32 s0, v254, 13
	s_add_i32 s11, s11, s0
	v_readlane_b32 s0, v254, 19
	s_add_i32 s10, s10, s0
	v_readlane_b32 s0, v254, 18
	s_add_i32 s9, s9, s0
	s_waitcnt lgkmcnt(0)
	global_store_dwordx4 v[6:7], v[2:5], off nt
	s_barrier
	s_cbranch_vccz .LBB0_785

; DI float bflo(unsigned u) { return __uint_as_float(u << 16); }
; DI float bfhi(unsigned u) { return __uint_as_float(u & 0xffff0000u); }
; DI float sigmoidf(float x) { return __builtin_amdgcn_rcpf(1.f + __expf(-x)); }
; template <class F>
; DI void gemm8_epi_staged(f32x4 (&acc)[8][4], int m0, int n0, bf16_t* L0, F f, bf16_t* dst, size_t ld, int nmax) {
;     ...
;     if (wm == half) {
; #pragma unroll
;       for (int i = 0; i < 8; ++i)
; #pragma unroll
;         for (int j = 0; j < 4; ++j) {
;           const int ml = i * 16 + (lane & 15);
;           const int nl = wn * 64 + j * 16 + (lane >> 4) * 4;
;           f32x4 a = acc[i][j];
;           f(m0 + half * 128 + ml, n0 + nl, a);
;           uint2 u;
;           u.x = pack2(a[0], a[1]);
;           u.y = pack2(a[2], a[3]);
;           *(uint2*)(L + ml * 264 + nl) = u;
;         }
;     }
;     __syncthreads();
; #pragma unroll
;     for (int it = 0; it < 8; ++it) {
;       const int idx = tid + 512 * it;
;       const int row = idx >> 5, ch = idx & 31;
;       const u32x4 v = *(const u32x4*)(L + row * 264 + ch * 8);
;       const int n = n0 + ch * 8;
;       if (n < nmax) *(u32x4*)(dst + (size_t)(m0 + half * 128 + row) * ld + n) = v;
;     }
;     __syncthreads();
; __global__ void __launch_bounds__(512, 2) mega(Params p) {
;     ...
;       gemm8_epi_staged(acc8, m0, n0, lds_all, [&](int m, int n, f32x4& a) {
;         uint2 ub = *(const uint2*)(z + (size_t)m * ZS + C_MB + n);
;         a[0] *= sigmoidf(bflo(ub.x)); a[1] *= sigmoidf(bfhi(ub.x));
;         a[2] *= sigmoidf(bflo(ub.y)); a[3] *= sigmoidf(bfhi(ub.y));
;       }, z + C_RK, ZS, 1024);
.LBB0_783:
	s_or_b64 exec, exec, s[0:1]
	v_lshlrev_b32_e32 v0, 3, v140
	v_and_b32_e32 v0, 0xf8, v0
	v_or_b32_e32 v131, s12, v0
	v_readlane_b32 s0, v252, 43
	v_lshl_add_u32 v158, v0, 1, s20
	v_lshlrev_b32_e32 v0, 1, v131
	v_readlane_b32 s1, v252, 44
	v_ashrrev_i32_e32 v136, 5, v140
	s_movk_i32 s6, 0x210
	v_lshl_add_u64 v[132:133], s[0:1], 0, v[0:1]
	v_mul_lo_u32 v0, v136, s6
	v_add_u32_e32 v141, v158, v0
	s_waitcnt lgkmcnt(0)
	s_barrier
	ds_read_b128 v[142:145], v141
	v_add_u32_e32 v0, s13, v136
	v_mad_i64_i32 v[134:135], s[0:1], v0, s35, v[132:133]
	v_add_u32_e32 v0, 0x200, v140
	v_ashrrev_i32_e32 v137, 5, v0
	v_mul_lo_u32 v0, v137, s6
	s_waitcnt lgkmcnt(0)
	global_store_dwordx4 v[134:135], v[142:145], off nt
	s_nop 1
	v_add_u32_e32 v142, v158, v0
	ds_read_b128 v[144:147], v142
	v_add_u32_e32 v0, s13, v137
	v_mad_i64_i32 v[134:135], s[0:1], v0, s35, v[132:133]
	v_add_u32_e32 v0, 0x400, v140
	v_ashrrev_i32_e32 v143, 5, v0
	v_mul_lo_u32 v0, v143, s6
	s_waitcnt lgkmcnt(0)
	global_store_dwordx4 v[134:135], v[144:147], off nt
	s_nop 1
	v_add_u32_e32 v145, v158, v0
	ds_read_b128 v[146:149], v145
	v_add_u32_e32 v0, s13, v143
	v_mad_i64_i32 v[134:135], s[0:1], v0, s35, v[132:133]
	v_add_u32_e32 v0, 0x600, v140
	v_ashrrev_i32_e32 v144, 5, v0
	v_mul_lo_u32 v0, v144, s6
	s_waitcnt lgkmcnt(0)
	global_store_dwordx4 v[134:135], v[146:149], off nt
	s_nop 1
	v_add_u32_e32 v146, v158, v0
	ds_read_b128 v[148:151], v146
	v_add_u32_e32 v0, s13, v144
	v_mad_i64_i32 v[134:135], s[0:1], v0, s35, v[132:133]
	v_add_u32_e32 v0, 0x800, v140
	v_ashrrev_i32_e32 v147, 5, v0
	v_mul_lo_u32 v0, v147, s6
	s_waitcnt lgkmcnt(0)
	global_store_dwordx4 v[134:135], v[148:151], off nt
	s_nop 1
	v_add_u32_e32 v149, v158, v0
	ds_read_b128 v[150:153], v149
	v_add_u32_e32 v0, s13, v147
	v_mad_i64_i32 v[134:135], s[0:1], v0, s35, v[132:133]
	v_add_u32_e32 v0, 0xa00, v140
	v_ashrrev_i32_e32 v148, 5, v0
	v_mul_lo_u32 v0, v148, s6
	s_waitcnt lgkmcnt(0)
	global_store_dwordx4 v[134:135], v[150:153], off nt
	s_nop 1
	v_add_u32_e32 v150, v158, v0
	ds_read_b128 v[152:155], v150
	v_add_u32_e32 v0, s13, v148
	v_mad_i64_i32 v[134:135], s[0:1], v0, s35, v[132:133]
	v_add_u32_e32 v0, 0xc00, v140
	v_ashrrev_i32_e32 v151, 5, v0
	v_mul_lo_u32 v0, v151, s6
	s_waitcnt lgkmcnt(0)
	global_store_dwordx4 v[134:135], v[152:155], off nt
	s_nop 1
	v_add_u32_e32 v153, v158, v0
	ds_read_b128 v[154:157], v153
	v_add_u32_e32 v0, s13, v151
	v_mad_i64_i32 v[134:135], s[0:1], v0, s35, v[132:133]
	v_add_u32_e32 v0, 0xe00, v140
	v_ashrrev_i32_e32 v152, 5, v0
	v_mul_lo_u32 v0, v152, s6
	s_waitcnt lgkmcnt(0)
	global_store_dwordx4 v[134:135], v[154:157], off nt
	s_nop 1
	v_add_u32_e32 v154, v158, v0
	ds_read_b128 v[156:159], v154
	v_add_u32_e32 v0, s13, v152
	v_mad_i64_i32 v[134:135], s[0:1], v0, s35, v[132:133]
	v_and_b32_e32 v0, 0xffffff00, v140
	s_movk_i32 s0, 0x100
	v_cmp_eq_u32_e32 vcc, s0, v0
	s_bitset1_b32 s13, 7
	s_waitcnt lgkmcnt(0)
	global_store_dwordx4 v[134:135], v[156:159], off nt
	s_barrier
	s_and_saveexec_b64 s[0:1], vcc
	s_cbranch_execz .LBB0_772
	v_or_b32_e32 v139, s13, v139
	v_mul_u32_u24_e32 v0, 0x2a30, v139
	v_lshl_add_u64 v[134:135], s[16:17], 0, v[0:1]
	s_mov_b64 s[6:7], 0x2230
	v_lshl_add_u64 v[134:135], v[134:135], 0, s[6:7]
	v_mov_b32_e32 v131, v1
	v_lshl_add_u64 v[156:157], v[134:135], 0, v[130:131]
	global_load_dwordx2 v[156:157], v[156:157], off
	s_waitcnt vmcnt(0)
	v_lshlrev_b32_e32 v0, 16, v156
	v_mul_f32_e32 v0, 0xbfb8aa3b, v0
	v_exp_f32_e32 v0, v0
	s_nop 0
	v_add_f32_e32 v0, 1.0, v0
	v_rcp_f32_e32 v158, v0
	v_and_b32_e32 v0, 0xffff0000, v156
	v_mul_f32_e32 v0, 0xbfb8aa3b, v0
	v_exp_f32_e32 v0, v0
	s_nop 0
	v_add_f32_e32 v0, 1.0, v0
	v_rcp_f32_e32 v159, v0
	v_lshlrev_b32_e32 v0, 16, v157
	v_mul_f32_e32 v0, 0xbfb8aa3b, v0
	v_exp_f32_e32 v0, v0
	v_pk_mul_f32 v[126:127], v[126:127], v[158:159]
	v_add_f32_e32 v0, 1.0, v0
	v_rcp_f32_e32 v156, v0
	v_and_b32_e32 v0, 0xffff0000, v157
	v_mul_f32_e32 v0, 0xbfb8aa3b, v0
	v_exp_f32_e32 v0, v0
	v_cvt_pk_bf16_f32 v126, v126, v127
	v_add_f32_e32 v0, 1.0, v0
	v_rcp_f32_e32 v157, v0
	v_or_b32_e32 v0, 32, v130
	v_pk_mul_f32 v[128:129], v[128:129], v[156:157]
	s_nop 0
	v_cvt_pk_bf16_f32 v127, v128, v129
	v_lshl_add_u64 v[128:129], v[134:135], 0, v[0:1]
	global_load_dwordx2 v[128:129], v[128:129], off
	s_waitcnt vmcnt(0)
	v_lshlrev_b32_e32 v140, 16, v128
	v_and_b32_e32 v128, 0xffff0000, v128
	v_mul_f32_e32 v128, 0xbfb8aa3b, v128
	v_exp_f32_e32 v128, v128
	v_mul_f32_e32 v140, 0xbfb8aa3b, v140
	v_exp_f32_e32 v140, v140
	v_add_f32_e32 v128, 1.0, v128
	v_rcp_f32_e32 v157, v128
	v_lshlrev_b32_e32 v128, 16, v129
	v_and_b32_e32 v129, 0xffff0000, v129
	v_mul_f32_e32 v128, 0xbfb8aa3b, v128
	v_mul_f32_e32 v129, 0xbfb8aa3b, v129
	v_exp_f32_e32 v128, v128
	v_exp_f32_e32 v129, v129
	v_add_f32_e32 v140, 1.0, v140
	v_rcp_f32_e32 v156, v140
	v_add_f32_e32 v128, 1.0, v128
	v_add_f32_e32 v129, 1.0, v129
	v_rcp_f32_e32 v128, v128
	v_rcp_f32_e32 v129, v129
	v_pk_mul_f32 v[122:123], v[122:123], v[156:157]
	v_pk_mul_f32 v[124:125], v[124:125], v[128:129]
	v_cvt_pk_bf16_f32 v122, v122, v123
	v_cvt_pk_bf16_f32 v123, v124, v125
	ds_write2_b64 v138, v[126:127], v[122:123] offset1:4
	v_or_b32_e32 v122, 64, v130
	v_mov_b32_e32 v123, v1
	v_lshl_add_u64 v[124:125], v[134:135], 0, v[122:123]
	global_load_dwordx2 v[124:125], v[124:125], off
	s_waitcnt vmcnt(0)
; DI float bflo(unsigned u) { return __uint_as_float(u << 16); }
; DI float bfhi(unsigned u) { return __uint_as_float(u & 0xffff0000u); }
; DI float sigmoidf(float x) { return __builtin_amdgcn_rcpf(1.f + __expf(-x)); }
; template <class F>
; DI void gemm8_epi_staged(f32x4 (&acc)[8][4], int m0, int n0, bf16_t* L0, F f, bf16_t* dst, size_t ld, int nmax) {
;     ...
;     if (wm == half) {
; #pragma unroll
;       for (int i = 0; i < 8; ++i)
; #pragma unroll
;         for (int j = 0; j < 4; ++j) {
;           const int ml = i * 16 + (lane & 15);
;           const int nl = wn * 64 + j * 16 + (lane >> 4) * 4;
;           f32x4 a = acc[i][j];
;           f(m0 + half * 128 + ml, n0 + nl, a);
;           uint2 u;
;           u.x = pack2(a[0], a[1]);
;           u.y = pack2(a[2], a[3]);
;           *(uint2*)(L + ml * 264 + nl) = u;
;         }
;     }
; __global__ void __launch_bounds__(512, 2) mega(Params p) {
;     ...
;       gemm8_epi_staged(acc8, m0, n0, lds_all, [&](int m, int n, f32x4& a) {
;         uint2 ub = *(const uint2*)(z + (size_t)m * ZS + C_MB + n);
;         a[0] *= sigmoidf(bflo(ub.x)); a[1] *= sigmoidf(bfhi(ub.x));
;         a[2] *= sigmoidf(bflo(ub.y)); a[3] *= sigmoidf(bfhi(ub.y));
;       }, z + C_RK, ZS, 1024);
	v_lshlrev_b32_e32 v126, 16, v124
	v_and_b32_e32 v124, 0xffff0000, v124
	v_mul_f32_e32 v124, 0xbfb8aa3b, v124
	v_exp_f32_e32 v124, v124
	v_mul_f32_e32 v126, 0xbfb8aa3b, v126
	v_exp_f32_e32 v126, v126
	v_add_f32_e32 v124, 1.0, v124
	v_rcp_f32_e32 v127, v124
	v_lshlrev_b32_e32 v124, 16, v125
	v_and_b32_e32 v125, 0xffff0000, v125
	v_mul_f32_e32 v124, 0xbfb8aa3b, v124
	v_mul_f32_e32 v125, 0xbfb8aa3b, v125
	v_exp_f32_e32 v124, v124
	v_exp_f32_e32 v125, v125
	v_add_f32_e32 v126, 1.0, v126
	v_rcp_f32_e32 v126, v126
	v_add_f32_e32 v124, 1.0, v124
	v_add_f32_e32 v125, 1.0, v125
	v_rcp_f32_e32 v124, v124
	v_rcp_f32_e32 v125, v125
	v_pk_mul_f32 v[118:119], v[118:119], v[126:127]
	v_pk_mul_f32 v[120:121], v[120:121], v[124:125]
	v_cvt_pk_bf16_f32 v124, v118, v119
	v_or_b32_e32 v118, 0x60, v130
	v_mov_b32_e32 v119, v1
	v_cvt_pk_bf16_f32 v125, v120, v121
	v_lshl_add_u64 v[120:121], v[134:135], 0, v[118:119]
	global_load_dwordx2 v[120:121], v[120:121], off
	s_waitcnt vmcnt(0)
	v_lshlrev_b32_e32 v126, 16, v120
	v_and_b32_e32 v120, 0xffff0000, v120
	v_mul_f32_e32 v120, 0xbfb8aa3b, v120
	v_exp_f32_e32 v120, v120
	v_mul_f32_e32 v126, 0xbfb8aa3b, v126
	v_exp_f32_e32 v126, v126
	v_add_f32_e32 v120, 1.0, v120
	v_rcp_f32_e32 v127, v120
	v_lshlrev_b32_e32 v120, 16, v121
	v_and_b32_e32 v121, 0xffff0000, v121
	v_mul_f32_e32 v120, 0xbfb8aa3b, v120
	v_mul_f32_e32 v121, 0xbfb8aa3b, v121
	v_exp_f32_e32 v120, v120
	v_exp_f32_e32 v121, v121
	v_add_f32_e32 v126, 1.0, v126
	v_rcp_f32_e32 v126, v126
	v_add_f32_e32 v120, 1.0, v120
	v_add_f32_e32 v121, 1.0, v121
	v_rcp_f32_e32 v120, v120
	v_rcp_f32_e32 v121, v121
	v_pk_mul_f32 v[114:115], v[114:115], v[126:127]
	v_pk_mul_f32 v[116:117], v[116:117], v[120:121]
	v_cvt_pk_bf16_f32 v114, v114, v115
	v_cvt_pk_bf16_f32 v115, v116, v117
	ds_write2_b64 v138, v[124:125], v[114:115] offset0:8 offset1:12
	v_or_b32_e32 v114, 16, v139
	v_mul_u32_u24_e32 v114, 0x2a30, v114
	v_mov_b32_e32 v115, v1
	v_lshl_add_u64 v[114:115], s[16:17], 0, v[114:115]
	v_lshl_add_u64 v[114:115], v[114:115], 0, s[6:7]
	v_lshl_add_u64 v[116:117], v[114:115], 0, v[130:131]
	global_load_dwordx2 v[116:117], v[116:117], off
	s_waitcnt vmcnt(0)
	v_lshlrev_b32_e32 v120, 16, v116
	v_and_b32_e32 v116, 0xffff0000, v116
	v_mul_f32_e32 v116, 0xbfb8aa3b, v116
	v_exp_f32_e32 v116, v116
	v_mul_f32_e32 v120, 0xbfb8aa3b, v120
	v_exp_f32_e32 v120, v120
	v_add_f32_e32 v116, 1.0, v116
	v_rcp_f32_e32 v121, v116
	v_lshlrev_b32_e32 v116, 16, v117
	v_and_b32_e32 v117, 0xffff0000, v117
	v_mul_f32_e32 v116, 0xbfb8aa3b, v116
	v_mul_f32_e32 v117, 0xbfb8aa3b, v117
	v_exp_f32_e32 v116, v116
	v_exp_f32_e32 v117, v117
	v_add_f32_e32 v120, 1.0, v120
	v_rcp_f32_e32 v120, v120
	v_add_f32_e32 v116, 1.0, v116
	v_add_f32_e32 v117, 1.0, v117
	v_rcp_f32_e32 v116, v116
	v_rcp_f32_e32 v117, v117
	v_pk_mul_f32 v[110:111], v[110:111], v[120:121]
	v_pk_mul_f32 v[112:113], v[112:113], v[116:117]
	v_cvt_pk_bf16_f32 v110, v110, v111
	v_cvt_pk_bf16_f32 v111, v112, v113
	v_lshl_add_u64 v[112:113], v[114:115], 0, v[0:1]
	global_load_dwordx2 v[112:113], v[112:113], off
	s_waitcnt vmcnt(0)
	v_lshlrev_b32_e32 v116, 16, v112
	v_and_b32_e32 v112, 0xffff0000, v112
	v_mul_f32_e32 v112, 0xbfb8aa3b, v112
	v_exp_f32_e32 v112, v112
	v_mul_f32_e32 v116, 0xbfb8aa3b, v116
	v_exp_f32_e32 v116, v116
	v_add_f32_e32 v112, 1.0, v112
	v_rcp_f32_e32 v117, v112
	v_lshlrev_b32_e32 v112, 16, v113
	v_and_b32_e32 v113, 0xffff0000, v113
	v_mul_f32_e32 v112, 0xbfb8aa3b, v112
	v_mul_f32_e32 v113, 0xbfb8aa3b, v113
	v_exp_f32_e32 v112, v112
	v_exp_f32_e32 v113, v113
	v_add_f32_e32 v116, 1.0, v116
	v_rcp_f32_e32 v116, v116
	v_add_f32_e32 v112, 1.0, v112
	v_add_f32_e32 v113, 1.0, v113
	v_rcp_f32_e32 v112, v112
	v_rcp_f32_e32 v113, v113
	v_pk_mul_f32 v[106:107], v[106:107], v[116:117]
	v_pk_mul_f32 v[108:109], v[108:109], v[112:113]
	s_nop 0
	v_cvt_pk_bf16_f32 v113, v108, v109
	v_lshl_add_u64 v[108:109], v[114:115], 0, v[122:123]
	global_load_dwordx2 v[108:109], v[108:109], off
	v_cvt_pk_bf16_f32 v112, v106, v107
	v_add_u32_e32 v106, 0x2000, v138
	ds_write2_b64 v106, v[110:111], v[112:113] offset0:32 offset1:36
	s_waitcnt vmcnt(0)
	v_lshlrev_b32_e32 v107, 16, v108
	v_mul_f32_e32 v107, 0xbfb8aa3b, v107
	v_exp_f32_e32 v107, v107
	s_nop 0
	v_add_f32_e32 v107, 1.0, v107
	v_rcp_f32_e32 v110, v107
	v_and_b32_e32 v107, 0xffff0000, v108
	v_mul_f32_e32 v107, 0xbfb8aa3b, v107
	v_exp_f32_e32 v107, v107
	s_nop 0
	v_add_f32_e32 v107, 1.0, v107
	v_rcp_f32_e32 v111, v107
	v_lshlrev_b32_e32 v107, 16, v109
	v_mul_f32_e32 v107, 0xbfb8aa3b, v107
	v_exp_f32_e32 v107, v107
	v_pk_mul_f32 v[102:103], v[102:103], v[110:111]
	v_add_f32_e32 v107, 1.0, v107
	v_rcp_f32_e32 v108, v107
	v_and_b32_e32 v107, 0xffff0000, v109
	v_mul_f32_e32 v107, 0xbfb8aa3b, v107
	v_exp_f32_e32 v107, v107
	v_cvt_pk_bf16_f32 v102, v102, v103
	v_add_f32_e32 v107, 1.0, v107
	v_rcp_f32_e32 v109, v107
	s_nop 0
	v_pk_mul_f32 v[104:105], v[104:105], v[108:109]
	s_nop 0
	v_cvt_pk_bf16_f32 v103, v104, v105
	v_lshl_add_u64 v[104:105], v[114:115], 0, v[118:119]
	global_load_dwordx2 v[104:105], v[104:105], off
	s_waitcnt vmcnt(0)
	v_lshlrev_b32_e32 v107, 16, v104
	v_and_b32_e32 v104, 0xffff0000, v104
	v_mul_f32_e32 v104, 0xbfb8aa3b, v104
	v_exp_f32_e32 v104, v104
	v_mul_f32_e32 v107, 0xbfb8aa3b, v107
	v_exp_f32_e32 v107, v107
	v_add_f32_e32 v104, 1.0, v104
	v_rcp_f32_e32 v109, v104
	v_lshlrev_b32_e32 v104, 16, v105
	v_and_b32_e32 v105, 0xffff0000, v105
	v_mul_f32_e32 v104, 0xbfb8aa3b, v104
	v_mul_f32_e32 v105, 0xbfb8aa3b, v105
	v_exp_f32_e32 v104, v104
	v_exp_f32_e32 v105, v105
	v_add_f32_e32 v107, 1.0, v107
	v_rcp_f32_e32 v108, v107
	v_add_f32_e32 v104, 1.0, v104
	v_add_f32_e32 v105, 1.0, v105
	v_rcp_f32_e32 v104, v104
	v_rcp_f32_e32 v105, v105
	v_pk_mul_f32 v[98:99], v[98:99], v[108:109]
	v_pk_mul_f32 v[100:101], v[100:101], v[104:105]
	v_cvt_pk_bf16_f32 v98, v98, v99
	v_cvt_pk_bf16_f32 v99, v100, v101
	ds_write2_b64 v106, v[102:103], v[98:99] offset0:40 offset1:44
	v_or_b32_e32 v98, 32, v139
	v_mul_u32_u24_e32 v98, 0x2a30, v98
	v_mov_b32_e32 v99, v1
	v_lshl_add_u64 v[98:99], s[16:17], 0, v[98:99]
	v_lshl_add_u64 v[98:99], v[98:99], 0, s[6:7]
	v_lshl_add_u64 v[100:101], v[98:99], 0, v[130:131]
	global_load_dwordx2 v[100:101], v[100:101], off
	s_waitcnt vmcnt(0)
; DI float bflo(unsigned u) { return __uint_as_float(u << 16); }
; DI float bfhi(unsigned u) { return __uint_as_float(u & 0xffff0000u); }
; DI float sigmoidf(float x) { return __builtin_amdgcn_rcpf(1.f + __expf(-x)); }
; template <class F>
; DI void gemm8_epi_staged(f32x4 (&acc)[8][4], int m0, int n0, bf16_t* L0, F f, bf16_t* dst, size_t ld, int nmax) {
;     ...
;     if (wm == half) {
; #pragma unroll
;       for (int i = 0; i < 8; ++i)
; #pragma unroll
;         for (int j = 0; j < 4; ++j) {
;           const int ml = i * 16 + (lane & 15);
;           const int nl = wn * 64 + j * 16 + (lane >> 4) * 4;
;           f32x4 a = acc[i][j];
;           f(m0 + half * 128 + ml, n0 + nl, a);
;           uint2 u;
;           u.x = pack2(a[0], a[1]);
;           u.y = pack2(a[2], a[3]);
;           *(uint2*)(L + ml * 264 + nl) = u;
;         }
;     }
; __global__ void __launch_bounds__(512, 2) mega(Params p) {
;     ...
;       gemm8_epi_staged(acc8, m0, n0, lds_all, [&](int m, int n, f32x4& a) {
;         uint2 ub = *(const uint2*)(z + (size_t)m * ZS + C_MB + n);
;         a[0] *= sigmoidf(bflo(ub.x)); a[1] *= sigmoidf(bfhi(ub.x));
;         a[2] *= sigmoidf(bflo(ub.y)); a[3] *= sigmoidf(bfhi(ub.y));
;       }, z + C_RK, ZS, 1024);
	v_lshlrev_b32_e32 v102, 16, v100
	v_and_b32_e32 v100, 0xffff0000, v100
	v_mul_f32_e32 v100, 0xbfb8aa3b, v100
	v_exp_f32_e32 v100, v100
	v_mul_f32_e32 v102, 0xbfb8aa3b, v102
	v_exp_f32_e32 v102, v102
	v_add_f32_e32 v100, 1.0, v100
	v_rcp_f32_e32 v103, v100
	v_lshlrev_b32_e32 v100, 16, v101
	v_and_b32_e32 v101, 0xffff0000, v101
	v_mul_f32_e32 v100, 0xbfb8aa3b, v100
	v_mul_f32_e32 v101, 0xbfb8aa3b, v101
	v_exp_f32_e32 v100, v100
	v_exp_f32_e32 v101, v101
	v_add_f32_e32 v102, 1.0, v102
	v_rcp_f32_e32 v102, v102
	v_add_f32_e32 v100, 1.0, v100
	v_add_f32_e32 v101, 1.0, v101
	v_rcp_f32_e32 v100, v100
	v_rcp_f32_e32 v101, v101
	v_pk_mul_f32 v[94:95], v[94:95], v[102:103]
	v_pk_mul_f32 v[96:97], v[96:97], v[100:101]
	v_cvt_pk_bf16_f32 v94, v94, v95
	v_cvt_pk_bf16_f32 v95, v96, v97
	v_lshl_add_u64 v[96:97], v[98:99], 0, v[0:1]
	global_load_dwordx2 v[96:97], v[96:97], off
	s_waitcnt vmcnt(0)
	v_lshlrev_b32_e32 v100, 16, v96
	v_and_b32_e32 v96, 0xffff0000, v96
	v_mul_f32_e32 v96, 0xbfb8aa3b, v96
	v_exp_f32_e32 v96, v96
	v_mul_f32_e32 v100, 0xbfb8aa3b, v100
	v_exp_f32_e32 v100, v100
	v_add_f32_e32 v96, 1.0, v96
	v_rcp_f32_e32 v101, v96
	v_lshlrev_b32_e32 v96, 16, v97
	v_and_b32_e32 v97, 0xffff0000, v97
	v_mul_f32_e32 v96, 0xbfb8aa3b, v96
	v_mul_f32_e32 v97, 0xbfb8aa3b, v97
	v_exp_f32_e32 v96, v96
	v_exp_f32_e32 v97, v97
	v_add_f32_e32 v100, 1.0, v100
	v_rcp_f32_e32 v100, v100
	v_add_f32_e32 v96, 1.0, v96
	v_add_f32_e32 v97, 1.0, v97
	v_rcp_f32_e32 v96, v96
	v_rcp_f32_e32 v97, v97
	v_pk_mul_f32 v[90:91], v[90:91], v[100:101]
	v_pk_mul_f32 v[92:93], v[92:93], v[96:97]
	v_cvt_pk_bf16_f32 v90, v90, v91
	v_cvt_pk_bf16_f32 v91, v92, v93
	v_add_u32_e32 v96, 0x4000, v138
	ds_write2_b64 v96, v[94:95], v[90:91] offset0:64 offset1:68
	v_lshl_add_u64 v[90:91], v[98:99], 0, v[122:123]
	global_load_dwordx2 v[90:91], v[90:91], off
	s_waitcnt vmcnt(0)
	v_lshlrev_b32_e32 v92, 16, v90
	v_and_b32_e32 v90, 0xffff0000, v90
	v_mul_f32_e32 v90, 0xbfb8aa3b, v90
	v_exp_f32_e32 v90, v90
	v_mul_f32_e32 v92, 0xbfb8aa3b, v92
	v_exp_f32_e32 v92, v92
	v_add_f32_e32 v90, 1.0, v90
	v_rcp_f32_e32 v93, v90
	v_lshlrev_b32_e32 v90, 16, v91
	v_and_b32_e32 v91, 0xffff0000, v91
	v_mul_f32_e32 v90, 0xbfb8aa3b, v90
	v_mul_f32_e32 v91, 0xbfb8aa3b, v91
	v_exp_f32_e32 v90, v90
	v_exp_f32_e32 v91, v91
	v_add_f32_e32 v92, 1.0, v92
	v_rcp_f32_e32 v92, v92
	v_add_f32_e32 v90, 1.0, v90
	v_add_f32_e32 v91, 1.0, v91
	v_rcp_f32_e32 v90, v90
	v_rcp_f32_e32 v91, v91
	v_pk_mul_f32 v[86:87], v[86:87], v[92:93]
	v_pk_mul_f32 v[88:89], v[88:89], v[90:91]
	v_cvt_pk_bf16_f32 v86, v86, v87
	v_cvt_pk_bf16_f32 v87, v88, v89
	v_lshl_add_u64 v[88:89], v[98:99], 0, v[118:119]
	global_load_dwordx2 v[88:89], v[88:89], off
	s_waitcnt vmcnt(0)
	v_lshlrev_b32_e32 v90, 16, v88
	v_and_b32_e32 v88, 0xffff0000, v88
	v_mul_f32_e32 v88, 0xbfb8aa3b, v88
	v_exp_f32_e32 v88, v88
	v_mul_f32_e32 v90, 0xbfb8aa3b, v90
	v_exp_f32_e32 v90, v90
	v_add_f32_e32 v88, 1.0, v88
	v_rcp_f32_e32 v91, v88
	v_lshlrev_b32_e32 v88, 16, v89
	v_and_b32_e32 v89, 0xffff0000, v89
	v_mul_f32_e32 v88, 0xbfb8aa3b, v88
	v_mul_f32_e32 v89, 0xbfb8aa3b, v89
	v_exp_f32_e32 v88, v88
	v_exp_f32_e32 v89, v89
	v_add_f32_e32 v90, 1.0, v90
	v_rcp_f32_e32 v90, v90
	v_add_f32_e32 v88, 1.0, v88
	v_add_f32_e32 v89, 1.0, v89
	v_rcp_f32_e32 v88, v88
	v_rcp_f32_e32 v89, v89
	v_pk_mul_f32 v[82:83], v[82:83], v[90:91]
	v_pk_mul_f32 v[84:85], v[84:85], v[88:89]
	v_cvt_pk_bf16_f32 v82, v82, v83
	v_cvt_pk_bf16_f32 v83, v84, v85
	ds_write2_b64 v96, v[86:87], v[82:83] offset0:72 offset1:76
	v_or_b32_e32 v82, 48, v139
	v_mul_u32_u24_e32 v82, 0x2a30, v82
	v_mov_b32_e32 v83, v1
	v_lshl_add_u64 v[82:83], s[16:17], 0, v[82:83]
	v_lshl_add_u64 v[82:83], v[82:83], 0, s[6:7]
	v_lshl_add_u64 v[84:85], v[82:83], 0, v[130:131]
	global_load_dwordx2 v[84:85], v[84:85], off
	s_waitcnt vmcnt(0)
	v_lshlrev_b32_e32 v86, 16, v84
	v_and_b32_e32 v84, 0xffff0000, v84
	v_mul_f32_e32 v84, 0xbfb8aa3b, v84
	v_exp_f32_e32 v84, v84
	v_mul_f32_e32 v86, 0xbfb8aa3b, v86
	v_exp_f32_e32 v86, v86
	v_add_f32_e32 v84, 1.0, v84
	v_rcp_f32_e32 v87, v84
	v_lshlrev_b32_e32 v84, 16, v85
	v_and_b32_e32 v85, 0xffff0000, v85
	v_mul_f32_e32 v84, 0xbfb8aa3b, v84
	v_mul_f32_e32 v85, 0xbfb8aa3b, v85
	v_exp_f32_e32 v84, v84
	v_exp_f32_e32 v85, v85
	v_add_f32_e32 v86, 1.0, v86
	v_rcp_f32_e32 v86, v86
	v_add_f32_e32 v84, 1.0, v84
	v_add_f32_e32 v85, 1.0, v85
	v_rcp_f32_e32 v84, v84
	v_rcp_f32_e32 v85, v85
	v_pk_mul_f32 v[78:79], v[78:79], v[86:87]
	v_pk_mul_f32 v[80:81], v[80:81], v[84:85]
	v_cvt_pk_bf16_f32 v78, v78, v79
	v_cvt_pk_bf16_f32 v79, v80, v81
	v_lshl_add_u64 v[80:81], v[82:83], 0, v[0:1]
	global_load_dwordx2 v[80:81], v[80:81], off
	s_waitcnt vmcnt(0)
	v_lshlrev_b32_e32 v84, 16, v80
	v_and_b32_e32 v80, 0xffff0000, v80
	v_mul_f32_e32 v80, 0xbfb8aa3b, v80
	v_exp_f32_e32 v80, v80
	v_mul_f32_e32 v84, 0xbfb8aa3b, v84
	v_exp_f32_e32 v84, v84
	v_add_f32_e32 v80, 1.0, v80
	v_rcp_f32_e32 v85, v80
	v_lshlrev_b32_e32 v80, 16, v81
	v_and_b32_e32 v81, 0xffff0000, v81
	v_mul_f32_e32 v80, 0xbfb8aa3b, v80
	v_mul_f32_e32 v81, 0xbfb8aa3b, v81
	v_exp_f32_e32 v80, v80
	v_exp_f32_e32 v81, v81
	v_add_f32_e32 v84, 1.0, v84
	v_rcp_f32_e32 v84, v84
	v_add_f32_e32 v80, 1.0, v80
	v_add_f32_e32 v81, 1.0, v81
	v_rcp_f32_e32 v80, v80
	v_rcp_f32_e32 v81, v81
	v_pk_mul_f32 v[74:75], v[74:75], v[84:85]
	v_pk_mul_f32 v[76:77], v[76:77], v[80:81]
	v_cvt_pk_bf16_f32 v74, v74, v75
	v_cvt_pk_bf16_f32 v75, v76, v77
	v_add_u32_e32 v80, 0x6000, v138
	ds_write2_b64 v80, v[78:79], v[74:75] offset0:96 offset1:100
	v_lshl_add_u64 v[74:75], v[82:83], 0, v[122:123]
	global_load_dwordx2 v[74:75], v[74:75], off
	s_waitcnt vmcnt(0)
; DI float bflo(unsigned u) { return __uint_as_float(u << 16); }
; DI float bfhi(unsigned u) { return __uint_as_float(u & 0xffff0000u); }
; DI float sigmoidf(float x) { return __builtin_amdgcn_rcpf(1.f + __expf(-x)); }
; template <class F>
; DI void gemm8_epi_staged(f32x4 (&acc)[8][4], int m0, int n0, bf16_t* L0, F f, bf16_t* dst, size_t ld, int nmax) {
;     ...
;     if (wm == half) {
; #pragma unroll
;       for (int i = 0; i < 8; ++i)
; #pragma unroll
;         for (int j = 0; j < 4; ++j) {
;           const int ml = i * 16 + (lane & 15);
;           const int nl = wn * 64 + j * 16 + (lane >> 4) * 4;
;           f32x4 a = acc[i][j];
;           f(m0 + half * 128 + ml, n0 + nl, a);
;           uint2 u;
;           u.x = pack2(a[0], a[1]);
;           u.y = pack2(a[2], a[3]);
;           *(uint2*)(L + ml * 264 + nl) = u;
;         }
;     }
; __global__ void __launch_bounds__(512, 2) mega(Params p) {
;     ...
;       gemm8_epi_staged(acc8, m0, n0, lds_all, [&](int m, int n, f32x4& a) {
;         uint2 ub = *(const uint2*)(z + (size_t)m * ZS + C_MB + n);
;         a[0] *= sigmoidf(bflo(ub.x)); a[1] *= sigmoidf(bfhi(ub.x));
;         a[2] *= sigmoidf(bflo(ub.y)); a[3] *= sigmoidf(bfhi(ub.y));
;       }, z + C_RK, ZS, 1024);
	v_lshlrev_b32_e32 v76, 16, v74
	v_and_b32_e32 v74, 0xffff0000, v74
	v_mul_f32_e32 v74, 0xbfb8aa3b, v74
	v_exp_f32_e32 v74, v74
	v_mul_f32_e32 v76, 0xbfb8aa3b, v76
	v_exp_f32_e32 v76, v76
	v_add_f32_e32 v74, 1.0, v74
	v_rcp_f32_e32 v77, v74
	v_lshlrev_b32_e32 v74, 16, v75
	v_and_b32_e32 v75, 0xffff0000, v75
	v_mul_f32_e32 v74, 0xbfb8aa3b, v74
	v_mul_f32_e32 v75, 0xbfb8aa3b, v75
	v_exp_f32_e32 v74, v74
	v_exp_f32_e32 v75, v75
	v_add_f32_e32 v76, 1.0, v76
	v_rcp_f32_e32 v76, v76
	v_add_f32_e32 v74, 1.0, v74
	v_add_f32_e32 v75, 1.0, v75
	v_rcp_f32_e32 v74, v74
	v_rcp_f32_e32 v75, v75
	v_pk_mul_f32 v[70:71], v[70:71], v[76:77]
	v_pk_mul_f32 v[72:73], v[72:73], v[74:75]
	v_cvt_pk_bf16_f32 v70, v70, v71
	v_cvt_pk_bf16_f32 v71, v72, v73
	v_lshl_add_u64 v[72:73], v[82:83], 0, v[118:119]
	global_load_dwordx2 v[72:73], v[72:73], off
	s_waitcnt vmcnt(0)
	v_lshlrev_b32_e32 v74, 16, v72
	v_and_b32_e32 v72, 0xffff0000, v72
	v_mul_f32_e32 v72, 0xbfb8aa3b, v72
	v_exp_f32_e32 v72, v72
	v_mul_f32_e32 v74, 0xbfb8aa3b, v74
	v_exp_f32_e32 v74, v74
	v_add_f32_e32 v72, 1.0, v72
	v_rcp_f32_e32 v75, v72
	v_lshlrev_b32_e32 v72, 16, v73
	v_and_b32_e32 v73, 0xffff0000, v73
	v_mul_f32_e32 v72, 0xbfb8aa3b, v72
	v_mul_f32_e32 v73, 0xbfb8aa3b, v73
	v_exp_f32_e32 v72, v72
	v_exp_f32_e32 v73, v73
	v_add_f32_e32 v74, 1.0, v74
	v_rcp_f32_e32 v74, v74
	v_add_f32_e32 v72, 1.0, v72
	v_add_f32_e32 v73, 1.0, v73
	v_rcp_f32_e32 v72, v72
	v_rcp_f32_e32 v73, v73
	v_pk_mul_f32 v[66:67], v[66:67], v[74:75]
	v_pk_mul_f32 v[68:69], v[68:69], v[72:73]
	v_cvt_pk_bf16_f32 v66, v66, v67
	v_cvt_pk_bf16_f32 v67, v68, v69
	ds_write2_b64 v80, v[70:71], v[66:67] offset0:104 offset1:108
	v_or_b32_e32 v66, 64, v139
	v_mul_u32_u24_e32 v66, 0x2a30, v66
	v_mov_b32_e32 v67, v1
	v_lshl_add_u64 v[66:67], s[16:17], 0, v[66:67]
	v_lshl_add_u64 v[66:67], v[66:67], 0, s[6:7]
	v_lshl_add_u64 v[68:69], v[66:67], 0, v[130:131]
	global_load_dwordx2 v[68:69], v[68:69], off
	s_waitcnt vmcnt(0)
	v_lshlrev_b32_e32 v70, 16, v68
	v_and_b32_e32 v68, 0xffff0000, v68
	v_mul_f32_e32 v68, 0xbfb8aa3b, v68
	v_exp_f32_e32 v68, v68
	v_mul_f32_e32 v70, 0xbfb8aa3b, v70
	v_exp_f32_e32 v70, v70
	v_add_f32_e32 v68, 1.0, v68
	v_rcp_f32_e32 v71, v68
	v_lshlrev_b32_e32 v68, 16, v69
	v_and_b32_e32 v69, 0xffff0000, v69
	v_mul_f32_e32 v68, 0xbfb8aa3b, v68
	v_mul_f32_e32 v69, 0xbfb8aa3b, v69
	v_exp_f32_e32 v68, v68
	v_exp_f32_e32 v69, v69
	v_add_f32_e32 v70, 1.0, v70
	v_rcp_f32_e32 v70, v70
	v_add_f32_e32 v68, 1.0, v68
	v_add_f32_e32 v69, 1.0, v69
	v_rcp_f32_e32 v68, v68
	v_rcp_f32_e32 v69, v69
	v_pk_mul_f32 v[62:63], v[62:63], v[70:71]
	v_pk_mul_f32 v[64:65], v[64:65], v[68:69]
	v_cvt_pk_bf16_f32 v62, v62, v63
	v_cvt_pk_bf16_f32 v63, v64, v65
	v_lshl_add_u64 v[64:65], v[66:67], 0, v[0:1]
	global_load_dwordx2 v[64:65], v[64:65], off
	s_waitcnt vmcnt(0)
	v_lshlrev_b32_e32 v68, 16, v64
	v_and_b32_e32 v64, 0xffff0000, v64
	v_mul_f32_e32 v64, 0xbfb8aa3b, v64
	v_exp_f32_e32 v64, v64
	v_mul_f32_e32 v68, 0xbfb8aa3b, v68
	v_exp_f32_e32 v68, v68
	v_add_f32_e32 v64, 1.0, v64
	v_rcp_f32_e32 v69, v64
	v_lshlrev_b32_e32 v64, 16, v65
	v_and_b32_e32 v65, 0xffff0000, v65
	v_mul_f32_e32 v64, 0xbfb8aa3b, v64
	v_mul_f32_e32 v65, 0xbfb8aa3b, v65
	v_exp_f32_e32 v64, v64
	v_exp_f32_e32 v65, v65
	v_add_f32_e32 v68, 1.0, v68
	v_rcp_f32_e32 v68, v68
	v_add_f32_e32 v64, 1.0, v64
	v_add_f32_e32 v65, 1.0, v65
	v_rcp_f32_e32 v64, v64
	v_rcp_f32_e32 v65, v65
	v_pk_mul_f32 v[58:59], v[58:59], v[68:69]
	v_pk_mul_f32 v[60:61], v[60:61], v[64:65]
	v_cvt_pk_bf16_f32 v58, v58, v59
	v_cvt_pk_bf16_f32 v59, v60, v61
	v_add_u32_e32 v64, 0x8000, v138
	ds_write2_b64 v64, v[62:63], v[58:59] offset0:128 offset1:132
	v_lshl_add_u64 v[58:59], v[66:67], 0, v[122:123]
	global_load_dwordx2 v[58:59], v[58:59], off
	s_waitcnt vmcnt(0)
	v_lshlrev_b32_e32 v60, 16, v58
	v_and_b32_e32 v58, 0xffff0000, v58
	v_mul_f32_e32 v58, 0xbfb8aa3b, v58
	v_exp_f32_e32 v58, v58
	v_mul_f32_e32 v60, 0xbfb8aa3b, v60
	v_exp_f32_e32 v60, v60
	v_add_f32_e32 v58, 1.0, v58
	v_rcp_f32_e32 v61, v58
	v_lshlrev_b32_e32 v58, 16, v59
	v_and_b32_e32 v59, 0xffff0000, v59
	v_mul_f32_e32 v58, 0xbfb8aa3b, v58
	v_mul_f32_e32 v59, 0xbfb8aa3b, v59
	v_exp_f32_e32 v58, v58
	v_exp_f32_e32 v59, v59
	v_add_f32_e32 v60, 1.0, v60
	v_rcp_f32_e32 v60, v60
	v_add_f32_e32 v58, 1.0, v58
	v_add_f32_e32 v59, 1.0, v59
	v_rcp_f32_e32 v58, v58
	v_rcp_f32_e32 v59, v59
	v_pk_mul_f32 v[54:55], v[54:55], v[60:61]
	v_pk_mul_f32 v[56:57], v[56:57], v[58:59]
	v_cvt_pk_bf16_f32 v54, v54, v55
	v_cvt_pk_bf16_f32 v55, v56, v57
	v_lshl_add_u64 v[56:57], v[66:67], 0, v[118:119]
	global_load_dwordx2 v[56:57], v[56:57], off
	s_waitcnt vmcnt(0)
	v_lshlrev_b32_e32 v58, 16, v56
	v_and_b32_e32 v56, 0xffff0000, v56
	v_mul_f32_e32 v56, 0xbfb8aa3b, v56
	v_exp_f32_e32 v56, v56
	v_mul_f32_e32 v58, 0xbfb8aa3b, v58
	v_exp_f32_e32 v58, v58
	v_add_f32_e32 v56, 1.0, v56
	v_rcp_f32_e32 v59, v56
	v_lshlrev_b32_e32 v56, 16, v57
	v_and_b32_e32 v57, 0xffff0000, v57
	v_mul_f32_e32 v56, 0xbfb8aa3b, v56
	v_mul_f32_e32 v57, 0xbfb8aa3b, v57
	v_exp_f32_e32 v56, v56
	v_exp_f32_e32 v57, v57
	v_add_f32_e32 v58, 1.0, v58
	v_rcp_f32_e32 v58, v58
	v_add_f32_e32 v56, 1.0, v56
	v_add_f32_e32 v57, 1.0, v57
	v_rcp_f32_e32 v56, v56
	v_rcp_f32_e32 v57, v57
	v_pk_mul_f32 v[50:51], v[50:51], v[58:59]
	v_pk_mul_f32 v[52:53], v[52:53], v[56:57]
	v_cvt_pk_bf16_f32 v50, v50, v51
	v_cvt_pk_bf16_f32 v51, v52, v53
	ds_write2_b64 v64, v[54:55], v[50:51] offset0:136 offset1:140
	v_or_b32_e32 v50, 0x50, v139
	v_mul_u32_u24_e32 v50, 0x2a30, v50
	v_mov_b32_e32 v51, v1
	v_lshl_add_u64 v[50:51], s[16:17], 0, v[50:51]
	v_lshl_add_u64 v[50:51], v[50:51], 0, s[6:7]
	v_lshl_add_u64 v[52:53], v[50:51], 0, v[130:131]
	global_load_dwordx2 v[52:53], v[52:53], off
	s_waitcnt vmcnt(0)
; DI float bflo(unsigned u) { return __uint_as_float(u << 16); }
; DI float bfhi(unsigned u) { return __uint_as_float(u & 0xffff0000u); }
; DI float sigmoidf(float x) { return __builtin_amdgcn_rcpf(1.f + __expf(-x)); }
; template <class F>
; DI void gemm8_epi_staged(f32x4 (&acc)[8][4], int m0, int n0, bf16_t* L0, F f, bf16_t* dst, size_t ld, int nmax) {
;     ...
;     if (wm == half) {
; #pragma unroll
;       for (int i = 0; i < 8; ++i)
; #pragma unroll
;         for (int j = 0; j < 4; ++j) {
;           const int ml = i * 16 + (lane & 15);
;           const int nl = wn * 64 + j * 16 + (lane >> 4) * 4;
;           f32x4 a = acc[i][j];
;           f(m0 + half * 128 + ml, n0 + nl, a);
;           uint2 u;
;           u.x = pack2(a[0], a[1]);
;           u.y = pack2(a[2], a[3]);
;           *(uint2*)(L + ml * 264 + nl) = u;
;         }
;     }
; __global__ void __launch_bounds__(512, 2) mega(Params p) {
;     ...
;       gemm8_epi_staged(acc8, m0, n0, lds_all, [&](int m, int n, f32x4& a) {
;         uint2 ub = *(const uint2*)(z + (size_t)m * ZS + C_MB + n);
;         a[0] *= sigmoidf(bflo(ub.x)); a[1] *= sigmoidf(bfhi(ub.x));
;         a[2] *= sigmoidf(bflo(ub.y)); a[3] *= sigmoidf(bfhi(ub.y));
;       }, z + C_RK, ZS, 1024);
	v_lshlrev_b32_e32 v54, 16, v52
	v_and_b32_e32 v52, 0xffff0000, v52
	v_mul_f32_e32 v52, 0xbfb8aa3b, v52
	v_exp_f32_e32 v52, v52
	v_mul_f32_e32 v54, 0xbfb8aa3b, v54
	v_exp_f32_e32 v54, v54
	v_add_f32_e32 v52, 1.0, v52
	v_rcp_f32_e32 v55, v52
	v_lshlrev_b32_e32 v52, 16, v53
	v_and_b32_e32 v53, 0xffff0000, v53
	v_mul_f32_e32 v52, 0xbfb8aa3b, v52
	v_mul_f32_e32 v53, 0xbfb8aa3b, v53
	v_exp_f32_e32 v52, v52
	v_exp_f32_e32 v53, v53
	v_add_f32_e32 v54, 1.0, v54
	v_rcp_f32_e32 v54, v54
	v_add_f32_e32 v52, 1.0, v52
	v_add_f32_e32 v53, 1.0, v53
	v_rcp_f32_e32 v52, v52
	v_rcp_f32_e32 v53, v53
	v_pk_mul_f32 v[46:47], v[46:47], v[54:55]
	v_pk_mul_f32 v[48:49], v[48:49], v[52:53]
	v_cvt_pk_bf16_f32 v46, v46, v47
	v_cvt_pk_bf16_f32 v47, v48, v49
	v_lshl_add_u64 v[48:49], v[50:51], 0, v[0:1]
	global_load_dwordx2 v[48:49], v[48:49], off
	s_waitcnt vmcnt(0)
	v_lshlrev_b32_e32 v52, 16, v48
	v_and_b32_e32 v48, 0xffff0000, v48
	v_mul_f32_e32 v48, 0xbfb8aa3b, v48
	v_exp_f32_e32 v48, v48
	v_mul_f32_e32 v52, 0xbfb8aa3b, v52
	v_exp_f32_e32 v52, v52
	v_add_f32_e32 v48, 1.0, v48
	v_rcp_f32_e32 v53, v48
	v_lshlrev_b32_e32 v48, 16, v49
	v_and_b32_e32 v49, 0xffff0000, v49
	v_mul_f32_e32 v48, 0xbfb8aa3b, v48
	v_mul_f32_e32 v49, 0xbfb8aa3b, v49
	v_exp_f32_e32 v48, v48
	v_exp_f32_e32 v49, v49
	v_add_f32_e32 v52, 1.0, v52
	v_rcp_f32_e32 v52, v52
	v_add_f32_e32 v48, 1.0, v48
	v_add_f32_e32 v49, 1.0, v49
	v_rcp_f32_e32 v48, v48
	v_rcp_f32_e32 v49, v49
	v_pk_mul_f32 v[42:43], v[42:43], v[52:53]
	v_pk_mul_f32 v[44:45], v[44:45], v[48:49]
	v_cvt_pk_bf16_f32 v42, v42, v43
	v_cvt_pk_bf16_f32 v43, v44, v45
	v_add_u32_e32 v48, 0xa000, v138
	ds_write2_b64 v48, v[46:47], v[42:43] offset0:160 offset1:164
	v_lshl_add_u64 v[42:43], v[50:51], 0, v[122:123]
	global_load_dwordx2 v[42:43], v[42:43], off
	s_waitcnt vmcnt(0)
	v_lshlrev_b32_e32 v44, 16, v42
	v_and_b32_e32 v42, 0xffff0000, v42
	v_mul_f32_e32 v42, 0xbfb8aa3b, v42
	v_exp_f32_e32 v42, v42
	v_mul_f32_e32 v44, 0xbfb8aa3b, v44
	v_exp_f32_e32 v44, v44
	v_add_f32_e32 v42, 1.0, v42
	v_rcp_f32_e32 v45, v42
	v_lshlrev_b32_e32 v42, 16, v43
	v_and_b32_e32 v43, 0xffff0000, v43
	v_mul_f32_e32 v42, 0xbfb8aa3b, v42
	v_mul_f32_e32 v43, 0xbfb8aa3b, v43
	v_exp_f32_e32 v42, v42
	v_exp_f32_e32 v43, v43
	v_add_f32_e32 v44, 1.0, v44
	v_rcp_f32_e32 v44, v44
	v_add_f32_e32 v42, 1.0, v42
	v_add_f32_e32 v43, 1.0, v43
	v_rcp_f32_e32 v42, v42
	v_rcp_f32_e32 v43, v43
	v_pk_mul_f32 v[38:39], v[38:39], v[44:45]
	v_pk_mul_f32 v[40:41], v[40:41], v[42:43]
	v_cvt_pk_bf16_f32 v38, v38, v39
	v_cvt_pk_bf16_f32 v39, v40, v41
	v_lshl_add_u64 v[40:41], v[50:51], 0, v[118:119]
	global_load_dwordx2 v[40:41], v[40:41], off
	s_waitcnt vmcnt(0)
	v_lshlrev_b32_e32 v42, 16, v40
	v_and_b32_e32 v40, 0xffff0000, v40
	v_mul_f32_e32 v40, 0xbfb8aa3b, v40
	v_exp_f32_e32 v40, v40
	v_mul_f32_e32 v42, 0xbfb8aa3b, v42
	v_exp_f32_e32 v42, v42
	v_add_f32_e32 v40, 1.0, v40
	v_rcp_f32_e32 v43, v40
	v_lshlrev_b32_e32 v40, 16, v41
	v_and_b32_e32 v41, 0xffff0000, v41
	v_mul_f32_e32 v40, 0xbfb8aa3b, v40
	v_mul_f32_e32 v41, 0xbfb8aa3b, v41
	v_exp_f32_e32 v40, v40
	v_exp_f32_e32 v41, v41
	v_add_f32_e32 v42, 1.0, v42
	v_rcp_f32_e32 v42, v42
	v_add_f32_e32 v40, 1.0, v40
	v_add_f32_e32 v41, 1.0, v41
	v_rcp_f32_e32 v40, v40
	v_rcp_f32_e32 v41, v41
	v_pk_mul_f32 v[34:35], v[34:35], v[42:43]
	v_pk_mul_f32 v[36:37], v[36:37], v[40:41]
	v_cvt_pk_bf16_f32 v34, v34, v35
	v_cvt_pk_bf16_f32 v35, v36, v37
	ds_write2_b64 v48, v[38:39], v[34:35] offset0:168 offset1:172
	v_or_b32_e32 v34, 0x60, v139
	v_mul_u32_u24_e32 v34, 0x2a30, v34
	v_mov_b32_e32 v35, v1
	v_lshl_add_u64 v[34:35], s[16:17], 0, v[34:35]
	v_lshl_add_u64 v[34:35], v[34:35], 0, s[6:7]
	v_lshl_add_u64 v[36:37], v[34:35], 0, v[130:131]
	global_load_dwordx2 v[36:37], v[36:37], off
	s_waitcnt vmcnt(0)
	v_lshlrev_b32_e32 v38, 16, v36
	v_and_b32_e32 v36, 0xffff0000, v36
	v_mul_f32_e32 v36, 0xbfb8aa3b, v36
	v_exp_f32_e32 v36, v36
	v_mul_f32_e32 v38, 0xbfb8aa3b, v38
	v_exp_f32_e32 v38, v38
	v_add_f32_e32 v36, 1.0, v36
	v_rcp_f32_e32 v39, v36
	v_lshlrev_b32_e32 v36, 16, v37
	v_and_b32_e32 v37, 0xffff0000, v37
	v_mul_f32_e32 v36, 0xbfb8aa3b, v36
	v_mul_f32_e32 v37, 0xbfb8aa3b, v37
	v_exp_f32_e32 v36, v36
	v_exp_f32_e32 v37, v37
	v_add_f32_e32 v38, 1.0, v38
	v_rcp_f32_e32 v38, v38
	v_add_f32_e32 v36, 1.0, v36
	v_add_f32_e32 v37, 1.0, v37
	v_rcp_f32_e32 v36, v36
	v_rcp_f32_e32 v37, v37
	v_pk_mul_f32 v[30:31], v[30:31], v[38:39]
	v_pk_mul_f32 v[32:33], v[32:33], v[36:37]
	v_cvt_pk_bf16_f32 v30, v30, v31
	v_cvt_pk_bf16_f32 v31, v32, v33
	v_lshl_add_u64 v[32:33], v[34:35], 0, v[0:1]
	global_load_dwordx2 v[32:33], v[32:33], off
	s_waitcnt vmcnt(0)
	v_lshlrev_b32_e32 v36, 16, v32
	v_and_b32_e32 v32, 0xffff0000, v32
	v_mul_f32_e32 v32, 0xbfb8aa3b, v32
	v_exp_f32_e32 v32, v32
	v_mul_f32_e32 v36, 0xbfb8aa3b, v36
	v_exp_f32_e32 v36, v36
	v_add_f32_e32 v32, 1.0, v32
	v_rcp_f32_e32 v37, v32
	v_lshlrev_b32_e32 v32, 16, v33
	v_and_b32_e32 v33, 0xffff0000, v33
	v_mul_f32_e32 v32, 0xbfb8aa3b, v32
	v_mul_f32_e32 v33, 0xbfb8aa3b, v33
	v_exp_f32_e32 v32, v32
	v_exp_f32_e32 v33, v33
	v_add_f32_e32 v36, 1.0, v36
	v_rcp_f32_e32 v36, v36
	v_add_f32_e32 v32, 1.0, v32
	v_add_f32_e32 v33, 1.0, v33
	v_rcp_f32_e32 v32, v32
	v_rcp_f32_e32 v33, v33
	v_pk_mul_f32 v[26:27], v[26:27], v[36:37]
	v_pk_mul_f32 v[28:29], v[28:29], v[32:33]
	v_cvt_pk_bf16_f32 v26, v26, v27
	v_cvt_pk_bf16_f32 v27, v28, v29
	v_add_u32_e32 v32, 0xc000, v138
	ds_write2_b64 v32, v[30:31], v[26:27] offset0:192 offset1:196
	v_lshl_add_u64 v[26:27], v[34:35], 0, v[122:123]
	global_load_dwordx2 v[26:27], v[26:27], off
	s_waitcnt vmcnt(0)
; DI float bflo(unsigned u) { return __uint_as_float(u << 16); }
; DI float bfhi(unsigned u) { return __uint_as_float(u & 0xffff0000u); }
; DI float sigmoidf(float x) { return __builtin_amdgcn_rcpf(1.f + __expf(-x)); }
; template <class F>
; DI void gemm8_epi_staged(f32x4 (&acc)[8][4], int m0, int n0, bf16_t* L0, F f, bf16_t* dst, size_t ld, int nmax) {
;     ...
;     if (wm == half) {
; #pragma unroll
;       for (int i = 0; i < 8; ++i)
; #pragma unroll
;         for (int j = 0; j < 4; ++j) {
;           const int ml = i * 16 + (lane & 15);
;           const int nl = wn * 64 + j * 16 + (lane >> 4) * 4;
;           f32x4 a = acc[i][j];
;           f(m0 + half * 128 + ml, n0 + nl, a);
;           uint2 u;
;           u.x = pack2(a[0], a[1]);
;           u.y = pack2(a[2], a[3]);
;           *(uint2*)(L + ml * 264 + nl) = u;
;         }
;     }
; __global__ void __launch_bounds__(512, 2) mega(Params p) {
;     ...
;       gemm8_epi_staged(acc8, m0, n0, lds_all, [&](int m, int n, f32x4& a) {
;         uint2 ub = *(const uint2*)(z + (size_t)m * ZS + C_MB + n);
;         a[0] *= sigmoidf(bflo(ub.x)); a[1] *= sigmoidf(bfhi(ub.x));
;         a[2] *= sigmoidf(bflo(ub.y)); a[3] *= sigmoidf(bfhi(ub.y));
;       }, z + C_RK, ZS, 1024);
	v_lshlrev_b32_e32 v28, 16, v26
	v_and_b32_e32 v26, 0xffff0000, v26
	v_mul_f32_e32 v26, 0xbfb8aa3b, v26
	v_exp_f32_e32 v26, v26
	v_mul_f32_e32 v28, 0xbfb8aa3b, v28
	v_exp_f32_e32 v28, v28
	v_add_f32_e32 v26, 1.0, v26
	v_rcp_f32_e32 v29, v26
	v_lshlrev_b32_e32 v26, 16, v27
	v_and_b32_e32 v27, 0xffff0000, v27
	v_mul_f32_e32 v26, 0xbfb8aa3b, v26
	v_mul_f32_e32 v27, 0xbfb8aa3b, v27
	v_exp_f32_e32 v26, v26
	v_exp_f32_e32 v27, v27
	v_add_f32_e32 v28, 1.0, v28
	v_rcp_f32_e32 v28, v28
	v_add_f32_e32 v26, 1.0, v26
	v_add_f32_e32 v27, 1.0, v27
	v_rcp_f32_e32 v26, v26
	v_rcp_f32_e32 v27, v27
	v_pk_mul_f32 v[22:23], v[22:23], v[28:29]
	v_pk_mul_f32 v[24:25], v[24:25], v[26:27]
	v_cvt_pk_bf16_f32 v22, v22, v23
	v_cvt_pk_bf16_f32 v23, v24, v25
	v_lshl_add_u64 v[24:25], v[34:35], 0, v[118:119]
	global_load_dwordx2 v[24:25], v[24:25], off
	s_waitcnt vmcnt(0)
	v_lshlrev_b32_e32 v26, 16, v24
	v_and_b32_e32 v24, 0xffff0000, v24
	v_mul_f32_e32 v24, 0xbfb8aa3b, v24
	v_exp_f32_e32 v24, v24
	v_mul_f32_e32 v26, 0xbfb8aa3b, v26
	v_exp_f32_e32 v26, v26
	v_add_f32_e32 v24, 1.0, v24
	v_rcp_f32_e32 v27, v24
	v_lshlrev_b32_e32 v24, 16, v25
	v_and_b32_e32 v25, 0xffff0000, v25
	v_mul_f32_e32 v24, 0xbfb8aa3b, v24
	v_mul_f32_e32 v25, 0xbfb8aa3b, v25
	v_exp_f32_e32 v24, v24
	v_exp_f32_e32 v25, v25
	v_add_f32_e32 v26, 1.0, v26
	v_rcp_f32_e32 v26, v26
	v_add_f32_e32 v24, 1.0, v24
	v_add_f32_e32 v25, 1.0, v25
	v_rcp_f32_e32 v24, v24
	v_rcp_f32_e32 v25, v25
	v_pk_mul_f32 v[18:19], v[18:19], v[26:27]
	v_pk_mul_f32 v[20:21], v[20:21], v[24:25]
	v_cvt_pk_bf16_f32 v18, v18, v19
	v_cvt_pk_bf16_f32 v19, v20, v21
	ds_write2_b64 v32, v[22:23], v[18:19] offset0:200 offset1:204
	v_or_b32_e32 v18, 0x70, v139
	v_mul_u32_u24_e32 v18, 0x2a30, v18
	v_mov_b32_e32 v19, v1
	v_lshl_add_u64 v[18:19], s[16:17], 0, v[18:19]
	v_lshl_add_u64 v[18:19], v[18:19], 0, s[6:7]
	v_lshl_add_u64 v[20:21], v[18:19], 0, v[130:131]
	global_load_dwordx2 v[20:21], v[20:21], off
	s_waitcnt vmcnt(0)
	v_lshlrev_b32_e32 v22, 16, v20
	v_and_b32_e32 v20, 0xffff0000, v20
	v_mul_f32_e32 v20, 0xbfb8aa3b, v20
	v_exp_f32_e32 v20, v20
	v_mul_f32_e32 v22, 0xbfb8aa3b, v22
	v_exp_f32_e32 v22, v22
	v_add_f32_e32 v20, 1.0, v20
	v_rcp_f32_e32 v23, v20
	v_lshlrev_b32_e32 v20, 16, v21
	v_and_b32_e32 v21, 0xffff0000, v21
	v_mul_f32_e32 v20, 0xbfb8aa3b, v20
	v_mul_f32_e32 v21, 0xbfb8aa3b, v21
	v_exp_f32_e32 v20, v20
	v_exp_f32_e32 v21, v21
	v_add_f32_e32 v22, 1.0, v22
	v_rcp_f32_e32 v22, v22
	v_add_f32_e32 v20, 1.0, v20
	v_add_f32_e32 v21, 1.0, v21
	v_rcp_f32_e32 v20, v20
	v_rcp_f32_e32 v21, v21
	v_pk_mul_f32 v[14:15], v[14:15], v[22:23]
	v_pk_mul_f32 v[16:17], v[16:17], v[20:21]
	v_cvt_pk_bf16_f32 v14, v14, v15
	v_cvt_pk_bf16_f32 v15, v16, v17
	v_lshl_add_u64 v[16:17], v[18:19], 0, v[0:1]
	global_load_dwordx2 v[16:17], v[16:17], off
	s_waitcnt vmcnt(0)
	v_lshlrev_b32_e32 v0, 16, v16
	v_mul_f32_e32 v0, 0xbfb8aa3b, v0
	v_exp_f32_e32 v0, v0
	s_nop 0
	v_add_f32_e32 v0, 1.0, v0
	v_rcp_f32_e32 v20, v0
	v_and_b32_e32 v0, 0xffff0000, v16
	v_mul_f32_e32 v0, 0xbfb8aa3b, v0
	v_exp_f32_e32 v0, v0
	s_nop 0
	v_add_f32_e32 v0, 1.0, v0
	v_rcp_f32_e32 v21, v0
	v_lshlrev_b32_e32 v0, 16, v17
	v_mul_f32_e32 v0, 0xbfb8aa3b, v0
	v_exp_f32_e32 v0, v0
	v_pk_mul_f32 v[10:11], v[10:11], v[20:21]
	v_add_f32_e32 v0, 1.0, v0
	v_rcp_f32_e32 v16, v0
	v_and_b32_e32 v0, 0xffff0000, v17
	v_mul_f32_e32 v0, 0xbfb8aa3b, v0
	v_exp_f32_e32 v0, v0
	v_cvt_pk_bf16_f32 v10, v10, v11
	v_add_f32_e32 v0, 1.0, v0
	v_rcp_f32_e32 v17, v0
	v_add_u32_e32 v0, 0xe000, v138
	v_pk_mul_f32 v[12:13], v[12:13], v[16:17]
	s_nop 0
	v_cvt_pk_bf16_f32 v11, v12, v13
	ds_write2_b64 v0, v[14:15], v[10:11] offset0:224 offset1:228
	v_lshl_add_u64 v[10:11], v[18:19], 0, v[122:123]
	global_load_dwordx2 v[10:11], v[10:11], off
	s_waitcnt vmcnt(0)
	v_lshlrev_b32_e32 v12, 16, v10
	v_and_b32_e32 v10, 0xffff0000, v10
	v_mul_f32_e32 v10, 0xbfb8aa3b, v10
	v_exp_f32_e32 v10, v10
	v_mul_f32_e32 v12, 0xbfb8aa3b, v12
	v_exp_f32_e32 v12, v12
	v_add_f32_e32 v10, 1.0, v10
	v_rcp_f32_e32 v13, v10
	v_lshlrev_b32_e32 v10, 16, v11
	v_and_b32_e32 v11, 0xffff0000, v11
	v_mul_f32_e32 v10, 0xbfb8aa3b, v10
	v_mul_f32_e32 v11, 0xbfb8aa3b, v11
	v_exp_f32_e32 v10, v10
	v_exp_f32_e32 v11, v11
	v_add_f32_e32 v12, 1.0, v12
	v_rcp_f32_e32 v12, v12
	v_add_f32_e32 v10, 1.0, v10
	v_add_f32_e32 v11, 1.0, v11
	v_rcp_f32_e32 v10, v10
	v_rcp_f32_e32 v11, v11
	v_pk_mul_f32 v[6:7], v[6:7], v[12:13]
	v_pk_mul_f32 v[8:9], v[8:9], v[10:11]
	v_cvt_pk_bf16_f32 v6, v6, v7
	v_cvt_pk_bf16_f32 v7, v8, v9
	v_lshl_add_u64 v[8:9], v[18:19], 0, v[118:119]
	global_load_dwordx2 v[8:9], v[8:9], off
	s_waitcnt vmcnt(0)
	v_lshlrev_b32_e32 v10, 16, v8
	v_and_b32_e32 v8, 0xffff0000, v8
	v_mul_f32_e32 v8, 0xbfb8aa3b, v8
	v_exp_f32_e32 v8, v8
	v_mul_f32_e32 v10, 0xbfb8aa3b, v10
	v_exp_f32_e32 v10, v10
	v_add_f32_e32 v8, 1.0, v8
	v_rcp_f32_e32 v11, v8
	v_lshlrev_b32_e32 v8, 16, v9
	v_and_b32_e32 v9, 0xffff0000, v9
	v_mul_f32_e32 v8, 0xbfb8aa3b, v8
	v_mul_f32_e32 v9, 0xbfb8aa3b, v9
	v_exp_f32_e32 v8, v8
	v_exp_f32_e32 v9, v9
	v_add_f32_e32 v10, 1.0, v10
	v_rcp_f32_e32 v10, v10
	v_add_f32_e32 v8, 1.0, v8
	v_add_f32_e32 v9, 1.0, v9
	v_rcp_f32_e32 v8, v8
	v_rcp_f32_e32 v9, v9
	v_pk_mul_f32 v[2:3], v[2:3], v[10:11]
	v_pk_mul_f32 v[4:5], v[4:5], v[8:9]
	v_cvt_pk_bf16_f32 v2, v2, v3
	v_cvt_pk_bf16_f32 v3, v4, v5
	ds_write2_b64 v0, v[6:7], v[2:3] offset0:232 offset1:236
	s_branch .LBB0_772

; DI f32x4 mfma16(bf16x8 a, bf16x8 b, f32x4 c) { return __builtin_amdgcn_mfma_f32_16x16x32_bf16(a, b, c, 0, 0, 0); }
; #pragma unroll
;   for (int ks = KS0; ks < KS1; ++ks) {
;     bf16x8 af[8], bfr[4];
; #pragma unroll
;     for (int i = 0; i < 8; ++i) {
;       const int r = wm * 128 + i * 16 + (lane & 15);
;       af[i] = *(const bf16x8*)(S + r * 64 + (((ks * 4 + (lane >> 4)) ^ ((r >> 1) & 7)) << 3));
;     }
; #pragma unroll
;     for (int j = 0; j < 4; ++j) {
;       const int r = wn * 64 + j * 16 + (lane & 15);
;       bfr[j] = *(const bf16x8*)(S + 16384 + r * 64 + (((ks * 4 + (lane >> 4)) ^ ((r >> 1) & 7)) << 3));
;     }
;     __builtin_amdgcn_s_setprio(1);
; #pragma unroll
;     for (int i = 0; i < 8; ++i)
; #pragma unroll
;       for (int j = 0; j < 4; ++j) acc[i][j] = mfma16(bfr[j], af[i], acc[i][j]);
;     __builtin_amdgcn_s_setprio(0);
;   }
; }
; DI void gemm8_accum(f32x4 (&acc)[8][4], const bf16_t* a, size_t lda, const bf16_t* b, size_t ldb, int nkb, bf16_t* L,
;                     const bool pre, const bf16_t* an, size_t ldan, const bf16_t* bn, size_t ldbn) {
;     ...
;   __syncthreads();
;   g8_store1(L + 32768, ra, lrow, lch);
;   g8_load1(ra, an, ldan, 0, lrow, lch);
;   __builtin_amdgcn_sched_barrier(0);
;   g8_compute<0, 1>(acc, L, wm, wn, lane);
;   __builtin_amdgcn_sched_barrier(0);
;   g8_store1(L + 32768 + 16384, rb, lrow, lch);
;   g8_load1(rb, bn, ldbn, 0, lrow, lch);
;   __builtin_amdgcn_sched_barrier(0);
;   g8_compute<1, 2>(acc, L, wm, wn, lane);
.Lstg_830_c:
	v_readlane_b32 s0, v254, 18
	s_add_i32 s12, s13, s0
	s_cmp_gt_u32 s12, 63
	s_cselect_b64 s[0:1], -1, 0
	s_cmp_lt_u32 s12, 64
	s_cselect_b32 s7, s12, s13
	s_lshl_b32 s2, s7, 1
	s_and_b32 s2, s2, 0x7fffffe0
	s_and_b32 s3, s7, 3
	s_or_b32 s2, s3, s2
	v_readlane_b32 s3, v252, 25
	s_or_b32 s2, s2, s3
	s_lshl_b32 s13, s11, 8
	s_mul_hi_u32 s3, s2, 0x2a3000
	s_mul_i32 s2, s2, 0x2a3000
	s_add_u32 s2, s16, s2
	s_addc_u32 s3, s17, s3
	v_mov_b32_e32 v177, v1
	v_mov_b32_e32 v175, v1
	v_mov_b32_e32 v173, v1
	v_lshl_add_u64 v[178:179], v[0:1], 1, s[2:3]
	v_lshl_add_u64 v[180:181], v[176:177], 1, s[2:3]
	v_lshl_add_u64 v[174:175], v[174:175], 1, s[2:3]
	v_lshl_add_u64 v[184:185], v[172:173], 1, s[2:3]
	s_barrier
	global_load_dwordx4 v[176:179], v[178:179], off offset:3632
	s_nop 0
	global_load_dwordx4 v[180:183], v[180:181], off offset:3632
	s_nop 0
	global_load_dwordx4 v[172:175], v[174:175], off offset:3632
	s_nop 0
	global_load_dwordx4 v[184:187], v[184:185], off offset:3632
	s_lshl_b32 s2, s7, 17
	s_and_b32 s2, s2, 0x180000
	v_readlane_b32 s20, v251, 63
	v_readlane_b32 s21, v252, 0
	s_add_u32 s2, s20, s2
	s_addc_u32 s3, s21, 0
	s_add_i32 s7, 0, 0x10000
	v_add3_u32 v0, s7, v165, v167
	s_waitcnt vmcnt(11)
	ds_write_b128 v0, v[18:21]
	s_waitcnt vmcnt(10)
	ds_write_b128 v0, v[22:25] offset:8192
	s_waitcnt vmcnt(9)
	ds_write_b128 v0, v[26:29] offset:16384
	s_waitcnt vmcnt(8)
	ds_write_b128 v0, v[30:33] offset:24576
	v_lshlrev_b32_e32 v0, 1, v169
	v_add_u32_e32 v169, 0, v0
	v_add_u32_e32 v171, v169, v195
	ds_read_b128 v[18:21], v171
	ds_read_b128 v[22:25], v171 offset:2048
	ds_read_b128 v[26:29], v171 offset:4096
	ds_read_b128 v[30:33], v171 offset:6144
	ds_read_b128 v[188:191], v171 offset:8192
	ds_read_b128 v[198:201], v171 offset:10240
	ds_read_b128 v[206:209], v171 offset:12288
	ds_read_b128 v[210:213], v171 offset:14336
	v_add_u32_e32 v169, v169, v194
	ds_read_b128 v[214:217], v169 offset:32768
	ds_read_b128 v[218:221], v169 offset:34816
	ds_read_b128 v[222:225], v169 offset:36864
	ds_read_b128 v[226:229], v169 offset:38912
	s_setprio 1
	s_waitcnt lgkmcnt(3)
	v_mfma_f32_16x16x32_bf16 v[158:161], v[214:217], v[18:21], v[158:161]
	s_waitcnt lgkmcnt(2)
	v_mfma_f32_16x16x32_bf16 v[154:157], v[218:221], v[18:21], v[154:157]
	s_waitcnt lgkmcnt(1)
	v_mfma_f32_16x16x32_bf16 v[150:153], v[222:225], v[18:21], v[150:153]
	s_waitcnt lgkmcnt(0)
	v_mfma_f32_16x16x32_bf16 v[18:21], v[226:229], v[18:21], v[146:149]
	v_mfma_f32_16x16x32_bf16 v[142:145], v[214:217], v[22:25], v[142:145]
	v_mfma_f32_16x16x32_bf16 v[138:141], v[218:221], v[22:25], v[138:141]
	v_mfma_f32_16x16x32_bf16 v[134:137], v[222:225], v[22:25], v[134:137]
	v_mfma_f32_16x16x32_bf16 v[22:25], v[226:229], v[22:25], v[130:133]
	v_mfma_f32_16x16x32_bf16 v[126:129], v[214:217], v[26:29], v[126:129]
	v_mfma_f32_16x16x32_bf16 v[122:125], v[218:221], v[26:29], v[122:125]
	v_mfma_f32_16x16x32_bf16 v[118:121], v[222:225], v[26:29], v[118:121]
	v_mfma_f32_16x16x32_bf16 v[26:29], v[226:229], v[26:29], v[114:117]
	v_mfma_f32_16x16x32_bf16 v[110:113], v[214:217], v[30:33], v[110:113]
	v_mfma_f32_16x16x32_bf16 v[106:109], v[218:221], v[30:33], v[106:109]
	v_mfma_f32_16x16x32_bf16 v[102:105], v[222:225], v[30:33], v[102:105]
	v_mfma_f32_16x16x32_bf16 v[30:33], v[226:229], v[30:33], v[98:101]
	v_mfma_f32_16x16x32_bf16 v[94:97], v[214:217], v[188:191], v[94:97]
	v_mfma_f32_16x16x32_bf16 v[90:93], v[218:221], v[188:191], v[90:93]
	v_mfma_f32_16x16x32_bf16 v[86:89], v[222:225], v[188:191], v[86:89]
	v_mfma_f32_16x16x32_bf16 v[82:85], v[226:229], v[188:191], v[82:85]
	v_mfma_f32_16x16x32_bf16 v[78:81], v[214:217], v[198:201], v[78:81]
	v_mfma_f32_16x16x32_bf16 v[74:77], v[218:221], v[198:201], v[74:77]
	v_mfma_f32_16x16x32_bf16 v[70:73], v[222:225], v[198:201], v[70:73]
	v_mfma_f32_16x16x32_bf16 v[66:69], v[226:229], v[198:201], v[66:69]
	v_mfma_f32_16x16x32_bf16 v[62:65], v[214:217], v[206:209], v[62:65]
	v_mfma_f32_16x16x32_bf16 v[58:61], v[218:221], v[206:209], v[58:61]
	v_mfma_f32_16x16x32_bf16 v[54:57], v[222:225], v[206:209], v[54:57]
	v_mfma_f32_16x16x32_bf16 v[50:53], v[226:229], v[206:209], v[50:53]
	v_mfma_f32_16x16x32_bf16 v[46:49], v[214:217], v[210:213], v[46:49]
	v_mfma_f32_16x16x32_bf16 v[38:41], v[222:225], v[210:213], v[38:41]
	v_mfma_f32_16x16x32_bf16 v[34:37], v[226:229], v[210:213], v[34:37]
	v_mfma_f32_16x16x32_bf16 v[42:45], v[218:221], v[210:213], v[42:45]
	s_setprio 0
	v_readlane_b32 s20, v254, 36
	v_mov_b32_e32 v171, v1
	v_mov_b32_e32 v169, v1
	v_add3_u32 v98, s20, v165, v167
	v_mov_b32_e32 v167, v1
	v_mov_b32_e32 v165, v1
	s_waitcnt vmcnt(7)
	ds_write_b128 v98, v[14:17]
	s_waitcnt vmcnt(6)
	ds_write_b128 v98, v[2:5] offset:8192
	s_waitcnt vmcnt(5)
	ds_write_b128 v98, v[6:9] offset:16384
	s_waitcnt vmcnt(4)
	ds_write_b128 v98, v[10:13] offset:24576
	v_lshl_add_u64 v[2:3], v[170:171], 1, s[2:3]
	v_lshl_add_u64 v[6:7], v[168:169], 1, s[2:3]
	v_lshl_add_u64 v[10:11], v[166:167], 1, s[2:3]
	v_lshl_add_u64 v[14:15], v[164:165], 1, s[2:3]
	global_load_dwordx4 v[2:5], v[2:3], off
	s_nop 0
	global_load_dwordx4 v[6:9], v[6:7], off
	s_nop 0
	global_load_dwordx4 v[10:13], v[10:11], off
	s_nop 0
	global_load_dwordx4 v[14:17], v[14:15], off
	v_lshlrev_b32_e32 v192, 1, v205
	v_add_u32_e32 v193, 0, v192
	v_add_u32_e32 v198, v193, v195
	ds_read_b128 v[98:101], v198
	ds_read_b128 v[114:117], v198 offset:2048
	ds_read_b128 v[130:133], v198 offset:4096
	ds_read_b128 v[146:149], v198 offset:6144
	ds_read_b128 v[164:167], v198 offset:8192
	ds_read_b128 v[168:171], v198 offset:10240
	ds_read_b128 v[188:191], v198 offset:12288
	ds_read_b128 v[198:201], v198 offset:14336
	v_add_u32_e32 v193, v193, v194
	ds_read_b128 v[206:209], v193 offset:32768
	ds_read_b128 v[210:213], v193 offset:34816
	ds_read_b128 v[214:217], v193 offset:36864
	ds_read_b128 v[218:221], v193 offset:38912
	s_setprio 1
	s_waitcnt lgkmcnt(3)
; DI f32x4 mfma16(bf16x8 a, bf16x8 b, f32x4 c) { return __builtin_amdgcn_mfma_f32_16x16x32_bf16(a, b, c, 0, 0, 0); }
; #pragma unroll
;   for (int ks = KS0; ks < KS1; ++ks) {
;     bf16x8 af[8], bfr[4];
; #pragma unroll
;     for (int i = 0; i < 8; ++i) {
;       const int r = wm * 128 + i * 16 + (lane & 15);
;       af[i] = *(const bf16x8*)(S + r * 64 + (((ks * 4 + (lane >> 4)) ^ ((r >> 1) & 7)) << 3));
;     }
; #pragma unroll
;     for (int j = 0; j < 4; ++j) {
;       const int r = wn * 64 + j * 16 + (lane & 15);
;       bfr[j] = *(const bf16x8*)(S + 16384 + r * 64 + (((ks * 4 + (lane >> 4)) ^ ((r >> 1) & 7)) << 3));
;     }
;     __builtin_amdgcn_s_setprio(1);
; #pragma unroll
;     for (int i = 0; i < 8; ++i)
; #pragma unroll
;       for (int j = 0; j < 4; ++j) acc[i][j] = mfma16(bfr[j], af[i], acc[i][j]);
;     __builtin_amdgcn_s_setprio(0);
;   }
; }
; DI void gemm8_accum(f32x4 (&acc)[8][4], const bf16_t* a, size_t lda, const bf16_t* b, size_t ldb, int nkb, bf16_t* L,
;                     const bool pre, const bf16_t* an, size_t ldan, const bf16_t* bn, size_t ldbn) {
;     ...
;   g8_compute<1, 2>(acc, L, wm, wn, lane);
;   __syncthreads();
;   g8_store1(L, ra, lrow, lch);
;   __builtin_amdgcn_sched_barrier(0);
;   g8_compute<0, 1>(acc, L + 32768, wm, wn, lane);
;   __builtin_amdgcn_sched_barrier(0);
;   g8_store1(L + 16384, rb, lrow, lch);
;   __builtin_amdgcn_sched_barrier(0);
;   g8_compute<1, 2>(acc, L + 32768, wm, wn, lane);
	v_mfma_f32_16x16x32_bf16 v[158:161], v[206:209], v[98:101], v[158:161]
	s_waitcnt lgkmcnt(2)
	v_mfma_f32_16x16x32_bf16 v[154:157], v[210:213], v[98:101], v[154:157]
	s_waitcnt lgkmcnt(1)
	v_mfma_f32_16x16x32_bf16 v[150:153], v[214:217], v[98:101], v[150:153]
	s_waitcnt lgkmcnt(0)
	v_mfma_f32_16x16x32_bf16 v[18:21], v[218:221], v[98:101], v[18:21]
	v_mfma_f32_16x16x32_bf16 v[98:101], v[206:209], v[114:117], v[142:145]
	v_mfma_f32_16x16x32_bf16 v[138:141], v[210:213], v[114:117], v[138:141]
	v_mfma_f32_16x16x32_bf16 v[134:137], v[214:217], v[114:117], v[134:137]
	v_mfma_f32_16x16x32_bf16 v[22:25], v[218:221], v[114:117], v[22:25]
	v_mfma_f32_16x16x32_bf16 v[114:117], v[206:209], v[130:133], v[126:129]
	v_mfma_f32_16x16x32_bf16 v[122:125], v[210:213], v[130:133], v[122:125]
	v_mfma_f32_16x16x32_bf16 v[118:121], v[214:217], v[130:133], v[118:121]
	v_mfma_f32_16x16x32_bf16 v[26:29], v[218:221], v[130:133], v[26:29]
	v_mfma_f32_16x16x32_bf16 v[110:113], v[206:209], v[146:149], v[110:113]
	v_mfma_f32_16x16x32_bf16 v[106:109], v[210:213], v[146:149], v[106:109]
	v_mfma_f32_16x16x32_bf16 v[102:105], v[214:217], v[146:149], v[102:105]
	v_mfma_f32_16x16x32_bf16 v[30:33], v[218:221], v[146:149], v[30:33]
	v_mfma_f32_16x16x32_bf16 v[94:97], v[206:209], v[164:167], v[94:97]
	v_mfma_f32_16x16x32_bf16 v[90:93], v[210:213], v[164:167], v[90:93]
	v_mfma_f32_16x16x32_bf16 v[86:89], v[214:217], v[164:167], v[86:89]
	v_mfma_f32_16x16x32_bf16 v[82:85], v[218:221], v[164:167], v[82:85]
	v_mfma_f32_16x16x32_bf16 v[78:81], v[206:209], v[168:171], v[78:81]
	v_mfma_f32_16x16x32_bf16 v[74:77], v[210:213], v[168:171], v[74:77]
	v_mfma_f32_16x16x32_bf16 v[70:73], v[214:217], v[168:171], v[70:73]
	v_mfma_f32_16x16x32_bf16 v[66:69], v[218:221], v[168:171], v[66:69]
	v_mfma_f32_16x16x32_bf16 v[62:65], v[206:209], v[188:191], v[62:65]
	v_mfma_f32_16x16x32_bf16 v[58:61], v[210:213], v[188:191], v[58:61]
	v_mfma_f32_16x16x32_bf16 v[54:57], v[214:217], v[188:191], v[54:57]
	v_mfma_f32_16x16x32_bf16 v[50:53], v[218:221], v[188:191], v[50:53]
	v_mfma_f32_16x16x32_bf16 v[46:49], v[206:209], v[198:201], v[46:49]
	v_mfma_f32_16x16x32_bf16 v[38:41], v[214:217], v[198:201], v[38:41]
	v_mfma_f32_16x16x32_bf16 v[34:37], v[218:221], v[198:201], v[34:37]
	v_mfma_f32_16x16x32_bf16 v[42:45], v[210:213], v[198:201], v[42:45]
	s_setprio 0
	s_barrier
	s_waitcnt vmcnt(7)
	ds_write_b128 v163, v[176:179]
	s_waitcnt vmcnt(6)
	ds_write_b128 v163, v[180:183] offset:8192
	s_waitcnt vmcnt(5)
	ds_write_b128 v163, v[172:175] offset:16384
	s_waitcnt vmcnt(4)
	ds_write_b128 v163, v[184:187] offset:24576
	v_add3_u32 v176, s7, v0, v195
	ds_read_b128 v[126:129], v176
	ds_read_b128 v[130:133], v176 offset:2048
	ds_read_b128 v[142:145], v176 offset:4096
	ds_read_b128 v[146:149], v176 offset:6144
	ds_read_b128 v[164:167], v176 offset:8192
	ds_read_b128 v[168:171], v176 offset:10240
	ds_read_b128 v[172:175], v176 offset:12288
	ds_read_b128 v[176:179], v176 offset:14336
	v_add3_u32 v0, s20, v0, v194
	ds_read_b128 v[180:183], v0
	ds_read_b128 v[184:187], v0 offset:2048
	ds_read_b128 v[188:191], v0 offset:4096
	ds_read_b128 v[198:201], v0 offset:6144
	s_setprio 1
	s_waitcnt lgkmcnt(3)
	v_mfma_f32_16x16x32_bf16 v[158:161], v[180:183], v[126:129], v[158:161]
	s_waitcnt lgkmcnt(2)
	v_mfma_f32_16x16x32_bf16 v[154:157], v[184:187], v[126:129], v[154:157]
	s_waitcnt lgkmcnt(1)
	v_mfma_f32_16x16x32_bf16 v[150:153], v[188:191], v[126:129], v[150:153]
	s_waitcnt lgkmcnt(0)
	v_mfma_f32_16x16x32_bf16 v[18:21], v[198:201], v[126:129], v[18:21]
	v_mfma_f32_16x16x32_bf16 v[98:101], v[180:183], v[130:133], v[98:101]
	v_mfma_f32_16x16x32_bf16 v[126:129], v[184:187], v[130:133], v[138:141]
	v_mfma_f32_16x16x32_bf16 v[134:137], v[188:191], v[130:133], v[134:137]
	v_mfma_f32_16x16x32_bf16 v[22:25], v[198:201], v[130:133], v[22:25]
	v_mfma_f32_16x16x32_bf16 v[114:117], v[180:183], v[142:145], v[114:117]
	v_mfma_f32_16x16x32_bf16 v[122:125], v[184:187], v[142:145], v[122:125]
	v_mfma_f32_16x16x32_bf16 v[118:121], v[188:191], v[142:145], v[118:121]
	v_mfma_f32_16x16x32_bf16 v[26:29], v[198:201], v[142:145], v[26:29]
	v_mfma_f32_16x16x32_bf16 v[130:133], v[180:183], v[146:149], v[110:113]
	v_mfma_f32_16x16x32_bf16 v[30:33], v[198:201], v[146:149], v[30:33]
	v_mfma_f32_16x16x32_bf16 v[138:141], v[184:187], v[146:149], v[106:109]
	v_mfma_f32_16x16x32_bf16 v[142:145], v[188:191], v[146:149], v[102:105]
	v_mfma_f32_16x16x32_bf16 v[146:149], v[180:183], v[164:167], v[94:97]
	v_mfma_f32_16x16x32_bf16 v[206:209], v[184:187], v[164:167], v[90:93]
	v_mfma_f32_16x16x32_bf16 v[210:213], v[188:191], v[164:167], v[86:89]
	v_mfma_f32_16x16x32_bf16 v[164:167], v[198:201], v[164:167], v[82:85]
	v_mfma_f32_16x16x32_bf16 v[214:217], v[180:183], v[168:171], v[78:81]
	v_mfma_f32_16x16x32_bf16 v[218:221], v[184:187], v[168:171], v[74:77]
	v_mfma_f32_16x16x32_bf16 v[222:225], v[188:191], v[168:171], v[70:73]
	v_mfma_f32_16x16x32_bf16 v[168:171], v[198:201], v[168:171], v[66:69]
	v_mfma_f32_16x16x32_bf16 v[226:229], v[180:183], v[172:175], v[62:65]
	v_mfma_f32_16x16x32_bf16 v[230:233], v[184:187], v[172:175], v[58:61]
	v_mfma_f32_16x16x32_bf16 v[234:237], v[188:191], v[172:175], v[54:57]
	v_mfma_f32_16x16x32_bf16 v[172:175], v[198:201], v[172:175], v[50:53]
	v_mfma_f32_16x16x32_bf16 v[180:183], v[180:183], v[176:179], v[46:49]
	v_mfma_f32_16x16x32_bf16 v[184:187], v[184:187], v[176:179], v[42:45]
	v_mfma_f32_16x16x32_bf16 v[188:191], v[188:191], v[176:179], v[38:41]
	v_mfma_f32_16x16x32_bf16 v[176:179], v[198:201], v[176:179], v[34:37]
	s_setprio 0
	s_waitcnt vmcnt(3)
	ds_write_b128 v163, v[2:5] offset:32768
	s_waitcnt vmcnt(2)
; DI int TID8() { int t = threadIdx.x; asm volatile("" : "+v"(t)); return t; }
; DI void gemm8_accum(f32x4 (&acc)[8][4], const bf16_t* a, size_t lda, const bf16_t* b, size_t ldb, int nkb, bf16_t* L,
;                     const bool pre, const bf16_t* an, size_t ldan, const bf16_t* bn, size_t ldbn) {
;     ...
;   g8_compute<1, 2>(acc, L, wm, wn, lane);
;   __syncthreads();
;   g8_store1(L, ra, lrow, lch);
;   __builtin_amdgcn_sched_barrier(0);
;   g8_compute<0, 1>(acc, L + 32768, wm, wn, lane);
;   __builtin_amdgcn_sched_barrier(0);
;   g8_store1(L + 16384, rb, lrow, lch);
;   __builtin_amdgcn_sched_barrier(0);
;   g8_compute<1, 2>(acc, L + 32768, wm, wn, lane);
;   __syncthreads();
; DI void gemm8_epi_resid(f32x4 (&acc)[8][4], int m0, int n0, int ntile8, bf16_t* L, const float* xin, float* out, bf16_t* xb, float* rowpart) {
;   const int tid = TID8(), lane = tid & 63, w = tid >> 6;
;   const int wm = w >> 2, wn = w & 3;
;   float* red = (float*)(L + 32768);
; #pragma unroll
;   for (int i = 0; i < 8; ++i) {
;     const int ml = wm * 128 + i * 16 + (lane & 15);
;     const size_t rowoff = (size_t)(m0 + ml) * DM;
;     float ss = 0.f;
; #pragma unroll
;     for (int j = 0; j < 4; ++j) {
;       const int n = n0 + wn * 64 + j * 16 + (lane >> 4) * 4;
;       const float4 xv = *(const float4*)(xin + rowoff + n);
	ds_write_b128 v163, v[6:9] offset:40960
	s_waitcnt vmcnt(1)
	ds_write_b128 v163, v[10:13] offset:49152
	s_waitcnt vmcnt(0)
	ds_write_b128 v163, v[14:17] offset:57344
	v_add3_u32 v0, s7, v192, v195
	ds_read_b128 v[2:5], v0
	ds_read_b128 v[6:9], v0 offset:2048
	ds_read_b128 v[10:13], v0 offset:4096
	ds_read_b128 v[14:17], v0 offset:6144
	ds_read_b128 v[34:37], v0 offset:8192
	ds_read_b128 v[198:201], v0 offset:10240
	ds_read_b128 v[238:241], v0 offset:12288
	ds_read_b128 v[242:245], v0 offset:14336
	v_add3_u32 v0, s20, v192, v194
	ds_read_b128 v[192:195], v0
	ds_read_b128 v[246:249], v0 offset:2048
	ds_read_b128 v[38:41], v0 offset:4096
	ds_read_b128 v[42:45], v0 offset:6144
	s_setprio 1
	s_waitcnt lgkmcnt(3)
	v_mfma_f32_16x16x32_bf16 v[158:161], v[192:195], v[2:5], v[158:161]
	s_waitcnt lgkmcnt(2)
	v_mfma_f32_16x16x32_bf16 v[154:157], v[246:249], v[2:5], v[154:157]
	s_waitcnt lgkmcnt(1)
	v_mfma_f32_16x16x32_bf16 v[150:153], v[38:41], v[2:5], v[150:153]
	s_waitcnt lgkmcnt(0)
	v_mfma_f32_16x16x32_bf16 v[2:5], v[42:45], v[2:5], v[18:21]
	v_mfma_f32_16x16x32_bf16 v[110:113], v[192:195], v[6:9], v[98:101]
	v_mfma_f32_16x16x32_bf16 v[106:109], v[246:249], v[6:9], v[126:129]
	v_mfma_f32_16x16x32_bf16 v[102:105], v[38:41], v[6:9], v[134:137]
	v_mfma_f32_16x16x32_bf16 v[98:101], v[42:45], v[6:9], v[22:25]
	v_mfma_f32_16x16x32_bf16 v[94:97], v[192:195], v[10:13], v[114:117]
	v_mfma_f32_16x16x32_bf16 v[90:93], v[246:249], v[10:13], v[122:125]
	v_mfma_f32_16x16x32_bf16 v[86:89], v[38:41], v[10:13], v[118:121]
	v_mfma_f32_16x16x32_bf16 v[82:85], v[42:45], v[10:13], v[26:29]
	v_mfma_f32_16x16x32_bf16 v[78:81], v[192:195], v[14:17], v[130:133]
	v_mfma_f32_16x16x32_bf16 v[74:77], v[246:249], v[14:17], v[138:141]
	v_mfma_f32_16x16x32_bf16 v[70:73], v[38:41], v[14:17], v[142:145]
	v_mfma_f32_16x16x32_bf16 v[66:69], v[42:45], v[14:17], v[30:33]
	v_mfma_f32_16x16x32_bf16 v[62:65], v[192:195], v[34:37], v[146:149]
	v_mfma_f32_16x16x32_bf16 v[58:61], v[246:249], v[34:37], v[206:209]
	v_mfma_f32_16x16x32_bf16 v[54:57], v[38:41], v[34:37], v[210:213]
	v_mfma_f32_16x16x32_bf16 v[50:53], v[42:45], v[34:37], v[164:167]
	v_mfma_f32_16x16x32_bf16 v[46:49], v[192:195], v[198:201], v[214:217]
	v_mfma_f32_16x16x32_bf16 v[128:131], v[246:249], v[198:201], v[218:221]
	v_mfma_f32_16x16x32_bf16 v[124:127], v[38:41], v[198:201], v[222:225]
	v_mfma_f32_16x16x32_bf16 v[34:37], v[42:45], v[198:201], v[168:171]
	v_mfma_f32_16x16x32_bf16 v[30:33], v[192:195], v[238:241], v[226:229]
	v_mfma_f32_16x16x32_bf16 v[26:29], v[246:249], v[238:241], v[230:233]
	v_mfma_f32_16x16x32_bf16 v[22:25], v[38:41], v[238:241], v[234:237]
	v_mfma_f32_16x16x32_bf16 v[18:21], v[42:45], v[238:241], v[172:175]
	v_mfma_f32_16x16x32_bf16 v[14:17], v[192:195], v[242:245], v[180:183]
	v_mfma_f32_16x16x32_bf16 v[10:13], v[246:249], v[242:245], v[184:187]
	v_mfma_f32_16x16x32_bf16 v[6:9], v[38:41], v[242:245], v[188:191]
	v_mfma_f32_16x16x32_bf16 v[38:41], v[42:45], v[242:245], v[176:179]
	s_setprio 0
	v_mov_b32_e32 v118, v196
	s_barrier
	s_movk_i32 s2, 0xff80
	v_ashrrev_i32_e32 v0, 1, v118
	v_and_b32_e32 v42, 15, v118
	v_and_or_b32 v121, v0, s2, v42
	v_bfe_u32 v119, v118, 6, 2
	v_lshrrev_b32_e32 v42, 2, v118
	v_add_u32_e32 v116, s6, v121
	v_lshlrev_b32_e32 v0, 6, v119
	v_and_b32_e32 v42, 12, v42
	v_ashrrev_i32_e32 v117, 31, v116
	v_readlane_b32 s2, v254, 51
	v_or3_b32 v114, v42, s13, v0
	v_lshlrev_b64 v[122:123], 12, v[116:117]
	v_readlane_b32 s3, v254, 52
	v_lshlrev_b32_e32 v0, 2, v114
	v_readlane_b32 s24, v251, 33
	v_lshl_add_u64 v[42:43], s[2:3], 0, v[122:123]
	v_lshl_add_u64 v[140:141], v[42:43], 0, v[0:1]
	v_lshlrev_b64 v[132:133], 11, v[116:117]
	v_readlane_b32 s26, v251, 35
	v_readlane_b32 s27, v251, 36
	v_mov_b32_e32 v115, v1
	v_lshlrev_b32_e32 v114, 1, v114
	v_lshl_add_u64 v[122:123], s[26:27], 0, v[122:123]
	v_lshl_add_u64 v[132:133], s[18:19], 0, v[132:133]
	v_lshl_add_u64 v[122:123], v[122:123], 0, v[0:1]
	v_lshl_add_u64 v[144:145], v[132:133], 0, v[114:115]
	v_and_b32_e32 v146, 63, v118
	v_lshlrev_b32_e32 v120, 2, v146
	v_xor_b32_e32 v117, 64, v120
	v_xor_b32_e32 v120, 0x80, v120
	v_cmp_gt_u32_e32 vcc, 16, v146
	v_readlane_b32 s25, v251, 34
	v_lshl_add_u32 v188, v119, 10, s7
	v_lshl_add_u32 v188, v121, 2, v188
	v_mov_b32_e32 v189, v117
	v_mov_b32_e32 v190, v120
	v_and_b32_e32 v240, 63, v118
	v_cmp_gt_u32_e64 s[88:89], 16, v240
	v_and_b32_e32 v243, 15, v118
	v_bfe_u32 v242, v118, 4, 2
	v_and_b32_e32 v240, 8, v243
	v_cmp_eq_u32_e64 s[90:91], 0, v240
	v_lshlrev_b32_e32 v236, 12, v243
	v_lshl_or_b32 v236, v242, 4, v236
	v_lshlrev_b32_e32 v237, 11, v243
	v_lshl_or_b32 v237, v242, 3, v237
	v_sub_co_u32_e32 v238, vcc, v140, v236
	v_subbrev_co_u32_e32 v239, vcc, 0, v141, vcc
	s_nop 0
	v_readfirstlane_b32 s40, v238
	v_readfirstlane_b32 s41, v239
	v_sub_co_u32_e32 v238, vcc, v122, v236
	v_subbrev_co_u32_e32 v239, vcc, 0, v123, vcc
	s_nop 0
	v_readfirstlane_b32 s44, v238
	v_readfirstlane_b32 s45, v239
	v_sub_co_u32_e32 v238, vcc, v144, v237
	v_subbrev_co_u32_e32 v239, vcc, 0, v145, vcc
	s_nop 0
	v_readfirstlane_b32 s48, v238
	v_readfirstlane_b32 s49, v239
	s_add_u32 s42, s40, 0x8000
	s_addc_u32 s43, s41, 0
	s_add_u32 s46, s44, 0x8000
	s_addc_u32 s47, s45, 0
	s_add_u32 s50, s48, 0x4000
	s_addc_u32 s51, s49, 0
	v_and_b32_e32 v238, 7, v243
	v_lshrrev_b32_e32 v239, 3, v243
	v_lshlrev_b32_e32 v244, 12, v238
	v_lshl_or_b32 v244, v239, 6, v244
	v_lshl_or_b32 v244, v242, 4, v244
	v_lshlrev_b32_e32 v245, 11, v238
	v_lshl_or_b32 v245, v239, 5, v245
	v_lshl_or_b32 v245, v242, 3, v245
	global_load_dwordx4 v[192:195], v244, s[40:41]
	global_load_dwordx4 v[198:201], v244, s[40:41] offset:128
	global_load_dwordx4 v[202:205], v244, s[42:43]
	global_load_dwordx4 v[206:209], v244, s[42:43] offset:128
	s_add_u32 s40, s40, 0x10000
	s_addc_u32 s41, s41, 0
	s_add_u32 s42, s42, 0x10000
	s_addc_u32 s43, s43, 0
	global_load_dwordx4 v[216:219], v244, s[40:41]
	global_load_dwordx4 v[220:223], v244, s[40:41] offset:128
	global_load_dwordx4 v[224:227], v244, s[42:43]
	global_load_dwordx4 v[228:231], v244, s[42:43] offset:128
	s_add_u32 s40, s40, 0x10000
	s_addc_u32 s41, s41, 0
	s_add_u32 s42, s42, 0x10000
	s_addc_u32 s43, s43, 0
	s_waitcnt vmcnt(4)
; DI void gemm8_epi_resid(f32x4 (&acc)[8][4], int m0, int n0, int ntile8, bf16_t* L, const float* xin, float* out, bf16_t* xb, float* rowpart) {
;     ...
; #pragma unroll
;   for (int i = 0; i < 8; ++i) {
;     const int ml = wm * 128 + i * 16 + (lane & 15);
;     const size_t rowoff = (size_t)(m0 + ml) * DM;
;     float ss = 0.f;
; #pragma unroll
;     for (int j = 0; j < 4; ++j) {
;       const int n = n0 + wn * 64 + j * 16 + (lane >> 4) * 4;
;       const float4 xv = *(const float4*)(xin + rowoff + n);
;       const float o0 = xv.x + acc[i][j][0], o1 = xv.y + acc[i][j][1], o2 = xv.z + acc[i][j][2], o3 = xv.w + acc[i][j][3];
;       *(float4*)(out + rowoff + n) = make_float4(o0, o1, o2, o3);
;       ss += o0 * o0 + o1 * o1 + o2 * o2 + o3 * o3;
;       uint2 u;
;       u.x = pack2(o0, o1);
;       u.y = pack2(o2, o3);
;       *(uint2*)(xb + rowoff + n) = u;
;     }
;     ss += shx(ss, 16, lane);
;     ss += shx(ss, 32, lane);
;     if ((lane >> 4) == 0) red[wn * 256 + ml] = ss;
;   }
	v_mov_b32_dpp v232, v154 row_ror:8 row_mask:0xf bank_mask:0xf
	v_mov_b32_dpp v233, v155 row_ror:8 row_mask:0xf bank_mask:0xf
	v_mov_b32_dpp v234, v156 row_ror:8 row_mask:0xf bank_mask:0xf
	v_mov_b32_dpp v235, v157 row_ror:8 row_mask:0xf bank_mask:0xf
	v_cndmask_b32_e64 v232, v232, v158, s[90:91]
	v_cndmask_b32_e64 v233, v233, v159, s[90:91]
	v_cndmask_b32_e64 v234, v234, v160, s[90:91]
	v_cndmask_b32_e64 v235, v235, v161, s[90:91]
	v_pk_add_f32 v[232:233], v[232:233], v[192:193]
	v_pk_add_f32 v[234:235], v[234:235], v[194:195]
	s_nop 0
	global_store_dwordx4 v244, v[232:235], s[44:45] nt
	v_cvt_pk_bf16_f32 v240, v232, v233
	v_cvt_pk_bf16_f32 v241, v234, v235
	v_pk_mul_f32 v[236:237], v[232:233], v[232:233]
	v_pk_mul_f32 v[238:239], v[234:235], v[234:235]
	global_store_dwordx2 v245, v[240:241], s[48:49] nt
	v_add_f32_e32 v242, v236, v237
	v_add_f32_e32 v242, v242, v238
	v_add_f32_e32 v242, v242, v239
	v_mov_b32_dpp v232, v158 row_ror:8 row_mask:0xf bank_mask:0xf
	v_mov_b32_dpp v233, v159 row_ror:8 row_mask:0xf bank_mask:0xf
	v_mov_b32_dpp v234, v160 row_ror:8 row_mask:0xf bank_mask:0xf
	v_mov_b32_dpp v235, v161 row_ror:8 row_mask:0xf bank_mask:0xf
	v_cndmask_b32_e64 v232, v154, v232, s[90:91]
	v_cndmask_b32_e64 v233, v155, v233, s[90:91]
	v_cndmask_b32_e64 v234, v156, v234, s[90:91]
	v_cndmask_b32_e64 v235, v157, v235, s[90:91]
	v_pk_add_f32 v[232:233], v[232:233], v[202:203]
	v_pk_add_f32 v[234:235], v[234:235], v[204:205]
	s_nop 0
	global_store_dwordx4 v244, v[232:235], s[46:47] nt
	v_cvt_pk_bf16_f32 v240, v232, v233
	v_cvt_pk_bf16_f32 v241, v234, v235
	v_pk_mul_f32 v[236:237], v[232:233], v[232:233]
	v_pk_mul_f32 v[238:239], v[234:235], v[234:235]
	global_store_dwordx2 v245, v[240:241], s[50:51] nt
	v_add_f32_e32 v191, v236, v237
	v_add_f32_e32 v191, v191, v238
	v_add_f32_e32 v191, v191, v239
	v_mov_b32_dpp v232, v2 row_ror:8 row_mask:0xf bank_mask:0xf
	v_mov_b32_dpp v233, v3 row_ror:8 row_mask:0xf bank_mask:0xf
	v_mov_b32_dpp v234, v4 row_ror:8 row_mask:0xf bank_mask:0xf
	v_mov_b32_dpp v235, v5 row_ror:8 row_mask:0xf bank_mask:0xf
	v_cndmask_b32_e64 v232, v232, v150, s[90:91]
	v_cndmask_b32_e64 v233, v233, v151, s[90:91]
	v_cndmask_b32_e64 v234, v234, v152, s[90:91]
	v_cndmask_b32_e64 v235, v235, v153, s[90:91]
	v_pk_add_f32 v[232:233], v[232:233], v[198:199]
	v_pk_add_f32 v[234:235], v[234:235], v[200:201]
	s_nop 0
	global_store_dwordx4 v244, v[232:235], s[44:45] offset:128 nt
	v_cvt_pk_bf16_f32 v240, v232, v233
	v_cvt_pk_bf16_f32 v241, v234, v235
	v_pk_mul_f32 v[236:237], v[232:233], v[232:233]
	v_pk_mul_f32 v[238:239], v[234:235], v[234:235]
	global_store_dwordx2 v245, v[240:241], s[48:49] offset:64 nt
	v_add_f32_e32 v242, v242, v236
	v_add_f32_e32 v242, v242, v237
	v_add_f32_e32 v242, v242, v238
	v_add_f32_e32 v242, v242, v239
	v_mov_b32_dpp v232, v150 row_ror:8 row_mask:0xf bank_mask:0xf
	v_mov_b32_dpp v233, v151 row_ror:8 row_mask:0xf bank_mask:0xf
	v_mov_b32_dpp v234, v152 row_ror:8 row_mask:0xf bank_mask:0xf
	v_mov_b32_dpp v235, v153 row_ror:8 row_mask:0xf bank_mask:0xf
	v_cndmask_b32_e64 v232, v2, v232, s[90:91]
	v_cndmask_b32_e64 v233, v3, v233, s[90:91]
	v_cndmask_b32_e64 v234, v4, v234, s[90:91]
	v_cndmask_b32_e64 v235, v5, v235, s[90:91]
	v_pk_add_f32 v[232:233], v[232:233], v[206:207]
	v_pk_add_f32 v[234:235], v[234:235], v[208:209]
	s_nop 0
	global_store_dwordx4 v244, v[232:235], s[46:47] offset:128 nt
	v_cvt_pk_bf16_f32 v240, v232, v233
	v_cvt_pk_bf16_f32 v241, v234, v235
	v_pk_mul_f32 v[236:237], v[232:233], v[232:233]
	v_pk_mul_f32 v[238:239], v[234:235], v[234:235]
	global_store_dwordx2 v245, v[240:241], s[50:51] offset:64 nt
	v_add_f32_e32 v191, v191, v236
	v_add_f32_e32 v191, v191, v237
	v_add_f32_e32 v191, v191, v238
	v_add_f32_e32 v191, v191, v239
	s_nop 1
	v_add_f32_dpp v242, v242, v242 row_ror:8 row_mask:0xf bank_mask:0xf
	v_add_f32_dpp v191, v191, v191 row_ror:8 row_mask:0xf bank_mask:0xf
	s_add_u32 s44, s44, 0x10000
	s_addc_u32 s45, s45, 0
	s_add_u32 s46, s46, 0x10000
	s_addc_u32 s47, s47, 0
	s_add_u32 s48, s48, 0x8000
	s_addc_u32 s49, s49, 0
	s_add_u32 s50, s50, 0x8000
	s_addc_u32 s51, s51, 0
	v_cndmask_b32_e64 v242, v191, v242, s[90:91]
	ds_bpermute_b32 v243, v189, v242
	global_load_dwordx4 v[192:195], v244, s[40:41]
	global_load_dwordx4 v[198:201], v244, s[40:41] offset:128
	global_load_dwordx4 v[202:205], v244, s[42:43]
	global_load_dwordx4 v[206:209], v244, s[42:43] offset:128
	s_add_u32 s40, s40, 0x10000
	s_addc_u32 s41, s41, 0
	s_add_u32 s42, s42, 0x10000
	s_addc_u32 s43, s43, 0
	s_waitcnt lgkmcnt(0)
	v_add_f32_e32 v242, v242, v243
	ds_bpermute_b32 v243, v190, v242
	s_waitcnt lgkmcnt(0)
	v_add_f32_e32 v242, v242, v243
	s_and_saveexec_b64 s[2:3], s[88:89]
	ds_write_b32 v188, v242
	s_or_b64 exec, exec, s[2:3]
	s_waitcnt vmcnt(12)
; DI void gemm8_epi_resid(f32x4 (&acc)[8][4], int m0, int n0, int ntile8, bf16_t* L, const float* xin, float* out, bf16_t* xb, float* rowpart) {
;     ...
; #pragma unroll
;   for (int i = 0; i < 8; ++i) {
;     const int ml = wm * 128 + i * 16 + (lane & 15);
;     const size_t rowoff = (size_t)(m0 + ml) * DM;
;     float ss = 0.f;
; #pragma unroll
;     for (int j = 0; j < 4; ++j) {
;       const int n = n0 + wn * 64 + j * 16 + (lane >> 4) * 4;
;       const float4 xv = *(const float4*)(xin + rowoff + n);
;       const float o0 = xv.x + acc[i][j][0], o1 = xv.y + acc[i][j][1], o2 = xv.z + acc[i][j][2], o3 = xv.w + acc[i][j][3];
;       *(float4*)(out + rowoff + n) = make_float4(o0, o1, o2, o3);
;       ss += o0 * o0 + o1 * o1 + o2 * o2 + o3 * o3;
;       uint2 u;
;       u.x = pack2(o0, o1);
;       u.y = pack2(o2, o3);
;       *(uint2*)(xb + rowoff + n) = u;
;     }
;     ss += shx(ss, 16, lane);
;     ss += shx(ss, 32, lane);
;     if ((lane >> 4) == 0) red[wn * 256 + ml] = ss;
;   }
	v_mov_b32_dpp v232, v106 row_ror:8 row_mask:0xf bank_mask:0xf
	v_mov_b32_dpp v233, v107 row_ror:8 row_mask:0xf bank_mask:0xf
	v_mov_b32_dpp v234, v108 row_ror:8 row_mask:0xf bank_mask:0xf
	v_mov_b32_dpp v235, v109 row_ror:8 row_mask:0xf bank_mask:0xf
	v_cndmask_b32_e64 v232, v232, v110, s[90:91]
	v_cndmask_b32_e64 v233, v233, v111, s[90:91]
	v_cndmask_b32_e64 v234, v234, v112, s[90:91]
	v_cndmask_b32_e64 v235, v235, v113, s[90:91]
	v_pk_add_f32 v[232:233], v[232:233], v[216:217]
	v_pk_add_f32 v[234:235], v[234:235], v[218:219]
	s_nop 0
	global_store_dwordx4 v244, v[232:235], s[44:45] nt
	v_cvt_pk_bf16_f32 v240, v232, v233
	v_cvt_pk_bf16_f32 v241, v234, v235
	v_pk_mul_f32 v[236:237], v[232:233], v[232:233]
	v_pk_mul_f32 v[238:239], v[234:235], v[234:235]
	global_store_dwordx2 v245, v[240:241], s[48:49] nt
	v_add_f32_e32 v242, v236, v237
	v_add_f32_e32 v242, v242, v238
	v_add_f32_e32 v242, v242, v239
	v_mov_b32_dpp v232, v110 row_ror:8 row_mask:0xf bank_mask:0xf
	v_mov_b32_dpp v233, v111 row_ror:8 row_mask:0xf bank_mask:0xf
	v_mov_b32_dpp v234, v112 row_ror:8 row_mask:0xf bank_mask:0xf
	v_mov_b32_dpp v235, v113 row_ror:8 row_mask:0xf bank_mask:0xf
	v_cndmask_b32_e64 v232, v106, v232, s[90:91]
	v_cndmask_b32_e64 v233, v107, v233, s[90:91]
	v_cndmask_b32_e64 v234, v108, v234, s[90:91]
	v_cndmask_b32_e64 v235, v109, v235, s[90:91]
	v_pk_add_f32 v[232:233], v[232:233], v[224:225]
	v_pk_add_f32 v[234:235], v[234:235], v[226:227]
	s_nop 0
	global_store_dwordx4 v244, v[232:235], s[46:47] nt
	v_cvt_pk_bf16_f32 v240, v232, v233
	v_cvt_pk_bf16_f32 v241, v234, v235
	v_pk_mul_f32 v[236:237], v[232:233], v[232:233]
	v_pk_mul_f32 v[238:239], v[234:235], v[234:235]
	global_store_dwordx2 v245, v[240:241], s[50:51] nt
	v_add_f32_e32 v191, v236, v237
	v_add_f32_e32 v191, v191, v238
	v_add_f32_e32 v191, v191, v239
	v_mov_b32_dpp v232, v98 row_ror:8 row_mask:0xf bank_mask:0xf
	v_mov_b32_dpp v233, v99 row_ror:8 row_mask:0xf bank_mask:0xf
	v_mov_b32_dpp v234, v100 row_ror:8 row_mask:0xf bank_mask:0xf
	v_mov_b32_dpp v235, v101 row_ror:8 row_mask:0xf bank_mask:0xf
	v_cndmask_b32_e64 v232, v232, v102, s[90:91]
	v_cndmask_b32_e64 v233, v233, v103, s[90:91]
	v_cndmask_b32_e64 v234, v234, v104, s[90:91]
	v_cndmask_b32_e64 v235, v235, v105, s[90:91]
	v_pk_add_f32 v[232:233], v[232:233], v[220:221]
	v_pk_add_f32 v[234:235], v[234:235], v[222:223]
	s_nop 0
	global_store_dwordx4 v244, v[232:235], s[44:45] offset:128 nt
	v_cvt_pk_bf16_f32 v240, v232, v233
	v_cvt_pk_bf16_f32 v241, v234, v235
	v_pk_mul_f32 v[236:237], v[232:233], v[232:233]
	v_pk_mul_f32 v[238:239], v[234:235], v[234:235]
	global_store_dwordx2 v245, v[240:241], s[48:49] offset:64 nt
	v_add_f32_e32 v242, v242, v236
	v_add_f32_e32 v242, v242, v237
	v_add_f32_e32 v242, v242, v238
	v_add_f32_e32 v242, v242, v239
	v_mov_b32_dpp v232, v102 row_ror:8 row_mask:0xf bank_mask:0xf
	v_mov_b32_dpp v233, v103 row_ror:8 row_mask:0xf bank_mask:0xf
	v_mov_b32_dpp v234, v104 row_ror:8 row_mask:0xf bank_mask:0xf
	v_mov_b32_dpp v235, v105 row_ror:8 row_mask:0xf bank_mask:0xf
	v_cndmask_b32_e64 v232, v98, v232, s[90:91]
	v_cndmask_b32_e64 v233, v99, v233, s[90:91]
	v_cndmask_b32_e64 v234, v100, v234, s[90:91]
	v_cndmask_b32_e64 v235, v101, v235, s[90:91]
	v_pk_add_f32 v[232:233], v[232:233], v[228:229]
	v_pk_add_f32 v[234:235], v[234:235], v[230:231]
	s_nop 0
	global_store_dwordx4 v244, v[232:235], s[46:47] offset:128 nt
	v_cvt_pk_bf16_f32 v240, v232, v233
	v_cvt_pk_bf16_f32 v241, v234, v235
	v_pk_mul_f32 v[236:237], v[232:233], v[232:233]
	v_pk_mul_f32 v[238:239], v[234:235], v[234:235]
	global_store_dwordx2 v245, v[240:241], s[50:51] offset:64 nt
	v_add_f32_e32 v191, v191, v236
	v_add_f32_e32 v191, v191, v237
	v_add_f32_e32 v191, v191, v238
	v_add_f32_e32 v191, v191, v239
	s_nop 1
	v_add_f32_dpp v242, v242, v242 row_ror:8 row_mask:0xf bank_mask:0xf
	v_add_f32_dpp v191, v191, v191 row_ror:8 row_mask:0xf bank_mask:0xf
	s_add_u32 s44, s44, 0x10000
	s_addc_u32 s45, s45, 0
	s_add_u32 s46, s46, 0x10000
	s_addc_u32 s47, s47, 0
	s_add_u32 s48, s48, 0x8000
	s_addc_u32 s49, s49, 0
	s_add_u32 s50, s50, 0x8000
	s_addc_u32 s51, s51, 0
	v_cndmask_b32_e64 v242, v191, v242, s[90:91]
	ds_bpermute_b32 v243, v189, v242
	global_load_dwordx4 v[216:219], v244, s[40:41]
	global_load_dwordx4 v[220:223], v244, s[40:41] offset:128
	global_load_dwordx4 v[224:227], v244, s[42:43]
	global_load_dwordx4 v[228:231], v244, s[42:43] offset:128
	s_add_u32 s40, s40, 0x10000
	s_addc_u32 s41, s41, 0
	s_add_u32 s42, s42, 0x10000
	s_addc_u32 s43, s43, 0
	s_waitcnt lgkmcnt(0)
	v_add_f32_e32 v242, v242, v243
	ds_bpermute_b32 v243, v190, v242
	s_waitcnt lgkmcnt(0)
	v_add_f32_e32 v242, v242, v243
	s_and_saveexec_b64 s[2:3], s[88:89]
	ds_write_b32 v188, v242 offset:64
	s_or_b64 exec, exec, s[2:3]
	s_waitcnt vmcnt(12)
; DI void gemm8_epi_resid(f32x4 (&acc)[8][4], int m0, int n0, int ntile8, bf16_t* L, const float* xin, float* out, bf16_t* xb, float* rowpart) {
;     ...
; #pragma unroll
;   for (int i = 0; i < 8; ++i) {
;     const int ml = wm * 128 + i * 16 + (lane & 15);
;     const size_t rowoff = (size_t)(m0 + ml) * DM;
;     float ss = 0.f;
; #pragma unroll
;     for (int j = 0; j < 4; ++j) {
;       const int n = n0 + wn * 64 + j * 16 + (lane >> 4) * 4;
;       const float4 xv = *(const float4*)(xin + rowoff + n);
;       const float o0 = xv.x + acc[i][j][0], o1 = xv.y + acc[i][j][1], o2 = xv.z + acc[i][j][2], o3 = xv.w + acc[i][j][3];
;       *(float4*)(out + rowoff + n) = make_float4(o0, o1, o2, o3);
;       ss += o0 * o0 + o1 * o1 + o2 * o2 + o3 * o3;
;       uint2 u;
;       u.x = pack2(o0, o1);
;       u.y = pack2(o2, o3);
;       *(uint2*)(xb + rowoff + n) = u;
;     }
;     ss += shx(ss, 16, lane);
;     ss += shx(ss, 32, lane);
;     if ((lane >> 4) == 0) red[wn * 256 + ml] = ss;
;   }
	v_mov_b32_dpp v232, v90 row_ror:8 row_mask:0xf bank_mask:0xf
	v_mov_b32_dpp v233, v91 row_ror:8 row_mask:0xf bank_mask:0xf
	v_mov_b32_dpp v234, v92 row_ror:8 row_mask:0xf bank_mask:0xf
	v_mov_b32_dpp v235, v93 row_ror:8 row_mask:0xf bank_mask:0xf
	v_cndmask_b32_e64 v232, v232, v94, s[90:91]
	v_cndmask_b32_e64 v233, v233, v95, s[90:91]
	v_cndmask_b32_e64 v234, v234, v96, s[90:91]
	v_cndmask_b32_e64 v235, v235, v97, s[90:91]
	v_pk_add_f32 v[232:233], v[232:233], v[192:193]
	v_pk_add_f32 v[234:235], v[234:235], v[194:195]
	s_nop 0
	global_store_dwordx4 v244, v[232:235], s[44:45] nt
	v_cvt_pk_bf16_f32 v240, v232, v233
	v_cvt_pk_bf16_f32 v241, v234, v235
	v_pk_mul_f32 v[236:237], v[232:233], v[232:233]
	v_pk_mul_f32 v[238:239], v[234:235], v[234:235]
	global_store_dwordx2 v245, v[240:241], s[48:49] nt
	v_add_f32_e32 v242, v236, v237
	v_add_f32_e32 v242, v242, v238
	v_add_f32_e32 v242, v242, v239
	v_mov_b32_dpp v232, v94 row_ror:8 row_mask:0xf bank_mask:0xf
	v_mov_b32_dpp v233, v95 row_ror:8 row_mask:0xf bank_mask:0xf
	v_mov_b32_dpp v234, v96 row_ror:8 row_mask:0xf bank_mask:0xf
	v_mov_b32_dpp v235, v97 row_ror:8 row_mask:0xf bank_mask:0xf
	v_cndmask_b32_e64 v232, v90, v232, s[90:91]
	v_cndmask_b32_e64 v233, v91, v233, s[90:91]
	v_cndmask_b32_e64 v234, v92, v234, s[90:91]
	v_cndmask_b32_e64 v235, v93, v235, s[90:91]
	v_pk_add_f32 v[232:233], v[232:233], v[202:203]
	v_pk_add_f32 v[234:235], v[234:235], v[204:205]
	s_nop 0
	global_store_dwordx4 v244, v[232:235], s[46:47] nt
	v_cvt_pk_bf16_f32 v240, v232, v233
	v_cvt_pk_bf16_f32 v241, v234, v235
	v_pk_mul_f32 v[236:237], v[232:233], v[232:233]
	v_pk_mul_f32 v[238:239], v[234:235], v[234:235]
	global_store_dwordx2 v245, v[240:241], s[50:51] nt
	v_add_f32_e32 v191, v236, v237
	v_add_f32_e32 v191, v191, v238
	v_add_f32_e32 v191, v191, v239
	v_mov_b32_dpp v232, v82 row_ror:8 row_mask:0xf bank_mask:0xf
	v_mov_b32_dpp v233, v83 row_ror:8 row_mask:0xf bank_mask:0xf
	v_mov_b32_dpp v234, v84 row_ror:8 row_mask:0xf bank_mask:0xf
	v_mov_b32_dpp v235, v85 row_ror:8 row_mask:0xf bank_mask:0xf
	v_cndmask_b32_e64 v232, v232, v86, s[90:91]
	v_cndmask_b32_e64 v233, v233, v87, s[90:91]
	v_cndmask_b32_e64 v234, v234, v88, s[90:91]
	v_cndmask_b32_e64 v235, v235, v89, s[90:91]
	v_pk_add_f32 v[232:233], v[232:233], v[198:199]
	v_pk_add_f32 v[234:235], v[234:235], v[200:201]
	s_nop 0
	global_store_dwordx4 v244, v[232:235], s[44:45] offset:128 nt
	v_cvt_pk_bf16_f32 v240, v232, v233
	v_cvt_pk_bf16_f32 v241, v234, v235
	v_pk_mul_f32 v[236:237], v[232:233], v[232:233]
	v_pk_mul_f32 v[238:239], v[234:235], v[234:235]
	global_store_dwordx2 v245, v[240:241], s[48:49] offset:64 nt
	v_add_f32_e32 v242, v242, v236
	v_add_f32_e32 v242, v242, v237
	v_add_f32_e32 v242, v242, v238
	v_add_f32_e32 v242, v242, v239
	v_mov_b32_dpp v232, v86 row_ror:8 row_mask:0xf bank_mask:0xf
	v_mov_b32_dpp v233, v87 row_ror:8 row_mask:0xf bank_mask:0xf
	v_mov_b32_dpp v234, v88 row_ror:8 row_mask:0xf bank_mask:0xf
	v_mov_b32_dpp v235, v89 row_ror:8 row_mask:0xf bank_mask:0xf
	v_cndmask_b32_e64 v232, v82, v232, s[90:91]
	v_cndmask_b32_e64 v233, v83, v233, s[90:91]
	v_cndmask_b32_e64 v234, v84, v234, s[90:91]
	v_cndmask_b32_e64 v235, v85, v235, s[90:91]
	v_pk_add_f32 v[232:233], v[232:233], v[206:207]
	v_pk_add_f32 v[234:235], v[234:235], v[208:209]
	s_nop 0
	global_store_dwordx4 v244, v[232:235], s[46:47] offset:128 nt
	v_cvt_pk_bf16_f32 v240, v232, v233
	v_cvt_pk_bf16_f32 v241, v234, v235
	v_pk_mul_f32 v[236:237], v[232:233], v[232:233]
	v_pk_mul_f32 v[238:239], v[234:235], v[234:235]
	global_store_dwordx2 v245, v[240:241], s[50:51] offset:64 nt
	v_add_f32_e32 v191, v191, v236
	v_add_f32_e32 v191, v191, v237
	v_add_f32_e32 v191, v191, v238
	v_add_f32_e32 v191, v191, v239
	s_nop 1
	v_add_f32_dpp v242, v242, v242 row_ror:8 row_mask:0xf bank_mask:0xf
	v_add_f32_dpp v191, v191, v191 row_ror:8 row_mask:0xf bank_mask:0xf
	s_add_u32 s44, s44, 0x10000
	s_addc_u32 s45, s45, 0
	s_add_u32 s46, s46, 0x10000
	s_addc_u32 s47, s47, 0
	s_add_u32 s48, s48, 0x8000
	s_addc_u32 s49, s49, 0
	s_add_u32 s50, s50, 0x8000
	s_addc_u32 s51, s51, 0
	v_cndmask_b32_e64 v242, v191, v242, s[90:91]
	ds_bpermute_b32 v243, v189, v242
	global_load_dwordx4 v[192:195], v244, s[40:41]
	global_load_dwordx4 v[198:201], v244, s[40:41] offset:128
	global_load_dwordx4 v[202:205], v244, s[42:43]
	global_load_dwordx4 v[206:209], v244, s[42:43] offset:128
	s_add_u32 s40, s40, 0x10000
	s_addc_u32 s41, s41, 0
	s_add_u32 s42, s42, 0x10000
	s_addc_u32 s43, s43, 0
	s_waitcnt lgkmcnt(0)
	v_add_f32_e32 v242, v242, v243
	ds_bpermute_b32 v243, v190, v242
	s_waitcnt lgkmcnt(0)
	v_add_f32_e32 v242, v242, v243
	s_and_saveexec_b64 s[2:3], s[88:89]
	ds_write_b32 v188, v242 offset:128
	s_or_b64 exec, exec, s[2:3]
	s_waitcnt vmcnt(12)
; DI void gemm8_epi_resid(f32x4 (&acc)[8][4], int m0, int n0, int ntile8, bf16_t* L, const float* xin, float* out, bf16_t* xb, float* rowpart) {
;     ...
; #pragma unroll
;   for (int i = 0; i < 8; ++i) {
;     const int ml = wm * 128 + i * 16 + (lane & 15);
;     const size_t rowoff = (size_t)(m0 + ml) * DM;
;     float ss = 0.f;
; #pragma unroll
;     for (int j = 0; j < 4; ++j) {
;       const int n = n0 + wn * 64 + j * 16 + (lane >> 4) * 4;
;       const float4 xv = *(const float4*)(xin + rowoff + n);
;       const float o0 = xv.x + acc[i][j][0], o1 = xv.y + acc[i][j][1], o2 = xv.z + acc[i][j][2], o3 = xv.w + acc[i][j][3];
;       *(float4*)(out + rowoff + n) = make_float4(o0, o1, o2, o3);
;       ss += o0 * o0 + o1 * o1 + o2 * o2 + o3 * o3;
;       uint2 u;
;       u.x = pack2(o0, o1);
;       u.y = pack2(o2, o3);
;       *(uint2*)(xb + rowoff + n) = u;
;     }
;     ss += shx(ss, 16, lane);
;     ss += shx(ss, 32, lane);
;     if ((lane >> 4) == 0) red[wn * 256 + ml] = ss;
;   }
	v_mov_b32_dpp v232, v74 row_ror:8 row_mask:0xf bank_mask:0xf
	v_mov_b32_dpp v233, v75 row_ror:8 row_mask:0xf bank_mask:0xf
	v_mov_b32_dpp v234, v76 row_ror:8 row_mask:0xf bank_mask:0xf
	v_mov_b32_dpp v235, v77 row_ror:8 row_mask:0xf bank_mask:0xf
	v_cndmask_b32_e64 v232, v232, v78, s[90:91]
	v_cndmask_b32_e64 v233, v233, v79, s[90:91]
	v_cndmask_b32_e64 v234, v234, v80, s[90:91]
	v_cndmask_b32_e64 v235, v235, v81, s[90:91]
	v_pk_add_f32 v[232:233], v[232:233], v[216:217]
	v_pk_add_f32 v[234:235], v[234:235], v[218:219]
	s_nop 0
	global_store_dwordx4 v244, v[232:235], s[44:45] nt
	v_cvt_pk_bf16_f32 v240, v232, v233
	v_cvt_pk_bf16_f32 v241, v234, v235
	v_pk_mul_f32 v[236:237], v[232:233], v[232:233]
	v_pk_mul_f32 v[238:239], v[234:235], v[234:235]
	global_store_dwordx2 v245, v[240:241], s[48:49] nt
	v_add_f32_e32 v242, v236, v237
	v_add_f32_e32 v242, v242, v238
	v_add_f32_e32 v242, v242, v239
	v_mov_b32_dpp v232, v78 row_ror:8 row_mask:0xf bank_mask:0xf
	v_mov_b32_dpp v233, v79 row_ror:8 row_mask:0xf bank_mask:0xf
	v_mov_b32_dpp v234, v80 row_ror:8 row_mask:0xf bank_mask:0xf
	v_mov_b32_dpp v235, v81 row_ror:8 row_mask:0xf bank_mask:0xf
	v_cndmask_b32_e64 v232, v74, v232, s[90:91]
	v_cndmask_b32_e64 v233, v75, v233, s[90:91]
	v_cndmask_b32_e64 v234, v76, v234, s[90:91]
	v_cndmask_b32_e64 v235, v77, v235, s[90:91]
	v_pk_add_f32 v[232:233], v[232:233], v[224:225]
	v_pk_add_f32 v[234:235], v[234:235], v[226:227]
	s_nop 0
	global_store_dwordx4 v244, v[232:235], s[46:47] nt
	v_cvt_pk_bf16_f32 v240, v232, v233
	v_cvt_pk_bf16_f32 v241, v234, v235
	v_pk_mul_f32 v[236:237], v[232:233], v[232:233]
	v_pk_mul_f32 v[238:239], v[234:235], v[234:235]
	global_store_dwordx2 v245, v[240:241], s[50:51] nt
	v_add_f32_e32 v191, v236, v237
	v_add_f32_e32 v191, v191, v238
	v_add_f32_e32 v191, v191, v239
	v_mov_b32_dpp v232, v66 row_ror:8 row_mask:0xf bank_mask:0xf
	v_mov_b32_dpp v233, v67 row_ror:8 row_mask:0xf bank_mask:0xf
	v_mov_b32_dpp v234, v68 row_ror:8 row_mask:0xf bank_mask:0xf
	v_mov_b32_dpp v235, v69 row_ror:8 row_mask:0xf bank_mask:0xf
	v_cndmask_b32_e64 v232, v232, v70, s[90:91]
	v_cndmask_b32_e64 v233, v233, v71, s[90:91]
	v_cndmask_b32_e64 v234, v234, v72, s[90:91]
	v_cndmask_b32_e64 v235, v235, v73, s[90:91]
	v_pk_add_f32 v[232:233], v[232:233], v[220:221]
	v_pk_add_f32 v[234:235], v[234:235], v[222:223]
	s_nop 0
	global_store_dwordx4 v244, v[232:235], s[44:45] offset:128 nt
	v_cvt_pk_bf16_f32 v240, v232, v233
	v_cvt_pk_bf16_f32 v241, v234, v235
	v_pk_mul_f32 v[236:237], v[232:233], v[232:233]
	v_pk_mul_f32 v[238:239], v[234:235], v[234:235]
	global_store_dwordx2 v245, v[240:241], s[48:49] offset:64 nt
	v_add_f32_e32 v242, v242, v236
	v_add_f32_e32 v242, v242, v237
	v_add_f32_e32 v242, v242, v238
	v_add_f32_e32 v242, v242, v239
	v_mov_b32_dpp v232, v70 row_ror:8 row_mask:0xf bank_mask:0xf
	v_mov_b32_dpp v233, v71 row_ror:8 row_mask:0xf bank_mask:0xf
	v_mov_b32_dpp v234, v72 row_ror:8 row_mask:0xf bank_mask:0xf
	v_mov_b32_dpp v235, v73 row_ror:8 row_mask:0xf bank_mask:0xf
	v_cndmask_b32_e64 v232, v66, v232, s[90:91]
	v_cndmask_b32_e64 v233, v67, v233, s[90:91]
	v_cndmask_b32_e64 v234, v68, v234, s[90:91]
	v_cndmask_b32_e64 v235, v69, v235, s[90:91]
	v_pk_add_f32 v[232:233], v[232:233], v[228:229]
	v_pk_add_f32 v[234:235], v[234:235], v[230:231]
	s_nop 0
	global_store_dwordx4 v244, v[232:235], s[46:47] offset:128 nt
	v_cvt_pk_bf16_f32 v240, v232, v233
	v_cvt_pk_bf16_f32 v241, v234, v235
	v_pk_mul_f32 v[236:237], v[232:233], v[232:233]
	v_pk_mul_f32 v[238:239], v[234:235], v[234:235]
	global_store_dwordx2 v245, v[240:241], s[50:51] offset:64 nt
	v_add_f32_e32 v191, v191, v236
	v_add_f32_e32 v191, v191, v237
	v_add_f32_e32 v191, v191, v238
	v_add_f32_e32 v191, v191, v239
	s_nop 1
	v_add_f32_dpp v242, v242, v242 row_ror:8 row_mask:0xf bank_mask:0xf
	v_add_f32_dpp v191, v191, v191 row_ror:8 row_mask:0xf bank_mask:0xf
	s_add_u32 s44, s44, 0x10000
	s_addc_u32 s45, s45, 0
	s_add_u32 s46, s46, 0x10000
	s_addc_u32 s47, s47, 0
	s_add_u32 s48, s48, 0x8000
	s_addc_u32 s49, s49, 0
	s_add_u32 s50, s50, 0x8000
	s_addc_u32 s51, s51, 0
	v_cndmask_b32_e64 v242, v191, v242, s[90:91]
	ds_bpermute_b32 v243, v189, v242
	global_load_dwordx4 v[216:219], v244, s[40:41]
	global_load_dwordx4 v[220:223], v244, s[40:41] offset:128
	global_load_dwordx4 v[224:227], v244, s[42:43]
	global_load_dwordx4 v[228:231], v244, s[42:43] offset:128
	s_add_u32 s40, s40, 0x10000
	s_addc_u32 s41, s41, 0
	s_add_u32 s42, s42, 0x10000
	s_addc_u32 s43, s43, 0
	s_waitcnt lgkmcnt(0)
	v_add_f32_e32 v242, v242, v243
	ds_bpermute_b32 v243, v190, v242
	s_waitcnt lgkmcnt(0)
	v_add_f32_e32 v242, v242, v243
	s_and_saveexec_b64 s[2:3], s[88:89]
	ds_write_b32 v188, v242 offset:192
	s_or_b64 exec, exec, s[2:3]
	s_waitcnt vmcnt(12)
; DI void gemm8_epi_resid(f32x4 (&acc)[8][4], int m0, int n0, int ntile8, bf16_t* L, const float* xin, float* out, bf16_t* xb, float* rowpart) {
;     ...
; #pragma unroll
;   for (int i = 0; i < 8; ++i) {
;     const int ml = wm * 128 + i * 16 + (lane & 15);
;     const size_t rowoff = (size_t)(m0 + ml) * DM;
;     float ss = 0.f;
; #pragma unroll
;     for (int j = 0; j < 4; ++j) {
;       const int n = n0 + wn * 64 + j * 16 + (lane >> 4) * 4;
;       const float4 xv = *(const float4*)(xin + rowoff + n);
;       const float o0 = xv.x + acc[i][j][0], o1 = xv.y + acc[i][j][1], o2 = xv.z + acc[i][j][2], o3 = xv.w + acc[i][j][3];
;       *(float4*)(out + rowoff + n) = make_float4(o0, o1, o2, o3);
;       ss += o0 * o0 + o1 * o1 + o2 * o2 + o3 * o3;
;       uint2 u;
;       u.x = pack2(o0, o1);
;       u.y = pack2(o2, o3);
;       *(uint2*)(xb + rowoff + n) = u;
;     }
;     ss += shx(ss, 16, lane);
;     ss += shx(ss, 32, lane);
;     if ((lane >> 4) == 0) red[wn * 256 + ml] = ss;
;   }
	v_mov_b32_dpp v232, v58 row_ror:8 row_mask:0xf bank_mask:0xf
	v_mov_b32_dpp v233, v59 row_ror:8 row_mask:0xf bank_mask:0xf
	v_mov_b32_dpp v234, v60 row_ror:8 row_mask:0xf bank_mask:0xf
	v_mov_b32_dpp v235, v61 row_ror:8 row_mask:0xf bank_mask:0xf
	v_cndmask_b32_e64 v232, v232, v62, s[90:91]
	v_cndmask_b32_e64 v233, v233, v63, s[90:91]
	v_cndmask_b32_e64 v234, v234, v64, s[90:91]
	v_cndmask_b32_e64 v235, v235, v65, s[90:91]
	v_pk_add_f32 v[232:233], v[232:233], v[192:193]
	v_pk_add_f32 v[234:235], v[234:235], v[194:195]
	s_nop 0
	global_store_dwordx4 v244, v[232:235], s[44:45] nt
	v_cvt_pk_bf16_f32 v240, v232, v233
	v_cvt_pk_bf16_f32 v241, v234, v235
	v_pk_mul_f32 v[236:237], v[232:233], v[232:233]
	v_pk_mul_f32 v[238:239], v[234:235], v[234:235]
	global_store_dwordx2 v245, v[240:241], s[48:49] nt
	v_add_f32_e32 v242, v236, v237
	v_add_f32_e32 v242, v242, v238
	v_add_f32_e32 v242, v242, v239
	v_mov_b32_dpp v232, v62 row_ror:8 row_mask:0xf bank_mask:0xf
	v_mov_b32_dpp v233, v63 row_ror:8 row_mask:0xf bank_mask:0xf
	v_mov_b32_dpp v234, v64 row_ror:8 row_mask:0xf bank_mask:0xf
	v_mov_b32_dpp v235, v65 row_ror:8 row_mask:0xf bank_mask:0xf
	v_cndmask_b32_e64 v232, v58, v232, s[90:91]
	v_cndmask_b32_e64 v233, v59, v233, s[90:91]
	v_cndmask_b32_e64 v234, v60, v234, s[90:91]
	v_cndmask_b32_e64 v235, v61, v235, s[90:91]
	v_pk_add_f32 v[232:233], v[232:233], v[202:203]
	v_pk_add_f32 v[234:235], v[234:235], v[204:205]
	s_nop 0
	global_store_dwordx4 v244, v[232:235], s[46:47] nt
	v_cvt_pk_bf16_f32 v240, v232, v233
	v_cvt_pk_bf16_f32 v241, v234, v235
	v_pk_mul_f32 v[236:237], v[232:233], v[232:233]
	v_pk_mul_f32 v[238:239], v[234:235], v[234:235]
	global_store_dwordx2 v245, v[240:241], s[50:51] nt
	v_add_f32_e32 v191, v236, v237
	v_add_f32_e32 v191, v191, v238
	v_add_f32_e32 v191, v191, v239
	v_mov_b32_dpp v232, v50 row_ror:8 row_mask:0xf bank_mask:0xf
	v_mov_b32_dpp v233, v51 row_ror:8 row_mask:0xf bank_mask:0xf
	v_mov_b32_dpp v234, v52 row_ror:8 row_mask:0xf bank_mask:0xf
	v_mov_b32_dpp v235, v53 row_ror:8 row_mask:0xf bank_mask:0xf
	v_cndmask_b32_e64 v232, v232, v54, s[90:91]
	v_cndmask_b32_e64 v233, v233, v55, s[90:91]
	v_cndmask_b32_e64 v234, v234, v56, s[90:91]
	v_cndmask_b32_e64 v235, v235, v57, s[90:91]
	v_pk_add_f32 v[232:233], v[232:233], v[198:199]
	v_pk_add_f32 v[234:235], v[234:235], v[200:201]
	s_nop 0
	global_store_dwordx4 v244, v[232:235], s[44:45] offset:128 nt
	v_cvt_pk_bf16_f32 v240, v232, v233
	v_cvt_pk_bf16_f32 v241, v234, v235
	v_pk_mul_f32 v[236:237], v[232:233], v[232:233]
	v_pk_mul_f32 v[238:239], v[234:235], v[234:235]
	global_store_dwordx2 v245, v[240:241], s[48:49] offset:64 nt
	v_add_f32_e32 v242, v242, v236
	v_add_f32_e32 v242, v242, v237
	v_add_f32_e32 v242, v242, v238
	v_add_f32_e32 v242, v242, v239
	v_mov_b32_dpp v232, v54 row_ror:8 row_mask:0xf bank_mask:0xf
	v_mov_b32_dpp v233, v55 row_ror:8 row_mask:0xf bank_mask:0xf
	v_mov_b32_dpp v234, v56 row_ror:8 row_mask:0xf bank_mask:0xf
	v_mov_b32_dpp v235, v57 row_ror:8 row_mask:0xf bank_mask:0xf
	v_cndmask_b32_e64 v232, v50, v232, s[90:91]
	v_cndmask_b32_e64 v233, v51, v233, s[90:91]
	v_cndmask_b32_e64 v234, v52, v234, s[90:91]
	v_cndmask_b32_e64 v235, v53, v235, s[90:91]
	v_pk_add_f32 v[232:233], v[232:233], v[206:207]
	v_pk_add_f32 v[234:235], v[234:235], v[208:209]
	s_nop 0
	global_store_dwordx4 v244, v[232:235], s[46:47] offset:128 nt
	v_cvt_pk_bf16_f32 v240, v232, v233
	v_cvt_pk_bf16_f32 v241, v234, v235
	v_pk_mul_f32 v[236:237], v[232:233], v[232:233]
	v_pk_mul_f32 v[238:239], v[234:235], v[234:235]
	global_store_dwordx2 v245, v[240:241], s[50:51] offset:64 nt
	v_add_f32_e32 v191, v191, v236
	v_add_f32_e32 v191, v191, v237
	v_add_f32_e32 v191, v191, v238
	v_add_f32_e32 v191, v191, v239
	s_nop 1
	v_add_f32_dpp v242, v242, v242 row_ror:8 row_mask:0xf bank_mask:0xf
	v_add_f32_dpp v191, v191, v191 row_ror:8 row_mask:0xf bank_mask:0xf
	s_add_u32 s44, s44, 0x10000
	s_addc_u32 s45, s45, 0
	s_add_u32 s46, s46, 0x10000
	s_addc_u32 s47, s47, 0
	s_add_u32 s48, s48, 0x8000
	s_addc_u32 s49, s49, 0
	s_add_u32 s50, s50, 0x8000
	s_addc_u32 s51, s51, 0
	v_cndmask_b32_e64 v242, v191, v242, s[90:91]
	ds_bpermute_b32 v243, v189, v242
	global_load_dwordx4 v[192:195], v244, s[40:41]
	global_load_dwordx4 v[198:201], v244, s[40:41] offset:128
	global_load_dwordx4 v[202:205], v244, s[42:43]
	global_load_dwordx4 v[206:209], v244, s[42:43] offset:128
	s_add_u32 s40, s40, 0x10000
	s_addc_u32 s41, s41, 0
	s_add_u32 s42, s42, 0x10000
	s_addc_u32 s43, s43, 0
	s_waitcnt lgkmcnt(0)
	v_add_f32_e32 v242, v242, v243
	ds_bpermute_b32 v243, v190, v242
	s_waitcnt lgkmcnt(0)
	v_add_f32_e32 v242, v242, v243
	s_and_saveexec_b64 s[2:3], s[88:89]
	ds_write_b32 v188, v242 offset:256
	s_or_b64 exec, exec, s[2:3]
	s_waitcnt vmcnt(12)
; DI void gemm8_epi_resid(f32x4 (&acc)[8][4], int m0, int n0, int ntile8, bf16_t* L, const float* xin, float* out, bf16_t* xb, float* rowpart) {
;     ...
; #pragma unroll
;   for (int i = 0; i < 8; ++i) {
;     const int ml = wm * 128 + i * 16 + (lane & 15);
;     const size_t rowoff = (size_t)(m0 + ml) * DM;
;     float ss = 0.f;
; #pragma unroll
;     for (int j = 0; j < 4; ++j) {
;       const int n = n0 + wn * 64 + j * 16 + (lane >> 4) * 4;
;       const float4 xv = *(const float4*)(xin + rowoff + n);
;       const float o0 = xv.x + acc[i][j][0], o1 = xv.y + acc[i][j][1], o2 = xv.z + acc[i][j][2], o3 = xv.w + acc[i][j][3];
;       *(float4*)(out + rowoff + n) = make_float4(o0, o1, o2, o3);
;       ss += o0 * o0 + o1 * o1 + o2 * o2 + o3 * o3;
;       uint2 u;
;       u.x = pack2(o0, o1);
;       u.y = pack2(o2, o3);
;       *(uint2*)(xb + rowoff + n) = u;
;     }
;     ss += shx(ss, 16, lane);
;     ss += shx(ss, 32, lane);
;     if ((lane >> 4) == 0) red[wn * 256 + ml] = ss;
;   }
	v_mov_b32_dpp v232, v128 row_ror:8 row_mask:0xf bank_mask:0xf
	v_mov_b32_dpp v233, v129 row_ror:8 row_mask:0xf bank_mask:0xf
	v_mov_b32_dpp v234, v130 row_ror:8 row_mask:0xf bank_mask:0xf
	v_mov_b32_dpp v235, v131 row_ror:8 row_mask:0xf bank_mask:0xf
	v_cndmask_b32_e64 v232, v232, v46, s[90:91]
	v_cndmask_b32_e64 v233, v233, v47, s[90:91]
	v_cndmask_b32_e64 v234, v234, v48, s[90:91]
	v_cndmask_b32_e64 v235, v235, v49, s[90:91]
	v_pk_add_f32 v[232:233], v[232:233], v[216:217]
	v_pk_add_f32 v[234:235], v[234:235], v[218:219]
	s_nop 0
	global_store_dwordx4 v244, v[232:235], s[44:45] nt
	v_cvt_pk_bf16_f32 v240, v232, v233
	v_cvt_pk_bf16_f32 v241, v234, v235
	v_pk_mul_f32 v[236:237], v[232:233], v[232:233]
	v_pk_mul_f32 v[238:239], v[234:235], v[234:235]
	global_store_dwordx2 v245, v[240:241], s[48:49] nt
	v_add_f32_e32 v242, v236, v237
	v_add_f32_e32 v242, v242, v238
	v_add_f32_e32 v242, v242, v239
	v_mov_b32_dpp v232, v46 row_ror:8 row_mask:0xf bank_mask:0xf
	v_mov_b32_dpp v233, v47 row_ror:8 row_mask:0xf bank_mask:0xf
	v_mov_b32_dpp v234, v48 row_ror:8 row_mask:0xf bank_mask:0xf
	v_mov_b32_dpp v235, v49 row_ror:8 row_mask:0xf bank_mask:0xf
	v_cndmask_b32_e64 v232, v128, v232, s[90:91]
	v_cndmask_b32_e64 v233, v129, v233, s[90:91]
	v_cndmask_b32_e64 v234, v130, v234, s[90:91]
	v_cndmask_b32_e64 v235, v131, v235, s[90:91]
	v_pk_add_f32 v[232:233], v[232:233], v[224:225]
	v_pk_add_f32 v[234:235], v[234:235], v[226:227]
	s_nop 0
	global_store_dwordx4 v244, v[232:235], s[46:47] nt
	v_cvt_pk_bf16_f32 v240, v232, v233
	v_cvt_pk_bf16_f32 v241, v234, v235
	v_pk_mul_f32 v[236:237], v[232:233], v[232:233]
	v_pk_mul_f32 v[238:239], v[234:235], v[234:235]
	global_store_dwordx2 v245, v[240:241], s[50:51] nt
	v_add_f32_e32 v191, v236, v237
	v_add_f32_e32 v191, v191, v238
	v_add_f32_e32 v191, v191, v239
	v_mov_b32_dpp v232, v34 row_ror:8 row_mask:0xf bank_mask:0xf
	v_mov_b32_dpp v233, v35 row_ror:8 row_mask:0xf bank_mask:0xf
	v_mov_b32_dpp v234, v36 row_ror:8 row_mask:0xf bank_mask:0xf
	v_mov_b32_dpp v235, v37 row_ror:8 row_mask:0xf bank_mask:0xf
	v_cndmask_b32_e64 v232, v232, v124, s[90:91]
	v_cndmask_b32_e64 v233, v233, v125, s[90:91]
	v_cndmask_b32_e64 v234, v234, v126, s[90:91]
	v_cndmask_b32_e64 v235, v235, v127, s[90:91]
	v_pk_add_f32 v[232:233], v[232:233], v[220:221]
	v_pk_add_f32 v[234:235], v[234:235], v[222:223]
	s_nop 0
	global_store_dwordx4 v244, v[232:235], s[44:45] offset:128 nt
	v_cvt_pk_bf16_f32 v240, v232, v233
	v_cvt_pk_bf16_f32 v241, v234, v235
	v_pk_mul_f32 v[236:237], v[232:233], v[232:233]
	v_pk_mul_f32 v[238:239], v[234:235], v[234:235]
	global_store_dwordx2 v245, v[240:241], s[48:49] offset:64 nt
	v_add_f32_e32 v242, v242, v236
	v_add_f32_e32 v242, v242, v237
	v_add_f32_e32 v242, v242, v238
	v_add_f32_e32 v242, v242, v239
	v_mov_b32_dpp v232, v124 row_ror:8 row_mask:0xf bank_mask:0xf
	v_mov_b32_dpp v233, v125 row_ror:8 row_mask:0xf bank_mask:0xf
	v_mov_b32_dpp v234, v126 row_ror:8 row_mask:0xf bank_mask:0xf
	v_mov_b32_dpp v235, v127 row_ror:8 row_mask:0xf bank_mask:0xf
	v_cndmask_b32_e64 v232, v34, v232, s[90:91]
	v_cndmask_b32_e64 v233, v35, v233, s[90:91]
	v_cndmask_b32_e64 v234, v36, v234, s[90:91]
	v_cndmask_b32_e64 v235, v37, v235, s[90:91]
	v_pk_add_f32 v[232:233], v[232:233], v[228:229]
	v_pk_add_f32 v[234:235], v[234:235], v[230:231]
	s_nop 0
	global_store_dwordx4 v244, v[232:235], s[46:47] offset:128 nt
	v_cvt_pk_bf16_f32 v240, v232, v233
	v_cvt_pk_bf16_f32 v241, v234, v235
	v_pk_mul_f32 v[236:237], v[232:233], v[232:233]
	v_pk_mul_f32 v[238:239], v[234:235], v[234:235]
	global_store_dwordx2 v245, v[240:241], s[50:51] offset:64 nt
	v_add_f32_e32 v191, v191, v236
	v_add_f32_e32 v191, v191, v237
	v_add_f32_e32 v191, v191, v238
	v_add_f32_e32 v191, v191, v239
	s_nop 1
	v_add_f32_dpp v242, v242, v242 row_ror:8 row_mask:0xf bank_mask:0xf
	v_add_f32_dpp v191, v191, v191 row_ror:8 row_mask:0xf bank_mask:0xf
	s_add_u32 s44, s44, 0x10000
	s_addc_u32 s45, s45, 0
	s_add_u32 s46, s46, 0x10000
	s_addc_u32 s47, s47, 0
	s_add_u32 s48, s48, 0x8000
	s_addc_u32 s49, s49, 0
	s_add_u32 s50, s50, 0x8000
	s_addc_u32 s51, s51, 0
	v_cndmask_b32_e64 v242, v191, v242, s[90:91]
	ds_bpermute_b32 v243, v189, v242
	global_load_dwordx4 v[216:219], v244, s[40:41]
	global_load_dwordx4 v[220:223], v244, s[40:41] offset:128
	global_load_dwordx4 v[224:227], v244, s[42:43]
	global_load_dwordx4 v[228:231], v244, s[42:43] offset:128
	s_add_u32 s40, s40, 0x10000
	s_addc_u32 s41, s41, 0
	s_add_u32 s42, s42, 0x10000
	s_addc_u32 s43, s43, 0
	s_waitcnt lgkmcnt(0)
	v_add_f32_e32 v242, v242, v243
	ds_bpermute_b32 v243, v190, v242
	s_waitcnt lgkmcnt(0)
	v_add_f32_e32 v242, v242, v243
	s_and_saveexec_b64 s[2:3], s[88:89]
	ds_write_b32 v188, v242 offset:320
	s_or_b64 exec, exec, s[2:3]
	s_waitcnt vmcnt(12)
; DI void gemm8_epi_resid(f32x4 (&acc)[8][4], int m0, int n0, int ntile8, bf16_t* L, const float* xin, float* out, bf16_t* xb, float* rowpart) {
;     ...
; #pragma unroll
;   for (int i = 0; i < 8; ++i) {
;     const int ml = wm * 128 + i * 16 + (lane & 15);
;     const size_t rowoff = (size_t)(m0 + ml) * DM;
;     float ss = 0.f;
; #pragma unroll
;     for (int j = 0; j < 4; ++j) {
;       const int n = n0 + wn * 64 + j * 16 + (lane >> 4) * 4;
;       const float4 xv = *(const float4*)(xin + rowoff + n);
;       const float o0 = xv.x + acc[i][j][0], o1 = xv.y + acc[i][j][1], o2 = xv.z + acc[i][j][2], o3 = xv.w + acc[i][j][3];
;       *(float4*)(out + rowoff + n) = make_float4(o0, o1, o2, o3);
;       ss += o0 * o0 + o1 * o1 + o2 * o2 + o3 * o3;
;       uint2 u;
;       u.x = pack2(o0, o1);
;       u.y = pack2(o2, o3);
;       *(uint2*)(xb + rowoff + n) = u;
;     }
;     ss += shx(ss, 16, lane);
;     ss += shx(ss, 32, lane);
;     if ((lane >> 4) == 0) red[wn * 256 + ml] = ss;
;   }
	v_mov_b32_dpp v232, v26 row_ror:8 row_mask:0xf bank_mask:0xf
	v_mov_b32_dpp v233, v27 row_ror:8 row_mask:0xf bank_mask:0xf
	v_mov_b32_dpp v234, v28 row_ror:8 row_mask:0xf bank_mask:0xf
	v_mov_b32_dpp v235, v29 row_ror:8 row_mask:0xf bank_mask:0xf
	v_cndmask_b32_e64 v232, v232, v30, s[90:91]
	v_cndmask_b32_e64 v233, v233, v31, s[90:91]
	v_cndmask_b32_e64 v234, v234, v32, s[90:91]
	v_cndmask_b32_e64 v235, v235, v33, s[90:91]
	v_pk_add_f32 v[232:233], v[232:233], v[192:193]
	v_pk_add_f32 v[234:235], v[234:235], v[194:195]
	s_nop 0
	global_store_dwordx4 v244, v[232:235], s[44:45] nt
	v_cvt_pk_bf16_f32 v240, v232, v233
	v_cvt_pk_bf16_f32 v241, v234, v235
	v_pk_mul_f32 v[236:237], v[232:233], v[232:233]
	v_pk_mul_f32 v[238:239], v[234:235], v[234:235]
	global_store_dwordx2 v245, v[240:241], s[48:49] nt
	v_add_f32_e32 v242, v236, v237
	v_add_f32_e32 v242, v242, v238
	v_add_f32_e32 v242, v242, v239
	v_mov_b32_dpp v232, v30 row_ror:8 row_mask:0xf bank_mask:0xf
	v_mov_b32_dpp v233, v31 row_ror:8 row_mask:0xf bank_mask:0xf
	v_mov_b32_dpp v234, v32 row_ror:8 row_mask:0xf bank_mask:0xf
	v_mov_b32_dpp v235, v33 row_ror:8 row_mask:0xf bank_mask:0xf
	v_cndmask_b32_e64 v232, v26, v232, s[90:91]
	v_cndmask_b32_e64 v233, v27, v233, s[90:91]
	v_cndmask_b32_e64 v234, v28, v234, s[90:91]
	v_cndmask_b32_e64 v235, v29, v235, s[90:91]
	v_pk_add_f32 v[232:233], v[232:233], v[202:203]
	v_pk_add_f32 v[234:235], v[234:235], v[204:205]
	s_nop 0
	global_store_dwordx4 v244, v[232:235], s[46:47] nt
	v_cvt_pk_bf16_f32 v240, v232, v233
	v_cvt_pk_bf16_f32 v241, v234, v235
	v_pk_mul_f32 v[236:237], v[232:233], v[232:233]
	v_pk_mul_f32 v[238:239], v[234:235], v[234:235]
	global_store_dwordx2 v245, v[240:241], s[50:51] nt
	v_add_f32_e32 v191, v236, v237
	v_add_f32_e32 v191, v191, v238
	v_add_f32_e32 v191, v191, v239
	v_mov_b32_dpp v232, v18 row_ror:8 row_mask:0xf bank_mask:0xf
	v_mov_b32_dpp v233, v19 row_ror:8 row_mask:0xf bank_mask:0xf
	v_mov_b32_dpp v234, v20 row_ror:8 row_mask:0xf bank_mask:0xf
	v_mov_b32_dpp v235, v21 row_ror:8 row_mask:0xf bank_mask:0xf
	v_cndmask_b32_e64 v232, v232, v22, s[90:91]
	v_cndmask_b32_e64 v233, v233, v23, s[90:91]
	v_cndmask_b32_e64 v234, v234, v24, s[90:91]
	v_cndmask_b32_e64 v235, v235, v25, s[90:91]
	v_pk_add_f32 v[232:233], v[232:233], v[198:199]
	v_pk_add_f32 v[234:235], v[234:235], v[200:201]
	s_nop 0
	global_store_dwordx4 v244, v[232:235], s[44:45] offset:128 nt
	v_cvt_pk_bf16_f32 v240, v232, v233
	v_cvt_pk_bf16_f32 v241, v234, v235
	v_pk_mul_f32 v[236:237], v[232:233], v[232:233]
	v_pk_mul_f32 v[238:239], v[234:235], v[234:235]
	global_store_dwordx2 v245, v[240:241], s[48:49] offset:64 nt
	v_add_f32_e32 v242, v242, v236
	v_add_f32_e32 v242, v242, v237
	v_add_f32_e32 v242, v242, v238
	v_add_f32_e32 v242, v242, v239
	v_mov_b32_dpp v232, v22 row_ror:8 row_mask:0xf bank_mask:0xf
	v_mov_b32_dpp v233, v23 row_ror:8 row_mask:0xf bank_mask:0xf
	v_mov_b32_dpp v234, v24 row_ror:8 row_mask:0xf bank_mask:0xf
	v_mov_b32_dpp v235, v25 row_ror:8 row_mask:0xf bank_mask:0xf
	v_cndmask_b32_e64 v232, v18, v232, s[90:91]
	v_cndmask_b32_e64 v233, v19, v233, s[90:91]
	v_cndmask_b32_e64 v234, v20, v234, s[90:91]
	v_cndmask_b32_e64 v235, v21, v235, s[90:91]
	v_pk_add_f32 v[232:233], v[232:233], v[206:207]
	v_pk_add_f32 v[234:235], v[234:235], v[208:209]
	s_nop 0
	global_store_dwordx4 v244, v[232:235], s[46:47] offset:128 nt
	v_cvt_pk_bf16_f32 v240, v232, v233
	v_cvt_pk_bf16_f32 v241, v234, v235
	v_pk_mul_f32 v[236:237], v[232:233], v[232:233]
	v_pk_mul_f32 v[238:239], v[234:235], v[234:235]
	global_store_dwordx2 v245, v[240:241], s[50:51] offset:64 nt
	v_add_f32_e32 v191, v191, v236
	v_add_f32_e32 v191, v191, v237
	v_add_f32_e32 v191, v191, v238
	v_add_f32_e32 v191, v191, v239
	s_nop 1
	v_add_f32_dpp v242, v242, v242 row_ror:8 row_mask:0xf bank_mask:0xf
	v_add_f32_dpp v191, v191, v191 row_ror:8 row_mask:0xf bank_mask:0xf
	s_add_u32 s44, s44, 0x10000
	s_addc_u32 s45, s45, 0
	s_add_u32 s46, s46, 0x10000
	s_addc_u32 s47, s47, 0
	s_add_u32 s48, s48, 0x8000
	s_addc_u32 s49, s49, 0
	s_add_u32 s50, s50, 0x8000
	s_addc_u32 s51, s51, 0
	v_cndmask_b32_e64 v242, v191, v242, s[90:91]
	ds_bpermute_b32 v243, v189, v242
	s_waitcnt lgkmcnt(0)
	v_add_f32_e32 v242, v242, v243
	ds_bpermute_b32 v243, v190, v242
	s_waitcnt lgkmcnt(0)
	v_add_f32_e32 v242, v242, v243
	s_and_saveexec_b64 s[2:3], s[88:89]
	ds_write_b32 v188, v242 offset:384
	s_or_b64 exec, exec, s[2:3]
	s_waitcnt vmcnt(8)
; DI void gemm8_epi_resid(f32x4 (&acc)[8][4], int m0, int n0, int ntile8, bf16_t* L, const float* xin, float* out, bf16_t* xb, float* rowpart) {
;     ...
;     for (int j = 0; j < 4; ++j) {
;       const int n = n0 + wn * 64 + j * 16 + (lane >> 4) * 4;
;       const float4 xv = *(const float4*)(xin + rowoff + n);
;       const float o0 = xv.x + acc[i][j][0], o1 = xv.y + acc[i][j][1], o2 = xv.z + acc[i][j][2], o3 = xv.w + acc[i][j][3];
;       *(float4*)(out + rowoff + n) = make_float4(o0, o1, o2, o3);
;       ss += o0 * o0 + o1 * o1 + o2 * o2 + o3 * o3;
;       uint2 u;
;       u.x = pack2(o0, o1);
;       u.y = pack2(o2, o3);
;       *(uint2*)(xb + rowoff + n) = u;
;     }
;     ss += shx(ss, 16, lane);
;     ss += shx(ss, 32, lane);
;     if ((lane >> 4) == 0) red[wn * 256 + ml] = ss;
	v_mov_b32_dpp v232, v10 row_ror:8 row_mask:0xf bank_mask:0xf
	v_mov_b32_dpp v233, v11 row_ror:8 row_mask:0xf bank_mask:0xf
	v_mov_b32_dpp v234, v12 row_ror:8 row_mask:0xf bank_mask:0xf
	v_mov_b32_dpp v235, v13 row_ror:8 row_mask:0xf bank_mask:0xf
	v_cndmask_b32_e64 v232, v232, v14, s[90:91]
	v_cndmask_b32_e64 v233, v233, v15, s[90:91]
	v_cndmask_b32_e64 v234, v234, v16, s[90:91]
	v_cndmask_b32_e64 v235, v235, v17, s[90:91]
	v_pk_add_f32 v[232:233], v[232:233], v[216:217]
	v_pk_add_f32 v[234:235], v[234:235], v[218:219]
	s_nop 0
	global_store_dwordx4 v244, v[232:235], s[44:45] nt
	v_cvt_pk_bf16_f32 v240, v232, v233
	v_cvt_pk_bf16_f32 v241, v234, v235
	v_pk_mul_f32 v[236:237], v[232:233], v[232:233]
	v_pk_mul_f32 v[238:239], v[234:235], v[234:235]
	global_store_dwordx2 v245, v[240:241], s[48:49] nt
	v_add_f32_e32 v242, v236, v237
	v_add_f32_e32 v242, v242, v238
	v_add_f32_e32 v242, v242, v239
	v_mov_b32_dpp v232, v14 row_ror:8 row_mask:0xf bank_mask:0xf
	v_mov_b32_dpp v233, v15 row_ror:8 row_mask:0xf bank_mask:0xf
	v_mov_b32_dpp v234, v16 row_ror:8 row_mask:0xf bank_mask:0xf
	v_mov_b32_dpp v235, v17 row_ror:8 row_mask:0xf bank_mask:0xf
	v_cndmask_b32_e64 v232, v10, v232, s[90:91]
	v_cndmask_b32_e64 v233, v11, v233, s[90:91]
	v_cndmask_b32_e64 v234, v12, v234, s[90:91]
	v_cndmask_b32_e64 v235, v13, v235, s[90:91]
	v_pk_add_f32 v[232:233], v[232:233], v[224:225]
	v_pk_add_f32 v[234:235], v[234:235], v[226:227]
	s_nop 0
	global_store_dwordx4 v244, v[232:235], s[46:47] nt
	v_cvt_pk_bf16_f32 v240, v232, v233
	v_cvt_pk_bf16_f32 v241, v234, v235
	v_pk_mul_f32 v[236:237], v[232:233], v[232:233]
	v_pk_mul_f32 v[238:239], v[234:235], v[234:235]
	global_store_dwordx2 v245, v[240:241], s[50:51] nt
	v_add_f32_e32 v191, v236, v237
	v_add_f32_e32 v191, v191, v238
	v_add_f32_e32 v191, v191, v239
	v_mov_b32_dpp v232, v38 row_ror:8 row_mask:0xf bank_mask:0xf
	v_mov_b32_dpp v233, v39 row_ror:8 row_mask:0xf bank_mask:0xf
	v_mov_b32_dpp v234, v40 row_ror:8 row_mask:0xf bank_mask:0xf
	v_mov_b32_dpp v235, v41 row_ror:8 row_mask:0xf bank_mask:0xf
	v_cndmask_b32_e64 v232, v232, v6, s[90:91]
	v_cndmask_b32_e64 v233, v233, v7, s[90:91]
	v_cndmask_b32_e64 v234, v234, v8, s[90:91]
	v_cndmask_b32_e64 v235, v235, v9, s[90:91]
	v_pk_add_f32 v[232:233], v[232:233], v[220:221]
	v_pk_add_f32 v[234:235], v[234:235], v[222:223]
	s_nop 0
	global_store_dwordx4 v244, v[232:235], s[44:45] offset:128 nt
	v_cvt_pk_bf16_f32 v240, v232, v233
	v_cvt_pk_bf16_f32 v241, v234, v235
	v_pk_mul_f32 v[236:237], v[232:233], v[232:233]
	v_pk_mul_f32 v[238:239], v[234:235], v[234:235]
	global_store_dwordx2 v245, v[240:241], s[48:49] offset:64 nt
	v_add_f32_e32 v242, v242, v236
	v_add_f32_e32 v242, v242, v237
	v_add_f32_e32 v242, v242, v238
	v_add_f32_e32 v242, v242, v239
	v_mov_b32_dpp v232, v6 row_ror:8 row_mask:0xf bank_mask:0xf
	v_mov_b32_dpp v233, v7 row_ror:8 row_mask:0xf bank_mask:0xf
	v_mov_b32_dpp v234, v8 row_ror:8 row_mask:0xf bank_mask:0xf
	v_mov_b32_dpp v235, v9 row_ror:8 row_mask:0xf bank_mask:0xf
	v_cndmask_b32_e64 v232, v38, v232, s[90:91]
	v_cndmask_b32_e64 v233, v39, v233, s[90:91]
	v_cndmask_b32_e64 v234, v40, v234, s[90:91]
	v_cndmask_b32_e64 v235, v41, v235, s[90:91]
	v_pk_add_f32 v[232:233], v[232:233], v[228:229]
	v_pk_add_f32 v[234:235], v[234:235], v[230:231]
	s_nop 0
	global_store_dwordx4 v244, v[232:235], s[46:47] offset:128 nt
	v_cvt_pk_bf16_f32 v240, v232, v233
	v_cvt_pk_bf16_f32 v241, v234, v235
	v_pk_mul_f32 v[236:237], v[232:233], v[232:233]
	v_pk_mul_f32 v[238:239], v[234:235], v[234:235]
	global_store_dwordx2 v245, v[240:241], s[50:51] offset:64 nt
	v_add_f32_e32 v191, v191, v236
	v_add_f32_e32 v191, v191, v237
	v_add_f32_e32 v191, v191, v238
	v_add_f32_e32 v191, v191, v239
	s_nop 1
	v_add_f32_dpp v242, v242, v242 row_ror:8 row_mask:0xf bank_mask:0xf
	v_add_f32_dpp v191, v191, v191 row_ror:8 row_mask:0xf bank_mask:0xf
	s_add_u32 s44, s44, 0x10000
	s_addc_u32 s45, s45, 0
	s_add_u32 s46, s46, 0x10000
	s_addc_u32 s47, s47, 0
	s_add_u32 s48, s48, 0x8000
	s_addc_u32 s49, s49, 0
	s_add_u32 s50, s50, 0x8000
	s_addc_u32 s51, s51, 0
	v_cndmask_b32_e64 v242, v191, v242, s[90:91]
	ds_bpermute_b32 v243, v189, v242
	s_waitcnt lgkmcnt(0)
	v_add_f32_e32 v242, v242, v243
	ds_bpermute_b32 v243, v190, v242
	s_waitcnt lgkmcnt(0)
	v_add_f32_e32 v242, v242, v243
	s_and_saveexec_b64 s[2:3], s[88:89]
	ds_write_b32 v188, v242 offset:448
	s_or_b64 exec, exec, s[2:3]
	s_branch .LBB0_824

; template <class F>
; DI void gemm8_epi_staged(f32x4 (&acc)[8][4], int m0, int n0, bf16_t* L0, F f, bf16_t* dst, size_t ld, int nmax) {
;     ...
; #pragma unroll
;     for (int it = 0; it < 8; ++it) {
;       const int idx = tid + 512 * it;
;       const int row = idx >> 5, ch = idx & 31;
;       const u32x4 v = *(const u32x4*)(L + row * 264 + ch * 8);
;       const int n = n0 + ch * 8;
;       if (n < nmax) *(u32x4*)(dst + (size_t)(m0 + half * 128 + row) * ld + n) = v;
;     }
;     __syncthreads();
.LBB0_886:
	s_or_b64 exec, exec, s[2:3]
	s_waitcnt lgkmcnt(0)
	s_barrier
	s_bitset1_b32 s6, 7
	ds_read_b128 v[4:7], v142
	v_add_u32_e32 v8, s6, v0
	v_ashrrev_i32_e32 v9, 31, v8
	v_lshlrev_b64 v[8:9], 13, v[8:9]
	v_lshl_add_u64 v[8:9], v[2:3], 0, v[8:9]
	s_waitcnt lgkmcnt(0)
	global_store_dwordx4 v[8:9], v[4:7], off nt
	ds_read_b128 v[4:7], v143
	v_add_u32_e32 v8, s6, v141
	v_ashrrev_i32_e32 v9, 31, v8
	v_lshlrev_b64 v[8:9], 13, v[8:9]
	v_lshl_add_u64 v[8:9], v[2:3], 0, v[8:9]
	s_waitcnt lgkmcnt(0)
	global_store_dwordx4 v[8:9], v[4:7], off nt
	ds_read_b128 v[4:7], v146
	v_add_u32_e32 v8, s6, v144
	v_ashrrev_i32_e32 v9, 31, v8
	v_lshlrev_b64 v[8:9], 13, v[8:9]
	v_lshl_add_u64 v[8:9], v[2:3], 0, v[8:9]
	s_waitcnt lgkmcnt(0)
	global_store_dwordx4 v[8:9], v[4:7], off nt
	ds_read_b128 v[4:7], v147
	v_add_u32_e32 v8, s6, v145
	v_ashrrev_i32_e32 v9, 31, v8
	v_lshlrev_b64 v[8:9], 13, v[8:9]
	v_lshl_add_u64 v[8:9], v[2:3], 0, v[8:9]
	s_waitcnt lgkmcnt(0)
	global_store_dwordx4 v[8:9], v[4:7], off nt
	ds_read_b128 v[4:7], v150
	v_add_u32_e32 v8, s6, v148
	v_ashrrev_i32_e32 v9, 31, v8
	v_lshlrev_b64 v[8:9], 13, v[8:9]
	v_lshl_add_u64 v[8:9], v[2:3], 0, v[8:9]
	s_waitcnt lgkmcnt(0)
	global_store_dwordx4 v[8:9], v[4:7], off nt
	ds_read_b128 v[4:7], v151
	v_add_u32_e32 v8, s6, v149
	v_ashrrev_i32_e32 v9, 31, v8
	v_lshlrev_b64 v[8:9], 13, v[8:9]
	v_lshl_add_u64 v[8:9], v[2:3], 0, v[8:9]
	s_waitcnt lgkmcnt(0)
	global_store_dwordx4 v[8:9], v[4:7], off nt
	ds_read_b128 v[4:7], v154
	v_add_u32_e32 v8, s6, v152
	v_ashrrev_i32_e32 v9, 31, v8
	v_lshlrev_b64 v[8:9], 13, v[8:9]
	v_lshl_add_u64 v[8:9], v[2:3], 0, v[8:9]
	s_waitcnt lgkmcnt(0)
	global_store_dwordx4 v[8:9], v[4:7], off nt
	ds_read_b128 v[4:7], v155
	v_add_u32_e32 v8, s6, v153
	v_ashrrev_i32_e32 v9, 31, v8
	v_readlane_b32 s2, v254, 13
	v_lshlrev_b64 v[8:9], 13, v[8:9]
	s_add_i32 s10, s10, s2
	v_readlane_b32 s2, v254, 18
	v_lshl_add_u64 v[2:3], v[2:3], 0, v[8:9]
	s_add_i32 s9, s9, s2
	s_mov_b64 s[6:7], -1
	s_andn2_b64 vcc, exec, s[0:1]
	s_mov_b32 s13, s12
	s_waitcnt lgkmcnt(0)
	global_store_dwordx4 v[2:3], v[4:7], off nt
	s_barrier
	s_cbranch_vccz .LBB0_897

; DI void gemm8_accum(f32x4 (&acc)[8][4], const bf16_t* a, size_t lda, const bf16_t* b, size_t ldb, int nkb, bf16_t* L,
;                     const bool pre, const bf16_t* an, size_t ldan, const bf16_t* bn, size_t ldbn) {
;     ...
;   __syncthreads();
;   g8_store1(L + 32768, ra, lrow, lch);
;   g8_load1(ra, an, ldan, 0, lrow, lch);
;   __builtin_amdgcn_sched_barrier(0);
;   g8_compute<0, 1>(acc, L, wm, wn, lane);
;   __builtin_amdgcn_sched_barrier(0);
;   g8_store1(L + 32768 + 16384, rb, lrow, lch);
;   g8_load1(rb, bn, ldbn, 0, lrow, lch);
;   __builtin_amdgcn_sched_barrier(0);
;   g8_compute<1, 2>(acc, L, wm, wn, lane);
.Lstg_942_c:
	v_readlane_b32 s0, v254, 18
	s_add_i32 s12, s13, s0
	s_cmp_gt_u32 s12, 63
	s_cselect_b64 s[0:1], -1, 0
	s_cmp_lt_u32 s12, 64
	s_cselect_b32 s7, s12, s13
	s_lshl_b32 s2, s7, 1
	s_and_b32 s2, s2, 0x7fffffe0
	s_and_b32 s3, s7, 3
	s_or_b32 s2, s3, s2
	v_readlane_b32 s3, v252, 25
	s_or_b32 s28, s2, s3
	s_lshl_b32 s13, s11, 8
	s_lshl_b64 s[2:3], s[28:29], 21
	s_add_u32 s2, s16, s2
	v_mov_b32_e32 v169, v1
	v_mov_b32_e32 v167, v1
	s_addc_u32 s3, s17, s3
	v_lshlrev_b64 v[184:185], 1, v[168:169]
	v_lshlrev_b64 v[166:167], 1, v[166:167]
	v_lshlrev_b64 v[226:227], 1, v[0:1]
	v_lshl_add_u64 v[170:171], s[2:3], 0, v[164:165]
	v_lshl_add_u64 v[172:173], s[2:3], 0, v[184:185]
	v_lshl_add_u64 v[176:177], s[2:3], 0, v[166:167]
	v_lshl_add_u64 v[180:181], s[2:3], 0, v[226:227]
	s_barrier
	global_load_dwordx4 v[168:171], v[170:171], off
	s_nop 0
	global_load_dwordx4 v[172:175], v[172:173], off
	s_nop 0
	global_load_dwordx4 v[176:179], v[176:177], off
	s_nop 0
	global_load_dwordx4 v[180:183], v[180:181], off
	s_lshl_b32 s2, s7, 19
	s_and_b32 s2, s2, 0x600000
	v_readlane_b32 s20, v251, 59
	v_readlane_b32 s21, v251, 60
	s_add_u32 s2, s20, s2
	s_addc_u32 s3, s21, 0
	s_add_i32 s7, 0, 0x10000
	v_add3_u32 v0, s7, v189, v190
	s_waitcnt vmcnt(11)
	ds_write_b128 v0, v[22:25]
	s_waitcnt vmcnt(9)
	ds_write_b128 v0, v[18:21] offset:8192
	ds_write_b128 v0, v[26:29] offset:16384
	s_waitcnt vmcnt(8)
	ds_write_b128 v0, v[30:33] offset:24576
	v_lshlrev_b32_e32 v0, 1, v191
	v_add_u32_e32 v191, 0, v0
	v_add_u32_e32 v206, v191, v187
	ds_read_b128 v[18:21], v206
	ds_read_b128 v[22:25], v206 offset:2048
	ds_read_b128 v[26:29], v206 offset:4096
	ds_read_b128 v[30:33], v206 offset:6144
	ds_read_b128 v[192:195], v206 offset:8192
	ds_read_b128 v[198:201], v206 offset:10240
	ds_read_b128 v[202:205], v206 offset:12288
	ds_read_b128 v[206:209], v206 offset:14336
	v_add_u32_e32 v191, v191, v186
	ds_read_b128 v[210:213], v191 offset:32768
	ds_read_b128 v[214:217], v191 offset:34816
	ds_read_b128 v[218:221], v191 offset:36864
	ds_read_b128 v[222:225], v191 offset:38912
	s_setprio 1
	s_waitcnt lgkmcnt(3)
	v_mfma_f32_16x16x32_bf16 v[158:161], v[210:213], v[18:21], v[158:161]
	s_waitcnt lgkmcnt(2)
	v_mfma_f32_16x16x32_bf16 v[154:157], v[214:217], v[18:21], v[154:157]
	s_waitcnt lgkmcnt(1)
	v_mfma_f32_16x16x32_bf16 v[150:153], v[218:221], v[18:21], v[150:153]
	s_waitcnt lgkmcnt(0)
	v_mfma_f32_16x16x32_bf16 v[18:21], v[222:225], v[18:21], v[146:149]
	v_mfma_f32_16x16x32_bf16 v[142:145], v[210:213], v[22:25], v[142:145]
	v_mfma_f32_16x16x32_bf16 v[138:141], v[214:217], v[22:25], v[138:141]
	v_mfma_f32_16x16x32_bf16 v[134:137], v[218:221], v[22:25], v[134:137]
	v_mfma_f32_16x16x32_bf16 v[22:25], v[222:225], v[22:25], v[130:133]
	v_mfma_f32_16x16x32_bf16 v[126:129], v[210:213], v[26:29], v[126:129]
	v_mfma_f32_16x16x32_bf16 v[122:125], v[214:217], v[26:29], v[122:125]
	v_mfma_f32_16x16x32_bf16 v[118:121], v[218:221], v[26:29], v[118:121]
	v_mfma_f32_16x16x32_bf16 v[26:29], v[222:225], v[26:29], v[114:117]
	v_mfma_f32_16x16x32_bf16 v[110:113], v[210:213], v[30:33], v[110:113]
	v_mfma_f32_16x16x32_bf16 v[106:109], v[214:217], v[30:33], v[106:109]
	v_mfma_f32_16x16x32_bf16 v[102:105], v[218:221], v[30:33], v[102:105]
	v_mfma_f32_16x16x32_bf16 v[30:33], v[222:225], v[30:33], v[98:101]
	v_mfma_f32_16x16x32_bf16 v[94:97], v[210:213], v[192:195], v[94:97]
	v_mfma_f32_16x16x32_bf16 v[90:93], v[214:217], v[192:195], v[90:93]
	v_mfma_f32_16x16x32_bf16 v[86:89], v[218:221], v[192:195], v[86:89]
	v_mfma_f32_16x16x32_bf16 v[82:85], v[222:225], v[192:195], v[82:85]
	v_mfma_f32_16x16x32_bf16 v[78:81], v[210:213], v[198:201], v[78:81]
	v_mfma_f32_16x16x32_bf16 v[74:77], v[214:217], v[198:201], v[74:77]
	v_mfma_f32_16x16x32_bf16 v[70:73], v[218:221], v[198:201], v[70:73]
	v_mfma_f32_16x16x32_bf16 v[66:69], v[222:225], v[198:201], v[66:69]
	v_mfma_f32_16x16x32_bf16 v[62:65], v[210:213], v[202:205], v[62:65]
	v_mfma_f32_16x16x32_bf16 v[58:61], v[214:217], v[202:205], v[58:61]
	v_mfma_f32_16x16x32_bf16 v[54:57], v[218:221], v[202:205], v[54:57]
	v_mfma_f32_16x16x32_bf16 v[50:53], v[222:225], v[202:205], v[50:53]
	v_mfma_f32_16x16x32_bf16 v[46:49], v[210:213], v[206:209], v[46:49]
	v_mfma_f32_16x16x32_bf16 v[42:45], v[214:217], v[206:209], v[42:45]
	v_mfma_f32_16x16x32_bf16 v[38:41], v[218:221], v[206:209], v[38:41]
	v_mfma_f32_16x16x32_bf16 v[34:37], v[222:225], v[206:209], v[34:37]
	s_setprio 0
	v_readlane_b32 s20, v254, 36
	s_nop 1
	v_add3_u32 v98, s20, v189, v190
	s_waitcnt vmcnt(7)
	ds_write_b128 v98, v[14:17]
	s_waitcnt vmcnt(6)
	ds_write_b128 v98, v[2:5] offset:8192
	s_waitcnt vmcnt(5)
	ds_write_b128 v98, v[6:9] offset:16384
	s_waitcnt vmcnt(4)
	ds_write_b128 v98, v[10:13] offset:24576
	v_lshl_add_u64 v[2:3], s[2:3], 0, v[164:165]
	v_lshl_add_u64 v[6:7], s[2:3], 0, v[184:185]
	v_lshl_add_u64 v[10:11], s[2:3], 0, v[166:167]
	v_lshl_add_u64 v[14:15], s[2:3], 0, v[226:227]
	global_load_dwordx4 v[2:5], v[2:3], off
	s_nop 0
	global_load_dwordx4 v[6:9], v[6:7], off
	s_nop 0
	global_load_dwordx4 v[10:13], v[10:11], off
	s_nop 0
	global_load_dwordx4 v[14:17], v[14:15], off
	v_lshlrev_b32_e32 v184, 1, v188
	v_add_u32_e32 v185, 0, v184
	v_add_u32_e32 v198, v185, v187
	ds_read_b128 v[98:101], v198
	ds_read_b128 v[114:117], v198 offset:2048
	ds_read_b128 v[130:133], v198 offset:4096
	ds_read_b128 v[146:149], v198 offset:6144
	ds_read_b128 v[164:167], v198 offset:8192
	ds_read_b128 v[188:191], v198 offset:10240
	ds_read_b128 v[192:195], v198 offset:12288
	ds_read_b128 v[198:201], v198 offset:14336
	v_add_u32_e32 v185, v185, v186
	ds_read_b128 v[202:205], v185 offset:32768
	ds_read_b128 v[206:209], v185 offset:34816
	ds_read_b128 v[210:213], v185 offset:36864
	ds_read_b128 v[214:217], v185 offset:38912
	s_setprio 1
	s_waitcnt lgkmcnt(3)
; DI void gemm8_accum(f32x4 (&acc)[8][4], const bf16_t* a, size_t lda, const bf16_t* b, size_t ldb, int nkb, bf16_t* L,
;                     const bool pre, const bf16_t* an, size_t ldan, const bf16_t* bn, size_t ldbn) {
;     ...
;   g8_compute<1, 2>(acc, L, wm, wn, lane);
;   __syncthreads();
;   g8_store1(L, ra, lrow, lch);
;   __builtin_amdgcn_sched_barrier(0);
;   g8_compute<0, 1>(acc, L + 32768, wm, wn, lane);
;   __builtin_amdgcn_sched_barrier(0);
;   g8_store1(L + 16384, rb, lrow, lch);
	v_mfma_f32_16x16x32_bf16 v[158:161], v[202:205], v[98:101], v[158:161]
	s_waitcnt lgkmcnt(2)
	v_mfma_f32_16x16x32_bf16 v[154:157], v[206:209], v[98:101], v[154:157]
	s_waitcnt lgkmcnt(1)
	v_mfma_f32_16x16x32_bf16 v[150:153], v[210:213], v[98:101], v[150:153]
	s_waitcnt lgkmcnt(0)
	v_mfma_f32_16x16x32_bf16 v[18:21], v[214:217], v[98:101], v[18:21]
	v_mfma_f32_16x16x32_bf16 v[98:101], v[202:205], v[114:117], v[142:145]
	v_mfma_f32_16x16x32_bf16 v[138:141], v[206:209], v[114:117], v[138:141]
	v_mfma_f32_16x16x32_bf16 v[134:137], v[210:213], v[114:117], v[134:137]
	v_mfma_f32_16x16x32_bf16 v[22:25], v[214:217], v[114:117], v[22:25]
	v_mfma_f32_16x16x32_bf16 v[114:117], v[202:205], v[130:133], v[126:129]
	v_mfma_f32_16x16x32_bf16 v[122:125], v[206:209], v[130:133], v[122:125]
	v_mfma_f32_16x16x32_bf16 v[118:121], v[210:213], v[130:133], v[118:121]
	v_mfma_f32_16x16x32_bf16 v[26:29], v[214:217], v[130:133], v[26:29]
	v_mfma_f32_16x16x32_bf16 v[110:113], v[202:205], v[146:149], v[110:113]
	v_mfma_f32_16x16x32_bf16 v[106:109], v[206:209], v[146:149], v[106:109]
	v_mfma_f32_16x16x32_bf16 v[102:105], v[210:213], v[146:149], v[102:105]
	v_mfma_f32_16x16x32_bf16 v[30:33], v[214:217], v[146:149], v[30:33]
	v_mfma_f32_16x16x32_bf16 v[94:97], v[202:205], v[164:167], v[94:97]
	v_mfma_f32_16x16x32_bf16 v[90:93], v[206:209], v[164:167], v[90:93]
	v_mfma_f32_16x16x32_bf16 v[86:89], v[210:213], v[164:167], v[86:89]
	v_mfma_f32_16x16x32_bf16 v[82:85], v[214:217], v[164:167], v[82:85]
	v_mfma_f32_16x16x32_bf16 v[78:81], v[202:205], v[188:191], v[78:81]
	v_mfma_f32_16x16x32_bf16 v[74:77], v[206:209], v[188:191], v[74:77]
	v_mfma_f32_16x16x32_bf16 v[70:73], v[210:213], v[188:191], v[70:73]
	v_mfma_f32_16x16x32_bf16 v[66:69], v[214:217], v[188:191], v[66:69]
	v_mfma_f32_16x16x32_bf16 v[62:65], v[202:205], v[192:195], v[62:65]
	v_mfma_f32_16x16x32_bf16 v[58:61], v[206:209], v[192:195], v[58:61]
	v_mfma_f32_16x16x32_bf16 v[54:57], v[210:213], v[192:195], v[54:57]
	v_mfma_f32_16x16x32_bf16 v[50:53], v[214:217], v[192:195], v[50:53]
	v_mfma_f32_16x16x32_bf16 v[46:49], v[202:205], v[198:201], v[46:49]
	v_mfma_f32_16x16x32_bf16 v[42:45], v[206:209], v[198:201], v[42:45]
	v_mfma_f32_16x16x32_bf16 v[38:41], v[210:213], v[198:201], v[38:41]
	v_mfma_f32_16x16x32_bf16 v[34:37], v[214:217], v[198:201], v[34:37]
	s_setprio 0
	s_barrier
	s_waitcnt vmcnt(7)
	ds_write_b128 v163, v[168:171]
	s_waitcnt vmcnt(6)
	ds_write_b128 v163, v[172:175] offset:8192
	s_waitcnt vmcnt(5)
	ds_write_b128 v163, v[176:179] offset:16384
	s_waitcnt vmcnt(4)
	ds_write_b128 v163, v[180:183] offset:24576
	v_add3_u32 v176, s7, v0, v187
	ds_read_b128 v[126:129], v176
	ds_read_b128 v[130:133], v176 offset:2048
	ds_read_b128 v[142:145], v176 offset:4096
	ds_read_b128 v[146:149], v176 offset:6144
	ds_read_b128 v[164:167], v176 offset:8192
	ds_read_b128 v[168:171], v176 offset:10240
	ds_read_b128 v[172:175], v176 offset:12288
	ds_read_b128 v[176:179], v176 offset:14336
	v_add3_u32 v0, s20, v0, v186
	ds_read_b128 v[180:183], v0
	ds_read_b128 v[188:191], v0 offset:2048
	ds_read_b128 v[192:195], v0 offset:4096
	ds_read_b128 v[198:201], v0 offset:6144
	s_setprio 1
	s_waitcnt lgkmcnt(3)
	v_mfma_f32_16x16x32_bf16 v[158:161], v[180:183], v[126:129], v[158:161]
	s_waitcnt lgkmcnt(2)
	v_mfma_f32_16x16x32_bf16 v[154:157], v[188:191], v[126:129], v[154:157]
	s_waitcnt lgkmcnt(1)
	v_mfma_f32_16x16x32_bf16 v[150:153], v[192:195], v[126:129], v[150:153]
	s_waitcnt lgkmcnt(0)
	v_mfma_f32_16x16x32_bf16 v[18:21], v[198:201], v[126:129], v[18:21]
	v_mfma_f32_16x16x32_bf16 v[98:101], v[180:183], v[130:133], v[98:101]
	v_mfma_f32_16x16x32_bf16 v[126:129], v[188:191], v[130:133], v[138:141]
	v_mfma_f32_16x16x32_bf16 v[22:25], v[198:201], v[130:133], v[22:25]
	v_mfma_f32_16x16x32_bf16 v[114:117], v[180:183], v[142:145], v[114:117]
	v_mfma_f32_16x16x32_bf16 v[122:125], v[188:191], v[142:145], v[122:125]
	v_mfma_f32_16x16x32_bf16 v[118:121], v[192:195], v[142:145], v[118:121]
	v_mfma_f32_16x16x32_bf16 v[26:29], v[198:201], v[142:145], v[26:29]
	v_mfma_f32_16x16x32_bf16 v[30:33], v[198:201], v[146:149], v[30:33]
	v_mfma_f32_16x16x32_bf16 v[134:137], v[192:195], v[130:133], v[134:137]
	v_mfma_f32_16x16x32_bf16 v[130:133], v[180:183], v[146:149], v[110:113]
	v_mfma_f32_16x16x32_bf16 v[138:141], v[188:191], v[146:149], v[106:109]
	v_mfma_f32_16x16x32_bf16 v[142:145], v[192:195], v[146:149], v[102:105]
	v_mfma_f32_16x16x32_bf16 v[146:149], v[180:183], v[164:167], v[94:97]
	v_mfma_f32_16x16x32_bf16 v[202:205], v[188:191], v[164:167], v[90:93]
	v_mfma_f32_16x16x32_bf16 v[206:209], v[192:195], v[164:167], v[86:89]
	v_mfma_f32_16x16x32_bf16 v[164:167], v[198:201], v[164:167], v[82:85]
	v_mfma_f32_16x16x32_bf16 v[210:213], v[180:183], v[168:171], v[78:81]
	v_mfma_f32_16x16x32_bf16 v[214:217], v[188:191], v[168:171], v[74:77]
	v_mfma_f32_16x16x32_bf16 v[218:221], v[192:195], v[168:171], v[70:73]
	v_mfma_f32_16x16x32_bf16 v[168:171], v[198:201], v[168:171], v[66:69]
	v_mfma_f32_16x16x32_bf16 v[222:225], v[180:183], v[172:175], v[62:65]
	v_mfma_f32_16x16x32_bf16 v[226:229], v[188:191], v[172:175], v[58:61]
	v_mfma_f32_16x16x32_bf16 v[230:233], v[192:195], v[172:175], v[54:57]
	v_mfma_f32_16x16x32_bf16 v[172:175], v[198:201], v[172:175], v[50:53]
	v_mfma_f32_16x16x32_bf16 v[180:183], v[180:183], v[176:179], v[46:49]
	v_mfma_f32_16x16x32_bf16 v[188:191], v[188:191], v[176:179], v[42:45]
	v_mfma_f32_16x16x32_bf16 v[192:195], v[192:195], v[176:179], v[38:41]
	v_mfma_f32_16x16x32_bf16 v[176:179], v[198:201], v[176:179], v[34:37]
	s_setprio 0
	s_waitcnt vmcnt(3)
	ds_write_b128 v163, v[2:5] offset:32768
	s_waitcnt vmcnt(2)
; DI int TID8() { int t = threadIdx.x; asm volatile("" : "+v"(t)); return t; }
; DI void gemm8_accum(f32x4 (&acc)[8][4], const bf16_t* a, size_t lda, const bf16_t* b, size_t ldb, int nkb, bf16_t* L,
;                     const bool pre, const bf16_t* an, size_t ldan, const bf16_t* bn, size_t ldbn) {
;     ...
;   g8_store1(L + 16384, rb, lrow, lch);
;   __builtin_amdgcn_sched_barrier(0);
;   g8_compute<1, 2>(acc, L + 32768, wm, wn, lane);
;   __syncthreads();
; DI void gemm8_epi_resid(f32x4 (&acc)[8][4], int m0, int n0, int ntile8, bf16_t* L, const float* xin, float* out, bf16_t* xb, float* rowpart) {
;   const int tid = TID8(), lane = tid & 63, w = tid >> 6;
;   const int wm = w >> 2, wn = w & 3;
;   float* red = (float*)(L + 32768);
; #pragma unroll
;   for (int i = 0; i < 8; ++i) {
;     const int ml = wm * 128 + i * 16 + (lane & 15);
;     const size_t rowoff = (size_t)(m0 + ml) * DM;
;     float ss = 0.f;
; #pragma unroll
;     for (int j = 0; j < 4; ++j) {
;       const int n = n0 + wn * 64 + j * 16 + (lane >> 4) * 4;
;       const float4 xv = *(const float4*)(xin + rowoff + n);
	ds_write_b128 v163, v[6:9] offset:40960
	s_waitcnt vmcnt(1)
	ds_write_b128 v163, v[10:13] offset:49152
	s_waitcnt vmcnt(0)
	ds_write_b128 v163, v[14:17] offset:57344
	v_add3_u32 v0, s7, v184, v187
	ds_read_b128 v[2:5], v0
	ds_read_b128 v[6:9], v0 offset:2048
	ds_read_b128 v[10:13], v0 offset:4096
	ds_read_b128 v[14:17], v0 offset:6144
	ds_read_b128 v[34:37], v0 offset:8192
	ds_read_b128 v[198:201], v0 offset:10240
	ds_read_b128 v[234:237], v0 offset:12288
	ds_read_b128 v[238:241], v0 offset:14336
	v_add3_u32 v0, s20, v184, v186
	ds_read_b128 v[184:187], v0
	ds_read_b128 v[242:245], v0 offset:2048
	ds_read_b128 v[246:249], v0 offset:4096
	ds_read_b128 v[38:41], v0 offset:6144
	s_setprio 1
	s_waitcnt lgkmcnt(3)
	v_mfma_f32_16x16x32_bf16 v[158:161], v[184:187], v[2:5], v[158:161]
	s_waitcnt lgkmcnt(2)
	v_mfma_f32_16x16x32_bf16 v[154:157], v[242:245], v[2:5], v[154:157]
	s_waitcnt lgkmcnt(1)
	v_mfma_f32_16x16x32_bf16 v[150:153], v[246:249], v[2:5], v[150:153]
	s_waitcnt lgkmcnt(0)
	v_mfma_f32_16x16x32_bf16 v[2:5], v[38:41], v[2:5], v[18:21]
	v_mfma_f32_16x16x32_bf16 v[110:113], v[184:187], v[6:9], v[98:101]
	v_mfma_f32_16x16x32_bf16 v[106:109], v[242:245], v[6:9], v[126:129]
	v_mfma_f32_16x16x32_bf16 v[102:105], v[246:249], v[6:9], v[134:137]
	v_mfma_f32_16x16x32_bf16 v[98:101], v[38:41], v[6:9], v[22:25]
	v_mfma_f32_16x16x32_bf16 v[94:97], v[184:187], v[10:13], v[114:117]
	v_mfma_f32_16x16x32_bf16 v[90:93], v[242:245], v[10:13], v[122:125]
	v_mfma_f32_16x16x32_bf16 v[86:89], v[246:249], v[10:13], v[118:121]
	v_mfma_f32_16x16x32_bf16 v[82:85], v[38:41], v[10:13], v[26:29]
	v_mfma_f32_16x16x32_bf16 v[78:81], v[184:187], v[14:17], v[130:133]
	v_mfma_f32_16x16x32_bf16 v[74:77], v[242:245], v[14:17], v[138:141]
	v_mfma_f32_16x16x32_bf16 v[70:73], v[246:249], v[14:17], v[142:145]
	v_mfma_f32_16x16x32_bf16 v[66:69], v[38:41], v[14:17], v[30:33]
	v_mfma_f32_16x16x32_bf16 v[62:65], v[184:187], v[34:37], v[146:149]
	v_mfma_f32_16x16x32_bf16 v[58:61], v[242:245], v[34:37], v[202:205]
	v_mfma_f32_16x16x32_bf16 v[54:57], v[246:249], v[34:37], v[206:209]
	v_mfma_f32_16x16x32_bf16 v[50:53], v[38:41], v[34:37], v[164:167]
	v_mfma_f32_16x16x32_bf16 v[46:49], v[184:187], v[198:201], v[210:213]
	v_mfma_f32_16x16x32_bf16 v[42:45], v[242:245], v[198:201], v[214:217]
	v_mfma_f32_16x16x32_bf16 v[124:127], v[246:249], v[198:201], v[218:221]
	v_mfma_f32_16x16x32_bf16 v[34:37], v[38:41], v[198:201], v[168:171]
	v_mfma_f32_16x16x32_bf16 v[30:33], v[184:187], v[234:237], v[222:225]
	v_mfma_f32_16x16x32_bf16 v[26:29], v[242:245], v[234:237], v[226:229]
	v_mfma_f32_16x16x32_bf16 v[22:25], v[246:249], v[234:237], v[230:233]
	v_mfma_f32_16x16x32_bf16 v[18:21], v[38:41], v[234:237], v[172:175]
	v_mfma_f32_16x16x32_bf16 v[14:17], v[184:187], v[238:241], v[180:183]
	v_mfma_f32_16x16x32_bf16 v[10:13], v[242:245], v[238:241], v[188:191]
	v_mfma_f32_16x16x32_bf16 v[6:9], v[246:249], v[238:241], v[192:195]
	v_mfma_f32_16x16x32_bf16 v[38:41], v[38:41], v[238:241], v[176:179]
	s_setprio 0
	v_mov_b32_e32 v118, v196
	s_barrier
	s_movk_i32 s2, 0xff80
	v_ashrrev_i32_e32 v115, 1, v118
	v_and_b32_e32 v116, 15, v118
	v_bfe_u32 v114, v118, 6, 2
	v_and_or_b32 v121, v115, s2, v116
	v_lshrrev_b32_e32 v116, 2, v118
	v_and_b32_e32 v0, 63, v118
	v_lshlrev_b32_e32 v115, 6, v114
	v_and_b32_e32 v116, 12, v116
	v_or3_b32 v138, v116, s13, v115
	v_lshlrev_b32_e32 v115, 2, v0
	v_lshl_add_u32 v146, v114, 10, s7
	v_add_u32_e32 v114, s6, v121
	v_xor_b32_e32 v120, 64, v115
	v_xor_b32_e32 v119, 0x80, v115
	v_ashrrev_i32_e32 v115, 31, v114
	v_readlane_b32 s24, v251, 33
	v_lshlrev_b64 v[116:117], 12, v[114:115]
	v_readlane_b32 s26, v251, 35
	v_readlane_b32 s27, v251, 36
	v_cmp_gt_u32_e32 vcc, 16, v0
	v_lshlrev_b32_e32 v0, 2, v138
	v_lshl_add_u64 v[116:117], s[26:27], 0, v[116:117]
	v_lshl_add_u64 v[132:133], v[116:117], 0, v[0:1]
	v_lshlrev_b64 v[122:123], 11, v[114:115]
	v_lshl_add_u64 v[122:123], s[18:19], 0, v[122:123]
	v_lshlrev_b32_e32 v116, 1, v138
	v_mov_b32_e32 v117, v1
	v_lshl_add_u64 v[122:123], v[122:123], 0, v[116:117]
	v_readlane_b32 s25, v251, 34
	v_lshl_add_u32 v188, v121, 2, v146
	v_mov_b32_e32 v189, v120
	v_mov_b32_e32 v190, v119
	v_and_b32_e32 v240, 63, v118
	v_cmp_gt_u32_e64 s[88:89], 16, v240
	v_and_b32_e32 v243, 15, v118
	v_bfe_u32 v242, v118, 4, 2
	v_and_b32_e32 v240, 8, v243
	v_cmp_eq_u32_e64 s[90:91], 0, v240
	v_lshlrev_b32_e32 v236, 12, v243
	v_lshl_or_b32 v236, v242, 4, v236
	v_lshlrev_b32_e32 v237, 11, v243
	v_lshl_or_b32 v237, v242, 3, v237
	v_sub_co_u32_e32 v238, vcc, v132, v236
	v_subbrev_co_u32_e32 v239, vcc, 0, v133, vcc
	s_nop 0
	v_readfirstlane_b32 s40, v238
	v_readfirstlane_b32 s41, v239
	v_sub_co_u32_e32 v238, vcc, v132, v236
	v_subbrev_co_u32_e32 v239, vcc, 0, v133, vcc
	s_nop 0
	v_readfirstlane_b32 s44, v238
	v_readfirstlane_b32 s45, v239
	v_sub_co_u32_e32 v238, vcc, v122, v237
	v_subbrev_co_u32_e32 v239, vcc, 0, v123, vcc
	s_nop 0
	v_readfirstlane_b32 s48, v238
	v_readfirstlane_b32 s49, v239
	s_add_u32 s42, s40, 0x8000
	s_addc_u32 s43, s41, 0
	s_add_u32 s46, s44, 0x8000
	s_addc_u32 s47, s45, 0
	s_add_u32 s50, s48, 0x4000
	s_addc_u32 s51, s49, 0
	v_and_b32_e32 v238, 7, v243
	v_lshrrev_b32_e32 v239, 3, v243
	v_lshlrev_b32_e32 v244, 12, v238
	v_lshl_or_b32 v244, v239, 6, v244
	v_lshl_or_b32 v244, v242, 4, v244
	v_lshlrev_b32_e32 v245, 11, v238
	v_lshl_or_b32 v245, v239, 5, v245
	v_lshl_or_b32 v245, v242, 3, v245
	global_load_dwordx4 v[192:195], v244, s[40:41]
	global_load_dwordx4 v[198:201], v244, s[40:41] offset:128
	global_load_dwordx4 v[202:205], v244, s[42:43]
	global_load_dwordx4 v[206:209], v244, s[42:43] offset:128
	s_add_u32 s40, s40, 0x10000
	s_addc_u32 s41, s41, 0
	s_add_u32 s42, s42, 0x10000
	s_addc_u32 s43, s43, 0
	global_load_dwordx4 v[216:219], v244, s[40:41]
	global_load_dwordx4 v[220:223], v244, s[40:41] offset:128
	global_load_dwordx4 v[224:227], v244, s[42:43]
	global_load_dwordx4 v[228:231], v244, s[42:43] offset:128
	s_add_u32 s40, s40, 0x10000
	s_addc_u32 s41, s41, 0
	s_add_u32 s42, s42, 0x10000
	s_addc_u32 s43, s43, 0
	s_waitcnt vmcnt(4)
; DI void gemm8_epi_resid(f32x4 (&acc)[8][4], int m0, int n0, int ntile8, bf16_t* L, const float* xin, float* out, bf16_t* xb, float* rowpart) {
;     ...
;     for (int j = 0; j < 4; ++j) {
;       const int n = n0 + wn * 64 + j * 16 + (lane >> 4) * 4;
;       const float4 xv = *(const float4*)(xin + rowoff + n);
;       const float o0 = xv.x + acc[i][j][0], o1 = xv.y + acc[i][j][1], o2 = xv.z + acc[i][j][2], o3 = xv.w + acc[i][j][3];
;       *(float4*)(out + rowoff + n) = make_float4(o0, o1, o2, o3);
;       ss += o0 * o0 + o1 * o1 + o2 * o2 + o3 * o3;
;       uint2 u;
;       u.x = pack2(o0, o1);
;       u.y = pack2(o2, o3);
;       *(uint2*)(xb + rowoff + n) = u;
;     }
;     ss += shx(ss, 16, lane);
;     ss += shx(ss, 32, lane);
;     if ((lane >> 4) == 0) red[wn * 256 + ml] = ss;
	v_mov_b32_dpp v232, v154 row_ror:8 row_mask:0xf bank_mask:0xf
	v_mov_b32_dpp v233, v155 row_ror:8 row_mask:0xf bank_mask:0xf
	v_mov_b32_dpp v234, v156 row_ror:8 row_mask:0xf bank_mask:0xf
	v_mov_b32_dpp v235, v157 row_ror:8 row_mask:0xf bank_mask:0xf
	v_cndmask_b32_e64 v232, v232, v158, s[90:91]
	v_cndmask_b32_e64 v233, v233, v159, s[90:91]
	v_cndmask_b32_e64 v234, v234, v160, s[90:91]
	v_cndmask_b32_e64 v235, v235, v161, s[90:91]
	v_pk_add_f32 v[232:233], v[232:233], v[192:193]
	v_pk_add_f32 v[234:235], v[234:235], v[194:195]
	s_nop 0
	global_store_dwordx4 v244, v[232:235], s[44:45] nt
	v_cvt_pk_bf16_f32 v240, v232, v233
	v_cvt_pk_bf16_f32 v241, v234, v235
	v_pk_mul_f32 v[236:237], v[232:233], v[232:233]
	v_pk_mul_f32 v[238:239], v[234:235], v[234:235]
	global_store_dwordx2 v245, v[240:241], s[48:49] nt
	v_add_f32_e32 v242, v236, v237
	v_add_f32_e32 v242, v242, v238
	v_add_f32_e32 v242, v242, v239
	v_mov_b32_dpp v232, v158 row_ror:8 row_mask:0xf bank_mask:0xf
	v_mov_b32_dpp v233, v159 row_ror:8 row_mask:0xf bank_mask:0xf
	v_mov_b32_dpp v234, v160 row_ror:8 row_mask:0xf bank_mask:0xf
	v_mov_b32_dpp v235, v161 row_ror:8 row_mask:0xf bank_mask:0xf
	v_cndmask_b32_e64 v232, v154, v232, s[90:91]
	v_cndmask_b32_e64 v233, v155, v233, s[90:91]
	v_cndmask_b32_e64 v234, v156, v234, s[90:91]
	v_cndmask_b32_e64 v235, v157, v235, s[90:91]
	v_pk_add_f32 v[232:233], v[232:233], v[202:203]
	v_pk_add_f32 v[234:235], v[234:235], v[204:205]
	s_nop 0
	global_store_dwordx4 v244, v[232:235], s[46:47] nt
	v_cvt_pk_bf16_f32 v240, v232, v233
	v_cvt_pk_bf16_f32 v241, v234, v235
	v_pk_mul_f32 v[236:237], v[232:233], v[232:233]
	v_pk_mul_f32 v[238:239], v[234:235], v[234:235]
	global_store_dwordx2 v245, v[240:241], s[50:51] nt
	v_add_f32_e32 v191, v236, v237
	v_add_f32_e32 v191, v191, v238
	v_add_f32_e32 v191, v191, v239
	v_mov_b32_dpp v232, v2 row_ror:8 row_mask:0xf bank_mask:0xf
	v_mov_b32_dpp v233, v3 row_ror:8 row_mask:0xf bank_mask:0xf
	v_mov_b32_dpp v234, v4 row_ror:8 row_mask:0xf bank_mask:0xf
	v_mov_b32_dpp v235, v5 row_ror:8 row_mask:0xf bank_mask:0xf
	v_cndmask_b32_e64 v232, v232, v150, s[90:91]
	v_cndmask_b32_e64 v233, v233, v151, s[90:91]
	v_cndmask_b32_e64 v234, v234, v152, s[90:91]
	v_cndmask_b32_e64 v235, v235, v153, s[90:91]
	v_pk_add_f32 v[232:233], v[232:233], v[198:199]
	v_pk_add_f32 v[234:235], v[234:235], v[200:201]
	s_nop 0
	global_store_dwordx4 v244, v[232:235], s[44:45] offset:128 nt
	v_cvt_pk_bf16_f32 v240, v232, v233
	v_cvt_pk_bf16_f32 v241, v234, v235
	v_pk_mul_f32 v[236:237], v[232:233], v[232:233]
	v_pk_mul_f32 v[238:239], v[234:235], v[234:235]
	global_store_dwordx2 v245, v[240:241], s[48:49] offset:64 nt
	v_add_f32_e32 v242, v242, v236
	v_add_f32_e32 v242, v242, v237
	v_add_f32_e32 v242, v242, v238
	v_add_f32_e32 v242, v242, v239
	v_mov_b32_dpp v232, v150 row_ror:8 row_mask:0xf bank_mask:0xf
	v_mov_b32_dpp v233, v151 row_ror:8 row_mask:0xf bank_mask:0xf
	v_mov_b32_dpp v234, v152 row_ror:8 row_mask:0xf bank_mask:0xf
	v_mov_b32_dpp v235, v153 row_ror:8 row_mask:0xf bank_mask:0xf
	v_cndmask_b32_e64 v232, v2, v232, s[90:91]
	v_cndmask_b32_e64 v233, v3, v233, s[90:91]
	v_cndmask_b32_e64 v234, v4, v234, s[90:91]
	v_cndmask_b32_e64 v235, v5, v235, s[90:91]
	v_pk_add_f32 v[232:233], v[232:233], v[206:207]
	v_pk_add_f32 v[234:235], v[234:235], v[208:209]
	s_nop 0
	global_store_dwordx4 v244, v[232:235], s[46:47] offset:128 nt
	v_cvt_pk_bf16_f32 v240, v232, v233
	v_cvt_pk_bf16_f32 v241, v234, v235
	v_pk_mul_f32 v[236:237], v[232:233], v[232:233]
	v_pk_mul_f32 v[238:239], v[234:235], v[234:235]
	global_store_dwordx2 v245, v[240:241], s[50:51] offset:64 nt
	v_add_f32_e32 v191, v191, v236
	v_add_f32_e32 v191, v191, v237
	v_add_f32_e32 v191, v191, v238
	v_add_f32_e32 v191, v191, v239
	s_nop 1
	v_add_f32_dpp v242, v242, v242 row_ror:8 row_mask:0xf bank_mask:0xf
	v_add_f32_dpp v191, v191, v191 row_ror:8 row_mask:0xf bank_mask:0xf
	s_add_u32 s44, s44, 0x10000
	s_addc_u32 s45, s45, 0
	s_add_u32 s46, s46, 0x10000
	s_addc_u32 s47, s47, 0
	s_add_u32 s48, s48, 0x8000
	s_addc_u32 s49, s49, 0
	s_add_u32 s50, s50, 0x8000
	s_addc_u32 s51, s51, 0
	v_cndmask_b32_e64 v242, v191, v242, s[90:91]
	ds_bpermute_b32 v243, v189, v242
	global_load_dwordx4 v[192:195], v244, s[40:41]
	global_load_dwordx4 v[198:201], v244, s[40:41] offset:128
	global_load_dwordx4 v[202:205], v244, s[42:43]
	global_load_dwordx4 v[206:209], v244, s[42:43] offset:128
	s_add_u32 s40, s40, 0x10000
	s_addc_u32 s41, s41, 0
	s_add_u32 s42, s42, 0x10000
	s_addc_u32 s43, s43, 0
	s_waitcnt lgkmcnt(0)
	v_add_f32_e32 v242, v242, v243
	ds_bpermute_b32 v243, v190, v242
	s_waitcnt lgkmcnt(0)
	v_add_f32_e32 v242, v242, v243
	s_and_saveexec_b64 s[2:3], s[88:89]
	ds_write_b32 v188, v242
	s_or_b64 exec, exec, s[2:3]
	s_waitcnt vmcnt(12)
; DI void gemm8_epi_resid(f32x4 (&acc)[8][4], int m0, int n0, int ntile8, bf16_t* L, const float* xin, float* out, bf16_t* xb, float* rowpart) {
;     ...
;     for (int j = 0; j < 4; ++j) {
;       const int n = n0 + wn * 64 + j * 16 + (lane >> 4) * 4;
;       const float4 xv = *(const float4*)(xin + rowoff + n);
;       const float o0 = xv.x + acc[i][j][0], o1 = xv.y + acc[i][j][1], o2 = xv.z + acc[i][j][2], o3 = xv.w + acc[i][j][3];
;       *(float4*)(out + rowoff + n) = make_float4(o0, o1, o2, o3);
;       ss += o0 * o0 + o1 * o1 + o2 * o2 + o3 * o3;
;       uint2 u;
;       u.x = pack2(o0, o1);
;       u.y = pack2(o2, o3);
;       *(uint2*)(xb + rowoff + n) = u;
;     }
;     ss += shx(ss, 16, lane);
;     ss += shx(ss, 32, lane);
;     if ((lane >> 4) == 0) red[wn * 256 + ml] = ss;
	v_mov_b32_dpp v232, v106 row_ror:8 row_mask:0xf bank_mask:0xf
	v_mov_b32_dpp v233, v107 row_ror:8 row_mask:0xf bank_mask:0xf
	v_mov_b32_dpp v234, v108 row_ror:8 row_mask:0xf bank_mask:0xf
	v_mov_b32_dpp v235, v109 row_ror:8 row_mask:0xf bank_mask:0xf
	v_cndmask_b32_e64 v232, v232, v110, s[90:91]
	v_cndmask_b32_e64 v233, v233, v111, s[90:91]
	v_cndmask_b32_e64 v234, v234, v112, s[90:91]
	v_cndmask_b32_e64 v235, v235, v113, s[90:91]
	v_pk_add_f32 v[232:233], v[232:233], v[216:217]
	v_pk_add_f32 v[234:235], v[234:235], v[218:219]
	s_nop 0
	global_store_dwordx4 v244, v[232:235], s[44:45] nt
	v_cvt_pk_bf16_f32 v240, v232, v233
	v_cvt_pk_bf16_f32 v241, v234, v235
	v_pk_mul_f32 v[236:237], v[232:233], v[232:233]
	v_pk_mul_f32 v[238:239], v[234:235], v[234:235]
	global_store_dwordx2 v245, v[240:241], s[48:49] nt
	v_add_f32_e32 v242, v236, v237
	v_add_f32_e32 v242, v242, v238
	v_add_f32_e32 v242, v242, v239
	v_mov_b32_dpp v232, v110 row_ror:8 row_mask:0xf bank_mask:0xf
	v_mov_b32_dpp v233, v111 row_ror:8 row_mask:0xf bank_mask:0xf
	v_mov_b32_dpp v234, v112 row_ror:8 row_mask:0xf bank_mask:0xf
	v_mov_b32_dpp v235, v113 row_ror:8 row_mask:0xf bank_mask:0xf
	v_cndmask_b32_e64 v232, v106, v232, s[90:91]
	v_cndmask_b32_e64 v233, v107, v233, s[90:91]
	v_cndmask_b32_e64 v234, v108, v234, s[90:91]
	v_cndmask_b32_e64 v235, v109, v235, s[90:91]
	v_pk_add_f32 v[232:233], v[232:233], v[224:225]
	v_pk_add_f32 v[234:235], v[234:235], v[226:227]
	s_nop 0
	global_store_dwordx4 v244, v[232:235], s[46:47] nt
	v_cvt_pk_bf16_f32 v240, v232, v233
	v_cvt_pk_bf16_f32 v241, v234, v235
	v_pk_mul_f32 v[236:237], v[232:233], v[232:233]
	v_pk_mul_f32 v[238:239], v[234:235], v[234:235]
	global_store_dwordx2 v245, v[240:241], s[50:51] nt
	v_add_f32_e32 v191, v236, v237
	v_add_f32_e32 v191, v191, v238
	v_add_f32_e32 v191, v191, v239
	v_mov_b32_dpp v232, v98 row_ror:8 row_mask:0xf bank_mask:0xf
	v_mov_b32_dpp v233, v99 row_ror:8 row_mask:0xf bank_mask:0xf
	v_mov_b32_dpp v234, v100 row_ror:8 row_mask:0xf bank_mask:0xf
	v_mov_b32_dpp v235, v101 row_ror:8 row_mask:0xf bank_mask:0xf
	v_cndmask_b32_e64 v232, v232, v102, s[90:91]
	v_cndmask_b32_e64 v233, v233, v103, s[90:91]
	v_cndmask_b32_e64 v234, v234, v104, s[90:91]
	v_cndmask_b32_e64 v235, v235, v105, s[90:91]
	v_pk_add_f32 v[232:233], v[232:233], v[220:221]
	v_pk_add_f32 v[234:235], v[234:235], v[222:223]
	s_nop 0
	global_store_dwordx4 v244, v[232:235], s[44:45] offset:128 nt
	v_cvt_pk_bf16_f32 v240, v232, v233
	v_cvt_pk_bf16_f32 v241, v234, v235
	v_pk_mul_f32 v[236:237], v[232:233], v[232:233]
	v_pk_mul_f32 v[238:239], v[234:235], v[234:235]
	global_store_dwordx2 v245, v[240:241], s[48:49] offset:64 nt
	v_add_f32_e32 v242, v242, v236
	v_add_f32_e32 v242, v242, v237
	v_add_f32_e32 v242, v242, v238
	v_add_f32_e32 v242, v242, v239
	v_mov_b32_dpp v232, v102 row_ror:8 row_mask:0xf bank_mask:0xf
	v_mov_b32_dpp v233, v103 row_ror:8 row_mask:0xf bank_mask:0xf
	v_mov_b32_dpp v234, v104 row_ror:8 row_mask:0xf bank_mask:0xf
	v_mov_b32_dpp v235, v105 row_ror:8 row_mask:0xf bank_mask:0xf
	v_cndmask_b32_e64 v232, v98, v232, s[90:91]
	v_cndmask_b32_e64 v233, v99, v233, s[90:91]
	v_cndmask_b32_e64 v234, v100, v234, s[90:91]
	v_cndmask_b32_e64 v235, v101, v235, s[90:91]
	v_pk_add_f32 v[232:233], v[232:233], v[228:229]
	v_pk_add_f32 v[234:235], v[234:235], v[230:231]
	s_nop 0
	global_store_dwordx4 v244, v[232:235], s[46:47] offset:128 nt
	v_cvt_pk_bf16_f32 v240, v232, v233
	v_cvt_pk_bf16_f32 v241, v234, v235
	v_pk_mul_f32 v[236:237], v[232:233], v[232:233]
	v_pk_mul_f32 v[238:239], v[234:235], v[234:235]
	global_store_dwordx2 v245, v[240:241], s[50:51] offset:64 nt
	v_add_f32_e32 v191, v191, v236
	v_add_f32_e32 v191, v191, v237
	v_add_f32_e32 v191, v191, v238
	v_add_f32_e32 v191, v191, v239
	s_nop 1
	v_add_f32_dpp v242, v242, v242 row_ror:8 row_mask:0xf bank_mask:0xf
	v_add_f32_dpp v191, v191, v191 row_ror:8 row_mask:0xf bank_mask:0xf
	s_add_u32 s44, s44, 0x10000
	s_addc_u32 s45, s45, 0
	s_add_u32 s46, s46, 0x10000
	s_addc_u32 s47, s47, 0
	s_add_u32 s48, s48, 0x8000
	s_addc_u32 s49, s49, 0
	s_add_u32 s50, s50, 0x8000
	s_addc_u32 s51, s51, 0
	v_cndmask_b32_e64 v242, v191, v242, s[90:91]
	ds_bpermute_b32 v243, v189, v242
	global_load_dwordx4 v[216:219], v244, s[40:41]
	global_load_dwordx4 v[220:223], v244, s[40:41] offset:128
	global_load_dwordx4 v[224:227], v244, s[42:43]
	global_load_dwordx4 v[228:231], v244, s[42:43] offset:128
	s_add_u32 s40, s40, 0x10000
	s_addc_u32 s41, s41, 0
	s_add_u32 s42, s42, 0x10000
	s_addc_u32 s43, s43, 0
	s_waitcnt lgkmcnt(0)
	v_add_f32_e32 v242, v242, v243
	ds_bpermute_b32 v243, v190, v242
	s_waitcnt lgkmcnt(0)
	v_add_f32_e32 v242, v242, v243
	s_and_saveexec_b64 s[2:3], s[88:89]
	ds_write_b32 v188, v242 offset:64
	s_or_b64 exec, exec, s[2:3]
	s_waitcnt vmcnt(12)
; DI void gemm8_epi_resid(f32x4 (&acc)[8][4], int m0, int n0, int ntile8, bf16_t* L, const float* xin, float* out, bf16_t* xb, float* rowpart) {
;     ...
;     for (int j = 0; j < 4; ++j) {
;       const int n = n0 + wn * 64 + j * 16 + (lane >> 4) * 4;
;       const float4 xv = *(const float4*)(xin + rowoff + n);
;       const float o0 = xv.x + acc[i][j][0], o1 = xv.y + acc[i][j][1], o2 = xv.z + acc[i][j][2], o3 = xv.w + acc[i][j][3];
;       *(float4*)(out + rowoff + n) = make_float4(o0, o1, o2, o3);
;       ss += o0 * o0 + o1 * o1 + o2 * o2 + o3 * o3;
;       uint2 u;
;       u.x = pack2(o0, o1);
;       u.y = pack2(o2, o3);
;       *(uint2*)(xb + rowoff + n) = u;
;     }
;     ss += shx(ss, 16, lane);
;     ss += shx(ss, 32, lane);
;     if ((lane >> 4) == 0) red[wn * 256 + ml] = ss;
	v_mov_b32_dpp v232, v90 row_ror:8 row_mask:0xf bank_mask:0xf
	v_mov_b32_dpp v233, v91 row_ror:8 row_mask:0xf bank_mask:0xf
	v_mov_b32_dpp v234, v92 row_ror:8 row_mask:0xf bank_mask:0xf
	v_mov_b32_dpp v235, v93 row_ror:8 row_mask:0xf bank_mask:0xf
	v_cndmask_b32_e64 v232, v232, v94, s[90:91]
	v_cndmask_b32_e64 v233, v233, v95, s[90:91]
	v_cndmask_b32_e64 v234, v234, v96, s[90:91]
	v_cndmask_b32_e64 v235, v235, v97, s[90:91]
	v_pk_add_f32 v[232:233], v[232:233], v[192:193]
	v_pk_add_f32 v[234:235], v[234:235], v[194:195]
	s_nop 0
	global_store_dwordx4 v244, v[232:235], s[44:45] nt
	v_cvt_pk_bf16_f32 v240, v232, v233
	v_cvt_pk_bf16_f32 v241, v234, v235
	v_pk_mul_f32 v[236:237], v[232:233], v[232:233]
	v_pk_mul_f32 v[238:239], v[234:235], v[234:235]
	global_store_dwordx2 v245, v[240:241], s[48:49] nt
	v_add_f32_e32 v242, v236, v237
	v_add_f32_e32 v242, v242, v238
	v_add_f32_e32 v242, v242, v239
	v_mov_b32_dpp v232, v94 row_ror:8 row_mask:0xf bank_mask:0xf
	v_mov_b32_dpp v233, v95 row_ror:8 row_mask:0xf bank_mask:0xf
	v_mov_b32_dpp v234, v96 row_ror:8 row_mask:0xf bank_mask:0xf
	v_mov_b32_dpp v235, v97 row_ror:8 row_mask:0xf bank_mask:0xf
	v_cndmask_b32_e64 v232, v90, v232, s[90:91]
	v_cndmask_b32_e64 v233, v91, v233, s[90:91]
	v_cndmask_b32_e64 v234, v92, v234, s[90:91]
	v_cndmask_b32_e64 v235, v93, v235, s[90:91]
	v_pk_add_f32 v[232:233], v[232:233], v[202:203]
	v_pk_add_f32 v[234:235], v[234:235], v[204:205]
	s_nop 0
	global_store_dwordx4 v244, v[232:235], s[46:47] nt
	v_cvt_pk_bf16_f32 v240, v232, v233
	v_cvt_pk_bf16_f32 v241, v234, v235
	v_pk_mul_f32 v[236:237], v[232:233], v[232:233]
	v_pk_mul_f32 v[238:239], v[234:235], v[234:235]
	global_store_dwordx2 v245, v[240:241], s[50:51] nt
	v_add_f32_e32 v191, v236, v237
	v_add_f32_e32 v191, v191, v238
	v_add_f32_e32 v191, v191, v239
	v_mov_b32_dpp v232, v82 row_ror:8 row_mask:0xf bank_mask:0xf
	v_mov_b32_dpp v233, v83 row_ror:8 row_mask:0xf bank_mask:0xf
	v_mov_b32_dpp v234, v84 row_ror:8 row_mask:0xf bank_mask:0xf
	v_mov_b32_dpp v235, v85 row_ror:8 row_mask:0xf bank_mask:0xf
	v_cndmask_b32_e64 v232, v232, v86, s[90:91]
	v_cndmask_b32_e64 v233, v233, v87, s[90:91]
	v_cndmask_b32_e64 v234, v234, v88, s[90:91]
	v_cndmask_b32_e64 v235, v235, v89, s[90:91]
	v_pk_add_f32 v[232:233], v[232:233], v[198:199]
	v_pk_add_f32 v[234:235], v[234:235], v[200:201]
	s_nop 0
	global_store_dwordx4 v244, v[232:235], s[44:45] offset:128 nt
	v_cvt_pk_bf16_f32 v240, v232, v233
	v_cvt_pk_bf16_f32 v241, v234, v235
	v_pk_mul_f32 v[236:237], v[232:233], v[232:233]
	v_pk_mul_f32 v[238:239], v[234:235], v[234:235]
	global_store_dwordx2 v245, v[240:241], s[48:49] offset:64 nt
	v_add_f32_e32 v242, v242, v236
	v_add_f32_e32 v242, v242, v237
	v_add_f32_e32 v242, v242, v238
	v_add_f32_e32 v242, v242, v239
	v_mov_b32_dpp v232, v86 row_ror:8 row_mask:0xf bank_mask:0xf
	v_mov_b32_dpp v233, v87 row_ror:8 row_mask:0xf bank_mask:0xf
	v_mov_b32_dpp v234, v88 row_ror:8 row_mask:0xf bank_mask:0xf
	v_mov_b32_dpp v235, v89 row_ror:8 row_mask:0xf bank_mask:0xf
	v_cndmask_b32_e64 v232, v82, v232, s[90:91]
	v_cndmask_b32_e64 v233, v83, v233, s[90:91]
	v_cndmask_b32_e64 v234, v84, v234, s[90:91]
	v_cndmask_b32_e64 v235, v85, v235, s[90:91]
	v_pk_add_f32 v[232:233], v[232:233], v[206:207]
	v_pk_add_f32 v[234:235], v[234:235], v[208:209]
	s_nop 0
	global_store_dwordx4 v244, v[232:235], s[46:47] offset:128 nt
	v_cvt_pk_bf16_f32 v240, v232, v233
	v_cvt_pk_bf16_f32 v241, v234, v235
	v_pk_mul_f32 v[236:237], v[232:233], v[232:233]
	v_pk_mul_f32 v[238:239], v[234:235], v[234:235]
	global_store_dwordx2 v245, v[240:241], s[50:51] offset:64 nt
	v_add_f32_e32 v191, v191, v236
	v_add_f32_e32 v191, v191, v237
	v_add_f32_e32 v191, v191, v238
	v_add_f32_e32 v191, v191, v239
	s_nop 1
	v_add_f32_dpp v242, v242, v242 row_ror:8 row_mask:0xf bank_mask:0xf
	v_add_f32_dpp v191, v191, v191 row_ror:8 row_mask:0xf bank_mask:0xf
	s_add_u32 s44, s44, 0x10000
	s_addc_u32 s45, s45, 0
	s_add_u32 s46, s46, 0x10000
	s_addc_u32 s47, s47, 0
	s_add_u32 s48, s48, 0x8000
	s_addc_u32 s49, s49, 0
	s_add_u32 s50, s50, 0x8000
	s_addc_u32 s51, s51, 0
	v_cndmask_b32_e64 v242, v191, v242, s[90:91]
	ds_bpermute_b32 v243, v189, v242
	global_load_dwordx4 v[192:195], v244, s[40:41]
	global_load_dwordx4 v[198:201], v244, s[40:41] offset:128
	global_load_dwordx4 v[202:205], v244, s[42:43]
	global_load_dwordx4 v[206:209], v244, s[42:43] offset:128
	s_add_u32 s40, s40, 0x10000
	s_addc_u32 s41, s41, 0
	s_add_u32 s42, s42, 0x10000
	s_addc_u32 s43, s43, 0
	s_waitcnt lgkmcnt(0)
	v_add_f32_e32 v242, v242, v243
	ds_bpermute_b32 v243, v190, v242
	s_waitcnt lgkmcnt(0)
	v_add_f32_e32 v242, v242, v243
	s_and_saveexec_b64 s[2:3], s[88:89]
	ds_write_b32 v188, v242 offset:128
	s_or_b64 exec, exec, s[2:3]
	s_waitcnt vmcnt(12)
; DI void gemm8_epi_resid(f32x4 (&acc)[8][4], int m0, int n0, int ntile8, bf16_t* L, const float* xin, float* out, bf16_t* xb, float* rowpart) {
;     ...
;     for (int j = 0; j < 4; ++j) {
;       const int n = n0 + wn * 64 + j * 16 + (lane >> 4) * 4;
;       const float4 xv = *(const float4*)(xin + rowoff + n);
;       const float o0 = xv.x + acc[i][j][0], o1 = xv.y + acc[i][j][1], o2 = xv.z + acc[i][j][2], o3 = xv.w + acc[i][j][3];
;       *(float4*)(out + rowoff + n) = make_float4(o0, o1, o2, o3);
;       ss += o0 * o0 + o1 * o1 + o2 * o2 + o3 * o3;
;       uint2 u;
;       u.x = pack2(o0, o1);
;       u.y = pack2(o2, o3);
;       *(uint2*)(xb + rowoff + n) = u;
;     }
;     ss += shx(ss, 16, lane);
;     ss += shx(ss, 32, lane);
;     if ((lane >> 4) == 0) red[wn * 256 + ml] = ss;
	v_mov_b32_dpp v232, v74 row_ror:8 row_mask:0xf bank_mask:0xf
	v_mov_b32_dpp v233, v75 row_ror:8 row_mask:0xf bank_mask:0xf
	v_mov_b32_dpp v234, v76 row_ror:8 row_mask:0xf bank_mask:0xf
	v_mov_b32_dpp v235, v77 row_ror:8 row_mask:0xf bank_mask:0xf
	v_cndmask_b32_e64 v232, v232, v78, s[90:91]
	v_cndmask_b32_e64 v233, v233, v79, s[90:91]
	v_cndmask_b32_e64 v234, v234, v80, s[90:91]
	v_cndmask_b32_e64 v235, v235, v81, s[90:91]
	v_pk_add_f32 v[232:233], v[232:233], v[216:217]
	v_pk_add_f32 v[234:235], v[234:235], v[218:219]
	s_nop 0
	global_store_dwordx4 v244, v[232:235], s[44:45] nt
	v_cvt_pk_bf16_f32 v240, v232, v233
	v_cvt_pk_bf16_f32 v241, v234, v235
	v_pk_mul_f32 v[236:237], v[232:233], v[232:233]
	v_pk_mul_f32 v[238:239], v[234:235], v[234:235]
	global_store_dwordx2 v245, v[240:241], s[48:49] nt
	v_add_f32_e32 v242, v236, v237
	v_add_f32_e32 v242, v242, v238
	v_add_f32_e32 v242, v242, v239
	v_mov_b32_dpp v232, v78 row_ror:8 row_mask:0xf bank_mask:0xf
	v_mov_b32_dpp v233, v79 row_ror:8 row_mask:0xf bank_mask:0xf
	v_mov_b32_dpp v234, v80 row_ror:8 row_mask:0xf bank_mask:0xf
	v_mov_b32_dpp v235, v81 row_ror:8 row_mask:0xf bank_mask:0xf
	v_cndmask_b32_e64 v232, v74, v232, s[90:91]
	v_cndmask_b32_e64 v233, v75, v233, s[90:91]
	v_cndmask_b32_e64 v234, v76, v234, s[90:91]
	v_cndmask_b32_e64 v235, v77, v235, s[90:91]
	v_pk_add_f32 v[232:233], v[232:233], v[224:225]
	v_pk_add_f32 v[234:235], v[234:235], v[226:227]
	s_nop 0
	global_store_dwordx4 v244, v[232:235], s[46:47] nt
	v_cvt_pk_bf16_f32 v240, v232, v233
	v_cvt_pk_bf16_f32 v241, v234, v235
	v_pk_mul_f32 v[236:237], v[232:233], v[232:233]
	v_pk_mul_f32 v[238:239], v[234:235], v[234:235]
	global_store_dwordx2 v245, v[240:241], s[50:51] nt
	v_add_f32_e32 v191, v236, v237
	v_add_f32_e32 v191, v191, v238
	v_add_f32_e32 v191, v191, v239
	v_mov_b32_dpp v232, v66 row_ror:8 row_mask:0xf bank_mask:0xf
	v_mov_b32_dpp v233, v67 row_ror:8 row_mask:0xf bank_mask:0xf
	v_mov_b32_dpp v234, v68 row_ror:8 row_mask:0xf bank_mask:0xf
	v_mov_b32_dpp v235, v69 row_ror:8 row_mask:0xf bank_mask:0xf
	v_cndmask_b32_e64 v232, v232, v70, s[90:91]
	v_cndmask_b32_e64 v233, v233, v71, s[90:91]
	v_cndmask_b32_e64 v234, v234, v72, s[90:91]
	v_cndmask_b32_e64 v235, v235, v73, s[90:91]
	v_pk_add_f32 v[232:233], v[232:233], v[220:221]
	v_pk_add_f32 v[234:235], v[234:235], v[222:223]
	s_nop 0
	global_store_dwordx4 v244, v[232:235], s[44:45] offset:128 nt
	v_cvt_pk_bf16_f32 v240, v232, v233
	v_cvt_pk_bf16_f32 v241, v234, v235
	v_pk_mul_f32 v[236:237], v[232:233], v[232:233]
	v_pk_mul_f32 v[238:239], v[234:235], v[234:235]
	global_store_dwordx2 v245, v[240:241], s[48:49] offset:64 nt
	v_add_f32_e32 v242, v242, v236
	v_add_f32_e32 v242, v242, v237
	v_add_f32_e32 v242, v242, v238
	v_add_f32_e32 v242, v242, v239
	v_mov_b32_dpp v232, v70 row_ror:8 row_mask:0xf bank_mask:0xf
	v_mov_b32_dpp v233, v71 row_ror:8 row_mask:0xf bank_mask:0xf
	v_mov_b32_dpp v234, v72 row_ror:8 row_mask:0xf bank_mask:0xf
	v_mov_b32_dpp v235, v73 row_ror:8 row_mask:0xf bank_mask:0xf
	v_cndmask_b32_e64 v232, v66, v232, s[90:91]
	v_cndmask_b32_e64 v233, v67, v233, s[90:91]
	v_cndmask_b32_e64 v234, v68, v234, s[90:91]
	v_cndmask_b32_e64 v235, v69, v235, s[90:91]
	v_pk_add_f32 v[232:233], v[232:233], v[228:229]
	v_pk_add_f32 v[234:235], v[234:235], v[230:231]
	s_nop 0
	global_store_dwordx4 v244, v[232:235], s[46:47] offset:128 nt
	v_cvt_pk_bf16_f32 v240, v232, v233
	v_cvt_pk_bf16_f32 v241, v234, v235
	v_pk_mul_f32 v[236:237], v[232:233], v[232:233]
	v_pk_mul_f32 v[238:239], v[234:235], v[234:235]
	global_store_dwordx2 v245, v[240:241], s[50:51] offset:64 nt
	v_add_f32_e32 v191, v191, v236
	v_add_f32_e32 v191, v191, v237
	v_add_f32_e32 v191, v191, v238
	v_add_f32_e32 v191, v191, v239
	s_nop 1
	v_add_f32_dpp v242, v242, v242 row_ror:8 row_mask:0xf bank_mask:0xf
	v_add_f32_dpp v191, v191, v191 row_ror:8 row_mask:0xf bank_mask:0xf
	s_add_u32 s44, s44, 0x10000
	s_addc_u32 s45, s45, 0
	s_add_u32 s46, s46, 0x10000
	s_addc_u32 s47, s47, 0
	s_add_u32 s48, s48, 0x8000
	s_addc_u32 s49, s49, 0
	s_add_u32 s50, s50, 0x8000
	s_addc_u32 s51, s51, 0
	v_cndmask_b32_e64 v242, v191, v242, s[90:91]
	ds_bpermute_b32 v243, v189, v242
	global_load_dwordx4 v[216:219], v244, s[40:41]
	global_load_dwordx4 v[220:223], v244, s[40:41] offset:128
	global_load_dwordx4 v[224:227], v244, s[42:43]
	global_load_dwordx4 v[228:231], v244, s[42:43] offset:128
	s_add_u32 s40, s40, 0x10000
	s_addc_u32 s41, s41, 0
	s_add_u32 s42, s42, 0x10000
	s_addc_u32 s43, s43, 0
	s_waitcnt lgkmcnt(0)
	v_add_f32_e32 v242, v242, v243
	ds_bpermute_b32 v243, v190, v242
	s_waitcnt lgkmcnt(0)
	v_add_f32_e32 v242, v242, v243
	s_and_saveexec_b64 s[2:3], s[88:89]
	ds_write_b32 v188, v242 offset:192
	s_or_b64 exec, exec, s[2:3]
	s_waitcnt vmcnt(12)
; DI void gemm8_epi_resid(f32x4 (&acc)[8][4], int m0, int n0, int ntile8, bf16_t* L, const float* xin, float* out, bf16_t* xb, float* rowpart) {
;     ...
;     for (int j = 0; j < 4; ++j) {
;       const int n = n0 + wn * 64 + j * 16 + (lane >> 4) * 4;
;       const float4 xv = *(const float4*)(xin + rowoff + n);
;       const float o0 = xv.x + acc[i][j][0], o1 = xv.y + acc[i][j][1], o2 = xv.z + acc[i][j][2], o3 = xv.w + acc[i][j][3];
;       *(float4*)(out + rowoff + n) = make_float4(o0, o1, o2, o3);
;       ss += o0 * o0 + o1 * o1 + o2 * o2 + o3 * o3;
;       uint2 u;
;       u.x = pack2(o0, o1);
;       u.y = pack2(o2, o3);
;       *(uint2*)(xb + rowoff + n) = u;
;     }
;     ss += shx(ss, 16, lane);
;     ss += shx(ss, 32, lane);
;     if ((lane >> 4) == 0) red[wn * 256 + ml] = ss;
	v_mov_b32_dpp v232, v58 row_ror:8 row_mask:0xf bank_mask:0xf
	v_mov_b32_dpp v233, v59 row_ror:8 row_mask:0xf bank_mask:0xf
	v_mov_b32_dpp v234, v60 row_ror:8 row_mask:0xf bank_mask:0xf
	v_mov_b32_dpp v235, v61 row_ror:8 row_mask:0xf bank_mask:0xf
	v_cndmask_b32_e64 v232, v232, v62, s[90:91]
	v_cndmask_b32_e64 v233, v233, v63, s[90:91]
	v_cndmask_b32_e64 v234, v234, v64, s[90:91]
	v_cndmask_b32_e64 v235, v235, v65, s[90:91]
	v_pk_add_f32 v[232:233], v[232:233], v[192:193]
	v_pk_add_f32 v[234:235], v[234:235], v[194:195]
	s_nop 0
	global_store_dwordx4 v244, v[232:235], s[44:45] nt
	v_cvt_pk_bf16_f32 v240, v232, v233
	v_cvt_pk_bf16_f32 v241, v234, v235
	v_pk_mul_f32 v[236:237], v[232:233], v[232:233]
	v_pk_mul_f32 v[238:239], v[234:235], v[234:235]
	global_store_dwordx2 v245, v[240:241], s[48:49] nt
	v_add_f32_e32 v242, v236, v237
	v_add_f32_e32 v242, v242, v238
	v_add_f32_e32 v242, v242, v239
	v_mov_b32_dpp v232, v62 row_ror:8 row_mask:0xf bank_mask:0xf
	v_mov_b32_dpp v233, v63 row_ror:8 row_mask:0xf bank_mask:0xf
	v_mov_b32_dpp v234, v64 row_ror:8 row_mask:0xf bank_mask:0xf
	v_mov_b32_dpp v235, v65 row_ror:8 row_mask:0xf bank_mask:0xf
	v_cndmask_b32_e64 v232, v58, v232, s[90:91]
	v_cndmask_b32_e64 v233, v59, v233, s[90:91]
	v_cndmask_b32_e64 v234, v60, v234, s[90:91]
	v_cndmask_b32_e64 v235, v61, v235, s[90:91]
	v_pk_add_f32 v[232:233], v[232:233], v[202:203]
	v_pk_add_f32 v[234:235], v[234:235], v[204:205]
	s_nop 0
	global_store_dwordx4 v244, v[232:235], s[46:47] nt
	v_cvt_pk_bf16_f32 v240, v232, v233
	v_cvt_pk_bf16_f32 v241, v234, v235
	v_pk_mul_f32 v[236:237], v[232:233], v[232:233]
	v_pk_mul_f32 v[238:239], v[234:235], v[234:235]
	global_store_dwordx2 v245, v[240:241], s[50:51] nt
	v_add_f32_e32 v191, v236, v237
	v_add_f32_e32 v191, v191, v238
	v_add_f32_e32 v191, v191, v239
	v_mov_b32_dpp v232, v50 row_ror:8 row_mask:0xf bank_mask:0xf
	v_mov_b32_dpp v233, v51 row_ror:8 row_mask:0xf bank_mask:0xf
	v_mov_b32_dpp v234, v52 row_ror:8 row_mask:0xf bank_mask:0xf
	v_mov_b32_dpp v235, v53 row_ror:8 row_mask:0xf bank_mask:0xf
	v_cndmask_b32_e64 v232, v232, v54, s[90:91]
	v_cndmask_b32_e64 v233, v233, v55, s[90:91]
	v_cndmask_b32_e64 v234, v234, v56, s[90:91]
	v_cndmask_b32_e64 v235, v235, v57, s[90:91]
	v_pk_add_f32 v[232:233], v[232:233], v[198:199]
	v_pk_add_f32 v[234:235], v[234:235], v[200:201]
	s_nop 0
	global_store_dwordx4 v244, v[232:235], s[44:45] offset:128 nt
	v_cvt_pk_bf16_f32 v240, v232, v233
	v_cvt_pk_bf16_f32 v241, v234, v235
	v_pk_mul_f32 v[236:237], v[232:233], v[232:233]
	v_pk_mul_f32 v[238:239], v[234:235], v[234:235]
	global_store_dwordx2 v245, v[240:241], s[48:49] offset:64 nt
	v_add_f32_e32 v242, v242, v236
	v_add_f32_e32 v242, v242, v237
	v_add_f32_e32 v242, v242, v238
	v_add_f32_e32 v242, v242, v239
	v_mov_b32_dpp v232, v54 row_ror:8 row_mask:0xf bank_mask:0xf
	v_mov_b32_dpp v233, v55 row_ror:8 row_mask:0xf bank_mask:0xf
	v_mov_b32_dpp v234, v56 row_ror:8 row_mask:0xf bank_mask:0xf
	v_mov_b32_dpp v235, v57 row_ror:8 row_mask:0xf bank_mask:0xf
	v_cndmask_b32_e64 v232, v50, v232, s[90:91]
	v_cndmask_b32_e64 v233, v51, v233, s[90:91]
	v_cndmask_b32_e64 v234, v52, v234, s[90:91]
	v_cndmask_b32_e64 v235, v53, v235, s[90:91]
	v_pk_add_f32 v[232:233], v[232:233], v[206:207]
	v_pk_add_f32 v[234:235], v[234:235], v[208:209]
	s_nop 0
	global_store_dwordx4 v244, v[232:235], s[46:47] offset:128 nt
	v_cvt_pk_bf16_f32 v240, v232, v233
	v_cvt_pk_bf16_f32 v241, v234, v235
	v_pk_mul_f32 v[236:237], v[232:233], v[232:233]
	v_pk_mul_f32 v[238:239], v[234:235], v[234:235]
	global_store_dwordx2 v245, v[240:241], s[50:51] offset:64 nt
	v_add_f32_e32 v191, v191, v236
	v_add_f32_e32 v191, v191, v237
	v_add_f32_e32 v191, v191, v238
	v_add_f32_e32 v191, v191, v239
	s_nop 1
	v_add_f32_dpp v242, v242, v242 row_ror:8 row_mask:0xf bank_mask:0xf
	v_add_f32_dpp v191, v191, v191 row_ror:8 row_mask:0xf bank_mask:0xf
	s_add_u32 s44, s44, 0x10000
	s_addc_u32 s45, s45, 0
	s_add_u32 s46, s46, 0x10000
	s_addc_u32 s47, s47, 0
	s_add_u32 s48, s48, 0x8000
	s_addc_u32 s49, s49, 0
	s_add_u32 s50, s50, 0x8000
	s_addc_u32 s51, s51, 0
	v_cndmask_b32_e64 v242, v191, v242, s[90:91]
	ds_bpermute_b32 v243, v189, v242
	global_load_dwordx4 v[192:195], v244, s[40:41]
	global_load_dwordx4 v[198:201], v244, s[40:41] offset:128
	global_load_dwordx4 v[202:205], v244, s[42:43]
	global_load_dwordx4 v[206:209], v244, s[42:43] offset:128
	s_add_u32 s40, s40, 0x10000
	s_addc_u32 s41, s41, 0
	s_add_u32 s42, s42, 0x10000
	s_addc_u32 s43, s43, 0
	s_waitcnt lgkmcnt(0)
	v_add_f32_e32 v242, v242, v243
	ds_bpermute_b32 v243, v190, v242
	s_waitcnt lgkmcnt(0)
	v_add_f32_e32 v242, v242, v243
	s_and_saveexec_b64 s[2:3], s[88:89]
	ds_write_b32 v188, v242 offset:256
	s_or_b64 exec, exec, s[2:3]
	s_waitcnt vmcnt(12)
; DI void gemm8_epi_resid(f32x4 (&acc)[8][4], int m0, int n0, int ntile8, bf16_t* L, const float* xin, float* out, bf16_t* xb, float* rowpart) {
;     ...
;     for (int j = 0; j < 4; ++j) {
;       const int n = n0 + wn * 64 + j * 16 + (lane >> 4) * 4;
;       const float4 xv = *(const float4*)(xin + rowoff + n);
;       const float o0 = xv.x + acc[i][j][0], o1 = xv.y + acc[i][j][1], o2 = xv.z + acc[i][j][2], o3 = xv.w + acc[i][j][3];
;       *(float4*)(out + rowoff + n) = make_float4(o0, o1, o2, o3);
;       ss += o0 * o0 + o1 * o1 + o2 * o2 + o3 * o3;
;       uint2 u;
;       u.x = pack2(o0, o1);
;       u.y = pack2(o2, o3);
;       *(uint2*)(xb + rowoff + n) = u;
;     }
;     ss += shx(ss, 16, lane);
;     ss += shx(ss, 32, lane);
;     if ((lane >> 4) == 0) red[wn * 256 + ml] = ss;
	v_mov_b32_dpp v232, v42 row_ror:8 row_mask:0xf bank_mask:0xf
	v_mov_b32_dpp v233, v43 row_ror:8 row_mask:0xf bank_mask:0xf
	v_mov_b32_dpp v234, v44 row_ror:8 row_mask:0xf bank_mask:0xf
	v_mov_b32_dpp v235, v45 row_ror:8 row_mask:0xf bank_mask:0xf
	v_cndmask_b32_e64 v232, v232, v46, s[90:91]
	v_cndmask_b32_e64 v233, v233, v47, s[90:91]
	v_cndmask_b32_e64 v234, v234, v48, s[90:91]
	v_cndmask_b32_e64 v235, v235, v49, s[90:91]
	v_pk_add_f32 v[232:233], v[232:233], v[216:217]
	v_pk_add_f32 v[234:235], v[234:235], v[218:219]
	s_nop 0
	global_store_dwordx4 v244, v[232:235], s[44:45] nt
	v_cvt_pk_bf16_f32 v240, v232, v233
	v_cvt_pk_bf16_f32 v241, v234, v235
	v_pk_mul_f32 v[236:237], v[232:233], v[232:233]
	v_pk_mul_f32 v[238:239], v[234:235], v[234:235]
	global_store_dwordx2 v245, v[240:241], s[48:49] nt
	v_add_f32_e32 v242, v236, v237
	v_add_f32_e32 v242, v242, v238
	v_add_f32_e32 v242, v242, v239
	v_mov_b32_dpp v232, v46 row_ror:8 row_mask:0xf bank_mask:0xf
	v_mov_b32_dpp v233, v47 row_ror:8 row_mask:0xf bank_mask:0xf
	v_mov_b32_dpp v234, v48 row_ror:8 row_mask:0xf bank_mask:0xf
	v_mov_b32_dpp v235, v49 row_ror:8 row_mask:0xf bank_mask:0xf
	v_cndmask_b32_e64 v232, v42, v232, s[90:91]
	v_cndmask_b32_e64 v233, v43, v233, s[90:91]
	v_cndmask_b32_e64 v234, v44, v234, s[90:91]
	v_cndmask_b32_e64 v235, v45, v235, s[90:91]
	v_pk_add_f32 v[232:233], v[232:233], v[224:225]
	v_pk_add_f32 v[234:235], v[234:235], v[226:227]
	s_nop 0
	global_store_dwordx4 v244, v[232:235], s[46:47] nt
	v_cvt_pk_bf16_f32 v240, v232, v233
	v_cvt_pk_bf16_f32 v241, v234, v235
	v_pk_mul_f32 v[236:237], v[232:233], v[232:233]
	v_pk_mul_f32 v[238:239], v[234:235], v[234:235]
	global_store_dwordx2 v245, v[240:241], s[50:51] nt
	v_add_f32_e32 v191, v236, v237
	v_add_f32_e32 v191, v191, v238
	v_add_f32_e32 v191, v191, v239
	v_mov_b32_dpp v232, v34 row_ror:8 row_mask:0xf bank_mask:0xf
	v_mov_b32_dpp v233, v35 row_ror:8 row_mask:0xf bank_mask:0xf
	v_mov_b32_dpp v234, v36 row_ror:8 row_mask:0xf bank_mask:0xf
	v_mov_b32_dpp v235, v37 row_ror:8 row_mask:0xf bank_mask:0xf
	v_cndmask_b32_e64 v232, v232, v124, s[90:91]
	v_cndmask_b32_e64 v233, v233, v125, s[90:91]
	v_cndmask_b32_e64 v234, v234, v126, s[90:91]
	v_cndmask_b32_e64 v235, v235, v127, s[90:91]
	v_pk_add_f32 v[232:233], v[232:233], v[220:221]
	v_pk_add_f32 v[234:235], v[234:235], v[222:223]
	s_nop 0
	global_store_dwordx4 v244, v[232:235], s[44:45] offset:128 nt
	v_cvt_pk_bf16_f32 v240, v232, v233
	v_cvt_pk_bf16_f32 v241, v234, v235
	v_pk_mul_f32 v[236:237], v[232:233], v[232:233]
	v_pk_mul_f32 v[238:239], v[234:235], v[234:235]
	global_store_dwordx2 v245, v[240:241], s[48:49] offset:64 nt
	v_add_f32_e32 v242, v242, v236
	v_add_f32_e32 v242, v242, v237
	v_add_f32_e32 v242, v242, v238
	v_add_f32_e32 v242, v242, v239
	v_mov_b32_dpp v232, v124 row_ror:8 row_mask:0xf bank_mask:0xf
	v_mov_b32_dpp v233, v125 row_ror:8 row_mask:0xf bank_mask:0xf
	v_mov_b32_dpp v234, v126 row_ror:8 row_mask:0xf bank_mask:0xf
	v_mov_b32_dpp v235, v127 row_ror:8 row_mask:0xf bank_mask:0xf
	v_cndmask_b32_e64 v232, v34, v232, s[90:91]
	v_cndmask_b32_e64 v233, v35, v233, s[90:91]
	v_cndmask_b32_e64 v234, v36, v234, s[90:91]
	v_cndmask_b32_e64 v235, v37, v235, s[90:91]
	v_pk_add_f32 v[232:233], v[232:233], v[228:229]
	v_pk_add_f32 v[234:235], v[234:235], v[230:231]
	s_nop 0
	global_store_dwordx4 v244, v[232:235], s[46:47] offset:128 nt
	v_cvt_pk_bf16_f32 v240, v232, v233
	v_cvt_pk_bf16_f32 v241, v234, v235
	v_pk_mul_f32 v[236:237], v[232:233], v[232:233]
	v_pk_mul_f32 v[238:239], v[234:235], v[234:235]
	global_store_dwordx2 v245, v[240:241], s[50:51] offset:64 nt
	v_add_f32_e32 v191, v191, v236
	v_add_f32_e32 v191, v191, v237
	v_add_f32_e32 v191, v191, v238
	v_add_f32_e32 v191, v191, v239
	s_nop 1
	v_add_f32_dpp v242, v242, v242 row_ror:8 row_mask:0xf bank_mask:0xf
	v_add_f32_dpp v191, v191, v191 row_ror:8 row_mask:0xf bank_mask:0xf
	s_add_u32 s44, s44, 0x10000
	s_addc_u32 s45, s45, 0
	s_add_u32 s46, s46, 0x10000
	s_addc_u32 s47, s47, 0
	s_add_u32 s48, s48, 0x8000
	s_addc_u32 s49, s49, 0
	s_add_u32 s50, s50, 0x8000
	s_addc_u32 s51, s51, 0
	v_cndmask_b32_e64 v242, v191, v242, s[90:91]
	ds_bpermute_b32 v243, v189, v242
	global_load_dwordx4 v[216:219], v244, s[40:41]
	global_load_dwordx4 v[220:223], v244, s[40:41] offset:128
	global_load_dwordx4 v[224:227], v244, s[42:43]
	global_load_dwordx4 v[228:231], v244, s[42:43] offset:128
	s_add_u32 s40, s40, 0x10000
	s_addc_u32 s41, s41, 0
	s_add_u32 s42, s42, 0x10000
	s_addc_u32 s43, s43, 0
	s_waitcnt lgkmcnt(0)
	v_add_f32_e32 v242, v242, v243
	ds_bpermute_b32 v243, v190, v242
	s_waitcnt lgkmcnt(0)
	v_add_f32_e32 v242, v242, v243
	s_and_saveexec_b64 s[2:3], s[88:89]
	ds_write_b32 v188, v242 offset:320
	s_or_b64 exec, exec, s[2:3]
	s_waitcnt vmcnt(12)
; DI void gemm8_epi_resid(f32x4 (&acc)[8][4], int m0, int n0, int ntile8, bf16_t* L, const float* xin, float* out, bf16_t* xb, float* rowpart) {
;     ...
;     for (int j = 0; j < 4; ++j) {
;       const int n = n0 + wn * 64 + j * 16 + (lane >> 4) * 4;
;       const float4 xv = *(const float4*)(xin + rowoff + n);
;       const float o0 = xv.x + acc[i][j][0], o1 = xv.y + acc[i][j][1], o2 = xv.z + acc[i][j][2], o3 = xv.w + acc[i][j][3];
;       *(float4*)(out + rowoff + n) = make_float4(o0, o1, o2, o3);
;       ss += o0 * o0 + o1 * o1 + o2 * o2 + o3 * o3;
;       uint2 u;
;       u.x = pack2(o0, o1);
;       u.y = pack2(o2, o3);
;       *(uint2*)(xb + rowoff + n) = u;
;     }
;     ss += shx(ss, 16, lane);
;     ss += shx(ss, 32, lane);
;     if ((lane >> 4) == 0) red[wn * 256 + ml] = ss;
	v_mov_b32_dpp v232, v26 row_ror:8 row_mask:0xf bank_mask:0xf
	v_mov_b32_dpp v233, v27 row_ror:8 row_mask:0xf bank_mask:0xf
	v_mov_b32_dpp v234, v28 row_ror:8 row_mask:0xf bank_mask:0xf
	v_mov_b32_dpp v235, v29 row_ror:8 row_mask:0xf bank_mask:0xf
	v_cndmask_b32_e64 v232, v232, v30, s[90:91]
	v_cndmask_b32_e64 v233, v233, v31, s[90:91]
	v_cndmask_b32_e64 v234, v234, v32, s[90:91]
	v_cndmask_b32_e64 v235, v235, v33, s[90:91]
	v_pk_add_f32 v[232:233], v[232:233], v[192:193]
	v_pk_add_f32 v[234:235], v[234:235], v[194:195]
	s_nop 0
	global_store_dwordx4 v244, v[232:235], s[44:45] nt
	v_cvt_pk_bf16_f32 v240, v232, v233
	v_cvt_pk_bf16_f32 v241, v234, v235
	v_pk_mul_f32 v[236:237], v[232:233], v[232:233]
	v_pk_mul_f32 v[238:239], v[234:235], v[234:235]
	global_store_dwordx2 v245, v[240:241], s[48:49] nt
	v_add_f32_e32 v242, v236, v237
	v_add_f32_e32 v242, v242, v238
	v_add_f32_e32 v242, v242, v239
	v_mov_b32_dpp v232, v30 row_ror:8 row_mask:0xf bank_mask:0xf
	v_mov_b32_dpp v233, v31 row_ror:8 row_mask:0xf bank_mask:0xf
	v_mov_b32_dpp v234, v32 row_ror:8 row_mask:0xf bank_mask:0xf
	v_mov_b32_dpp v235, v33 row_ror:8 row_mask:0xf bank_mask:0xf
	v_cndmask_b32_e64 v232, v26, v232, s[90:91]
	v_cndmask_b32_e64 v233, v27, v233, s[90:91]
	v_cndmask_b32_e64 v234, v28, v234, s[90:91]
	v_cndmask_b32_e64 v235, v29, v235, s[90:91]
	v_pk_add_f32 v[232:233], v[232:233], v[202:203]
	v_pk_add_f32 v[234:235], v[234:235], v[204:205]
	s_nop 0
	global_store_dwordx4 v244, v[232:235], s[46:47] nt
	v_cvt_pk_bf16_f32 v240, v232, v233
	v_cvt_pk_bf16_f32 v241, v234, v235
	v_pk_mul_f32 v[236:237], v[232:233], v[232:233]
	v_pk_mul_f32 v[238:239], v[234:235], v[234:235]
	global_store_dwordx2 v245, v[240:241], s[50:51] nt
	v_add_f32_e32 v191, v236, v237
	v_add_f32_e32 v191, v191, v238
	v_add_f32_e32 v191, v191, v239
	v_mov_b32_dpp v232, v18 row_ror:8 row_mask:0xf bank_mask:0xf
	v_mov_b32_dpp v233, v19 row_ror:8 row_mask:0xf bank_mask:0xf
	v_mov_b32_dpp v234, v20 row_ror:8 row_mask:0xf bank_mask:0xf
	v_mov_b32_dpp v235, v21 row_ror:8 row_mask:0xf bank_mask:0xf
	v_cndmask_b32_e64 v232, v232, v22, s[90:91]
	v_cndmask_b32_e64 v233, v233, v23, s[90:91]
	v_cndmask_b32_e64 v234, v234, v24, s[90:91]
	v_cndmask_b32_e64 v235, v235, v25, s[90:91]
	v_pk_add_f32 v[232:233], v[232:233], v[198:199]
	v_pk_add_f32 v[234:235], v[234:235], v[200:201]
	s_nop 0
	global_store_dwordx4 v244, v[232:235], s[44:45] offset:128 nt
	v_cvt_pk_bf16_f32 v240, v232, v233
	v_cvt_pk_bf16_f32 v241, v234, v235
	v_pk_mul_f32 v[236:237], v[232:233], v[232:233]
	v_pk_mul_f32 v[238:239], v[234:235], v[234:235]
	global_store_dwordx2 v245, v[240:241], s[48:49] offset:64 nt
	v_add_f32_e32 v242, v242, v236
	v_add_f32_e32 v242, v242, v237
	v_add_f32_e32 v242, v242, v238
	v_add_f32_e32 v242, v242, v239
	v_mov_b32_dpp v232, v22 row_ror:8 row_mask:0xf bank_mask:0xf
	v_mov_b32_dpp v233, v23 row_ror:8 row_mask:0xf bank_mask:0xf
	v_mov_b32_dpp v234, v24 row_ror:8 row_mask:0xf bank_mask:0xf
	v_mov_b32_dpp v235, v25 row_ror:8 row_mask:0xf bank_mask:0xf
	v_cndmask_b32_e64 v232, v18, v232, s[90:91]
	v_cndmask_b32_e64 v233, v19, v233, s[90:91]
	v_cndmask_b32_e64 v234, v20, v234, s[90:91]
	v_cndmask_b32_e64 v235, v21, v235, s[90:91]
	v_pk_add_f32 v[232:233], v[232:233], v[206:207]
	v_pk_add_f32 v[234:235], v[234:235], v[208:209]
	s_nop 0
	global_store_dwordx4 v244, v[232:235], s[46:47] offset:128 nt
	v_cvt_pk_bf16_f32 v240, v232, v233
	v_cvt_pk_bf16_f32 v241, v234, v235
	v_pk_mul_f32 v[236:237], v[232:233], v[232:233]
	v_pk_mul_f32 v[238:239], v[234:235], v[234:235]
	global_store_dwordx2 v245, v[240:241], s[50:51] offset:64 nt
	v_add_f32_e32 v191, v191, v236
	v_add_f32_e32 v191, v191, v237
	v_add_f32_e32 v191, v191, v238
	v_add_f32_e32 v191, v191, v239
	s_nop 1
	v_add_f32_dpp v242, v242, v242 row_ror:8 row_mask:0xf bank_mask:0xf
	v_add_f32_dpp v191, v191, v191 row_ror:8 row_mask:0xf bank_mask:0xf
	s_add_u32 s44, s44, 0x10000
	s_addc_u32 s45, s45, 0
	s_add_u32 s46, s46, 0x10000
	s_addc_u32 s47, s47, 0
	s_add_u32 s48, s48, 0x8000
	s_addc_u32 s49, s49, 0
	s_add_u32 s50, s50, 0x8000
	s_addc_u32 s51, s51, 0
	v_cndmask_b32_e64 v242, v191, v242, s[90:91]
	ds_bpermute_b32 v243, v189, v242
	s_waitcnt lgkmcnt(0)
	v_add_f32_e32 v242, v242, v243
	ds_bpermute_b32 v243, v190, v242
	s_waitcnt lgkmcnt(0)
	v_add_f32_e32 v242, v242, v243
	s_and_saveexec_b64 s[2:3], s[88:89]
	ds_write_b32 v188, v242 offset:384
	s_or_b64 exec, exec, s[2:3]
	s_waitcnt vmcnt(8)
; DI void gemm8_epi_resid(f32x4 (&acc)[8][4], int m0, int n0, int ntile8, bf16_t* L, const float* xin, float* out, bf16_t* xb, float* rowpart) {
;     ...
;     for (int j = 0; j < 4; ++j) {
;       const int n = n0 + wn * 64 + j * 16 + (lane >> 4) * 4;
;       const float4 xv = *(const float4*)(xin + rowoff + n);
;       const float o0 = xv.x + acc[i][j][0], o1 = xv.y + acc[i][j][1], o2 = xv.z + acc[i][j][2], o3 = xv.w + acc[i][j][3];
;       *(float4*)(out + rowoff + n) = make_float4(o0, o1, o2, o3);
;       ss += o0 * o0 + o1 * o1 + o2 * o2 + o3 * o3;
;       uint2 u;
;       u.x = pack2(o0, o1);
;       u.y = pack2(o2, o3);
;       *(uint2*)(xb + rowoff + n) = u;
;     }
;     ss += shx(ss, 16, lane);
;     ss += shx(ss, 32, lane);
;     if ((lane >> 4) == 0) red[wn * 256 + ml] = ss;
	v_mov_b32_dpp v232, v10 row_ror:8 row_mask:0xf bank_mask:0xf
	v_mov_b32_dpp v233, v11 row_ror:8 row_mask:0xf bank_mask:0xf
	v_mov_b32_dpp v234, v12 row_ror:8 row_mask:0xf bank_mask:0xf
	v_mov_b32_dpp v235, v13 row_ror:8 row_mask:0xf bank_mask:0xf
	v_cndmask_b32_e64 v232, v232, v14, s[90:91]
	v_cndmask_b32_e64 v233, v233, v15, s[90:91]
	v_cndmask_b32_e64 v234, v234, v16, s[90:91]
	v_cndmask_b32_e64 v235, v235, v17, s[90:91]
	v_pk_add_f32 v[232:233], v[232:233], v[216:217]
	v_pk_add_f32 v[234:235], v[234:235], v[218:219]
	s_nop 0
	global_store_dwordx4 v244, v[232:235], s[44:45] nt
	v_cvt_pk_bf16_f32 v240, v232, v233
	v_cvt_pk_bf16_f32 v241, v234, v235
	v_pk_mul_f32 v[236:237], v[232:233], v[232:233]
	v_pk_mul_f32 v[238:239], v[234:235], v[234:235]
	global_store_dwordx2 v245, v[240:241], s[48:49] nt
	v_add_f32_e32 v242, v236, v237
	v_add_f32_e32 v242, v242, v238
	v_add_f32_e32 v242, v242, v239
	v_mov_b32_dpp v232, v14 row_ror:8 row_mask:0xf bank_mask:0xf
	v_mov_b32_dpp v233, v15 row_ror:8 row_mask:0xf bank_mask:0xf
	v_mov_b32_dpp v234, v16 row_ror:8 row_mask:0xf bank_mask:0xf
	v_mov_b32_dpp v235, v17 row_ror:8 row_mask:0xf bank_mask:0xf
	v_cndmask_b32_e64 v232, v10, v232, s[90:91]
	v_cndmask_b32_e64 v233, v11, v233, s[90:91]
	v_cndmask_b32_e64 v234, v12, v234, s[90:91]
	v_cndmask_b32_e64 v235, v13, v235, s[90:91]
	v_pk_add_f32 v[232:233], v[232:233], v[224:225]
	v_pk_add_f32 v[234:235], v[234:235], v[226:227]
	s_nop 0
	global_store_dwordx4 v244, v[232:235], s[46:47] nt
	v_cvt_pk_bf16_f32 v240, v232, v233
	v_cvt_pk_bf16_f32 v241, v234, v235
	v_pk_mul_f32 v[236:237], v[232:233], v[232:233]
	v_pk_mul_f32 v[238:239], v[234:235], v[234:235]
	global_store_dwordx2 v245, v[240:241], s[50:51] nt
	v_add_f32_e32 v191, v236, v237
	v_add_f32_e32 v191, v191, v238
	v_add_f32_e32 v191, v191, v239
	v_mov_b32_dpp v232, v38 row_ror:8 row_mask:0xf bank_mask:0xf
	v_mov_b32_dpp v233, v39 row_ror:8 row_mask:0xf bank_mask:0xf
	v_mov_b32_dpp v234, v40 row_ror:8 row_mask:0xf bank_mask:0xf
	v_mov_b32_dpp v235, v41 row_ror:8 row_mask:0xf bank_mask:0xf
	v_cndmask_b32_e64 v232, v232, v6, s[90:91]
	v_cndmask_b32_e64 v233, v233, v7, s[90:91]
	v_cndmask_b32_e64 v234, v234, v8, s[90:91]
	v_cndmask_b32_e64 v235, v235, v9, s[90:91]
	v_pk_add_f32 v[232:233], v[232:233], v[220:221]
	v_pk_add_f32 v[234:235], v[234:235], v[222:223]
	s_nop 0
	global_store_dwordx4 v244, v[232:235], s[44:45] offset:128 nt
	v_cvt_pk_bf16_f32 v240, v232, v233
	v_cvt_pk_bf16_f32 v241, v234, v235
	v_pk_mul_f32 v[236:237], v[232:233], v[232:233]
	v_pk_mul_f32 v[238:239], v[234:235], v[234:235]
	global_store_dwordx2 v245, v[240:241], s[48:49] offset:64 nt
	v_add_f32_e32 v242, v242, v236
	v_add_f32_e32 v242, v242, v237
	v_add_f32_e32 v242, v242, v238
	v_add_f32_e32 v242, v242, v239
	v_mov_b32_dpp v232, v6 row_ror:8 row_mask:0xf bank_mask:0xf
	v_mov_b32_dpp v233, v7 row_ror:8 row_mask:0xf bank_mask:0xf
	v_mov_b32_dpp v234, v8 row_ror:8 row_mask:0xf bank_mask:0xf
	v_mov_b32_dpp v235, v9 row_ror:8 row_mask:0xf bank_mask:0xf
	v_cndmask_b32_e64 v232, v38, v232, s[90:91]
	v_cndmask_b32_e64 v233, v39, v233, s[90:91]
	v_cndmask_b32_e64 v234, v40, v234, s[90:91]
	v_cndmask_b32_e64 v235, v41, v235, s[90:91]
	v_pk_add_f32 v[232:233], v[232:233], v[228:229]
	v_pk_add_f32 v[234:235], v[234:235], v[230:231]
	s_nop 0
	global_store_dwordx4 v244, v[232:235], s[46:47] offset:128 nt
	v_cvt_pk_bf16_f32 v240, v232, v233
	v_cvt_pk_bf16_f32 v241, v234, v235
	v_pk_mul_f32 v[236:237], v[232:233], v[232:233]
	v_pk_mul_f32 v[238:239], v[234:235], v[234:235]
	global_store_dwordx2 v245, v[240:241], s[50:51] offset:64 nt
	v_add_f32_e32 v191, v191, v236
	v_add_f32_e32 v191, v191, v237
	v_add_f32_e32 v191, v191, v238
	v_add_f32_e32 v191, v191, v239
	s_nop 1
	v_add_f32_dpp v242, v242, v242 row_ror:8 row_mask:0xf bank_mask:0xf
	v_add_f32_dpp v191, v191, v191 row_ror:8 row_mask:0xf bank_mask:0xf
	s_add_u32 s44, s44, 0x10000
	s_addc_u32 s45, s45, 0
	s_add_u32 s46, s46, 0x10000
	s_addc_u32 s47, s47, 0
	s_add_u32 s48, s48, 0x8000
	s_addc_u32 s49, s49, 0
	s_add_u32 s50, s50, 0x8000
	s_addc_u32 s51, s51, 0
	v_cndmask_b32_e64 v242, v191, v242, s[90:91]
	ds_bpermute_b32 v243, v189, v242
	s_waitcnt lgkmcnt(0)
	v_add_f32_e32 v242, v242, v243
	ds_bpermute_b32 v243, v190, v242
	s_waitcnt lgkmcnt(0)
	v_add_f32_e32 v242, v242, v243
	s_and_saveexec_b64 s[2:3], s[88:89]
	ds_write_b32 v188, v242 offset:448
	s_or_b64 exec, exec, s[2:3]
	s_branch .LBB0_936

; template <class F>
; DI void gemm8_epi_staged(f32x4 (&acc)[8][4], int m0, int n0, bf16_t* L0, F f, bf16_t* dst, size_t ld, int nmax) {
;     ...
; #pragma unroll
;   for (int half = 0; half < 2; ++half) {
;     if (wm == half) {
; #pragma unroll
;       for (int i = 0; i < 8; ++i)
; #pragma unroll
;         for (int j = 0; j < 4; ++j) {
;           const int ml = i * 16 + (lane & 15);
;           const int nl = wn * 64 + j * 16 + (lane >> 4) * 4;
;           f32x4 a = acc[i][j];
;           f(m0 + half * 128 + ml, n0 + nl, a);
;           uint2 u;
;           u.x = pack2(a[0], a[1]);
;           u.y = pack2(a[2], a[3]);
;           *(uint2*)(L + ml * 264 + nl) = u;
;         }
;     }
;     __syncthreads();
; #pragma unroll
;     for (int it = 0; it < 8; ++it) {
;       const int idx = tid + 512 * it;
;       const int row = idx >> 5, ch = idx & 31;
;       const u32x4 v = *(const u32x4*)(L + row * 264 + ch * 8);
;       const int n = n0 + ch * 8;
;       if (n < nmax) *(u32x4*)(dst + (size_t)(m0 + half * 128 + row) * ld + n) = v;
;     }
;     __syncthreads();
.LBB0_1004:
	s_or_b64 exec, exec, s[4:5]
	v_lshlrev_b32_e32 v0, 3, v76
	v_and_b32_e32 v0, 0xf8, v0
	v_or_b32_e32 v66, s12, v0
	v_readlane_b32 s4, v252, 47
	v_lshl_add_u32 v96, v0, 1, s7
	v_lshlrev_b32_e32 v0, 1, v66
	v_readlane_b32 s5, v252, 48
	s_waitcnt lgkmcnt(0)
	s_barrier
	v_lshl_add_u64 v[66:67], s[4:5], 0, v[0:1]
	v_ashrrev_i32_e32 v0, 5, v76
	s_movk_i32 s4, 0x210
	v_mul_lo_u32 v77, v0, s4
	v_add_u32_e32 v77, v96, v77
	ds_read_b128 v[78:81], v77
	v_add_u32_e32 v82, s13, v0
	v_ashrrev_i32_e32 v83, 31, v82
	v_lshlrev_b64 v[82:83], 11, v[82:83]
	v_lshl_add_u64 v[82:83], v[66:67], 0, v[82:83]
	s_waitcnt lgkmcnt(0)
	global_store_dwordx4 v[82:83], v[78:81], off nt
	s_nop 1
	v_add_u32_e32 v78, 0x200, v76
	v_ashrrev_i32_e32 v78, 5, v78
	v_mul_lo_u32 v79, v78, s4
	v_add_u32_e32 v79, v96, v79
	ds_read_b128 v[80:83], v79
	v_add_u32_e32 v84, s13, v78
	v_ashrrev_i32_e32 v85, 31, v84
	v_lshlrev_b64 v[84:85], 11, v[84:85]
	v_lshl_add_u64 v[84:85], v[66:67], 0, v[84:85]
	s_waitcnt lgkmcnt(0)
	global_store_dwordx4 v[84:85], v[80:83], off nt
	s_nop 1
	v_add_u32_e32 v80, 0x400, v76
	v_ashrrev_i32_e32 v80, 5, v80
	v_mul_lo_u32 v81, v80, s4
	v_add_u32_e32 v81, v96, v81
	ds_read_b128 v[82:85], v81
	v_add_u32_e32 v86, s13, v80
	v_ashrrev_i32_e32 v87, 31, v86
	v_lshlrev_b64 v[86:87], 11, v[86:87]
	v_lshl_add_u64 v[86:87], v[66:67], 0, v[86:87]
	s_waitcnt lgkmcnt(0)
	global_store_dwordx4 v[86:87], v[82:85], off nt
	s_nop 1
	v_add_u32_e32 v82, 0x600, v76
	v_ashrrev_i32_e32 v82, 5, v82
	v_mul_lo_u32 v83, v82, s4
	v_add_u32_e32 v83, v96, v83
	ds_read_b128 v[84:87], v83
	v_add_u32_e32 v88, s13, v82
	v_ashrrev_i32_e32 v89, 31, v88
	v_lshlrev_b64 v[88:89], 11, v[88:89]
	v_lshl_add_u64 v[88:89], v[66:67], 0, v[88:89]
	s_waitcnt lgkmcnt(0)
	global_store_dwordx4 v[88:89], v[84:87], off nt
	s_nop 1
	v_add_u32_e32 v84, 0x800, v76
	v_ashrrev_i32_e32 v84, 5, v84
	v_mul_lo_u32 v85, v84, s4
	v_add_u32_e32 v85, v96, v85
	ds_read_b128 v[86:89], v85
	v_add_u32_e32 v90, s13, v84
	v_ashrrev_i32_e32 v91, 31, v90
	v_lshlrev_b64 v[90:91], 11, v[90:91]
	v_lshl_add_u64 v[90:91], v[66:67], 0, v[90:91]
	s_waitcnt lgkmcnt(0)
	global_store_dwordx4 v[90:91], v[86:89], off nt
	s_nop 1
	v_add_u32_e32 v86, 0xa00, v76
	v_ashrrev_i32_e32 v86, 5, v86
	v_mul_lo_u32 v87, v86, s4
	v_add_u32_e32 v87, v96, v87
	ds_read_b128 v[88:91], v87
	v_add_u32_e32 v92, s13, v86
	v_ashrrev_i32_e32 v93, 31, v92
	v_lshlrev_b64 v[92:93], 11, v[92:93]
	v_lshl_add_u64 v[92:93], v[66:67], 0, v[92:93]
	s_waitcnt lgkmcnt(0)
	global_store_dwordx4 v[92:93], v[88:91], off nt
	s_nop 1
	v_add_u32_e32 v88, 0xc00, v76
	v_ashrrev_i32_e32 v88, 5, v88
	v_mul_lo_u32 v89, v88, s4
	v_add_u32_e32 v89, v96, v89
	ds_read_b128 v[90:93], v89
	v_add_u32_e32 v94, s13, v88
	v_ashrrev_i32_e32 v95, 31, v94
	v_lshlrev_b64 v[94:95], 11, v[94:95]
	v_lshl_add_u64 v[94:95], v[66:67], 0, v[94:95]
	s_waitcnt lgkmcnt(0)
	global_store_dwordx4 v[94:95], v[90:93], off nt
	s_nop 1
	v_add_u32_e32 v90, 0xe00, v76
	v_ashrrev_i32_e32 v90, 5, v90
	v_mul_lo_u32 v91, v90, s4
	v_add_u32_e32 v91, v96, v91
	ds_read_b128 v[92:95], v91
	v_add_u32_e32 v96, s13, v90
	v_ashrrev_i32_e32 v97, 31, v96
	v_lshlrev_b64 v[96:97], 11, v[96:97]
	v_and_b32_e32 v76, 0xffffff00, v76
	s_movk_i32 s4, 0x100
	v_lshl_add_u64 v[96:97], v[66:67], 0, v[96:97]
	v_cmp_eq_u32_e32 vcc, s4, v76
	s_waitcnt lgkmcnt(0)
	global_store_dwordx4 v[96:97], v[92:95], off nt
	s_barrier
	s_and_saveexec_b64 s[4:5], vcc
	s_cbranch_execz .LBB0_1006
	ds_write2_b64 v71, v[60:61], v[64:65] offset1:4
	ds_write2_b64 v71, v[54:55], v[62:63] offset0:8 offset1:12
	ds_write2_b64 v75, v[48:49], v[58:59] offset0:32 offset1:36
	ds_write2_b64 v75, v[46:47], v[56:57] offset0:40 offset1:44
	ds_write2_b64 v74, v[40:41], v[52:53] offset0:64 offset1:68
	ds_write2_b64 v74, v[38:39], v[50:51] offset0:72 offset1:76
	ds_write2_b64 v73, v[32:33], v[44:45] offset0:96 offset1:100
	ds_write2_b64 v73, v[30:31], v[42:43] offset0:104 offset1:108
	ds_write2_b64 v72, v[24:25], v[36:37] offset0:128 offset1:132
	ds_write2_b64 v72, v[22:23], v[34:35] offset0:136 offset1:140
	ds_write2_b64 v70, v[16:17], v[28:29] offset0:160 offset1:164
	ds_write2_b64 v70, v[14:15], v[26:27] offset0:168 offset1:172
	ds_write2_b64 v69, v[8:9], v[20:21] offset0:192 offset1:196
	ds_write2_b64 v69, v[6:7], v[18:19] offset0:200 offset1:204
	ds_write2_b64 v68, v[4:5], v[12:13] offset0:224 offset1:228
	ds_write2_b64 v68, v[2:3], v[10:11] offset0:232 offset1:236
; template <class F>
; DI void gemm8_epi_staged(f32x4 (&acc)[8][4], int m0, int n0, bf16_t* L0, F f, bf16_t* dst, size_t ld, int nmax) {
;     ...
; #pragma unroll
;     for (int it = 0; it < 8; ++it) {
;       const int idx = tid + 512 * it;
;       const int row = idx >> 5, ch = idx & 31;
;       const u32x4 v = *(const u32x4*)(L + row * 264 + ch * 8);
;       const int n = n0 + ch * 8;
;       if (n < nmax) *(u32x4*)(dst + (size_t)(m0 + half * 128 + row) * ld + n) = v;
;     }
;     __syncthreads();
.LBB0_1006:
	s_or_b64 exec, exec, s[4:5]
	s_and_b32 s5, s10, 0x60
	v_readlane_b32 s6, v252, 25
	s_or_b32 s5, s6, s5
	s_and_b32 s6, s9, 3
	s_add_i32 s5, s5, s6
	s_waitcnt lgkmcnt(0)
	s_barrier
	s_or_b32 s6, s13, 0x80
	ds_read_b128 v[2:5], v77
	v_add_u32_e32 v6, s6, v0
	v_ashrrev_i32_e32 v7, 31, v6
	v_lshlrev_b64 v[6:7], 11, v[6:7]
	v_lshl_add_u64 v[10:11], v[66:67], 0, v[6:7]
	ds_read_b128 v[6:9], v79
	s_waitcnt lgkmcnt(1)
	global_store_dwordx4 v[10:11], v[2:5], off nt
	v_mov_b32_e32 v26, v196
	s_lshl_b32 s4, s11, 11
	v_add_u32_e32 v2, s6, v78
	v_ashrrev_i32_e32 v3, 31, v2
	v_lshlrev_b64 v[2:3], 11, v[2:3]
	v_lshl_add_u64 v[2:3], v[66:67], 0, v[2:3]
	s_waitcnt lgkmcnt(0)
	global_store_dwordx4 v[2:3], v[6:9], off nt
	ds_read_b128 v[2:5], v81
	s_and_b32 s4, s4, 0x180000
	v_add_u32_e32 v6, s6, v80
	v_ashrrev_i32_e32 v7, 31, v6
	v_lshlrev_b64 v[6:7], 11, v[6:7]
	v_lshl_add_u64 v[10:11], v[66:67], 0, v[6:7]
	ds_read_b128 v[6:9], v83
	s_waitcnt lgkmcnt(1)
	global_store_dwordx4 v[10:11], v[2:5], off nt
	s_lshl_b32 s5, s5, 19
	s_nop 0
	v_add_u32_e32 v2, s6, v82
	v_ashrrev_i32_e32 v3, 31, v2
	v_lshlrev_b64 v[2:3], 11, v[2:3]
	v_lshl_add_u64 v[2:3], v[66:67], 0, v[2:3]
	s_waitcnt lgkmcnt(0)
	global_store_dwordx4 v[2:3], v[6:9], off nt
	ds_read_b128 v[2:5], v85
	s_nop 0
	v_add_u32_e32 v6, s6, v84
	v_ashrrev_i32_e32 v7, 31, v6
	v_lshlrev_b64 v[6:7], 11, v[6:7]
	v_lshl_add_u64 v[10:11], v[66:67], 0, v[6:7]
	ds_read_b128 v[6:9], v87
	s_waitcnt lgkmcnt(1)
	global_store_dwordx4 v[10:11], v[2:5], off nt
	s_nop 1
	v_add_u32_e32 v2, s6, v86
	v_ashrrev_i32_e32 v3, 31, v2
	v_lshlrev_b64 v[2:3], 11, v[2:3]
	v_lshl_add_u64 v[2:3], v[66:67], 0, v[2:3]
	s_waitcnt lgkmcnt(0)
	global_store_dwordx4 v[2:3], v[6:9], off nt
	ds_read_b128 v[2:5], v89
	s_nop 0
	v_add_u32_e32 v6, s6, v88
	v_ashrrev_i32_e32 v7, 31, v6
	v_lshlrev_b64 v[6:7], 11, v[6:7]
	v_lshl_add_u64 v[10:11], v[66:67], 0, v[6:7]
	ds_read_b128 v[6:9], v91
	s_waitcnt lgkmcnt(1)
	global_store_dwordx4 v[10:11], v[2:5], off nt
	s_nop 1
	v_add_u32_e32 v2, s6, v90
	v_ashrrev_i32_e32 v3, 31, v2
	v_lshlrev_b64 v[2:3], 11, v[2:3]
	v_lshl_add_u64 v[2:3], v[66:67], 0, v[2:3]
	s_waitcnt lgkmcnt(0)
	global_store_dwordx4 v[2:3], v[6:9], off nt
	s_barrier
; DI int TID8() { int t = threadIdx.x; asm volatile("" : "+v"(t)); return t; }
; DI void gemm8_accum(f32x4 (&acc)[8][4], const bf16_t* a, size_t lda, const bf16_t* b, size_t ldb, int nkb, bf16_t* L,
;                     const bool pre, const bf16_t* an, size_t ldan, const bf16_t* bn, size_t ldbn) {
;   const int tid = TID8(), lane = tid & 63, w = tid >> 6;
;   const int wm = w >> 2, wn = w & 3;
;   const int lrow = tid >> 3, lch = tid & 7;
;   u32x4 ra[4], rb[4];
;   unsigned offa[4], offb[4];
; #pragma unroll
;   for (int i = 0; i < 4; ++i) {
;     offa[i] = (unsigned)(lrow + 64 * i) * (unsigned)lda + (unsigned)(lch * 8);
;     offb[i] = (unsigned)(lrow + 64 * i) * (unsigned)ldb + (unsigned)(lch * 8);
;   }
;   if (!pre) {
;     g8_load1o(ra, a, offa);
;     g8_load1o(rb, b, offb);
;     __syncthreads();
;     g8_store(L, ra, rb, lrow, lch);
;   }
;   g8_load1o(ra, a + 64, offa);
;   g8_load1o(rb, b + 64, offb);
; __global__ void __launch_bounds__(512, 2) mega(Params p) {
;     ...
;       gemm8_accum(acc8, p16 + (size_t)m0 * 256, 256, wl + W_PLE + (size_t)n0 * 256, 256, 4, lds_all, !first_,
;                   hbuf + (size_t)m0 * DM, DM, wl + W_PG + (size_t)n0 * 1024, 1024);
;       bf16_t* ppb = z + (size_t)T_TOK * 256;
;       gemm8_epi_staged(acc8, m0, n0, lds_all, [&](int, int, f32x4&) {}, ppb, DM, 1024);
;       zero_acc8(acc8);
;       gemm8_accum(acc8, hbuf + (size_t)m0 * DM, DM, wl + W_PG + (size_t)n0 * 1024, 1024, 16, lds_all, true,
	v_mov_b32_e32 v3, v1
	v_ashrrev_i32_e32 v189, 3, v26
	v_lshlrev_b32_e32 v0, 3, v26
	v_and_b32_e32 v184, 56, v0
	v_add_u32_e32 v188, 64, v189
	v_lshrrev_b32_e32 v8, 1, v189
	v_lshl_or_b32 v0, v189, 10, v184
	v_lshl_or_b32 v2, v188, 10, v184
	v_add_u32_e32 v187, 0x80, v189
	v_add_u32_e32 v185, 0xc0, v189
	v_xor_b32_e32 v8, v8, v26
	v_lshl_or_b32 v4, v187, 10, v184
	v_lshl_or_b32 v6, v185, 10, v184
	v_mov_b32_e32 v5, v1
	v_mov_b32_e32 v7, v1
	v_lshlrev_b32_e32 v8, 3, v8
	v_lshlrev_b64 v[18:19], 1, v[0:1]
	v_lshlrev_b64 v[20:21], 1, v[2:3]
	v_and_b32_e32 v27, 56, v8
	v_lshl_add_u64 v[8:9], s[2:3], 0, v[18:19]
	v_lshl_add_u64 v[2:3], s[2:3], 0, v[20:21]
	v_lshlrev_b64 v[22:23], 1, v[4:5]
	v_lshlrev_b64 v[24:25], 1, v[6:7]
	global_load_dwordx4 v[34:37], v[8:9], off offset:128
	global_load_dwordx4 v[42:45], v[2:3], off offset:128
	v_lshl_add_u64 v[2:3], s[2:3], 0, v[22:23]
	v_lshl_add_u64 v[4:5], s[2:3], 0, v[24:25]
	global_load_dwordx4 v[54:57], v[2:3], off offset:128
	global_load_dwordx4 v[94:97], v[4:5], off offset:128
	v_lshl_add_u64 v[2:3], s[0:1], 0, v[18:19]
	v_lshl_add_u64 v[4:5], s[0:1], 0, v[20:21]
	v_lshl_add_u64 v[6:7], s[0:1], 0, v[22:23]
	v_lshl_add_u64 v[10:11], s[0:1], 0, v[24:25]
	global_load_dwordx4 v[14:17], v[2:3], off offset:128
	s_nop 0
	global_load_dwordx4 v[2:5], v[4:5], off offset:128
	s_nop 0
	global_load_dwordx4 v[6:9], v[6:7], off offset:128
	s_nop 0
	global_load_dwordx4 v[10:13], v[10:11], off offset:128
	v_bfe_u32 v0, v26, 4, 2
	v_lshrrev_b32_e32 v28, 1, v26
	v_bitop3_b32 v28, v28, v0, 7 bitop3:0x6c
	v_lshlrev_b32_e32 v186, 3, v28
	v_lshlrev_b32_e32 v28, 5, v26
	v_bfe_u32 v29, v26, 1, 3
	v_and_b32_e32 v28, 0xffffe000, v28
	v_lshlrev_b32_e32 v26, 6, v26
	s_movk_i32 s0, 0x3c0
	v_and_or_b32 v28, v26, s0, v28
	v_readlane_b32 s0, v254, 34
	s_add_u32 s0, s0, s4
	v_readlane_b32 s1, v254, 35
	s_addc_u32 s1, s1, 0
	v_bitop3_b32 v0, v0, v29, 4 bitop3:0x36
	v_lshl_add_u64 v[164:165], s[0:1], 0, v[24:25]
	v_lshl_add_u64 v[166:167], s[0:1], 0, v[22:23]
	v_lshl_add_u64 v[168:169], s[0:1], 0, v[20:21]
	v_lshl_add_u64 v[170:171], s[0:1], 0, v[18:19]
	v_readlane_b32 s0, v253, 57
	s_add_u32 s0, s0, s5
	v_readlane_b32 s1, v253, 58
	s_addc_u32 s1, s1, 0
	v_and_b32_e32 v26, 0x33c0, v26
	v_lshlrev_b32_e32 v182, 3, v0
	v_lshlrev_b32_e32 v183, 1, v27
	v_lshlrev_b32_e32 v0, 7, v189
	v_lshl_add_u64 v[178:179], s[0:1], 0, v[18:19]
	v_mov_b32_e32 v18, 0
	v_lshlrev_b32_e32 v190, 6, v189
	v_add3_u32 v163, 0, v183, v0
	v_lshl_add_u64 v[172:173], s[0:1], 0, v[24:25]
	v_lshl_add_u64 v[174:175], s[0:1], 0, v[22:23]
	v_lshl_add_u64 v[176:177], s[0:1], 0, v[20:21]
	s_mov_b64 s[0:1], 0
	s_mov_b32 s2, 0
	v_lshlrev_b32_e32 v181, 1, v28
	v_lshlrev_b32_e32 v180, 1, v26
	v_mov_b32_e32 v19, v18
	v_mov_b32_e32 v20, v18
	v_mov_b32_e32 v21, v18
	v_mov_b32_e32 v22, v18
	v_mov_b32_e32 v23, v18
	v_mov_b32_e32 v24, v18
	v_mov_b32_e32 v25, v18
	v_mov_b32_e32 v26, v18
	v_mov_b32_e32 v27, v18
	v_mov_b32_e32 v28, v18
	v_mov_b32_e32 v29, v18
	v_mov_b32_e32 v30, v18
	v_mov_b32_e32 v31, v18
	v_mov_b32_e32 v32, v18
	v_mov_b32_e32 v33, v18
	v_mov_b32_e32 v38, v18
	v_mov_b32_e32 v39, v18
	v_mov_b32_e32 v40, v18
	v_mov_b32_e32 v41, v18
	v_mov_b32_e32 v46, v18
	v_mov_b32_e32 v47, v18
	v_mov_b32_e32 v48, v18
	v_mov_b32_e32 v49, v18
	v_mov_b32_e32 v50, v18
	v_mov_b32_e32 v51, v18
	v_mov_b32_e32 v52, v18
	v_mov_b32_e32 v53, v18
	v_mov_b32_e32 v58, v18
	v_mov_b32_e32 v59, v18
	v_mov_b32_e32 v60, v18
	v_mov_b32_e32 v61, v18
	v_mov_b32_e32 v62, v18
	v_mov_b32_e32 v63, v18
	v_mov_b32_e32 v64, v18
	v_mov_b32_e32 v65, v18
	v_mov_b32_e32 v66, v18
	v_mov_b32_e32 v67, v18
	v_mov_b32_e32 v68, v18
	v_mov_b32_e32 v69, v18
	v_mov_b32_e32 v70, v18
	v_mov_b32_e32 v71, v18
	v_mov_b32_e32 v72, v18
	v_mov_b32_e32 v73, v18
	v_mov_b32_e32 v74, v18
	v_mov_b32_e32 v75, v18
	v_mov_b32_e32 v76, v18
	v_mov_b32_e32 v77, v18
	v_mov_b32_e32 v78, v18
	v_mov_b32_e32 v79, v18
	v_mov_b32_e32 v80, v18
	v_mov_b32_e32 v81, v18
	v_mov_b32_e32 v82, v18
	v_mov_b32_e32 v83, v18
	v_mov_b32_e32 v84, v18
	v_mov_b32_e32 v85, v18
	v_mov_b32_e32 v86, v18
	v_mov_b32_e32 v87, v18
	v_mov_b32_e32 v88, v18
	v_mov_b32_e32 v89, v18
	v_mov_b32_e32 v90, v18
	v_mov_b32_e32 v91, v18
	v_mov_b32_e32 v92, v18
	v_mov_b32_e32 v93, v18
	v_mov_b32_e32 v98, v18
	v_mov_b32_e32 v99, v18
	v_mov_b32_e32 v100, v18
	v_mov_b32_e32 v101, v18
	v_mov_b32_e32 v102, v18
	v_mov_b32_e32 v103, v18
	v_mov_b32_e32 v104, v18
	v_mov_b32_e32 v105, v18
	v_mov_b32_e32 v106, v18
	v_mov_b32_e32 v107, v18
	v_mov_b32_e32 v108, v18
	v_mov_b32_e32 v109, v18
	v_mov_b32_e32 v110, v18
	v_mov_b32_e32 v111, v18
	v_mov_b32_e32 v112, v18
	v_mov_b32_e32 v113, v18
	v_mov_b32_e32 v114, v18
	v_mov_b32_e32 v115, v18
	v_mov_b32_e32 v116, v18
	v_mov_b32_e32 v117, v18
	v_mov_b32_e32 v118, v18
	v_mov_b32_e32 v119, v18
	v_mov_b32_e32 v120, v18
	v_mov_b32_e32 v121, v18
	v_mov_b32_e32 v122, v18
	v_mov_b32_e32 v123, v18
	v_mov_b32_e32 v124, v18
	v_mov_b32_e32 v125, v18
	v_mov_b32_e32 v126, v18
	v_mov_b32_e32 v127, v18
	v_mov_b32_e32 v128, v18
	v_mov_b32_e32 v129, v18
	v_mov_b32_e32 v130, v18
	v_mov_b32_e32 v131, v18
	v_mov_b32_e32 v132, v18
	v_mov_b32_e32 v133, v18
	v_mov_b32_e32 v134, v18
	v_mov_b32_e32 v135, v18
	v_mov_b32_e32 v136, v18
	v_mov_b32_e32 v137, v18
	v_mov_b32_e32 v138, v18
	v_mov_b32_e32 v139, v18
	v_mov_b32_e32 v140, v18
	v_mov_b32_e32 v141, v18
	v_mov_b32_e32 v142, v18
	v_mov_b32_e32 v143, v18
	v_mov_b32_e32 v144, v18
	v_mov_b32_e32 v145, v18
	v_mov_b32_e32 v146, v18
	v_mov_b32_e32 v147, v18
	v_mov_b32_e32 v148, v18
	v_mov_b32_e32 v149, v18
	v_mov_b32_e32 v150, v18
	v_mov_b32_e32 v151, v18
	v_mov_b32_e32 v152, v18
	v_mov_b32_e32 v153, v18
	v_mov_b32_e32 v154, v18
	v_mov_b32_e32 v155, v18
	v_mov_b32_e32 v156, v18
	v_mov_b32_e32 v157, v18
	v_mov_b32_e32 v158, v18
	v_mov_b32_e32 v159, v18
	v_mov_b32_e32 v160, v18
	v_mov_b32_e32 v161, v18

; DI void gemm8_accum(f32x4 (&acc)[8][4], const bf16_t* a, size_t lda, const bf16_t* b, size_t ldb, int nkb, bf16_t* L,
;                     const bool pre, const bf16_t* an, size_t ldan, const bf16_t* bn, size_t ldbn) {
;     ...
;   __syncthreads();
;   g8_store1(L + 32768, ra, lrow, lch);
;   g8_load1(ra, an, ldan, 0, lrow, lch);
;   __builtin_amdgcn_sched_barrier(0);
;   g8_compute<0, 1>(acc, L, wm, wn, lane);
;   __builtin_amdgcn_sched_barrier(0);
;   g8_store1(L + 32768 + 16384, rb, lrow, lch);
;   g8_load1(rb, bn, ldbn, 0, lrow, lch);
;   __builtin_amdgcn_sched_barrier(0);
;   g8_compute<1, 2>(acc, L, wm, wn, lane);
.Lstg_1007_c:
	v_readlane_b32 s21, v254, 18
	s_add_i32 s6, s20, s21
	s_cmp_lt_u32 s6, 64
	s_cselect_b64 s[4:5], -1, 0
	s_and_b64 s[0:1], s[4:5], exec
	s_cselect_b32 s2, s6, s20
	s_lshl_b32 s0, s2, 1
	v_lshlrev_b32_e32 v226, 1, v190
	s_and_b32 s0, s0, 0x7fffffe0
	s_and_b32 s1, s2, 3
	v_add3_u32 v0, s7, v183, v226
	s_or_b32 s0, s1, s0
	v_readlane_b32 s26, v252, 25
	s_barrier
	s_waitcnt vmcnt(7)
	ds_write_b128 v0, v[34:37]
	s_waitcnt vmcnt(6)
	ds_write_b128 v0, v[42:45] offset:8192
	s_waitcnt vmcnt(5)
	ds_write_b128 v0, v[54:57] offset:16384
	s_waitcnt vmcnt(4)
	ds_write_b128 v0, v[94:97] offset:24576
	v_lshl_or_b32 v0, v189, 8, v184
	s_or_b32 s28, s0, s26
	s_lshl_b32 s2, s2, 15
	v_lshlrev_b64 v[218:219], 1, v[0:1]
	v_lshl_or_b32 v0, v188, 8, v184
	s_lshl_b64 s[0:1], s[28:29], 17
	s_and_b32 s20, s2, 0x60000
	v_lshlrev_b64 v[220:221], 1, v[0:1]
	v_lshl_or_b32 v0, v187, 8, v184
	s_add_u32 s2, s38, s0
	v_lshlrev_b64 v[222:223], 1, v[0:1]
	v_lshl_or_b32 v0, v185, 8, v184
	s_addc_u32 s3, s39, s1
	v_lshlrev_b64 v[224:225], 1, v[0:1]
	v_lshl_add_u64 v[34:35], s[2:3], 0, v[218:219]
	v_lshl_add_u64 v[42:43], s[2:3], 0, v[220:221]
	v_lshl_add_u64 v[54:55], s[2:3], 0, v[222:223]
	v_lshl_add_u64 v[94:95], s[2:3], 0, v[224:225]
	global_load_dwordx4 v[34:37], v[34:35], off
	v_readlane_b32 s24, v254, 47
	global_load_dwordx4 v[42:45], v[42:43], off
	v_readlane_b32 s25, v254, 48
	global_load_dwordx4 v[54:57], v[54:55], off
	s_add_u32 s0, s24, s20
	global_load_dwordx4 v[94:97], v[94:95], off
	s_addc_u32 s1, s25, 0
	v_lshlrev_b32_e32 v0, 1, v186
	v_add_u32_e32 v202, 0, v0
	v_add_u32_e32 v198, v202, v181
	ds_read_b128 v[164:167], v198
	ds_read_b128 v[168:171], v198 offset:2048
	ds_read_b128 v[172:175], v198 offset:4096
	ds_read_b128 v[176:179], v198 offset:6144
	ds_read_b128 v[184:187], v198 offset:8192
	ds_read_b128 v[188:191], v198 offset:10240
	ds_read_b128 v[192:195], v198 offset:12288
	ds_read_b128 v[198:201], v198 offset:14336
	v_add_u32_e32 v214, v202, v180
	ds_read_b128 v[202:205], v214 offset:32768
	ds_read_b128 v[206:209], v214 offset:34816
	ds_read_b128 v[210:213], v214 offset:36864
	ds_read_b128 v[214:217], v214 offset:38912
	s_setprio 1
	s_waitcnt lgkmcnt(3)
	v_mfma_f32_16x16x32_bf16 v[158:161], v[202:205], v[164:167], v[158:161]
	s_waitcnt lgkmcnt(2)
	v_mfma_f32_16x16x32_bf16 v[154:157], v[206:209], v[164:167], v[154:157]
	s_waitcnt lgkmcnt(1)
	v_mfma_f32_16x16x32_bf16 v[150:153], v[210:213], v[164:167], v[150:153]
	s_waitcnt lgkmcnt(0)
	v_mfma_f32_16x16x32_bf16 v[146:149], v[214:217], v[164:167], v[146:149]
	v_mfma_f32_16x16x32_bf16 v[142:145], v[202:205], v[168:171], v[142:145]
	v_mfma_f32_16x16x32_bf16 v[138:141], v[206:209], v[168:171], v[138:141]
	v_mfma_f32_16x16x32_bf16 v[134:137], v[210:213], v[168:171], v[134:137]
	v_mfma_f32_16x16x32_bf16 v[130:133], v[214:217], v[168:171], v[130:133]
	v_mfma_f32_16x16x32_bf16 v[126:129], v[202:205], v[172:175], v[126:129]
	v_mfma_f32_16x16x32_bf16 v[122:125], v[206:209], v[172:175], v[122:125]
	v_mfma_f32_16x16x32_bf16 v[118:121], v[210:213], v[172:175], v[118:121]
	v_mfma_f32_16x16x32_bf16 v[114:117], v[214:217], v[172:175], v[114:117]
	v_mfma_f32_16x16x32_bf16 v[110:113], v[202:205], v[176:179], v[110:113]
	v_mfma_f32_16x16x32_bf16 v[106:109], v[206:209], v[176:179], v[106:109]
	v_mfma_f32_16x16x32_bf16 v[102:105], v[210:213], v[176:179], v[102:105]
	v_mfma_f32_16x16x32_bf16 v[98:101], v[214:217], v[176:179], v[98:101]
	v_mfma_f32_16x16x32_bf16 v[90:93], v[202:205], v[184:187], v[90:93]
	v_mfma_f32_16x16x32_bf16 v[86:89], v[206:209], v[184:187], v[86:89]
	v_mfma_f32_16x16x32_bf16 v[82:85], v[210:213], v[184:187], v[82:85]
	v_mfma_f32_16x16x32_bf16 v[78:81], v[214:217], v[184:187], v[78:81]
	v_mfma_f32_16x16x32_bf16 v[74:77], v[202:205], v[188:191], v[74:77]
	v_mfma_f32_16x16x32_bf16 v[70:73], v[206:209], v[188:191], v[70:73]
	v_mfma_f32_16x16x32_bf16 v[66:69], v[210:213], v[188:191], v[66:69]
	v_mfma_f32_16x16x32_bf16 v[62:65], v[214:217], v[188:191], v[62:65]
	v_mfma_f32_16x16x32_bf16 v[58:61], v[202:205], v[192:195], v[58:61]
	v_mfma_f32_16x16x32_bf16 v[50:53], v[206:209], v[192:195], v[50:53]
	v_mfma_f32_16x16x32_bf16 v[46:49], v[210:213], v[192:195], v[46:49]
	v_mfma_f32_16x16x32_bf16 v[38:41], v[214:217], v[192:195], v[38:41]
	v_mfma_f32_16x16x32_bf16 v[30:33], v[202:205], v[198:201], v[30:33]
	v_mfma_f32_16x16x32_bf16 v[26:29], v[206:209], v[198:201], v[26:29]
	v_mfma_f32_16x16x32_bf16 v[22:25], v[210:213], v[198:201], v[22:25]
	v_mfma_f32_16x16x32_bf16 v[18:21], v[214:217], v[198:201], v[18:21]
	s_setprio 0
	v_readlane_b32 s2, v254, 36
	s_nop 1
	v_add3_u32 v164, s2, v183, v226
	s_waitcnt vmcnt(7)
	ds_write_b128 v164, v[14:17]
	s_waitcnt vmcnt(6)
	ds_write_b128 v164, v[2:5] offset:8192
	s_waitcnt vmcnt(5)
	ds_write_b128 v164, v[6:9] offset:16384
	s_waitcnt vmcnt(4)
	ds_write_b128 v164, v[10:13] offset:24576
	v_lshl_add_u64 v[2:3], s[0:1], 0, v[218:219]
	v_lshl_add_u64 v[6:7], s[0:1], 0, v[220:221]
	v_lshl_add_u64 v[10:11], s[0:1], 0, v[222:223]
	v_lshl_add_u64 v[14:15], s[0:1], 0, v[224:225]
	global_load_dwordx4 v[2:5], v[2:3], off
	s_nop 0
	global_load_dwordx4 v[6:9], v[6:7], off
	s_nop 0
	global_load_dwordx4 v[10:13], v[10:11], off
	s_nop 0
	global_load_dwordx4 v[14:17], v[14:15], off
	v_lshlrev_b32_e32 v194, 1, v182
	v_add_u32_e32 v195, 0, v194
	v_add_u32_e32 v198, v195, v181
	ds_read_b128 v[164:167], v198
	ds_read_b128 v[168:171], v198 offset:2048
	ds_read_b128 v[172:175], v198 offset:4096
	ds_read_b128 v[176:179], v198 offset:6144
	ds_read_b128 v[182:185], v198 offset:8192
	ds_read_b128 v[186:189], v198 offset:10240
	ds_read_b128 v[190:193], v198 offset:12288
	ds_read_b128 v[198:201], v198 offset:14336
	v_add_u32_e32 v195, v195, v180
	ds_read_b128 v[202:205], v195 offset:32768
	ds_read_b128 v[206:209], v195 offset:34816
	ds_read_b128 v[210:213], v195 offset:36864
	ds_read_b128 v[214:217], v195 offset:38912
	s_setprio 1
	s_waitcnt lgkmcnt(3)
; DI void gemm8_accum(f32x4 (&acc)[8][4], const bf16_t* a, size_t lda, const bf16_t* b, size_t ldb, int nkb, bf16_t* L,
;                     const bool pre, const bf16_t* an, size_t ldan, const bf16_t* bn, size_t ldbn) {
;     ...
;   g8_compute<1, 2>(acc, L, wm, wn, lane);
;   __syncthreads();
;   g8_store1(L, ra, lrow, lch);
;   __builtin_amdgcn_sched_barrier(0);
;   g8_compute<0, 1>(acc, L + 32768, wm, wn, lane);
;   __builtin_amdgcn_sched_barrier(0);
;   g8_store1(L + 16384, rb, lrow, lch);
	v_mfma_f32_16x16x32_bf16 v[158:161], v[202:205], v[164:167], v[158:161]
	s_waitcnt lgkmcnt(2)
	v_mfma_f32_16x16x32_bf16 v[154:157], v[206:209], v[164:167], v[154:157]
	s_waitcnt lgkmcnt(1)
	v_mfma_f32_16x16x32_bf16 v[150:153], v[210:213], v[164:167], v[150:153]
	s_waitcnt lgkmcnt(0)
	v_mfma_f32_16x16x32_bf16 v[146:149], v[214:217], v[164:167], v[146:149]
	v_mfma_f32_16x16x32_bf16 v[142:145], v[202:205], v[168:171], v[142:145]
	v_mfma_f32_16x16x32_bf16 v[138:141], v[206:209], v[168:171], v[138:141]
	v_mfma_f32_16x16x32_bf16 v[134:137], v[210:213], v[168:171], v[134:137]
	v_mfma_f32_16x16x32_bf16 v[130:133], v[214:217], v[168:171], v[130:133]
	v_mfma_f32_16x16x32_bf16 v[126:129], v[202:205], v[172:175], v[126:129]
	v_mfma_f32_16x16x32_bf16 v[122:125], v[206:209], v[172:175], v[122:125]
	v_mfma_f32_16x16x32_bf16 v[118:121], v[210:213], v[172:175], v[118:121]
	v_mfma_f32_16x16x32_bf16 v[114:117], v[214:217], v[172:175], v[114:117]
	v_mfma_f32_16x16x32_bf16 v[110:113], v[202:205], v[176:179], v[110:113]
	v_mfma_f32_16x16x32_bf16 v[106:109], v[206:209], v[176:179], v[106:109]
	v_mfma_f32_16x16x32_bf16 v[102:105], v[210:213], v[176:179], v[102:105]
	v_mfma_f32_16x16x32_bf16 v[98:101], v[214:217], v[176:179], v[98:101]
	v_mfma_f32_16x16x32_bf16 v[90:93], v[202:205], v[182:185], v[90:93]
	v_mfma_f32_16x16x32_bf16 v[86:89], v[206:209], v[182:185], v[86:89]
	v_mfma_f32_16x16x32_bf16 v[82:85], v[210:213], v[182:185], v[82:85]
	v_mfma_f32_16x16x32_bf16 v[78:81], v[214:217], v[182:185], v[78:81]
	v_mfma_f32_16x16x32_bf16 v[74:77], v[202:205], v[186:189], v[74:77]
	v_mfma_f32_16x16x32_bf16 v[70:73], v[206:209], v[186:189], v[70:73]
	v_mfma_f32_16x16x32_bf16 v[66:69], v[210:213], v[186:189], v[66:69]
	v_mfma_f32_16x16x32_bf16 v[62:65], v[214:217], v[186:189], v[62:65]
	v_mfma_f32_16x16x32_bf16 v[58:61], v[202:205], v[190:193], v[58:61]
	v_mfma_f32_16x16x32_bf16 v[50:53], v[206:209], v[190:193], v[50:53]
	v_mfma_f32_16x16x32_bf16 v[46:49], v[210:213], v[190:193], v[46:49]
	v_mfma_f32_16x16x32_bf16 v[38:41], v[214:217], v[190:193], v[38:41]
	v_mfma_f32_16x16x32_bf16 v[30:33], v[202:205], v[198:201], v[30:33]
	v_mfma_f32_16x16x32_bf16 v[26:29], v[206:209], v[198:201], v[26:29]
	v_mfma_f32_16x16x32_bf16 v[22:25], v[210:213], v[198:201], v[22:25]
	v_mfma_f32_16x16x32_bf16 v[18:21], v[214:217], v[198:201], v[18:21]
	s_setprio 0
	s_barrier
	s_waitcnt vmcnt(7)
	ds_write_b128 v163, v[34:37]
	s_waitcnt vmcnt(6)
	ds_write_b128 v163, v[42:45] offset:8192
	s_waitcnt vmcnt(5)
	ds_write_b128 v163, v[54:57] offset:16384
	s_waitcnt vmcnt(4)
	ds_write_b128 v163, v[94:97] offset:24576
	v_add3_u32 v176, s7, v0, v181
	ds_read_b128 v[34:37], v176
	ds_read_b128 v[42:45], v176 offset:2048
	ds_read_b128 v[54:57], v176 offset:4096
	ds_read_b128 v[94:97], v176 offset:6144
	ds_read_b128 v[164:167], v176 offset:8192
	ds_read_b128 v[168:171], v176 offset:10240
	ds_read_b128 v[172:175], v176 offset:12288
	ds_read_b128 v[176:179], v176 offset:14336
	v_add3_u32 v0, s2, v0, v180
	ds_read_b128 v[182:185], v0
	ds_read_b128 v[186:189], v0 offset:2048
	ds_read_b128 v[190:193], v0 offset:4096
	ds_read_b128 v[198:201], v0 offset:6144
	s_setprio 1
	s_waitcnt lgkmcnt(3)
	v_mfma_f32_16x16x32_bf16 v[158:161], v[182:185], v[34:37], v[158:161]
	s_waitcnt lgkmcnt(2)
	v_mfma_f32_16x16x32_bf16 v[154:157], v[186:189], v[34:37], v[154:157]
	s_waitcnt lgkmcnt(1)
	v_mfma_f32_16x16x32_bf16 v[150:153], v[190:193], v[34:37], v[150:153]
	s_waitcnt lgkmcnt(0)
	v_mfma_f32_16x16x32_bf16 v[34:37], v[198:201], v[34:37], v[146:149]
	v_mfma_f32_16x16x32_bf16 v[142:145], v[182:185], v[42:45], v[142:145]
	v_mfma_f32_16x16x32_bf16 v[138:141], v[186:189], v[42:45], v[138:141]
	v_mfma_f32_16x16x32_bf16 v[134:137], v[190:193], v[42:45], v[134:137]
	v_mfma_f32_16x16x32_bf16 v[42:45], v[198:201], v[42:45], v[130:133]
	v_mfma_f32_16x16x32_bf16 v[130:133], v[182:185], v[54:57], v[126:129]
	v_mfma_f32_16x16x32_bf16 v[146:149], v[186:189], v[54:57], v[122:125]
	v_mfma_f32_16x16x32_bf16 v[202:205], v[190:193], v[54:57], v[118:121]
	v_mfma_f32_16x16x32_bf16 v[54:57], v[198:201], v[54:57], v[114:117]
	v_mfma_f32_16x16x32_bf16 v[206:209], v[182:185], v[94:97], v[110:113]
	v_mfma_f32_16x16x32_bf16 v[210:213], v[186:189], v[94:97], v[106:109]
	v_mfma_f32_16x16x32_bf16 v[214:217], v[190:193], v[94:97], v[102:105]
	v_mfma_f32_16x16x32_bf16 v[218:221], v[198:201], v[94:97], v[98:101]
	v_mfma_f32_16x16x32_bf16 v[222:225], v[182:185], v[164:167], v[90:93]
	v_mfma_f32_16x16x32_bf16 v[226:229], v[186:189], v[164:167], v[86:89]
	v_mfma_f32_16x16x32_bf16 v[230:233], v[190:193], v[164:167], v[82:85]
	v_mfma_f32_16x16x32_bf16 v[164:167], v[198:201], v[164:167], v[78:81]
	v_mfma_f32_16x16x32_bf16 v[234:237], v[182:185], v[168:171], v[74:77]
	v_mfma_f32_16x16x32_bf16 v[238:241], v[186:189], v[168:171], v[70:73]
	v_mfma_f32_16x16x32_bf16 v[242:245], v[190:193], v[168:171], v[66:69]
	v_mfma_f32_16x16x32_bf16 v[168:171], v[198:201], v[168:171], v[62:65]
	v_mfma_f32_16x16x32_bf16 v[246:249], v[182:185], v[172:175], v[58:61]
	v_mfma_f32_16x16x32_bf16 v[50:53], v[186:189], v[172:175], v[50:53]
	v_mfma_f32_16x16x32_bf16 v[46:49], v[190:193], v[172:175], v[46:49]
	v_mfma_f32_16x16x32_bf16 v[172:175], v[198:201], v[172:175], v[38:41]
	v_mfma_f32_16x16x32_bf16 v[182:185], v[182:185], v[176:179], v[30:33]
	v_mfma_f32_16x16x32_bf16 v[186:189], v[186:189], v[176:179], v[26:29]
	v_mfma_f32_16x16x32_bf16 v[190:193], v[190:193], v[176:179], v[22:25]
	v_mfma_f32_16x16x32_bf16 v[176:179], v[198:201], v[176:179], v[18:21]
	s_setprio 0
	s_waitcnt vmcnt(3)
	ds_write_b128 v163, v[2:5] offset:32768
	s_waitcnt vmcnt(2)
	ds_write_b128 v163, v[6:9] offset:40960
	s_waitcnt vmcnt(1)
; DI int TID8() { int t = threadIdx.x; asm volatile("" : "+v"(t)); return t; }
; DI void gemm8_accum(f32x4 (&acc)[8][4], const bf16_t* a, size_t lda, const bf16_t* b, size_t ldb, int nkb, bf16_t* L,
;                     const bool pre, const bf16_t* an, size_t ldan, const bf16_t* bn, size_t ldbn) {
;     ...
;   g8_store1(L + 16384, rb, lrow, lch);
;   __builtin_amdgcn_sched_barrier(0);
;   g8_compute<1, 2>(acc, L + 32768, wm, wn, lane);
;   __syncthreads();
; DI void row_rs8(float (&rsv)[8], const float* rowpart, int m0) {
;   const int tid = TID8(), lane = tid & 63, wm = tid >> 8;
; #pragma unroll
;   for (int i = 0; i < 8; ++i) {
;     const int m = m0 + wm * 128 + i * 16 + (lane & 15);
;     float s = 0.f;
; #pragma unroll
;     for (int t = 0; t < 8; ++t) s += rowpart[(size_t)t * T_TOK + m];
;     rsv[i] = rsqrtf(s * (1.f / 1024.f) + 1e-6f);
;   }
	ds_write_b128 v163, v[10:13] offset:49152
	s_waitcnt vmcnt(0)
	ds_write_b128 v163, v[14:17] offset:57344
	v_add3_u32 v0, s7, v194, v181
	ds_read_b128 v[2:5], v0
	ds_read_b128 v[6:9], v0 offset:2048
	ds_read_b128 v[10:13], v0 offset:4096
	ds_read_b128 v[14:17], v0 offset:6144
	ds_read_b128 v[18:21], v0 offset:8192
	ds_read_b128 v[22:25], v0 offset:10240
	ds_read_b128 v[198:201], v0 offset:12288
	ds_read_b128 v[26:29], v0 offset:14336
	v_add3_u32 v0, s2, v194, v180
	ds_read_b128 v[30:33], v0
	ds_read_b128 v[38:41], v0 offset:2048
	ds_read_b128 v[58:61], v0 offset:4096
	ds_read_b128 v[62:65], v0 offset:6144
	s_setprio 1
	s_waitcnt lgkmcnt(3)
	v_mfma_f32_16x16x32_bf16 v[126:129], v[30:33], v[2:5], v[158:161]
	s_waitcnt lgkmcnt(2)
	v_mfma_f32_16x16x32_bf16 v[122:125], v[38:41], v[2:5], v[154:157]
	s_waitcnt lgkmcnt(1)
	v_mfma_f32_16x16x32_bf16 v[118:121], v[58:61], v[2:5], v[150:153]
	s_waitcnt lgkmcnt(0)
	v_mfma_f32_16x16x32_bf16 v[114:117], v[62:65], v[2:5], v[34:37]
	v_mfma_f32_16x16x32_bf16 v[110:113], v[30:33], v[6:9], v[142:145]
	v_mfma_f32_16x16x32_bf16 v[106:109], v[38:41], v[6:9], v[138:141]
	v_mfma_f32_16x16x32_bf16 v[102:105], v[58:61], v[6:9], v[134:137]
	v_mfma_f32_16x16x32_bf16 v[98:101], v[62:65], v[6:9], v[42:45]
	v_mfma_f32_16x16x32_bf16 v[94:97], v[30:33], v[10:13], v[130:133]
	v_mfma_f32_16x16x32_bf16 v[90:93], v[38:41], v[10:13], v[146:149]
	v_mfma_f32_16x16x32_bf16 v[86:89], v[58:61], v[10:13], v[202:205]
	v_mfma_f32_16x16x32_bf16 v[82:85], v[62:65], v[10:13], v[54:57]
	v_mfma_f32_16x16x32_bf16 v[78:81], v[30:33], v[14:17], v[206:209]
	v_mfma_f32_16x16x32_bf16 v[74:77], v[38:41], v[14:17], v[210:213]
	v_mfma_f32_16x16x32_bf16 v[70:73], v[58:61], v[14:17], v[214:217]
	v_mfma_f32_16x16x32_bf16 v[66:69], v[62:65], v[14:17], v[218:221]
	v_mfma_f32_16x16x32_bf16 v[214:217], v[30:33], v[18:21], v[222:225]
	v_mfma_f32_16x16x32_bf16 v[210:213], v[38:41], v[18:21], v[226:229]
	v_mfma_f32_16x16x32_bf16 v[54:57], v[58:61], v[18:21], v[230:233]
	v_mfma_f32_16x16x32_bf16 v[158:161], v[62:65], v[18:21], v[164:167]
	v_mfma_f32_16x16x32_bf16 v[164:167], v[30:33], v[22:25], v[234:237]
	v_mfma_f32_16x16x32_bf16 v[42:45], v[38:41], v[22:25], v[238:241]
	v_mfma_f32_16x16x32_bf16 v[206:209], v[58:61], v[22:25], v[242:245]
	v_mfma_f32_16x16x32_bf16 v[34:37], v[62:65], v[22:25], v[168:171]
	v_mfma_f32_16x16x32_bf16 v[202:205], v[30:33], v[198:201], v[246:249]
	v_mfma_f32_16x16x32_bf16 v[168:171], v[38:41], v[198:201], v[50:53]
	v_mfma_f32_16x16x32_bf16 v[22:25], v[58:61], v[198:201], v[46:49]
	v_mfma_f32_16x16x32_bf16 v[18:21], v[62:65], v[198:201], v[172:175]
	v_mfma_f32_16x16x32_bf16 v[14:17], v[30:33], v[26:29], v[182:185]
	v_mfma_f32_16x16x32_bf16 v[10:13], v[38:41], v[26:29], v[186:189]
	v_mfma_f32_16x16x32_bf16 v[6:9], v[58:61], v[26:29], v[190:193]
	v_mfma_f32_16x16x32_bf16 v[2:5], v[62:65], v[26:29], v[176:179]
	s_setprio 0
	v_mov_b32_e32 v0, v196
	s_barrier
	v_readlane_b32 s0, v251, 51
	v_ashrrev_i32_e32 v26, 1, v0
	v_and_b32_e32 v26, 0xffffff80, v26
	v_and_or_b32 v0, v0, 15, s13
	v_add_u32_e32 v26, v0, v26
	v_ashrrev_i32_e32 v27, 31, v26
	v_readlane_b32 s1, v251, 52
	s_mov_b32 s20, 0x3a800000
	s_mov_b32 s28, 0x45800000
	v_lshl_add_u64 v[148:149], v[26:27], 2, s[0:1]
	s_mov_b32 s0, 0x20000
	v_add_co_u32_e32 v146, vcc, s0, v148
	s_mov_b32 s0, 0x40000
	s_nop 0
	v_addc_co_u32_e32 v147, vcc, 0, v149, vcc
	v_add_co_u32_e32 v144, vcc, s0, v148
	s_mov_b32 s0, 0x60000
	s_nop 0
	v_addc_co_u32_e32 v145, vcc, 0, v149, vcc
	v_add_co_u32_e32 v142, vcc, s0, v148
	s_mov_b32 s0, 0x80000
	s_nop 0
	v_addc_co_u32_e32 v143, vcc, 0, v149, vcc
	v_add_co_u32_e32 v136, vcc, s0, v148
	s_mov_b32 s0, 0xa0000
	s_nop 0
	v_addc_co_u32_e32 v137, vcc, 0, v149, vcc
	v_add_co_u32_e32 v134, vcc, s0, v148
	s_mov_b32 s0, 0xc0000
	s_nop 0
	v_addc_co_u32_e32 v135, vcc, 0, v149, vcc
	v_add_co_u32_e32 v132, vcc, s0, v148
	s_mov_b32 s0, 0xe0000
	s_nop 0
	v_addc_co_u32_e32 v133, vcc, 0, v149, vcc
	v_add_co_u32_e32 v130, vcc, s0, v148
	global_load_dword v26, v[148:149], off
	global_load_dword v28, v[146:147], off
	global_load_dword v30, v[144:145], off
	global_load_dword v32, v[142:143], off
	global_load_dword v38, v[136:137], off
	global_load_dword v40, v[134:135], off
	global_load_dword v46, v[132:133], off
	v_addc_co_u32_e32 v131, vcc, 0, v149, vcc
	global_load_dword v48, v[130:131], off
	global_load_dword v27, v[148:149], off offset:64
	global_load_dword v29, v[146:147], off offset:64
	global_load_dword v31, v[144:145], off offset:64
	global_load_dword v33, v[142:143], off offset:64
	global_load_dword v39, v[136:137], off offset:64
	global_load_dword v41, v[134:135], off offset:64
	global_load_dword v47, v[132:133], off offset:64
	global_load_dword v49, v[130:131], off offset:64
	s_mov_b32 s0, 0x358637bd
	v_mov_b64_e32 v[140:141], s[0:1]
	s_mov_b32 s0, 0x800000
	s_add_i32 s9, s9, s21
	s_waitcnt vmcnt(7)
	v_pk_add_f32 v[26:27], v[26:27], 0 op_sel_hi:[1,0]
	s_waitcnt vmcnt(6)
	v_pk_add_f32 v[26:27], v[26:27], v[28:29]
	s_waitcnt vmcnt(5)
	v_pk_add_f32 v[26:27], v[26:27], v[30:31]
	s_waitcnt vmcnt(4)
	v_pk_add_f32 v[26:27], v[26:27], v[32:33]
	s_waitcnt vmcnt(3)
	v_pk_add_f32 v[26:27], v[26:27], v[38:39]
	s_waitcnt vmcnt(2)
	v_pk_add_f32 v[26:27], v[26:27], v[40:41]
	s_waitcnt vmcnt(1)
	v_pk_add_f32 v[26:27], v[26:27], v[46:47]
	s_waitcnt vmcnt(0)
; DI void row_rs8(float (&rsv)[8], const float* rowpart, int m0) {
;     ...
; #pragma unroll
;   for (int i = 0; i < 8; ++i) {
;     const int m = m0 + wm * 128 + i * 16 + (lane & 15);
;     float s = 0.f;
; #pragma unroll
;     for (int t = 0; t < 8; ++t) s += rowpart[(size_t)t * T_TOK + m];
;     rsv[i] = rsqrtf(s * (1.f / 1024.f) + 1e-6f);
;   }
; DI void scale_rows8(f32x4 (&acc)[8][4], const float (&rsv)[8]) {
; #pragma unroll
;   for (int i = 0; i < 8; ++i)
; #pragma unroll
;     for (int j = 0; j < 4; ++j) acc[i][j] *= rsv[i];
	v_pk_add_f32 v[26:27], v[26:27], v[48:49]
	s_nop 0
	v_pk_fma_f32 v[26:27], v[26:27], s[20:21], v[140:141] op_sel_hi:[1,0,0]
	s_nop 0
	v_mul_f32_e32 v0, 0x4b800000, v26
	v_cmp_gt_f32_e64 s[2:3], s0, v26
	v_cmp_gt_f32_e32 vcc, s0, v27
	s_nop 0
	v_cndmask_b32_e64 v0, v26, v0, s[2:3]
	v_rsq_f32_e32 v26, v0
	v_mul_f32_e32 v0, 0x4b800000, v27
	v_cndmask_b32_e32 v0, v27, v0, vcc
	v_rsq_f32_e32 v27, v0
	s_nop 0
	v_pk_mul_f32 v[28:29], v[26:27], s[28:29] op_sel_hi:[1,0]
	s_nop 0
	v_cndmask_b32_e32 v0, v27, v29, vcc
	v_cndmask_b32_e64 v138, v26, v28, s[2:3]
	global_load_dword v26, v[148:149], off offset:128
	global_load_dword v28, v[146:147], off offset:128
	global_load_dword v30, v[144:145], off offset:128
	global_load_dword v32, v[142:143], off offset:128
	global_load_dword v38, v[136:137], off offset:128
	global_load_dword v40, v[134:135], off offset:128
	global_load_dword v46, v[132:133], off offset:128
	global_load_dword v48, v[130:131], off offset:128
	global_load_dword v27, v[148:149], off offset:192
	global_load_dword v29, v[146:147], off offset:192
	global_load_dword v31, v[144:145], off offset:192
	global_load_dword v33, v[142:143], off offset:192
	global_load_dword v39, v[136:137], off offset:192
	global_load_dword v41, v[134:135], off offset:192
	global_load_dword v47, v[132:133], off offset:192
	global_load_dword v49, v[130:131], off offset:192
	s_waitcnt vmcnt(7)
	v_pk_add_f32 v[26:27], v[26:27], 0 op_sel_hi:[1,0]
	s_waitcnt vmcnt(6)
	v_pk_add_f32 v[26:27], v[26:27], v[28:29]
	s_waitcnt vmcnt(5)
	v_pk_add_f32 v[26:27], v[26:27], v[30:31]
	s_waitcnt vmcnt(4)
	v_pk_add_f32 v[26:27], v[26:27], v[32:33]
	s_waitcnt vmcnt(3)
	v_pk_add_f32 v[26:27], v[26:27], v[38:39]
	s_waitcnt vmcnt(2)
	v_pk_add_f32 v[26:27], v[26:27], v[40:41]
	s_waitcnt vmcnt(1)
	v_pk_add_f32 v[26:27], v[26:27], v[46:47]
	s_waitcnt vmcnt(0)
	v_pk_add_f32 v[26:27], v[26:27], v[48:49]
	s_nop 0
	v_pk_fma_f32 v[26:27], v[26:27], s[20:21], v[140:141] op_sel_hi:[1,0,0]
	s_nop 0
	v_mul_f32_e32 v28, 0x4b800000, v26
	v_cmp_gt_f32_e64 s[2:3], s0, v26
	v_cmp_gt_f32_e32 vcc, s0, v27
	s_nop 0
	v_cndmask_b32_e64 v26, v26, v28, s[2:3]
	v_mul_f32_e32 v28, 0x4b800000, v27
	v_cndmask_b32_e32 v27, v27, v28, vcc
	v_rsq_f32_e32 v26, v26
	v_rsq_f32_e32 v27, v27
	s_nop 0
	v_pk_mul_f32 v[28:29], v[26:27], s[28:29] op_sel_hi:[1,0]
	s_nop 0
	v_cndmask_b32_e32 v150, v27, v29, vcc
	v_cndmask_b32_e64 v152, v26, v28, s[2:3]
	global_load_dword v26, v[148:149], off offset:256
	global_load_dword v28, v[146:147], off offset:256
	global_load_dword v30, v[144:145], off offset:256
	global_load_dword v32, v[142:143], off offset:256
	global_load_dword v38, v[136:137], off offset:256
	global_load_dword v40, v[134:135], off offset:256
	global_load_dword v46, v[132:133], off offset:256
	global_load_dword v48, v[130:131], off offset:256
	global_load_dword v27, v[148:149], off offset:320
	global_load_dword v29, v[146:147], off offset:320
	global_load_dword v31, v[144:145], off offset:320
	global_load_dword v33, v[142:143], off offset:320
	global_load_dword v39, v[136:137], off offset:320
	global_load_dword v41, v[134:135], off offset:320
	global_load_dword v47, v[132:133], off offset:320
	global_load_dword v49, v[130:131], off offset:320
	s_waitcnt vmcnt(7)
	v_pk_add_f32 v[26:27], v[26:27], 0 op_sel_hi:[1,0]
	s_waitcnt vmcnt(6)
	v_pk_add_f32 v[26:27], v[26:27], v[28:29]
	s_waitcnt vmcnt(5)
	v_pk_add_f32 v[26:27], v[26:27], v[30:31]
	s_waitcnt vmcnt(4)
	v_pk_add_f32 v[26:27], v[26:27], v[32:33]
	s_waitcnt vmcnt(3)
	v_pk_add_f32 v[26:27], v[26:27], v[38:39]
	s_waitcnt vmcnt(2)
	v_pk_add_f32 v[26:27], v[26:27], v[40:41]
	s_waitcnt vmcnt(1)
	v_pk_add_f32 v[26:27], v[26:27], v[46:47]
	s_waitcnt vmcnt(0)
	v_pk_add_f32 v[26:27], v[26:27], v[48:49]
	s_nop 0
	v_pk_fma_f32 v[26:27], v[26:27], s[20:21], v[140:141] op_sel_hi:[1,0,0]
	s_nop 0
	v_mul_f32_e32 v28, 0x4b800000, v26
	v_cmp_gt_f32_e64 s[2:3], s0, v26
	v_cmp_gt_f32_e32 vcc, s0, v27
	s_nop 0
	v_cndmask_b32_e64 v26, v26, v28, s[2:3]
	v_mul_f32_e32 v28, 0x4b800000, v27
	v_cndmask_b32_e32 v27, v27, v28, vcc
	v_rsq_f32_e32 v26, v26
	v_rsq_f32_e32 v27, v27
	s_nop 0
	v_pk_mul_f32 v[28:29], v[26:27], s[28:29] op_sel_hi:[1,0]
	s_nop 0
	v_cndmask_b32_e32 v154, v27, v29, vcc
	v_cndmask_b32_e64 v156, v26, v28, s[2:3]
	global_load_dword v26, v[148:149], off offset:384
	global_load_dword v28, v[146:147], off offset:384
	global_load_dword v30, v[144:145], off offset:384
	global_load_dword v32, v[142:143], off offset:384
	global_load_dword v38, v[136:137], off offset:384
	global_load_dword v40, v[134:135], off offset:384
	global_load_dword v46, v[132:133], off offset:384
	global_load_dword v48, v[130:131], off offset:384
	global_load_dword v27, v[148:149], off offset:448
	global_load_dword v29, v[146:147], off offset:448
	global_load_dword v31, v[144:145], off offset:448
	global_load_dword v33, v[142:143], off offset:448
	global_load_dword v39, v[136:137], off offset:448
	global_load_dword v41, v[134:135], off offset:448
	global_load_dword v47, v[132:133], off offset:448
	global_load_dword v49, v[130:131], off offset:448
	v_pk_mul_f32 v[134:135], v[128:129], v[138:139] op_sel_hi:[1,0]
	v_pk_mul_f32 v[128:129], v[124:125], v[138:139] op_sel_hi:[1,0]
	v_pk_mul_f32 v[132:133], v[122:123], v[138:139] op_sel_hi:[1,0]
	v_pk_mul_f32 v[122:123], v[120:121], v[138:139] op_sel_hi:[1,0]
	v_pk_mul_f32 v[124:125], v[118:119], v[138:139] op_sel_hi:[1,0]
	v_pk_mul_f32 v[118:119], v[116:117], v[138:139] op_sel_hi:[1,0]
	v_pk_mul_f32 v[120:121], v[114:115], v[138:139] op_sel_hi:[1,0]
	v_pk_mul_f32 v[114:115], v[112:113], v[0:1] op_sel_hi:[1,0]
	v_pk_mul_f32 v[116:117], v[110:111], v[0:1] op_sel_hi:[1,0]
; DI float bflo(unsigned u) { return __uint_as_float(u << 16); }
; DI float bfhi(unsigned u) { return __uint_as_float(u & 0xffff0000u); }
; DI float sigmoidf(float x) { return __builtin_amdgcn_rcpf(1.f + __expf(-x)); }
; DI void scale_rows8(f32x4 (&acc)[8][4], const float (&rsv)[8]) {
; #pragma unroll
;   for (int i = 0; i < 8; ++i)
; #pragma unroll
;     for (int j = 0; j < 4; ++j) acc[i][j] *= rsv[i];
; __global__ void __launch_bounds__(512, 2) mega(Params p) {
;     ...
;       gemm8_epi(acc8, m0, n0, [&](int m, int n, f32x4& a) {
;         uint2 pv = *(const uint2*)(ppb + (size_t)m * DM + n);
;         float4* o = (float4*)(p.out + (size_t)m * DM + n);
;         float4 xv = *o;
;         *o = make_float4(xv.x + sigmoidf(a[0]) * bflo(pv.x), xv.y + sigmoidf(a[1]) * bfhi(pv.x),
;                          xv.z + sigmoidf(a[2]) * bflo(pv.y), xv.w + sigmoidf(a[3]) * bfhi(pv.y));
;       });
	v_pk_mul_f32 v[110:111], v[108:109], v[0:1] op_sel_hi:[1,0]
	v_pk_mul_f32 v[112:113], v[106:107], v[0:1] op_sel_hi:[1,0]
	v_pk_mul_f32 v[106:107], v[104:105], v[0:1] op_sel_hi:[1,0]
	v_pk_mul_f32 v[108:109], v[102:103], v[0:1] op_sel_hi:[1,0]
	v_pk_mul_f32 v[102:103], v[100:101], v[0:1] op_sel_hi:[1,0]
	v_pk_mul_f32 v[104:105], v[98:99], v[0:1] op_sel_hi:[1,0]
	v_mov_b32_e32 v0, v196
	v_pk_mul_f32 v[136:137], v[126:127], v[138:139] op_sel_hi:[1,0]
	v_pk_mul_f32 v[100:101], v[94:95], v[152:153] op_sel_hi:[1,0]
	v_pk_mul_f32 v[98:99], v[96:97], v[152:153] op_sel_hi:[1,0]
	v_pk_mul_f32 v[96:97], v[90:91], v[152:153] op_sel_hi:[1,0]
	v_pk_mul_f32 v[94:95], v[92:93], v[152:153] op_sel_hi:[1,0]
	v_pk_mul_f32 v[92:93], v[86:87], v[152:153] op_sel_hi:[1,0]
	v_pk_mul_f32 v[90:91], v[88:89], v[152:153] op_sel_hi:[1,0]
	v_pk_mul_f32 v[88:89], v[82:83], v[152:153] op_sel_hi:[1,0]
	v_pk_mul_f32 v[86:87], v[84:85], v[152:153] op_sel_hi:[1,0]
	v_pk_mul_f32 v[84:85], v[78:79], v[150:151] op_sel_hi:[1,0]
	v_pk_mul_f32 v[82:83], v[80:81], v[150:151] op_sel_hi:[1,0]
	v_pk_mul_f32 v[80:81], v[74:75], v[150:151] op_sel_hi:[1,0]
	v_pk_mul_f32 v[78:79], v[76:77], v[150:151] op_sel_hi:[1,0]
	v_pk_mul_f32 v[76:77], v[70:71], v[150:151] op_sel_hi:[1,0]
	v_pk_mul_f32 v[74:75], v[72:73], v[150:151] op_sel_hi:[1,0]
	v_pk_mul_f32 v[72:73], v[66:67], v[150:151] op_sel_hi:[1,0]
	v_pk_mul_f32 v[70:71], v[68:69], v[150:151] op_sel_hi:[1,0]
	v_pk_mul_f32 v[68:69], v[214:215], v[156:157] op_sel_hi:[1,0]
	v_pk_mul_f32 v[66:67], v[216:217], v[156:157] op_sel_hi:[1,0]
	v_pk_mul_f32 v[64:65], v[210:211], v[156:157] op_sel_hi:[1,0]
	v_pk_mul_f32 v[62:63], v[212:213], v[156:157] op_sel_hi:[1,0]
	v_pk_mul_f32 v[60:61], v[54:55], v[156:157] op_sel_hi:[1,0]
	v_pk_mul_f32 v[58:59], v[56:57], v[156:157] op_sel_hi:[1,0]
	v_pk_mul_f32 v[56:57], v[158:159], v[156:157] op_sel_hi:[1,0]
	v_pk_mul_f32 v[54:55], v[160:161], v[156:157] op_sel_hi:[1,0]
	v_pk_mul_f32 v[52:53], v[164:165], v[154:155] op_sel_hi:[1,0]
	v_pk_mul_f32 v[50:51], v[166:167], v[154:155] op_sel_hi:[1,0]
	s_waitcnt vmcnt(7)
	v_pk_add_f32 v[26:27], v[26:27], 0 op_sel_hi:[1,0]
	s_waitcnt vmcnt(6)
	v_pk_add_f32 v[26:27], v[26:27], v[28:29]
	s_waitcnt vmcnt(5)
	v_pk_add_f32 v[26:27], v[26:27], v[30:31]
	s_waitcnt vmcnt(4)
	v_pk_add_f32 v[26:27], v[26:27], v[32:33]
	s_waitcnt vmcnt(3)
	v_pk_add_f32 v[26:27], v[26:27], v[38:39]
	v_pk_mul_f32 v[38:39], v[36:37], v[154:155] op_sel_hi:[1,0]
	s_waitcnt vmcnt(2)
	v_pk_add_f32 v[26:27], v[26:27], v[40:41]
	v_pk_mul_f32 v[40:41], v[34:35], v[154:155] op_sel_hi:[1,0]
	s_waitcnt vmcnt(1)
	v_pk_add_f32 v[26:27], v[26:27], v[46:47]
	v_pk_mul_f32 v[46:47], v[44:45], v[154:155] op_sel_hi:[1,0]
	s_waitcnt vmcnt(0)
	v_pk_add_f32 v[26:27], v[26:27], v[48:49]
	v_pk_mul_f32 v[48:49], v[42:43], v[154:155] op_sel_hi:[1,0]
	v_pk_fma_f32 v[26:27], v[26:27], s[20:21], v[140:141] op_sel_hi:[1,0,0]
	v_pk_mul_f32 v[44:45], v[206:207], v[154:155] op_sel_hi:[1,0]
	v_mul_f32_e32 v28, 0x4b800000, v26
	v_cmp_gt_f32_e64 s[2:3], s0, v26
	v_cmp_gt_f32_e32 vcc, s0, v27
	v_pk_mul_f32 v[42:43], v[208:209], v[154:155] op_sel_hi:[1,0]
	v_cndmask_b32_e64 v26, v26, v28, s[2:3]
	v_mul_f32_e32 v28, 0x4b800000, v27
	v_cndmask_b32_e32 v27, v27, v28, vcc
	v_rsq_f32_e32 v26, v26
	v_rsq_f32_e32 v27, v27
	s_mov_b32 s20, s6
	v_pk_mul_f32 v[28:29], v[26:27], s[28:29] op_sel_hi:[1,0]
	s_nop 0
	v_cndmask_b32_e64 v28, v26, v28, s[2:3]
	v_cndmask_b32_e32 v130, v27, v29, vcc
	v_pk_mul_f32 v[26:27], v[22:23], v[28:29] op_sel_hi:[1,0]
	v_ashrrev_i32_e32 v23, 1, v0
	v_pk_mul_f32 v[34:35], v[204:205], v[28:29] op_sel_hi:[1,0]
	v_pk_mul_f32 v[36:37], v[202:203], v[28:29] op_sel_hi:[1,0]
	v_pk_mul_f32 v[30:31], v[170:171], v[28:29] op_sel_hi:[1,0]
	v_pk_mul_f32 v[32:33], v[168:169], v[28:29] op_sel_hi:[1,0]
	v_pk_mul_f32 v[24:25], v[24:25], v[28:29] op_sel_hi:[1,0]
	v_pk_mul_f32 v[20:21], v[20:21], v[28:29] op_sel_hi:[1,0]
	v_pk_mul_f32 v[18:19], v[18:19], v[28:29] op_sel_hi:[1,0]
	v_and_b32_e32 v22, 0xc0, v0
	v_and_b32_e32 v23, 0xffffff80, v23
	v_and_or_b32 v28, v0, 15, s13
	v_lshrrev_b32_e32 v0, 2, v0
	v_add_u32_e32 v28, v28, v23
	v_and_b32_e32 v0, 12, v0
	v_or3_b32 v140, v22, v0, s12
	v_ashrrev_i32_e32 v29, 31, v28
	v_readlane_b32 s12, v252, 47
	v_lshlrev_b64 v[22:23], 11, v[28:29]
	v_readlane_b32 s13, v252, 48
	v_lshlrev_b32_e32 v0, 1, v140
	v_pk_mul_f32 v[16:17], v[16:17], v[130:131] op_sel_hi:[1,0]
	v_lshl_add_u64 v[22:23], s[12:13], 0, v[22:23]
	v_pk_mul_f32 v[14:15], v[14:15], v[130:131] op_sel_hi:[1,0]
	v_pk_mul_f32 v[12:13], v[12:13], v[130:131] op_sel_hi:[1,0]
	v_pk_mul_f32 v[10:11], v[10:11], v[130:131] op_sel_hi:[1,0]
	v_pk_mul_f32 v[8:9], v[8:9], v[130:131] op_sel_hi:[1,0]
	v_pk_mul_f32 v[6:7], v[6:7], v[130:131] op_sel_hi:[1,0]
	v_pk_mul_f32 v[4:5], v[4:5], v[130:131] op_sel_hi:[1,0]
	v_pk_mul_f32 v[2:3], v[2:3], v[130:131] op_sel_hi:[1,0]
	v_lshl_add_u64 v[130:131], v[22:23], 0, v[0:1]
	v_lshlrev_b64 v[22:23], 12, v[28:29]
	v_mul_f32_e32 v29, 0xbfb8aa3b, v136
	v_exp_f32_e32 v29, v29
	v_readlane_b32 s0, v251, 33
	v_readlane_b32 s2, v251, 35
	v_readlane_b32 s3, v251, 36
	v_add_f32_e32 v29, 1.0, v29
	global_load_dwordx2 v[138:139], v[130:131], off
	v_lshl_add_u64 v[126:127], s[2:3], 0, v[22:23]
	v_lshlrev_b32_e32 v22, 2, v140
	v_rcp_f32_e32 v140, v29
	v_mul_f32_e32 v29, 0xbfb8aa3b, v137
	v_exp_f32_e32 v29, v29
	v_mov_b32_e32 v23, v1
	v_lshl_add_u64 v[126:127], v[126:127], 0, v[22:23]
	v_mul_f32_e32 v26, 0xbfb8aa3b, v26
	v_add_f32_e32 v29, 1.0, v29
	v_rcp_f32_e32 v141, v29
	v_mul_f32_e32 v29, 0xbfb8aa3b, v134
	v_exp_f32_e32 v29, v29
	v_mul_f32_e32 v24, 0xbfb8aa3b, v24
	v_exp_f32_e32 v26, v26
	v_exp_f32_e32 v24, v24
	v_add_f32_e32 v29, 1.0, v29
	v_rcp_f32_e32 v144, v29
	v_mul_f32_e32 v29, 0xbfb8aa3b, v135
	global_load_dwordx4 v[134:137], v[126:127], off
	v_exp_f32_e32 v29, v29
	v_add_f32_e32 v26, 1.0, v26
	v_add_f32_e32 v24, 1.0, v24
	v_mul_f32_e32 v18, 0xbfb8aa3b, v18
	v_add_f32_e32 v29, 1.0, v29
	v_rcp_f32_e32 v145, v29
	v_mul_f32_e32 v29, 0xbfb8aa3b, v132
	v_exp_f32_e32 v29, v29
	v_exp_f32_e32 v18, v18
	v_readlane_b32 s0, v254, 13
	v_readlane_b32 s1, v251, 34
	v_add_f32_e32 v29, 1.0, v29
	v_rcp_f32_e32 v132, v29
	v_mul_f32_e32 v29, 0xbfb8aa3b, v133
	v_exp_f32_e32 v29, v29
	v_add_f32_e32 v18, 1.0, v18
	s_add_i32 s11, s11, s0
	v_readlane_b32 s0, v254, 19
	v_add_f32_e32 v29, 1.0, v29
	v_rcp_f32_e32 v133, v29
	v_mul_f32_e32 v29, 0xbfb8aa3b, v128
	v_exp_f32_e32 v29, v29
	s_add_i32 s10, s10, s0
	s_mov_b64 s[0:1], -1
	s_and_b64 vcc, s[4:5], exec
	v_add_f32_e32 v29, 1.0, v29
	v_rcp_f32_e32 v128, v29
	v_mul_f32_e32 v29, 0xbfb8aa3b, v129
	v_exp_f32_e32 v29, v29
	s_waitcnt vmcnt(1)
; DI float bflo(unsigned u) { return __uint_as_float(u << 16); }
; DI float bfhi(unsigned u) { return __uint_as_float(u & 0xffff0000u); }
; DI float sigmoidf(float x) { return __builtin_amdgcn_rcpf(1.f + __expf(-x)); }
; __global__ void __launch_bounds__(512, 2) mega(Params p) {
;     ...
;       gemm8_epi(acc8, m0, n0, [&](int m, int n, f32x4& a) {
;         uint2 pv = *(const uint2*)(ppb + (size_t)m * DM + n);
;         float4* o = (float4*)(p.out + (size_t)m * DM + n);
;         float4 xv = *o;
;         *o = make_float4(xv.x + sigmoidf(a[0]) * bflo(pv.x), xv.y + sigmoidf(a[1]) * bfhi(pv.x),
;                          xv.z + sigmoidf(a[2]) * bflo(pv.y), xv.w + sigmoidf(a[3]) * bfhi(pv.y));
;       });
	v_lshlrev_b32_e32 v142, 16, v138
	v_and_b32_e32 v143, 0xffff0000, v138
	v_lshlrev_b32_e32 v138, 16, v139
	v_and_b32_e32 v139, 0xffff0000, v139
	v_add_f32_e32 v29, 1.0, v29
	v_rcp_f32_e32 v129, v29
	v_mul_f32_e32 v29, 0xbfb8aa3b, v124
	v_exp_f32_e32 v29, v29
	s_waitcnt vmcnt(0)
	v_pk_fma_f32 v[134:135], v[140:141], v[142:143], v[134:135]
	v_pk_fma_f32 v[136:137], v[144:145], v[138:139], v[136:137]
	global_store_dwordx4 v[126:127], v[134:137], off nt
	global_load_dwordx2 v[136:137], v[130:131], off offset:32
	v_add_f32_e32 v29, 1.0, v29
	global_load_dwordx4 v[138:141], v[126:127], off offset:64
	s_waitcnt vmcnt(1)
	v_lshlrev_b32_e32 v134, 16, v136
	v_and_b32_e32 v135, 0xffff0000, v136
	v_lshlrev_b32_e32 v136, 16, v137
	v_and_b32_e32 v137, 0xffff0000, v137
	s_waitcnt vmcnt(0)
	v_pk_fma_f32 v[132:133], v[132:133], v[134:135], v[138:139]
	v_pk_fma_f32 v[134:135], v[128:129], v[136:137], v[140:141]
	global_store_dwordx4 v[126:127], v[132:135], off offset:64 nt
	global_load_dwordx2 v[128:129], v[130:131], off offset:64
	s_nop 0
	v_rcp_f32_e32 v132, v29
	v_mul_f32_e32 v29, 0xbfb8aa3b, v125
	v_exp_f32_e32 v29, v29
	s_waitcnt vmcnt(0)
	v_lshlrev_b32_e32 v134, 16, v128
	v_add_f32_e32 v29, 1.0, v29
	v_rcp_f32_e32 v133, v29
	v_mul_f32_e32 v29, 0xbfb8aa3b, v122
	v_exp_f32_e32 v29, v29
	v_and_b32_e32 v135, 0xffff0000, v128
	v_lshlrev_b32_e32 v128, 16, v129
	v_and_b32_e32 v129, 0xffff0000, v129
	v_add_f32_e32 v29, 1.0, v29
	v_rcp_f32_e32 v136, v29
	v_mul_f32_e32 v29, 0xbfb8aa3b, v123
	global_load_dwordx4 v[122:125], v[126:127], off offset:128
	v_exp_f32_e32 v29, v29
	s_waitcnt vmcnt(0)
	v_pk_fma_f32 v[122:123], v[132:133], v[134:135], v[122:123]
	v_add_f32_e32 v29, 1.0, v29
	v_rcp_f32_e32 v137, v29
	v_mul_f32_e32 v29, 0xbfb8aa3b, v120
	v_exp_f32_e32 v29, v29
	v_pk_fma_f32 v[124:125], v[136:137], v[128:129], v[124:125]
	global_store_dwordx4 v[126:127], v[122:125], off offset:128 nt
	v_add_f32_e32 v29, 1.0, v29
	global_load_dwordx2 v[122:123], v[130:131], off offset:96
	v_rcp_f32_e32 v124, v29
	v_mul_f32_e32 v29, 0xbfb8aa3b, v121
	v_exp_f32_e32 v29, v29
	s_waitcnt vmcnt(0)
	v_lshlrev_b32_e32 v128, 16, v122
	v_add_f32_e32 v29, 1.0, v29
	v_rcp_f32_e32 v125, v29
	v_mul_f32_e32 v29, 0xbfb8aa3b, v118
	v_exp_f32_e32 v29, v29
	v_and_b32_e32 v129, 0xffff0000, v122
	v_lshlrev_b32_e32 v122, 16, v123
	v_and_b32_e32 v123, 0xffff0000, v123
	v_add_f32_e32 v29, 1.0, v29
	v_rcp_f32_e32 v130, v29
	v_mul_f32_e32 v29, 0xbfb8aa3b, v119
	global_load_dwordx4 v[118:121], v[126:127], off offset:192
	v_exp_f32_e32 v29, v29
	s_waitcnt vmcnt(0)
	v_pk_fma_f32 v[118:119], v[124:125], v[128:129], v[118:119]
	v_add_f32_e32 v29, 1.0, v29
	v_rcp_f32_e32 v131, v29
	v_mul_f32_e32 v29, 0xbfb8aa3b, v116
	v_exp_f32_e32 v29, v29
	v_pk_fma_f32 v[120:121], v[130:131], v[122:123], v[120:121]
	global_store_dwordx4 v[126:127], v[118:121], off offset:192 nt
	v_add_f32_e32 v29, 1.0, v29
	v_rcp_f32_e32 v124, v29
	v_mul_f32_e32 v29, 0xbfb8aa3b, v117
	v_exp_f32_e32 v29, v29
	v_or_b32_e32 v118, 16, v28
	v_ashrrev_i32_e32 v119, 31, v118
	v_lshlrev_b64 v[120:121], 11, v[118:119]
	v_add_f32_e32 v29, 1.0, v29
	v_rcp_f32_e32 v125, v29
	v_mul_f32_e32 v29, 0xbfb8aa3b, v114
	v_exp_f32_e32 v29, v29
	v_lshl_add_u64 v[120:121], s[12:13], 0, v[120:121]
	v_lshlrev_b64 v[118:119], 12, v[118:119]
	v_lshl_add_u64 v[120:121], v[120:121], 0, v[0:1]
	v_lshl_add_u64 v[118:119], s[2:3], 0, v[118:119]
	global_load_dwordx2 v[122:123], v[120:121], off
	v_lshl_add_u64 v[118:119], v[118:119], 0, v[22:23]
	v_add_f32_e32 v29, 1.0, v29
	v_rcp_f32_e32 v128, v29
	v_mul_f32_e32 v29, 0xbfb8aa3b, v115
	global_load_dwordx4 v[114:117], v[118:119], off
	v_exp_f32_e32 v29, v29
	s_waitcnt vmcnt(1)
	v_lshlrev_b32_e32 v126, 16, v122
	v_add_f32_e32 v29, 1.0, v29
	v_rcp_f32_e32 v129, v29
	v_and_b32_e32 v127, 0xffff0000, v122
	v_lshlrev_b32_e32 v122, 16, v123
	v_and_b32_e32 v123, 0xffff0000, v123
	s_waitcnt vmcnt(0)
	v_pk_fma_f32 v[114:115], v[124:125], v[126:127], v[114:115]
	v_pk_fma_f32 v[116:117], v[128:129], v[122:123], v[116:117]
	global_store_dwordx4 v[118:119], v[114:117], off nt
	global_load_dwordx2 v[116:117], v[120:121], off offset:32
	v_mul_f32_e32 v29, 0xbfb8aa3b, v112
	global_load_dwordx4 v[122:125], v[118:119], off offset:64
	v_exp_f32_e32 v29, v29
	s_waitcnt vmcnt(1)
	v_lshlrev_b32_e32 v114, 16, v116
	v_add_f32_e32 v29, 1.0, v29
	v_rcp_f32_e32 v112, v29
	v_mul_f32_e32 v29, 0xbfb8aa3b, v113
	v_exp_f32_e32 v29, v29
	v_and_b32_e32 v115, 0xffff0000, v116
	v_lshlrev_b32_e32 v116, 16, v117
	v_and_b32_e32 v117, 0xffff0000, v117
	v_add_f32_e32 v29, 1.0, v29
	v_rcp_f32_e32 v113, v29
	v_mul_f32_e32 v29, 0xbfb8aa3b, v110
	v_exp_f32_e32 v29, v29
	s_waitcnt vmcnt(0)
	v_pk_fma_f32 v[112:113], v[112:113], v[114:115], v[122:123]
	v_add_f32_e32 v29, 1.0, v29
	v_rcp_f32_e32 v110, v29
	v_mul_f32_e32 v29, 0xbfb8aa3b, v111
	v_exp_f32_e32 v29, v29
	s_nop 0
	v_add_f32_e32 v29, 1.0, v29
	v_rcp_f32_e32 v111, v29
	v_mul_f32_e32 v29, 0xbfb8aa3b, v108
	v_exp_f32_e32 v29, v29
	v_pk_fma_f32 v[114:115], v[110:111], v[116:117], v[124:125]
	global_store_dwordx4 v[118:119], v[112:115], off offset:64 nt
	v_add_f32_e32 v29, 1.0, v29
	global_load_dwordx2 v[110:111], v[120:121], off offset:64
	v_rcp_f32_e32 v112, v29
	v_mul_f32_e32 v29, 0xbfb8aa3b, v109
	v_exp_f32_e32 v29, v29
	s_waitcnt vmcnt(0)
	v_lshlrev_b32_e32 v114, 16, v110
	v_add_f32_e32 v29, 1.0, v29
	v_rcp_f32_e32 v113, v29
	v_mul_f32_e32 v29, 0xbfb8aa3b, v106
	v_exp_f32_e32 v29, v29
	v_and_b32_e32 v115, 0xffff0000, v110
	v_lshlrev_b32_e32 v110, 16, v111
	v_and_b32_e32 v111, 0xffff0000, v111
	v_add_f32_e32 v29, 1.0, v29
	v_rcp_f32_e32 v116, v29
	v_mul_f32_e32 v29, 0xbfb8aa3b, v107
	global_load_dwordx4 v[106:109], v[118:119], off offset:128
	v_exp_f32_e32 v29, v29
	s_waitcnt vmcnt(0)
; DI float bflo(unsigned u) { return __uint_as_float(u << 16); }
; DI float bfhi(unsigned u) { return __uint_as_float(u & 0xffff0000u); }
; DI float sigmoidf(float x) { return __builtin_amdgcn_rcpf(1.f + __expf(-x)); }
; __global__ void __launch_bounds__(512, 2) mega(Params p) {
;     ...
;       gemm8_epi(acc8, m0, n0, [&](int m, int n, f32x4& a) {
;         uint2 pv = *(const uint2*)(ppb + (size_t)m * DM + n);
;         float4* o = (float4*)(p.out + (size_t)m * DM + n);
;         float4 xv = *o;
;         *o = make_float4(xv.x + sigmoidf(a[0]) * bflo(pv.x), xv.y + sigmoidf(a[1]) * bfhi(pv.x),
;                          xv.z + sigmoidf(a[2]) * bflo(pv.y), xv.w + sigmoidf(a[3]) * bfhi(pv.y));
;       });
	v_pk_fma_f32 v[106:107], v[112:113], v[114:115], v[106:107]
	v_add_f32_e32 v29, 1.0, v29
	v_rcp_f32_e32 v117, v29
	v_mul_f32_e32 v29, 0xbfb8aa3b, v104
	v_exp_f32_e32 v29, v29
	v_pk_fma_f32 v[108:109], v[116:117], v[110:111], v[108:109]
	global_store_dwordx4 v[118:119], v[106:109], off offset:128 nt
	v_add_f32_e32 v29, 1.0, v29
	global_load_dwordx2 v[106:107], v[120:121], off offset:96
	v_rcp_f32_e32 v108, v29
	v_mul_f32_e32 v29, 0xbfb8aa3b, v105
	v_exp_f32_e32 v29, v29
	s_waitcnt vmcnt(0)
	v_lshlrev_b32_e32 v110, 16, v106
	v_add_f32_e32 v29, 1.0, v29
	v_rcp_f32_e32 v109, v29
	v_mul_f32_e32 v29, 0xbfb8aa3b, v102
	v_exp_f32_e32 v29, v29
	v_and_b32_e32 v111, 0xffff0000, v106
	v_lshlrev_b32_e32 v106, 16, v107
	v_and_b32_e32 v107, 0xffff0000, v107
	v_add_f32_e32 v29, 1.0, v29
	v_rcp_f32_e32 v112, v29
	v_mul_f32_e32 v29, 0xbfb8aa3b, v103
	global_load_dwordx4 v[102:105], v[118:119], off offset:192
	v_exp_f32_e32 v29, v29
	s_waitcnt vmcnt(0)
	v_pk_fma_f32 v[102:103], v[108:109], v[110:111], v[102:103]
	v_add_f32_e32 v29, 1.0, v29
	v_rcp_f32_e32 v113, v29
	v_mul_f32_e32 v29, 0xbfb8aa3b, v100
	v_exp_f32_e32 v29, v29
	v_pk_fma_f32 v[104:105], v[112:113], v[106:107], v[104:105]
	global_store_dwordx4 v[118:119], v[102:105], off offset:192 nt
	v_add_f32_e32 v29, 1.0, v29
	v_rcp_f32_e32 v108, v29
	v_mul_f32_e32 v29, 0xbfb8aa3b, v101
	v_exp_f32_e32 v29, v29
	v_or_b32_e32 v102, 32, v28
	v_ashrrev_i32_e32 v103, 31, v102
	v_lshlrev_b64 v[104:105], 11, v[102:103]
	v_add_f32_e32 v29, 1.0, v29
	v_rcp_f32_e32 v109, v29
	v_mul_f32_e32 v29, 0xbfb8aa3b, v98
	v_exp_f32_e32 v29, v29
	v_lshl_add_u64 v[104:105], s[12:13], 0, v[104:105]
	v_lshlrev_b64 v[102:103], 12, v[102:103]
	v_lshl_add_u64 v[104:105], v[104:105], 0, v[0:1]
	v_lshl_add_u64 v[102:103], s[2:3], 0, v[102:103]
	global_load_dwordx2 v[106:107], v[104:105], off
	v_lshl_add_u64 v[102:103], v[102:103], 0, v[22:23]
	v_add_f32_e32 v29, 1.0, v29
	v_rcp_f32_e32 v112, v29
	v_mul_f32_e32 v29, 0xbfb8aa3b, v99
	global_load_dwordx4 v[98:101], v[102:103], off
	v_exp_f32_e32 v29, v29
	s_waitcnt vmcnt(1)
	v_lshlrev_b32_e32 v110, 16, v106
	v_add_f32_e32 v29, 1.0, v29
	v_rcp_f32_e32 v113, v29
	v_and_b32_e32 v111, 0xffff0000, v106
	v_lshlrev_b32_e32 v106, 16, v107
	v_and_b32_e32 v107, 0xffff0000, v107
	s_waitcnt vmcnt(0)
	v_pk_fma_f32 v[98:99], v[108:109], v[110:111], v[98:99]
	v_pk_fma_f32 v[100:101], v[112:113], v[106:107], v[100:101]
	global_store_dwordx4 v[102:103], v[98:101], off nt
	global_load_dwordx2 v[100:101], v[104:105], off offset:32
	v_mul_f32_e32 v29, 0xbfb8aa3b, v96
	global_load_dwordx4 v[106:109], v[102:103], off offset:64
	v_exp_f32_e32 v29, v29
	s_waitcnt vmcnt(1)
	v_lshlrev_b32_e32 v98, 16, v100
	v_add_f32_e32 v29, 1.0, v29
	v_rcp_f32_e32 v96, v29
	v_mul_f32_e32 v29, 0xbfb8aa3b, v97
	v_exp_f32_e32 v29, v29
	v_and_b32_e32 v99, 0xffff0000, v100
	v_lshlrev_b32_e32 v100, 16, v101
	v_and_b32_e32 v101, 0xffff0000, v101
	v_add_f32_e32 v29, 1.0, v29
	v_rcp_f32_e32 v97, v29
	v_mul_f32_e32 v29, 0xbfb8aa3b, v94
	v_exp_f32_e32 v29, v29
	s_waitcnt vmcnt(0)
	v_pk_fma_f32 v[96:97], v[96:97], v[98:99], v[106:107]
	v_add_f32_e32 v29, 1.0, v29
	v_rcp_f32_e32 v94, v29
	v_mul_f32_e32 v29, 0xbfb8aa3b, v95
	v_exp_f32_e32 v29, v29
	s_nop 0
	v_add_f32_e32 v29, 1.0, v29
	v_rcp_f32_e32 v95, v29
	v_mul_f32_e32 v29, 0xbfb8aa3b, v92
	v_exp_f32_e32 v29, v29
	v_pk_fma_f32 v[98:99], v[94:95], v[100:101], v[108:109]
	global_store_dwordx4 v[102:103], v[96:99], off offset:64 nt
	v_add_f32_e32 v29, 1.0, v29
	global_load_dwordx2 v[94:95], v[104:105], off offset:64
	v_rcp_f32_e32 v96, v29
	v_mul_f32_e32 v29, 0xbfb8aa3b, v93
	v_exp_f32_e32 v29, v29
	s_waitcnt vmcnt(0)
	v_lshlrev_b32_e32 v98, 16, v94
	v_add_f32_e32 v29, 1.0, v29
	v_rcp_f32_e32 v97, v29
	v_mul_f32_e32 v29, 0xbfb8aa3b, v90
	v_exp_f32_e32 v29, v29
	v_and_b32_e32 v99, 0xffff0000, v94
	v_lshlrev_b32_e32 v94, 16, v95
	v_and_b32_e32 v95, 0xffff0000, v95
	v_add_f32_e32 v29, 1.0, v29
	v_rcp_f32_e32 v100, v29
	v_mul_f32_e32 v29, 0xbfb8aa3b, v91
	global_load_dwordx4 v[90:93], v[102:103], off offset:128
	v_exp_f32_e32 v29, v29
	s_waitcnt vmcnt(0)
	v_pk_fma_f32 v[90:91], v[96:97], v[98:99], v[90:91]
	v_add_f32_e32 v29, 1.0, v29
	v_rcp_f32_e32 v101, v29
	v_mul_f32_e32 v29, 0xbfb8aa3b, v88
	v_exp_f32_e32 v29, v29
	v_pk_fma_f32 v[92:93], v[100:101], v[94:95], v[92:93]
	global_store_dwordx4 v[102:103], v[90:93], off offset:128 nt
	v_add_f32_e32 v29, 1.0, v29
	global_load_dwordx2 v[90:91], v[104:105], off offset:96
	v_rcp_f32_e32 v92, v29
	v_mul_f32_e32 v29, 0xbfb8aa3b, v89
	v_exp_f32_e32 v29, v29
	s_waitcnt vmcnt(0)
	v_lshlrev_b32_e32 v94, 16, v90
	v_add_f32_e32 v29, 1.0, v29
	v_rcp_f32_e32 v93, v29
	v_mul_f32_e32 v29, 0xbfb8aa3b, v86
	v_exp_f32_e32 v29, v29
	v_and_b32_e32 v95, 0xffff0000, v90
	v_lshlrev_b32_e32 v90, 16, v91
	v_and_b32_e32 v91, 0xffff0000, v91
	v_add_f32_e32 v29, 1.0, v29
	v_rcp_f32_e32 v96, v29
	v_mul_f32_e32 v29, 0xbfb8aa3b, v87
	global_load_dwordx4 v[86:89], v[102:103], off offset:192
	v_exp_f32_e32 v29, v29
	s_waitcnt vmcnt(0)
	v_pk_fma_f32 v[86:87], v[92:93], v[94:95], v[86:87]
	v_add_f32_e32 v29, 1.0, v29
	v_rcp_f32_e32 v97, v29
	v_mul_f32_e32 v29, 0xbfb8aa3b, v84
	v_exp_f32_e32 v29, v29
	v_pk_fma_f32 v[88:89], v[96:97], v[90:91], v[88:89]
	global_store_dwordx4 v[102:103], v[86:89], off offset:192 nt
	v_add_f32_e32 v29, 1.0, v29
	v_rcp_f32_e32 v92, v29
	v_mul_f32_e32 v29, 0xbfb8aa3b, v85
	v_exp_f32_e32 v29, v29
	v_or_b32_e32 v86, 48, v28
	v_ashrrev_i32_e32 v87, 31, v86
	v_lshlrev_b64 v[88:89], 11, v[86:87]
	v_add_f32_e32 v29, 1.0, v29
	v_rcp_f32_e32 v93, v29
	v_mul_f32_e32 v29, 0xbfb8aa3b, v82
	v_exp_f32_e32 v29, v29
	v_lshl_add_u64 v[88:89], s[12:13], 0, v[88:89]
	v_lshlrev_b64 v[86:87], 12, v[86:87]
	v_lshl_add_u64 v[88:89], v[88:89], 0, v[0:1]
	v_lshl_add_u64 v[86:87], s[2:3], 0, v[86:87]
	global_load_dwordx2 v[90:91], v[88:89], off
	v_lshl_add_u64 v[86:87], v[86:87], 0, v[22:23]
	v_add_f32_e32 v29, 1.0, v29
	v_rcp_f32_e32 v96, v29
	v_mul_f32_e32 v29, 0xbfb8aa3b, v83
	global_load_dwordx4 v[82:85], v[86:87], off
	v_exp_f32_e32 v29, v29
	s_waitcnt vmcnt(1)
; DI float bflo(unsigned u) { return __uint_as_float(u << 16); }
; DI float bfhi(unsigned u) { return __uint_as_float(u & 0xffff0000u); }
; DI float sigmoidf(float x) { return __builtin_amdgcn_rcpf(1.f + __expf(-x)); }
; __global__ void __launch_bounds__(512, 2) mega(Params p) {
;     ...
;       gemm8_epi(acc8, m0, n0, [&](int m, int n, f32x4& a) {
;         uint2 pv = *(const uint2*)(ppb + (size_t)m * DM + n);
;         float4* o = (float4*)(p.out + (size_t)m * DM + n);
;         float4 xv = *o;
;         *o = make_float4(xv.x + sigmoidf(a[0]) * bflo(pv.x), xv.y + sigmoidf(a[1]) * bfhi(pv.x),
;                          xv.z + sigmoidf(a[2]) * bflo(pv.y), xv.w + sigmoidf(a[3]) * bfhi(pv.y));
;       });
	v_lshlrev_b32_e32 v94, 16, v90
	v_add_f32_e32 v29, 1.0, v29
	v_rcp_f32_e32 v97, v29
	v_and_b32_e32 v95, 0xffff0000, v90
	v_lshlrev_b32_e32 v90, 16, v91
	v_and_b32_e32 v91, 0xffff0000, v91
	s_waitcnt vmcnt(0)
	v_pk_fma_f32 v[82:83], v[92:93], v[94:95], v[82:83]
	v_pk_fma_f32 v[84:85], v[96:97], v[90:91], v[84:85]
	global_store_dwordx4 v[86:87], v[82:85], off nt
	global_load_dwordx2 v[84:85], v[88:89], off offset:32
	v_mul_f32_e32 v29, 0xbfb8aa3b, v80
	global_load_dwordx4 v[90:93], v[86:87], off offset:64
	v_exp_f32_e32 v29, v29
	s_waitcnt vmcnt(1)
	v_lshlrev_b32_e32 v82, 16, v84
	v_add_f32_e32 v29, 1.0, v29
	v_rcp_f32_e32 v80, v29
	v_mul_f32_e32 v29, 0xbfb8aa3b, v81
	v_exp_f32_e32 v29, v29
	v_and_b32_e32 v83, 0xffff0000, v84
	v_lshlrev_b32_e32 v84, 16, v85
	v_and_b32_e32 v85, 0xffff0000, v85
	v_add_f32_e32 v29, 1.0, v29
	v_rcp_f32_e32 v81, v29
	v_mul_f32_e32 v29, 0xbfb8aa3b, v78
	v_exp_f32_e32 v29, v29
	s_waitcnt vmcnt(0)
	v_pk_fma_f32 v[80:81], v[80:81], v[82:83], v[90:91]
	v_add_f32_e32 v29, 1.0, v29
	v_rcp_f32_e32 v78, v29
	v_mul_f32_e32 v29, 0xbfb8aa3b, v79
	v_exp_f32_e32 v29, v29
	s_nop 0
	v_add_f32_e32 v29, 1.0, v29
	v_rcp_f32_e32 v79, v29
	v_mul_f32_e32 v29, 0xbfb8aa3b, v76
	v_exp_f32_e32 v29, v29
	v_pk_fma_f32 v[82:83], v[78:79], v[84:85], v[92:93]
	global_store_dwordx4 v[86:87], v[80:83], off offset:64 nt
	v_add_f32_e32 v29, 1.0, v29
	global_load_dwordx2 v[78:79], v[88:89], off offset:64
	v_rcp_f32_e32 v80, v29
	v_mul_f32_e32 v29, 0xbfb8aa3b, v77
	v_exp_f32_e32 v29, v29
	s_waitcnt vmcnt(0)
	v_lshlrev_b32_e32 v82, 16, v78
	v_add_f32_e32 v29, 1.0, v29
	v_rcp_f32_e32 v81, v29
	v_mul_f32_e32 v29, 0xbfb8aa3b, v74
	v_exp_f32_e32 v29, v29
	v_and_b32_e32 v83, 0xffff0000, v78
	v_lshlrev_b32_e32 v78, 16, v79
	v_and_b32_e32 v79, 0xffff0000, v79
	v_add_f32_e32 v29, 1.0, v29
	v_rcp_f32_e32 v84, v29
	v_mul_f32_e32 v29, 0xbfb8aa3b, v75
	global_load_dwordx4 v[74:77], v[86:87], off offset:128
	v_exp_f32_e32 v29, v29
	s_waitcnt vmcnt(0)
	v_pk_fma_f32 v[74:75], v[80:81], v[82:83], v[74:75]
	v_add_f32_e32 v29, 1.0, v29
	v_rcp_f32_e32 v85, v29
	v_mul_f32_e32 v29, 0xbfb8aa3b, v72
	v_exp_f32_e32 v29, v29
	v_pk_fma_f32 v[76:77], v[84:85], v[78:79], v[76:77]
	global_store_dwordx4 v[86:87], v[74:77], off offset:128 nt
	v_add_f32_e32 v29, 1.0, v29
	global_load_dwordx2 v[74:75], v[88:89], off offset:96
	v_rcp_f32_e32 v76, v29
	v_mul_f32_e32 v29, 0xbfb8aa3b, v73
	v_exp_f32_e32 v29, v29
	s_waitcnt vmcnt(0)
	v_lshlrev_b32_e32 v78, 16, v74
	v_add_f32_e32 v29, 1.0, v29
	v_rcp_f32_e32 v77, v29
	v_mul_f32_e32 v29, 0xbfb8aa3b, v70
	v_exp_f32_e32 v29, v29
	v_and_b32_e32 v79, 0xffff0000, v74
	v_lshlrev_b32_e32 v74, 16, v75
	v_and_b32_e32 v75, 0xffff0000, v75
	v_add_f32_e32 v29, 1.0, v29
	v_rcp_f32_e32 v80, v29
	v_mul_f32_e32 v29, 0xbfb8aa3b, v71
	global_load_dwordx4 v[70:73], v[86:87], off offset:192
	v_exp_f32_e32 v29, v29
	s_waitcnt vmcnt(0)
	v_pk_fma_f32 v[70:71], v[76:77], v[78:79], v[70:71]
	v_add_f32_e32 v29, 1.0, v29
	v_rcp_f32_e32 v81, v29
	v_mul_f32_e32 v29, 0xbfb8aa3b, v68
	v_exp_f32_e32 v29, v29
	v_pk_fma_f32 v[72:73], v[80:81], v[74:75], v[72:73]
	global_store_dwordx4 v[86:87], v[70:73], off offset:192 nt
	v_add_f32_e32 v29, 1.0, v29
	v_rcp_f32_e32 v76, v29
	v_mul_f32_e32 v29, 0xbfb8aa3b, v69
	v_exp_f32_e32 v29, v29
	v_or_b32_e32 v70, 64, v28
	v_ashrrev_i32_e32 v71, 31, v70
	v_lshlrev_b64 v[72:73], 11, v[70:71]
	v_add_f32_e32 v29, 1.0, v29
	v_rcp_f32_e32 v77, v29
	v_mul_f32_e32 v29, 0xbfb8aa3b, v66
	v_exp_f32_e32 v29, v29
	v_lshl_add_u64 v[72:73], s[12:13], 0, v[72:73]
	v_lshlrev_b64 v[70:71], 12, v[70:71]
	v_lshl_add_u64 v[72:73], v[72:73], 0, v[0:1]
	v_lshl_add_u64 v[70:71], s[2:3], 0, v[70:71]
	global_load_dwordx2 v[74:75], v[72:73], off
	v_lshl_add_u64 v[70:71], v[70:71], 0, v[22:23]
	v_add_f32_e32 v29, 1.0, v29
	v_rcp_f32_e32 v80, v29
	v_mul_f32_e32 v29, 0xbfb8aa3b, v67
	global_load_dwordx4 v[66:69], v[70:71], off
	v_exp_f32_e32 v29, v29
	s_waitcnt vmcnt(1)
	v_lshlrev_b32_e32 v78, 16, v74
	v_add_f32_e32 v29, 1.0, v29
	v_rcp_f32_e32 v81, v29
	v_and_b32_e32 v79, 0xffff0000, v74
	v_lshlrev_b32_e32 v74, 16, v75
	v_and_b32_e32 v75, 0xffff0000, v75
	s_waitcnt vmcnt(0)
	v_pk_fma_f32 v[66:67], v[76:77], v[78:79], v[66:67]
	v_pk_fma_f32 v[68:69], v[80:81], v[74:75], v[68:69]
	global_store_dwordx4 v[70:71], v[66:69], off nt
	global_load_dwordx2 v[68:69], v[72:73], off offset:32
	v_mul_f32_e32 v29, 0xbfb8aa3b, v64
	global_load_dwordx4 v[74:77], v[70:71], off offset:64
	v_exp_f32_e32 v29, v29
	s_waitcnt vmcnt(1)
	v_lshlrev_b32_e32 v66, 16, v68
	v_add_f32_e32 v29, 1.0, v29
	v_rcp_f32_e32 v64, v29
	v_mul_f32_e32 v29, 0xbfb8aa3b, v65
	v_exp_f32_e32 v29, v29
	v_and_b32_e32 v67, 0xffff0000, v68
	v_lshlrev_b32_e32 v68, 16, v69
	v_and_b32_e32 v69, 0xffff0000, v69
	v_add_f32_e32 v29, 1.0, v29
	v_rcp_f32_e32 v65, v29
	v_mul_f32_e32 v29, 0xbfb8aa3b, v62
	v_exp_f32_e32 v29, v29
	s_waitcnt vmcnt(0)
	v_pk_fma_f32 v[64:65], v[64:65], v[66:67], v[74:75]
	v_add_f32_e32 v29, 1.0, v29
	v_rcp_f32_e32 v62, v29
	v_mul_f32_e32 v29, 0xbfb8aa3b, v63
	v_exp_f32_e32 v29, v29
	s_nop 0
	v_add_f32_e32 v29, 1.0, v29
	v_rcp_f32_e32 v63, v29
	v_mul_f32_e32 v29, 0xbfb8aa3b, v60
	v_exp_f32_e32 v29, v29
	v_pk_fma_f32 v[66:67], v[62:63], v[68:69], v[76:77]
	global_store_dwordx4 v[70:71], v[64:67], off offset:64 nt
	v_add_f32_e32 v29, 1.0, v29
	global_load_dwordx2 v[62:63], v[72:73], off offset:64
	v_rcp_f32_e32 v64, v29
	v_mul_f32_e32 v29, 0xbfb8aa3b, v61
	v_exp_f32_e32 v29, v29
	s_waitcnt vmcnt(0)
; DI float bflo(unsigned u) { return __uint_as_float(u << 16); }
; DI float bfhi(unsigned u) { return __uint_as_float(u & 0xffff0000u); }
; DI float sigmoidf(float x) { return __builtin_amdgcn_rcpf(1.f + __expf(-x)); }
; __global__ void __launch_bounds__(512, 2) mega(Params p) {
;     ...
;       gemm8_epi(acc8, m0, n0, [&](int m, int n, f32x4& a) {
;         uint2 pv = *(const uint2*)(ppb + (size_t)m * DM + n);
;         float4* o = (float4*)(p.out + (size_t)m * DM + n);
;         float4 xv = *o;
;         *o = make_float4(xv.x + sigmoidf(a[0]) * bflo(pv.x), xv.y + sigmoidf(a[1]) * bfhi(pv.x),
;                          xv.z + sigmoidf(a[2]) * bflo(pv.y), xv.w + sigmoidf(a[3]) * bfhi(pv.y));
;       });
	v_lshlrev_b32_e32 v66, 16, v62
	v_add_f32_e32 v29, 1.0, v29
	v_rcp_f32_e32 v65, v29
	v_mul_f32_e32 v29, 0xbfb8aa3b, v58
	v_exp_f32_e32 v29, v29
	v_and_b32_e32 v67, 0xffff0000, v62
	v_lshlrev_b32_e32 v62, 16, v63
	v_and_b32_e32 v63, 0xffff0000, v63
	v_add_f32_e32 v29, 1.0, v29
	v_rcp_f32_e32 v68, v29
	v_mul_f32_e32 v29, 0xbfb8aa3b, v59
	global_load_dwordx4 v[58:61], v[70:71], off offset:128
	v_exp_f32_e32 v29, v29
	s_waitcnt vmcnt(0)
	v_pk_fma_f32 v[58:59], v[64:65], v[66:67], v[58:59]
	v_add_f32_e32 v29, 1.0, v29
	v_rcp_f32_e32 v69, v29
	v_mul_f32_e32 v29, 0xbfb8aa3b, v56
	v_exp_f32_e32 v29, v29
	v_pk_fma_f32 v[60:61], v[68:69], v[62:63], v[60:61]
	global_store_dwordx4 v[70:71], v[58:61], off offset:128 nt
	v_add_f32_e32 v29, 1.0, v29
	global_load_dwordx2 v[58:59], v[72:73], off offset:96
	v_rcp_f32_e32 v60, v29
	v_mul_f32_e32 v29, 0xbfb8aa3b, v57
	v_exp_f32_e32 v29, v29
	s_waitcnt vmcnt(0)
	v_lshlrev_b32_e32 v62, 16, v58
	v_add_f32_e32 v29, 1.0, v29
	v_rcp_f32_e32 v61, v29
	v_mul_f32_e32 v29, 0xbfb8aa3b, v54
	v_exp_f32_e32 v29, v29
	v_and_b32_e32 v63, 0xffff0000, v58
	v_lshlrev_b32_e32 v58, 16, v59
	v_and_b32_e32 v59, 0xffff0000, v59
	v_add_f32_e32 v29, 1.0, v29
	v_rcp_f32_e32 v64, v29
	v_mul_f32_e32 v29, 0xbfb8aa3b, v55
	global_load_dwordx4 v[54:57], v[70:71], off offset:192
	v_exp_f32_e32 v29, v29
	s_waitcnt vmcnt(0)
	v_pk_fma_f32 v[54:55], v[60:61], v[62:63], v[54:55]
	v_add_f32_e32 v29, 1.0, v29
	v_rcp_f32_e32 v65, v29
	v_mul_f32_e32 v29, 0xbfb8aa3b, v52
	v_exp_f32_e32 v29, v29
	v_pk_fma_f32 v[56:57], v[64:65], v[58:59], v[56:57]
	global_store_dwordx4 v[70:71], v[54:57], off offset:192 nt
	v_add_f32_e32 v29, 1.0, v29
	v_rcp_f32_e32 v60, v29
	v_mul_f32_e32 v29, 0xbfb8aa3b, v53
	v_exp_f32_e32 v29, v29
	v_or_b32_e32 v54, 0x50, v28
	v_ashrrev_i32_e32 v55, 31, v54
	v_lshlrev_b64 v[56:57], 11, v[54:55]
	v_add_f32_e32 v29, 1.0, v29
	v_rcp_f32_e32 v61, v29
	v_mul_f32_e32 v29, 0xbfb8aa3b, v50
	v_exp_f32_e32 v29, v29
	v_lshl_add_u64 v[56:57], s[12:13], 0, v[56:57]
	v_lshlrev_b64 v[54:55], 12, v[54:55]
	v_lshl_add_u64 v[56:57], v[56:57], 0, v[0:1]
	v_lshl_add_u64 v[54:55], s[2:3], 0, v[54:55]
	global_load_dwordx2 v[58:59], v[56:57], off
	v_lshl_add_u64 v[54:55], v[54:55], 0, v[22:23]
	v_add_f32_e32 v29, 1.0, v29
	v_rcp_f32_e32 v64, v29
	v_mul_f32_e32 v29, 0xbfb8aa3b, v51
	global_load_dwordx4 v[50:53], v[54:55], off
	v_exp_f32_e32 v29, v29
	s_waitcnt vmcnt(1)
	v_lshlrev_b32_e32 v62, 16, v58
	v_add_f32_e32 v29, 1.0, v29
	v_rcp_f32_e32 v65, v29
	v_and_b32_e32 v63, 0xffff0000, v58
	v_lshlrev_b32_e32 v58, 16, v59
	v_and_b32_e32 v59, 0xffff0000, v59
	s_waitcnt vmcnt(0)
	v_pk_fma_f32 v[50:51], v[60:61], v[62:63], v[50:51]
	v_pk_fma_f32 v[52:53], v[64:65], v[58:59], v[52:53]
	global_store_dwordx4 v[54:55], v[50:53], off nt
	global_load_dwordx2 v[52:53], v[56:57], off offset:32
	v_mul_f32_e32 v29, 0xbfb8aa3b, v48
	global_load_dwordx4 v[58:61], v[54:55], off offset:64
	v_exp_f32_e32 v29, v29
	s_waitcnt vmcnt(1)
	v_lshlrev_b32_e32 v50, 16, v52
	v_add_f32_e32 v29, 1.0, v29
	v_rcp_f32_e32 v48, v29
	v_mul_f32_e32 v29, 0xbfb8aa3b, v49
	v_exp_f32_e32 v29, v29
	v_and_b32_e32 v51, 0xffff0000, v52
	v_lshlrev_b32_e32 v52, 16, v53
	v_and_b32_e32 v53, 0xffff0000, v53
	v_add_f32_e32 v29, 1.0, v29
	v_rcp_f32_e32 v49, v29
	v_mul_f32_e32 v29, 0xbfb8aa3b, v46
	v_exp_f32_e32 v29, v29
	s_waitcnt vmcnt(0)
	v_pk_fma_f32 v[48:49], v[48:49], v[50:51], v[58:59]
	v_add_f32_e32 v29, 1.0, v29
	v_rcp_f32_e32 v46, v29
	v_mul_f32_e32 v29, 0xbfb8aa3b, v47
	v_exp_f32_e32 v29, v29
	s_nop 0
	v_add_f32_e32 v29, 1.0, v29
	v_rcp_f32_e32 v47, v29
	v_mul_f32_e32 v29, 0xbfb8aa3b, v44
	v_exp_f32_e32 v29, v29
	v_pk_fma_f32 v[50:51], v[46:47], v[52:53], v[60:61]
	global_store_dwordx4 v[54:55], v[48:51], off offset:64 nt
	v_add_f32_e32 v29, 1.0, v29
	global_load_dwordx2 v[46:47], v[56:57], off offset:64
	v_rcp_f32_e32 v48, v29
	v_mul_f32_e32 v29, 0xbfb8aa3b, v45
	v_exp_f32_e32 v29, v29
	s_waitcnt vmcnt(0)
	v_lshlrev_b32_e32 v50, 16, v46
	v_add_f32_e32 v29, 1.0, v29
	v_rcp_f32_e32 v49, v29
	v_mul_f32_e32 v29, 0xbfb8aa3b, v42
	v_exp_f32_e32 v29, v29
	v_and_b32_e32 v51, 0xffff0000, v46
	v_lshlrev_b32_e32 v46, 16, v47
	v_and_b32_e32 v47, 0xffff0000, v47
	v_add_f32_e32 v29, 1.0, v29
	v_rcp_f32_e32 v52, v29
	v_mul_f32_e32 v29, 0xbfb8aa3b, v43
	global_load_dwordx4 v[42:45], v[54:55], off offset:128
	v_exp_f32_e32 v29, v29
	s_waitcnt vmcnt(0)
	v_pk_fma_f32 v[42:43], v[48:49], v[50:51], v[42:43]
	v_add_f32_e32 v29, 1.0, v29
	v_rcp_f32_e32 v53, v29
	v_mul_f32_e32 v29, 0xbfb8aa3b, v40
	v_exp_f32_e32 v29, v29
	v_pk_fma_f32 v[44:45], v[52:53], v[46:47], v[44:45]
	global_store_dwordx4 v[54:55], v[42:45], off offset:128 nt
	v_add_f32_e32 v29, 1.0, v29
	global_load_dwordx2 v[42:43], v[56:57], off offset:96
	v_rcp_f32_e32 v44, v29
	v_mul_f32_e32 v29, 0xbfb8aa3b, v41
	v_exp_f32_e32 v29, v29
	s_waitcnt vmcnt(0)
	v_lshlrev_b32_e32 v46, 16, v42
	v_add_f32_e32 v29, 1.0, v29
	v_rcp_f32_e32 v45, v29
	v_mul_f32_e32 v29, 0xbfb8aa3b, v38
	v_exp_f32_e32 v29, v29
	v_and_b32_e32 v47, 0xffff0000, v42
	v_lshlrev_b32_e32 v42, 16, v43
	v_and_b32_e32 v43, 0xffff0000, v43
	v_add_f32_e32 v29, 1.0, v29
	v_rcp_f32_e32 v48, v29
	v_mul_f32_e32 v29, 0xbfb8aa3b, v39
	global_load_dwordx4 v[38:41], v[54:55], off offset:192
	v_exp_f32_e32 v29, v29
	s_waitcnt vmcnt(0)
; DI float bflo(unsigned u) { return __uint_as_float(u << 16); }
; DI float bfhi(unsigned u) { return __uint_as_float(u & 0xffff0000u); }
; DI float sigmoidf(float x) { return __builtin_amdgcn_rcpf(1.f + __expf(-x)); }
; __global__ void __launch_bounds__(512, 2) mega(Params p) {
;     ...
;       gemm8_epi(acc8, m0, n0, [&](int m, int n, f32x4& a) {
;         uint2 pv = *(const uint2*)(ppb + (size_t)m * DM + n);
;         float4* o = (float4*)(p.out + (size_t)m * DM + n);
;         float4 xv = *o;
;         *o = make_float4(xv.x + sigmoidf(a[0]) * bflo(pv.x), xv.y + sigmoidf(a[1]) * bfhi(pv.x),
;                          xv.z + sigmoidf(a[2]) * bflo(pv.y), xv.w + sigmoidf(a[3]) * bfhi(pv.y));
;       });
	v_pk_fma_f32 v[38:39], v[44:45], v[46:47], v[38:39]
	v_add_f32_e32 v29, 1.0, v29
	v_rcp_f32_e32 v49, v29
	v_mul_f32_e32 v29, 0xbfb8aa3b, v36
	v_exp_f32_e32 v29, v29
	v_pk_fma_f32 v[40:41], v[48:49], v[42:43], v[40:41]
	global_store_dwordx4 v[54:55], v[38:41], off offset:192 nt
	v_add_f32_e32 v29, 1.0, v29
	v_rcp_f32_e32 v44, v29
	v_mul_f32_e32 v29, 0xbfb8aa3b, v37
	v_exp_f32_e32 v29, v29
	v_or_b32_e32 v38, 0x60, v28
	v_ashrrev_i32_e32 v39, 31, v38
	v_lshlrev_b64 v[40:41], 11, v[38:39]
	v_add_f32_e32 v29, 1.0, v29
	v_rcp_f32_e32 v45, v29
	v_mul_f32_e32 v29, 0xbfb8aa3b, v34
	v_exp_f32_e32 v29, v29
	v_lshl_add_u64 v[40:41], s[12:13], 0, v[40:41]
	v_lshlrev_b64 v[38:39], 12, v[38:39]
	v_lshl_add_u64 v[40:41], v[40:41], 0, v[0:1]
	v_lshl_add_u64 v[38:39], s[2:3], 0, v[38:39]
	global_load_dwordx2 v[42:43], v[40:41], off
	v_lshl_add_u64 v[38:39], v[38:39], 0, v[22:23]
	v_add_f32_e32 v29, 1.0, v29
	v_rcp_f32_e32 v48, v29
	v_mul_f32_e32 v29, 0xbfb8aa3b, v35
	global_load_dwordx4 v[34:37], v[38:39], off
	v_exp_f32_e32 v29, v29
	s_waitcnt vmcnt(1)
	v_lshlrev_b32_e32 v46, 16, v42
	v_add_f32_e32 v29, 1.0, v29
	v_rcp_f32_e32 v49, v29
	v_and_b32_e32 v47, 0xffff0000, v42
	v_lshlrev_b32_e32 v42, 16, v43
	v_and_b32_e32 v43, 0xffff0000, v43
	s_waitcnt vmcnt(0)
	v_pk_fma_f32 v[34:35], v[44:45], v[46:47], v[34:35]
	v_pk_fma_f32 v[36:37], v[48:49], v[42:43], v[36:37]
	global_store_dwordx4 v[38:39], v[34:37], off nt
	global_load_dwordx2 v[36:37], v[40:41], off offset:32
	v_mul_f32_e32 v29, 0xbfb8aa3b, v32
	global_load_dwordx4 v[42:45], v[38:39], off offset:64
	v_exp_f32_e32 v29, v29
	s_waitcnt vmcnt(1)
	v_lshlrev_b32_e32 v34, 16, v36
	v_add_f32_e32 v29, 1.0, v29
	v_rcp_f32_e32 v32, v29
	v_mul_f32_e32 v29, 0xbfb8aa3b, v33
	v_exp_f32_e32 v29, v29
	v_and_b32_e32 v35, 0xffff0000, v36
	v_lshlrev_b32_e32 v36, 16, v37
	v_and_b32_e32 v37, 0xffff0000, v37
	v_add_f32_e32 v29, 1.0, v29
	v_rcp_f32_e32 v33, v29
	v_mul_f32_e32 v29, 0xbfb8aa3b, v30
	v_exp_f32_e32 v29, v29
	s_waitcnt vmcnt(0)
	v_pk_fma_f32 v[32:33], v[32:33], v[34:35], v[42:43]
	v_add_f32_e32 v29, 1.0, v29
	v_rcp_f32_e32 v30, v29
	v_mul_f32_e32 v29, 0xbfb8aa3b, v31
	v_exp_f32_e32 v29, v29
	s_nop 0
	v_add_f32_e32 v29, 1.0, v29
	v_rcp_f32_e32 v31, v29
	s_nop 0
	v_pk_fma_f32 v[34:35], v[30:31], v[36:37], v[44:45]
	global_store_dwordx4 v[38:39], v[32:35], off offset:64 nt
	v_rcp_f32_e32 v36, v24
	v_mul_f32_e32 v24, 0xbfb8aa3b, v25
	v_rcp_f32_e32 v32, v26
	v_mul_f32_e32 v26, 0xbfb8aa3b, v27
	v_exp_f32_e32 v26, v26
	v_exp_f32_e32 v24, v24
	global_load_dwordx2 v[30:31], v[40:41], off offset:64
	v_add_f32_e32 v26, 1.0, v26
	v_add_f32_e32 v24, 1.0, v24
	v_rcp_f32_e32 v33, v26
	v_rcp_f32_e32 v37, v24
	global_load_dwordx4 v[24:27], v[38:39], off offset:128
	s_waitcnt vmcnt(1)
	v_lshlrev_b32_e32 v34, 16, v30
	v_and_b32_e32 v35, 0xffff0000, v30
	v_lshlrev_b32_e32 v30, 16, v31
	v_and_b32_e32 v31, 0xffff0000, v31
	s_waitcnt vmcnt(0)
	v_pk_fma_f32 v[24:25], v[32:33], v[34:35], v[24:25]
	v_pk_fma_f32 v[26:27], v[36:37], v[30:31], v[26:27]
	global_store_dwordx4 v[38:39], v[24:27], off offset:128 nt
	global_load_dwordx2 v[24:25], v[40:41], off offset:96
	s_waitcnt vmcnt(0)
	v_lshlrev_b32_e32 v30, 16, v24
	v_rcp_f32_e32 v26, v18
	v_mul_f32_e32 v18, 0xbfb8aa3b, v19
	v_exp_f32_e32 v18, v18
	v_and_b32_e32 v31, 0xffff0000, v24
	v_lshlrev_b32_e32 v24, 16, v25
	v_and_b32_e32 v25, 0xffff0000, v25
	v_add_f32_e32 v18, 1.0, v18
	v_rcp_f32_e32 v27, v18
	v_mul_f32_e32 v18, 0xbfb8aa3b, v20
	v_exp_f32_e32 v18, v18
	s_nop 0
	v_add_f32_e32 v18, 1.0, v18
	v_rcp_f32_e32 v32, v18
	v_mul_f32_e32 v18, 0xbfb8aa3b, v21
	v_exp_f32_e32 v18, v18
	s_nop 0
	v_add_f32_e32 v18, 1.0, v18
	v_rcp_f32_e32 v33, v18
	global_load_dwordx4 v[18:21], v[38:39], off offset:192
	s_waitcnt vmcnt(0)
; DI float bflo(unsigned u) { return __uint_as_float(u << 16); }
; DI float bfhi(unsigned u) { return __uint_as_float(u & 0xffff0000u); }
; DI float sigmoidf(float x) { return __builtin_amdgcn_rcpf(1.f + __expf(-x)); }
; template <class E>
; DI void gemm8_epi(f32x4 (&acc)[8][4], int m0, int n0, E e) {
;     ...
; #pragma unroll
;   for (int i = 0; i < 8; ++i)
; #pragma unroll
;     for (int j = 0; j < 4; ++j) {
;       const int m = m0 + wm * 128 + i * 16 + (lane & 15);
;       const int n = n0 + wn * 64 + j * 16 + (lane >> 4) * 4;
;       e(m, n, acc[i][j]);
;     }
; __global__ void __launch_bounds__(512, 2) mega(Params p) {
;     ...
;       gemm8_epi(acc8, m0, n0, [&](int m, int n, f32x4& a) {
;         uint2 pv = *(const uint2*)(ppb + (size_t)m * DM + n);
;         float4* o = (float4*)(p.out + (size_t)m * DM + n);
;         float4 xv = *o;
;         *o = make_float4(xv.x + sigmoidf(a[0]) * bflo(pv.x), xv.y + sigmoidf(a[1]) * bfhi(pv.x),
;                          xv.z + sigmoidf(a[2]) * bflo(pv.y), xv.w + sigmoidf(a[3]) * bfhi(pv.y));
;       });
	v_pk_fma_f32 v[18:19], v[26:27], v[30:31], v[18:19]
	v_pk_fma_f32 v[20:21], v[32:33], v[24:25], v[20:21]
	global_store_dwordx4 v[38:39], v[18:21], off offset:192 nt
	s_nop 1
	v_or_b32_e32 v18, 0x70, v28
	v_ashrrev_i32_e32 v19, 31, v18
	v_lshlrev_b64 v[20:21], 11, v[18:19]
	v_lshl_add_u64 v[20:21], s[12:13], 0, v[20:21]
	v_lshl_add_u64 v[20:21], v[20:21], 0, v[0:1]
	v_mul_f32_e32 v0, 0xbfb8aa3b, v14
	v_exp_f32_e32 v0, v0
	v_lshlrev_b64 v[18:19], 12, v[18:19]
	v_lshl_add_u64 v[18:19], s[2:3], 0, v[18:19]
	v_lshl_add_u64 v[18:19], v[18:19], 0, v[22:23]
	v_add_f32_e32 v0, 1.0, v0
	v_rcp_f32_e32 v22, v0
	v_mul_f32_e32 v0, 0xbfb8aa3b, v15
	v_exp_f32_e32 v0, v0
	global_load_dwordx2 v[24:25], v[20:21], off
	v_add_f32_e32 v0, 1.0, v0
	v_rcp_f32_e32 v23, v0
	v_mul_f32_e32 v0, 0xbfb8aa3b, v16
	v_exp_f32_e32 v0, v0
	s_waitcnt vmcnt(0)
	v_lshlrev_b32_e32 v26, 16, v24
	v_add_f32_e32 v0, 1.0, v0
	v_rcp_f32_e32 v28, v0
	v_mul_f32_e32 v0, 0xbfb8aa3b, v17
	global_load_dwordx4 v[14:17], v[18:19], off
	v_exp_f32_e32 v0, v0
	v_and_b32_e32 v27, 0xffff0000, v24
	v_lshlrev_b32_e32 v24, 16, v25
	v_and_b32_e32 v25, 0xffff0000, v25
	v_add_f32_e32 v0, 1.0, v0
	v_rcp_f32_e32 v29, v0
	v_mul_f32_e32 v0, 0xbfb8aa3b, v10
	v_exp_f32_e32 v0, v0
	s_waitcnt vmcnt(0)
	v_pk_fma_f32 v[14:15], v[22:23], v[26:27], v[14:15]
	v_pk_fma_f32 v[16:17], v[28:29], v[24:25], v[16:17]
	global_store_dwordx4 v[18:19], v[14:17], off nt
	global_load_dwordx2 v[16:17], v[20:21], off offset:32
	v_add_f32_e32 v0, 1.0, v0
	global_load_dwordx4 v[22:25], v[18:19], off offset:64
	v_rcp_f32_e32 v10, v0
	v_mul_f32_e32 v0, 0xbfb8aa3b, v11
	v_exp_f32_e32 v0, v0
	s_waitcnt vmcnt(1)
	v_lshlrev_b32_e32 v14, 16, v16
	v_add_f32_e32 v0, 1.0, v0
	v_rcp_f32_e32 v11, v0
	v_mul_f32_e32 v0, 0xbfb8aa3b, v12
	v_exp_f32_e32 v0, v0
	v_and_b32_e32 v15, 0xffff0000, v16
	v_lshlrev_b32_e32 v16, 16, v17
	v_and_b32_e32 v17, 0xffff0000, v17
	v_add_f32_e32 v0, 1.0, v0
	v_rcp_f32_e32 v12, v0
	v_mul_f32_e32 v0, 0xbfb8aa3b, v13
	v_exp_f32_e32 v0, v0
	s_waitcnt vmcnt(0)
	v_pk_fma_f32 v[10:11], v[10:11], v[14:15], v[22:23]
	v_add_f32_e32 v0, 1.0, v0
	v_rcp_f32_e32 v13, v0
	v_mul_f32_e32 v0, 0xbfb8aa3b, v6
	v_exp_f32_e32 v0, v0
	v_pk_fma_f32 v[12:13], v[12:13], v[16:17], v[24:25]
	global_store_dwordx4 v[18:19], v[10:13], off offset:64 nt
	v_add_f32_e32 v0, 1.0, v0
	global_load_dwordx2 v[10:11], v[20:21], off offset:64
	v_rcp_f32_e32 v12, v0
	v_mul_f32_e32 v0, 0xbfb8aa3b, v7
	v_exp_f32_e32 v0, v0
	s_waitcnt vmcnt(0)
	v_lshlrev_b32_e32 v14, 16, v10
	v_add_f32_e32 v0, 1.0, v0
	v_rcp_f32_e32 v13, v0
	v_mul_f32_e32 v0, 0xbfb8aa3b, v8
	v_exp_f32_e32 v0, v0
	v_and_b32_e32 v15, 0xffff0000, v10
	v_lshlrev_b32_e32 v10, 16, v11
	v_and_b32_e32 v11, 0xffff0000, v11
	v_add_f32_e32 v0, 1.0, v0
	v_rcp_f32_e32 v16, v0
	v_mul_f32_e32 v0, 0xbfb8aa3b, v9
	global_load_dwordx4 v[6:9], v[18:19], off offset:128
	v_exp_f32_e32 v0, v0
	s_waitcnt vmcnt(0)
	v_pk_fma_f32 v[6:7], v[12:13], v[14:15], v[6:7]
	v_add_f32_e32 v0, 1.0, v0
	v_rcp_f32_e32 v17, v0
	v_mul_f32_e32 v0, 0xbfb8aa3b, v2
	v_exp_f32_e32 v0, v0
	v_pk_fma_f32 v[8:9], v[16:17], v[10:11], v[8:9]
	global_store_dwordx4 v[18:19], v[6:9], off offset:128 nt
	v_add_f32_e32 v0, 1.0, v0
	global_load_dwordx2 v[6:7], v[20:21], off offset:96
	v_rcp_f32_e32 v8, v0
	v_mul_f32_e32 v0, 0xbfb8aa3b, v3
	v_exp_f32_e32 v0, v0
	s_waitcnt vmcnt(0)
	v_lshlrev_b32_e32 v10, 16, v6
	v_add_f32_e32 v0, 1.0, v0
	v_rcp_f32_e32 v9, v0
	v_mul_f32_e32 v0, 0xbfb8aa3b, v4
	v_exp_f32_e32 v0, v0
	v_and_b32_e32 v11, 0xffff0000, v6
	v_lshlrev_b32_e32 v6, 16, v7
	v_and_b32_e32 v7, 0xffff0000, v7
	v_add_f32_e32 v0, 1.0, v0
	v_rcp_f32_e32 v12, v0
	v_mul_f32_e32 v0, 0xbfb8aa3b, v5
	global_load_dwordx4 v[2:5], v[18:19], off offset:192
	v_exp_f32_e32 v0, v0
	s_waitcnt vmcnt(0)
	v_pk_fma_f32 v[2:3], v[8:9], v[10:11], v[2:3]
	v_add_f32_e32 v0, 1.0, v0
	v_rcp_f32_e32 v13, v0
	s_nop 0
	v_pk_fma_f32 v[4:5], v[12:13], v[6:7], v[4:5]
	global_store_dwordx4 v[18:19], v[2:5], off offset:192 nt
	s_cbranch_vccnz .LBB0_998
